# v24: attention softmax max-reductions: 632 canonicalising v_max x,x dropped (consumer max reads the score directly; slots near MFMA/trans kept as s_nop)
# baseline (speedup 1.0000x reference)
; #define LAS __attribute__((address_space(3)))
; #define LAS __attribute__((address_space(3)))
; template <bool DO_SWA, bool DO_MEM>
; __device__ __forceinline__ void attn_unit(const Args& a, unsigned char* ws, LAS unsigned char* lds, int l, int tid_in, int lane_in, int wave, int unit) {
;     ...
;         if constexpr (DO_MEM)
; #pragma unroll
;         for (int hp = 0; hp < 2; ++hp) { const bf16* qp = UB + qrow * UBW + 1152 + (hp * 2 + g) * 64 + fq * 8; qmm[hp][0] = __builtin_nontemporal_load((const bf16x8*)qp); qmm[hp][1] = __builtin_nontemporal_load((const bf16x8*)(qp + 32)); }
;     ...
;         if constexpr (DO_MEM) {
; #pragma unroll
;             for (int i = 0; i < 8; ++i) {
;                 const int chn = tid + 512 * i;
;                 mkst[i] = DO_SWA ? *(const v4u*)(MKb + (size_t)(chn >> 4) * 256 + (chn & 15) * 8) : __builtin_nontemporal_load((const v4u*)(MKb + (size_t)(chn >> 4) * 256 + (chn & 15) * 8));
;                 mvst[i] = DO_SWA ? *(const v4u*)(MVTb + (size_t)(chn >> 5) * 256 + (chn & 31) * 8) : __builtin_nontemporal_load((const v4u*)(MVTb + (size_t)(chn >> 5) * 256 + (chn & 31) * 8));
;             }
;         }
;         __syncthreads();
;         if constexpr (DO_MEM)
; #pragma unroll
;         for (int i = 0; i < 8; ++i) {
;             const int chn = tid + 512 * i;
;             { const int key = chn >> 4, c16 = chn & 15; *(LAS v4u*)(lds + A_KS + ((c16 >> 3) * 256 + key) * 144 + (c16 & 7) * 16) = mkst[i]; }
;             { const int col = chn >> 5, kc = chn & 31; *(LAS v4u*)(lds + A_VT2 + col * 528 + kc * 16) = mvst[i]; }
.LBB0_257:
	s_cmpk_gt_i32 s94, 0xff
	s_mov_b64 s[0:1], -1
	s_cbranch_scc0 .LBB0_275
	s_cmpk_gt_u32 s94, 0x11f
	s_cbranch_scc0 .LBB0_262
	v_mov_b32_e32 v142, v216
	v_and_b32_e32 v175, 63, v216
	v_readlane_b32 s0, v251, 21
	s_add_i32 s0, s0, s93
	v_and_b32_e32 v141, 15, v175
	v_add_u32_e32 v0, s0, v141
	v_add_u32_e32 v140, 0xfffff7fd, v0
	v_mov_b32_e32 v0, v185
	v_ashrrev_i32_e32 v174, 4, v175
	s_movk_i32 s0, 0xb00
	v_mov_b64_e32 v[0:1], s[48:49]
	v_lshlrev_b32_e32 v2, 3, v174
	v_mad_u64_u32 v[0:1], s[0:1], v140, s0, v[0:1]
	v_ashrrev_i32_e32 v3, 31, v2
	v_readlane_b32 s6, v251, 22
	v_lshl_add_u64 v[0:1], v[2:3], 1, v[0:1]
	s_lshl_b32 s34, s6, 1
	v_lshl_add_u64 v[0:1], v[0:1], 0, s[34:35]
	s_mov_b64 s[0:1], 0xbd00900
	v_lshl_add_u64 v[2:3], v[0:1], 0, s[0:1]
	s_mov_b32 s0, 0xbd00000
	v_add_co_u32_e32 v0, vcc, s0, v0
	s_nop 1
	v_addc_co_u32_e32 v1, vcc, 0, v1, vcc
	global_load_dwordx4 v[72:75], v[2:3], off offset:64 nt
	global_load_dwordx4 v[4:7], v[2:3], off offset:256 nt
	global_load_dwordx4 v[76:79], v[0:1], off offset:2304 nt
	s_nop 0
	global_load_dwordx4 v[0:3], v[2:3], off offset:320 nt
	s_add_i32 s0, s40, s94
	s_ashr_i32 s1, s0, 31
	s_lshl_b64 s[2:3], s[0:1], 17
	s_add_u32 s0, s7, s2
	s_addc_u32 s1, s24, s3
	s_add_u32 s2, s26, s2
	s_addc_u32 s3, s27, s3
	v_lshlrev_b32_e32 v143, 4, v142
	v_and_b32_e32 v14, 0x1f0, v143
	v_mov_b32_e32 v15, v185
	v_lshl_add_u64 v[18:19], s[2:3], 0, v[14:15]
	v_add_u32_e32 v15, 0x200, v142
	v_ashrrev_i32_e32 v30, 4, v15
	v_ashrrev_i32_e32 v34, 5, v15
	v_add_u32_e32 v15, 0x400, v142
	v_ashrrev_i32_e32 v38, 4, v15
	v_ashrrev_i32_e32 v42, 5, v15
	v_add_u32_e32 v15, 0x600, v142
	v_ashrrev_i32_e32 v46, 4, v15
	v_ashrrev_i32_e32 v50, 5, v15
	v_add_u32_e32 v15, 0x800, v142
	v_ashrrev_i32_e32 v54, 4, v15
	v_ashrrev_i32_e32 v58, 5, v15
	v_add_u32_e32 v15, 0xa00, v142
	v_ashrrev_i32_e32 v62, 4, v15
	v_ashrrev_i32_e32 v66, 5, v15
	v_add_u32_e32 v15, 0xc00, v142
	v_ashrrev_i32_e32 v70, 4, v15
	v_ashrrev_i32_e32 v168, 5, v15
	v_add_u32_e32 v15, 0xe00, v142
	v_ashrrev_i32_e32 v22, 4, v142
	v_ashrrev_i32_e32 v170, 4, v15
	v_and_b32_e32 v184, 0xf0, v143
	v_ashrrev_i32_e32 v23, 31, v22
	v_ashrrev_i32_e32 v31, 31, v30
	v_ashrrev_i32_e32 v39, 31, v38
	v_ashrrev_i32_e32 v47, 31, v46
	v_ashrrev_i32_e32 v55, 31, v54
	v_ashrrev_i32_e32 v63, 31, v62
	v_ashrrev_i32_e32 v71, 31, v70
	v_ashrrev_i32_e32 v171, 31, v170
	v_lshl_add_u64 v[10:11], s[0:1], 0, v[184:185]
	v_lshlrev_b64 v[8:9], 9, v[22:23]
	v_ashrrev_i32_e32 v26, 5, v142
	v_lshlrev_b64 v[16:17], 9, v[30:31]
	v_lshlrev_b64 v[24:25], 9, v[38:39]
	v_lshlrev_b64 v[32:33], 9, v[46:47]
	v_lshlrev_b64 v[40:41], 9, v[54:55]
	v_lshlrev_b64 v[48:49], 9, v[62:63]
	v_lshlrev_b64 v[56:57], 9, v[70:71]
	v_lshlrev_b64 v[64:65], 9, v[170:171]
	v_lshl_add_u64 v[12:13], v[10:11], 0, v[8:9]
	v_ashrrev_i32_e32 v27, 31, v26
	v_lshl_add_u64 v[20:21], v[10:11], 0, v[16:17]
	v_lshl_add_u64 v[28:29], v[10:11], 0, v[24:25]
	v_lshl_add_u64 v[36:37], v[10:11], 0, v[32:33]
	v_lshl_add_u64 v[44:45], v[10:11], 0, v[40:41]
	v_lshl_add_u64 v[52:53], v[10:11], 0, v[48:49]
	v_lshl_add_u64 v[60:61], v[10:11], 0, v[56:57]
	v_lshl_add_u64 v[10:11], v[10:11], 0, v[64:65]
	s_waitcnt vmcnt(0)
	s_barrier
	global_load_dwordx4 v[80:83], v[12:13], off nt
	global_load_dwordx4 v[136:139], v[10:11], off nt
	v_lshlrev_b64 v[12:13], 9, v[26:27]
	v_lshl_add_u64 v[12:13], v[18:19], 0, v[12:13]
	v_ashrrev_i32_e32 v35, 31, v34
	global_load_dwordx4 v[84:87], v[12:13], off nt
	global_load_dwordx4 v[88:91], v[20:21], off nt
	v_lshlrev_b64 v[20:21], 9, v[34:35]
	v_lshl_add_u64 v[20:21], v[18:19], 0, v[20:21]
	v_ashrrev_i32_e32 v43, 31, v42
	global_load_dwordx4 v[92:95], v[20:21], off nt
	global_load_dwordx4 v[96:99], v[28:29], off nt
	v_lshlrev_b64 v[28:29], 9, v[42:43]
	v_lshl_add_u64 v[28:29], v[18:19], 0, v[28:29]
	v_ashrrev_i32_e32 v51, 31, v50
	global_load_dwordx4 v[100:103], v[28:29], off nt
	global_load_dwordx4 v[104:107], v[36:37], off nt
	v_lshlrev_b64 v[36:37], 9, v[50:51]
	v_lshl_add_u64 v[36:37], v[18:19], 0, v[36:37]
	v_ashrrev_i32_e32 v59, 31, v58
	global_load_dwordx4 v[108:111], v[36:37], off nt
	global_load_dwordx4 v[112:115], v[44:45], off nt
	v_lshlrev_b64 v[44:45], 9, v[58:59]
	v_lshl_add_u64 v[44:45], v[18:19], 0, v[44:45]
	v_ashrrev_i32_e32 v67, 31, v66
	v_ashrrev_i32_e32 v10, 5, v15
	global_load_dwordx4 v[116:119], v[44:45], off nt
	global_load_dwordx4 v[120:123], v[52:53], off nt
	v_lshlrev_b64 v[52:53], 9, v[66:67]
	v_ashrrev_i32_e32 v11, 31, v10
	v_lshl_add_u64 v[52:53], v[18:19], 0, v[52:53]
	v_ashrrev_i32_e32 v169, 31, v168
	v_lshlrev_b64 v[68:69], 9, v[10:11]
	v_lshlrev_b32_e32 v11, 5, v142
	global_load_dwordx4 v[124:127], v[52:53], off nt
	global_load_dwordx4 v[128:131], v[60:61], off nt
	v_lshlrev_b64 v[60:61], 9, v[168:169]
	v_and_b32_e32 v11, 0x100, v11
	v_and_b32_e32 v15, 0x70, v143
	s_add_i32 s2, 0, 0x12000
	v_lshl_add_u64 v[60:61], v[18:19], 0, v[60:61]
	v_lshl_add_u64 v[68:69], v[18:19], 0, v[68:69]
	v_add_u32_e32 v18, 0, v15
	v_add_u32_e32 v14, s2, v14
	v_add_u32_e32 v15, v11, v22
	s_movk_i32 s3, 0x90
	s_movk_i32 s8, 0x210
	v_mad_u64_u32 v[142:143], s[4:5], v15, s3, v[18:19]
	v_mad_u64_u32 v[144:145], s[4:5], v26, s8, v[14:15]
	v_add_u32_e32 v15, v30, v11
	v_mad_u64_u32 v[146:147], s[4:5], v15, s3, v[18:19]
	v_mad_u64_u32 v[148:149], s[4:5], v34, s8, v[14:15]
	v_add_u32_e32 v15, v38, v11
	v_mad_u64_u32 v[150:151], s[4:5], v15, s3, v[18:19]
	v_mad_u64_u32 v[152:153], s[4:5], v42, s8, v[14:15]
	v_add_u32_e32 v15, v46, v11
	v_mad_u64_u32 v[154:155], s[4:5], v15, s3, v[18:19]
	v_mad_u64_u32 v[156:157], s[4:5], v50, s8, v[14:15]
	v_add_u32_e32 v15, v54, v11
	v_mad_u64_u32 v[158:159], s[4:5], v15, s3, v[18:19]
; #define LAS __attribute__((address_space(3)))
; #define LAS __attribute__((address_space(3)))
; __device__ __forceinline__ f32x4 mfma16(bf16x8 a, bf16x8 b, f32x4 c) { return __builtin_amdgcn_mfma_f32_16x16x32_bf16(a, b, c, 0, 0, 0); }
; template <int NKT, int VSTR, bool SINK>
; __device__ __forceinline__ void attn_core(LAS const unsigned char* kb_, LAS const unsigned char* vb_, bf16x8 q0, bf16x8 q1, float sk, unsigned mskbits, int fr, f32x4 (&o)[4]) {
;     f32x4 S[NKT];
;     const int krow = ((fr >> 2) << 3) + (fr & 3);
; #pragma unroll
;     for (int kt = 0; kt < NKT; ++kt) {
;         const int key = (kt >> 1) * 32 + ((kt & 1) << 2) + krow;
;         LAS const unsigned char* kp = kb_ + key * 144;
;         const bf16x8 a0 = *(LAS const bf16x8*)kp, a1 = *(LAS const bf16x8*)(kp + 64);
;         const float bias = ((mskbits >> (kt >> 2)) & 1u) ? -1e30f : 0.f;
;         f32x4 s = mfma16(a0, q0, (f32x4){bias, bias, bias, bias});
;         s = mfma16(a1, q1, s);
;         S[kt] = s;
; template <bool DO_SWA, bool DO_MEM>
; __device__ __forceinline__ void attn_unit(const Args& a, unsigned char* ws, LAS unsigned char* lds, int l, int tid_in, int lane_in, int wave, int unit) {
;     ...
;         if constexpr (DO_MEM)
; #pragma unroll
;         for (int i = 0; i < 8; ++i) {
;             const int chn = tid + 512 * i;
;             { const int key = chn >> 4, c16 = chn & 15; *(LAS v4u*)(lds + A_KS + ((c16 >> 3) * 256 + key) * 144 + (c16 & 7) * 16) = mkst[i]; }
;             { const int col = chn >> 5, kc = chn & 31; *(LAS v4u*)(lds + A_VT2 + col * 528 + kc * 16) = mvst[i]; }
;         }
;         if constexpr (DO_MEM)
; #pragma unroll
;         for (int i = 0; i < 8; ++i) {
;             const int chn = tid + 512 * i;
;             mkst[i] = DO_SWA ? *(const v4u*)(MKb + (size_t)(chn >> 4) * 256 + 128 + (chn & 15) * 8) : __builtin_nontemporal_load((const v4u*)(MKb + (size_t)(chn >> 4) * 256 + 128 + (chn & 15) * 8));
;             mvst[i] = DO_SWA ? *(const v4u*)(MVTb + (size_t)(128 + (chn >> 5)) * 256 + (chn & 31) * 8) : __builtin_nontemporal_load((const v4u*)(MVTb + (size_t)(128 + (chn >> 5)) * 256 + (chn & 31) * 8));
;         }
	v_mad_u64_u32 v[160:161], s[4:5], v58, s8, v[14:15]
	v_add_u32_e32 v15, v62, v11
	v_mad_u64_u32 v[162:163], s[4:5], v15, s3, v[18:19]
	v_mad_u64_u32 v[164:165], s[4:5], v66, s8, v[14:15]
	v_add_u32_e32 v15, v70, v11
	v_add_u32_e32 v11, v170, v11
	v_mad_u64_u32 v[166:167], s[4:5], v15, s3, v[18:19]
	v_mad_u64_u32 v[170:171], s[4:5], v11, s3, v[18:19]
	s_mov_b32 s3, 0x10000
	v_add_co_u32_e32 v12, vcc, s3, v12
	global_load_dwordx4 v[132:135], v[60:61], off nt
	global_load_dwordx4 v[176:179], v[68:69], off nt
	v_addc_co_u32_e32 v13, vcc, 0, v13, vcc
	v_add_co_u32_e32 v20, vcc, s3, v20
	v_lshl_add_u64 v[32:33], s[0:1], 0, v[32:33]
	s_nop 0
	v_addc_co_u32_e32 v21, vcc, 0, v21, vcc
	v_add_co_u32_e32 v28, vcc, s3, v28
	v_lshl_add_u64 v[40:41], s[0:1], 0, v[40:41]
	s_nop 0
	v_addc_co_u32_e32 v29, vcc, 0, v29, vcc
	v_add_co_u32_e32 v36, vcc, s3, v36
	v_lshl_add_u64 v[8:9], s[0:1], 0, v[8:9]
	s_nop 0
	v_addc_co_u32_e32 v37, vcc, 0, v37, vcc
	v_add_co_u32_e32 v44, vcc, s3, v44
	v_lshl_add_u64 v[16:17], s[0:1], 0, v[16:17]
	s_nop 0
	v_addc_co_u32_e32 v45, vcc, 0, v45, vcc
	v_add_co_u32_e32 v52, vcc, s3, v52
	v_lshl_add_u64 v[24:25], s[0:1], 0, v[24:25]
	s_nop 0
	v_addc_co_u32_e32 v53, vcc, 0, v53, vcc
	v_add_co_u32_e32 v60, vcc, s3, v60
	v_lshl_add_u64 v[32:33], v[32:33], 0, v[184:185]
	s_nop 0
	v_addc_co_u32_e32 v61, vcc, 0, v61, vcc
	v_lshl_add_u64 v[40:41], v[40:41], 0, v[184:185]
	v_lshl_add_u64 v[48:49], s[0:1], 0, v[48:49]
	v_lshl_add_u64 v[56:57], s[0:1], 0, v[56:57]
	v_lshl_add_u64 v[64:65], s[0:1], 0, v[64:65]
	v_add_co_u32_e32 v68, vcc, s3, v68
	s_barrier
	v_lshl_add_u64 v[8:9], v[8:9], 0, v[184:185]
	v_lshl_add_u64 v[16:17], v[16:17], 0, v[184:185]
	v_lshl_add_u64 v[24:25], v[24:25], 0, v[184:185]
	global_load_dwordx4 v[32:35], v[32:33], off offset:256 nt
	v_lshl_add_u64 v[48:49], v[48:49], 0, v[184:185]
	global_load_dwordx4 v[36:39], v[36:37], off nt
	v_lshl_add_u64 v[56:57], v[56:57], 0, v[184:185]
	global_load_dwordx4 v[40:43], v[40:41], off offset:256 nt
	v_lshl_add_u64 v[64:65], v[64:65], 0, v[184:185]
	global_load_dwordx4 v[44:47], v[44:45], off nt
	v_addc_co_u32_e32 v69, vcc, 0, v69, vcc
	v_mad_u64_u32 v[168:169], s[4:5], v168, s8, v[14:15]
	v_mad_u64_u32 v[172:173], s[4:5], v10, s8, v[14:15]
	global_load_dwordx4 v[8:11], v[8:9], off offset:256 nt
	s_waitcnt vmcnt(20)
	ds_write_b128 v142, v[80:83]
	global_load_dwordx4 v[12:15], v[12:13], off nt
	s_waitcnt vmcnt(19)
	ds_write_b128 v144, v[84:87]
	global_load_dwordx4 v[16:19], v[16:17], off offset:256 nt
	s_waitcnt vmcnt(19)
	ds_write_b128 v146, v[88:91]
	global_load_dwordx4 v[20:23], v[20:21], off nt
	s_waitcnt vmcnt(19)
	ds_write_b128 v148, v[92:95]
	global_load_dwordx4 v[24:27], v[24:25], off offset:256 nt
	s_waitcnt vmcnt(19)
	ds_write_b128 v150, v[96:99]
	global_load_dwordx4 v[28:31], v[28:29], off nt
	s_waitcnt vmcnt(19)
	ds_write_b128 v152, v[100:103]
	global_load_dwordx4 v[48:51], v[48:49], off offset:256 nt
	s_waitcnt vmcnt(19)
	ds_write_b128 v154, v[104:107]
	global_load_dwordx4 v[52:55], v[52:53], off nt
	s_waitcnt vmcnt(19)
	ds_write_b128 v156, v[108:111]
	global_load_dwordx4 v[56:59], v[56:57], off offset:256 nt
	s_waitcnt vmcnt(19)
	ds_write_b128 v158, v[112:115]
	global_load_dwordx4 v[60:63], v[60:61], off nt
	s_waitcnt vmcnt(19)
	ds_write_b128 v160, v[116:119]
	global_load_dwordx4 v[64:67], v[64:65], off offset:256 nt
	s_waitcnt vmcnt(19)
	ds_write_b128 v162, v[120:123]
	global_load_dwordx4 v[68:71], v[68:69], off nt
	s_waitcnt vmcnt(19)
	ds_write_b128 v164, v[124:127]
	s_waitcnt vmcnt(18)
	ds_write_b128 v166, v[128:131]
	s_waitcnt vmcnt(17)
	ds_write_b128 v168, v[132:135]
	ds_write_b128 v170, v[136:139]
	s_waitcnt vmcnt(16)
	ds_write_b128 v172, v[176:179]
	v_or_b32_e32 v81, s6, v141
	v_and_b32_e32 v80, -16, v175
	v_mul_lo_u32 v81, v81, s8
	v_add3_u32 v143, s2, v81, v80
	v_lshlrev_b32_e32 v81, 1, v175
	v_and_b32_e32 v82, 3, v175
	v_and_or_b32 v81, v81, 24, v82
	v_mul_u32_u24_e32 v81, 0x90, v81
	v_readlane_b32 s0, v251, 23
	s_waitcnt lgkmcnt(0)
	s_barrier
	v_add3_u32 v149, s0, v80, v81
	s_waitcnt lgkmcnt(0)
	ds_read_b128 v[196:199], v149
	ds_read_b128 v[200:203], v149 offset:64
	ds_read_b128 v[204:207], v149 offset:576
	ds_read_b128 v[208:211], v149 offset:640
	ds_read_b128 v[212:215], v149 offset:4608
	ds_read_b128 v[228:231], v149 offset:4672
	ds_read_b128 v[232:235], v149 offset:5184
	ds_read_b128 v[236:239], v149 offset:5248
	ds_read_b128 v[240:243], v149 offset:9216
	ds_read_b128 v[244:247], v149 offset:9280
	s_waitcnt lgkmcnt(9)
	v_mfma_f32_16x16x32_bf16 v[80:83], v[196:199], v[76:79], 0
	s_waitcnt lgkmcnt(8)
	v_mfma_f32_16x16x32_bf16 v[136:139], v[200:203], v[72:75], v[80:83]
	ds_read_b128 v[196:199], v149 offset:9792
	ds_read_b128 v[200:203], v149 offset:9856
	s_waitcnt lgkmcnt(9)
	v_mfma_f32_16x16x32_bf16 v[80:83], v[204:207], v[76:79], 0
	s_waitcnt lgkmcnt(8)
	v_mfma_f32_16x16x32_bf16 v[132:135], v[208:211], v[72:75], v[80:83]
	ds_read_b128 v[204:207], v149 offset:13824
	ds_read_b128 v[208:211], v149 offset:13888
	s_waitcnt lgkmcnt(9)
	v_mfma_f32_16x16x32_bf16 v[80:83], v[212:215], v[76:79], 0
	s_waitcnt lgkmcnt(8)
	v_mfma_f32_16x16x32_bf16 v[128:131], v[228:231], v[72:75], v[80:83]
	ds_read_b128 v[212:215], v149 offset:14400
	ds_read_b128 v[228:231], v149 offset:14464
	s_waitcnt lgkmcnt(9)
	v_mfma_f32_16x16x32_bf16 v[80:83], v[232:235], v[76:79], 0
	s_waitcnt lgkmcnt(8)
	v_mfma_f32_16x16x32_bf16 v[124:127], v[236:239], v[72:75], v[80:83]
	ds_read_b128 v[232:235], v149 offset:18432
	ds_read_b128 v[236:239], v149 offset:18496
	s_waitcnt lgkmcnt(9)
	v_mfma_f32_16x16x32_bf16 v[80:83], v[240:243], v[76:79], 0
	s_waitcnt lgkmcnt(8)
; #define LAS __attribute__((address_space(3)))
; #define LAS __attribute__((address_space(3)))
; __device__ __forceinline__ f32x4 mfma16(bf16x8 a, bf16x8 b, f32x4 c) { return __builtin_amdgcn_mfma_f32_16x16x32_bf16(a, b, c, 0, 0, 0); }
; template <int NKT, int VSTR, bool SINK>
; __device__ __forceinline__ void attn_core(LAS const unsigned char* kb_, LAS const unsigned char* vb_, bf16x8 q0, bf16x8 q1, float sk, unsigned mskbits, int fr, f32x4 (&o)[4]) {
;     ...
;     for (int kt = 0; kt < NKT; ++kt) {
;         const int key = (kt >> 1) * 32 + ((kt & 1) << 2) + krow;
;         LAS const unsigned char* kp = kb_ + key * 144;
;         const bf16x8 a0 = *(LAS const bf16x8*)kp, a1 = *(LAS const bf16x8*)(kp + 64);
;         const float bias = ((mskbits >> (kt >> 2)) & 1u) ? -1e30f : 0.f;
;         f32x4 s = mfma16(a0, q0, (f32x4){bias, bias, bias, bias});
;         s = mfma16(a1, q1, s);
;         S[kt] = s;
;     }
;     float mx = S[0][0];
; #pragma unroll
;     for (int kt = 0; kt < NKT; ++kt) mx = fmaxf(fmaxf(mx, fmaxf(S[kt][0], S[kt][1])), fmaxf(S[kt][2], S[kt][3]));
;     mx = fmaxf(mx, __shfl_xor(mx, 16)); mx = fmaxf(mx, __shfl_xor(mx, 32));
	v_mfma_f32_16x16x32_bf16 v[120:123], v[244:247], v[72:75], v[80:83]
	ds_read_b128 v[240:243], v149 offset:19008
	ds_read_b128 v[244:247], v149 offset:19072
	s_waitcnt lgkmcnt(9)
	v_mfma_f32_16x16x32_bf16 v[80:83], v[196:199], v[76:79], 0
	s_waitcnt lgkmcnt(8)
	v_mfma_f32_16x16x32_bf16 v[116:119], v[200:203], v[72:75], v[80:83]
	ds_read_b128 v[196:199], v149 offset:23040
	ds_read_b128 v[200:203], v149 offset:23104
	s_waitcnt lgkmcnt(9)
	v_mfma_f32_16x16x32_bf16 v[80:83], v[204:207], v[76:79], 0
	s_waitcnt lgkmcnt(8)
	v_mfma_f32_16x16x32_bf16 v[112:115], v[208:211], v[72:75], v[80:83]
	ds_read_b128 v[204:207], v149 offset:23616
	ds_read_b128 v[208:211], v149 offset:23680
	s_waitcnt lgkmcnt(9)
	v_mfma_f32_16x16x32_bf16 v[80:83], v[212:215], v[76:79], 0
	s_waitcnt lgkmcnt(8)
	v_mfma_f32_16x16x32_bf16 v[108:111], v[228:231], v[72:75], v[80:83]
	ds_read_b128 v[212:215], v149 offset:27648
	ds_read_b128 v[228:231], v149 offset:27712
	s_waitcnt lgkmcnt(9)
	v_mfma_f32_16x16x32_bf16 v[80:83], v[232:235], v[76:79], 0
	s_waitcnt lgkmcnt(8)
	v_mfma_f32_16x16x32_bf16 v[104:107], v[236:239], v[72:75], v[80:83]
	ds_read_b128 v[232:235], v149 offset:28224
	ds_read_b128 v[236:239], v149 offset:28288
	s_waitcnt lgkmcnt(9)
	v_mfma_f32_16x16x32_bf16 v[80:83], v[240:243], v[76:79], 0
	s_waitcnt lgkmcnt(8)
	v_mfma_f32_16x16x32_bf16 v[100:103], v[244:247], v[72:75], v[80:83]
	ds_read_b128 v[240:243], v149 offset:32256
	ds_read_b128 v[244:247], v149 offset:32320
	s_waitcnt lgkmcnt(9)
	v_mfma_f32_16x16x32_bf16 v[80:83], v[196:199], v[76:79], 0
	s_waitcnt lgkmcnt(8)
	v_mfma_f32_16x16x32_bf16 v[96:99], v[200:203], v[72:75], v[80:83]
	ds_read_b128 v[196:199], v149 offset:32832
	ds_read_b128 v[200:203], v149 offset:32896
	s_waitcnt lgkmcnt(9)
	v_mfma_f32_16x16x32_bf16 v[80:83], v[204:207], v[76:79], 0
	s_waitcnt lgkmcnt(8)
	v_mfma_f32_16x16x32_bf16 v[92:95], v[208:211], v[72:75], v[80:83]
	s_waitcnt lgkmcnt(7)
	v_mfma_f32_16x16x32_bf16 v[80:83], v[212:215], v[76:79], 0
	s_waitcnt lgkmcnt(6)
	v_mfma_f32_16x16x32_bf16 v[88:91], v[228:231], v[72:75], v[80:83]
	s_waitcnt lgkmcnt(5)
	v_mfma_f32_16x16x32_bf16 v[80:83], v[232:235], v[76:79], 0
	s_waitcnt lgkmcnt(4)
	v_mfma_f32_16x16x32_bf16 v[84:87], v[236:239], v[72:75], v[80:83]
	s_waitcnt lgkmcnt(3)
	v_mfma_f32_16x16x32_bf16 v[80:83], v[240:243], v[76:79], 0
	s_waitcnt lgkmcnt(2)
	v_mfma_f32_16x16x32_bf16 v[80:83], v[244:247], v[72:75], v[80:83]
	s_waitcnt lgkmcnt(1)
	v_mfma_f32_16x16x32_bf16 v[76:79], v[196:199], v[76:79], 0
	s_waitcnt lgkmcnt(0)
	v_mfma_f32_16x16x32_bf16 v[72:75], v[200:203], v[72:75], v[76:79]
	s_nop 5
	s_nop 0
	s_nop 0
	v_max_f32_e32 v76, v138, v139
	s_nop 0
	s_nop 0
	v_max_f32_e32 v77, v132, v133
	s_nop 0
	s_nop 0
	v_max3_f32 v76, v136, v137, v76
	v_max_f32_e32 v78, v134, v135
	v_max3_f32 v76, v76, v77, v78
	s_nop 0
	s_nop 0
	v_max_f32_e32 v77, v128, v129
	s_nop 0
	s_nop 0
	v_max_f32_e32 v78, v130, v131
	v_max3_f32 v76, v76, v77, v78
	s_nop 0
	s_nop 0
	v_max_f32_e32 v77, v124, v125
	s_nop 0
	s_nop 0
	v_max_f32_e32 v78, v126, v127
	v_max3_f32 v76, v76, v77, v78
	v_max_f32_e32 v77, v120, v121
	v_max_f32_e32 v78, v122, v123
	v_max3_f32 v76, v76, v77, v78
	v_max_f32_e32 v77, v116, v117
	v_max_f32_e32 v78, v118, v119
	v_max3_f32 v76, v76, v77, v78
	v_max_f32_e32 v77, v112, v113
	v_max_f32_e32 v78, v114, v115
	v_max3_f32 v76, v76, v77, v78
	v_max_f32_e32 v77, v108, v109
	v_max_f32_e32 v78, v110, v111
	v_max3_f32 v76, v76, v77, v78
	v_max_f32_e32 v77, v104, v105
	v_max_f32_e32 v78, v106, v107
	v_max3_f32 v76, v76, v77, v78
	v_max_f32_e32 v77, v100, v101
	v_max_f32_e32 v78, v102, v103
	v_max3_f32 v76, v76, v77, v78
	v_max_f32_e32 v77, v96, v97
	v_max_f32_e32 v78, v98, v99
	v_max3_f32 v76, v76, v77, v78
	v_max_f32_e32 v77, v92, v93
	v_max_f32_e32 v78, v94, v95
	v_max3_f32 v76, v76, v77, v78
	v_max_f32_e32 v77, v88, v89
	v_max_f32_e32 v78, v90, v91
	v_max3_f32 v76, v76, v77, v78
	v_max_f32_e32 v77, v84, v85
	v_max_f32_e32 v78, v86, v87
	v_max3_f32 v76, v76, v77, v78
	v_max_f32_e32 v77, v80, v81
	v_max_f32_e32 v78, v82, v83
	v_max3_f32 v76, v76, v77, v78
	v_max_f32_e32 v77, v72, v73
	v_max_f32_e32 v78, v74, v75
	v_max3_f32 v76, v76, v77, v78
	v_and_b32_e32 v78, 64, v222
	v_xor_b32_e32 v77, 16, v222
	v_add_u32_e32 v78, 64, v78
	v_cmp_lt_i32_e32 vcc, v77, v78
	s_nop 1
	v_cndmask_b32_e32 v77, v222, v77, vcc
	v_lshlrev_b32_e32 v145, 2, v77
	ds_bpermute_b32 v77, v145, v76
	s_waitcnt lgkmcnt(0)
	s_nop 0
	v_max_f32_e32 v76, v76, v77
	v_xor_b32_e32 v77, 32, v222
	v_cmp_lt_i32_e32 vcc, v77, v78
	s_nop 1
	v_cndmask_b32_e32 v77, v222, v77, vcc
	v_lshlrev_b32_e32 v147, 2, v77
	ds_bpermute_b32 v77, v147, v76
	s_waitcnt lgkmcnt(0)
; __device__ __forceinline__ unsigned pk2(float lo, float hi) { return pg8::cvt_pk_bf16(lo, hi); }
; template <int NKT, int VSTR, bool SINK>
; __device__ __forceinline__ void attn_core(LAS const unsigned char* kb_, LAS const unsigned char* vb_, bf16x8 q0, bf16x8 q1, float sk, unsigned mskbits, int fr, f32x4 (&o)[4]) {
;     ...
;     mx = fmaxf(mx, __shfl_xor(mx, 16)); mx = fmaxf(mx, __shfl_xor(mx, 32));
;     if (SINK) mx = fmaxf(mx, sk);
;     float sum = 0.f;
; #pragma unroll
;     for (int kt = 0; kt < NKT; ++kt)
; #pragma unroll
;         for (int r = 0; r < 4; ++r) { const float p = __builtin_amdgcn_exp2f(S[kt][r] - mx); S[kt][r] = p; sum += p; }
;     sum += __shfl_xor(sum, 16); sum += __shfl_xor(sum, 32);
;     if (SINK) sum += __builtin_amdgcn_exp2f(sk - mx);
;     const float inv = 1.0f / sum;
;     bf16x8 pf[NKT / 2];
; #pragma unroll
;     for (int kb = 0; kb < NKT / 2; ++kb) {
;         v4u w; w.x = pk2(S[2 * kb][0], S[2 * kb][1]); w.y = pk2(S[2 * kb][2], S[2 * kb][3]); w.z = pk2(S[2 * kb + 1][0], S[2 * kb + 1][1]); w.w = pk2(S[2 * kb + 1][2], S[2 * kb + 1][3]);
	s_nop 0
	v_max_f32_e32 v151, v76, v77
	v_sub_f32_e32 v76, v136, v151
	v_exp_f32_e32 v76, v76
	v_sub_f32_e32 v77, v137, v151
	v_exp_f32_e32 v77, v77
	v_sub_f32_e32 v132, v132, v151
	v_add_f32_e32 v78, 0, v76
	v_exp_f32_e32 v132, v132
	v_add_f32_e32 v79, v77, v78
	v_sub_f32_e32 v78, v138, v151
	v_exp_f32_e32 v78, v78
	v_sub_f32_e32 v133, v133, v151
	v_exp_f32_e32 v133, v133
	v_sub_f32_e32 v134, v134, v151
	v_add_f32_e32 v136, v78, v79
	v_sub_f32_e32 v79, v139, v151
	v_exp_f32_e32 v79, v79
	v_exp_f32_e32 v134, v134
	v_sub_f32_e32 v135, v135, v151
	v_exp_f32_e32 v135, v135
	v_add_f32_e32 v136, v79, v136
	v_sub_f32_e32 v128, v128, v151
	v_add_f32_e32 v136, v132, v136
	v_exp_f32_e32 v128, v128
	v_sub_f32_e32 v129, v129, v151
	v_add_f32_e32 v136, v133, v136
	v_exp_f32_e32 v129, v129
	v_sub_f32_e32 v130, v130, v151
	v_add_f32_e32 v136, v134, v136
	v_exp_f32_e32 v130, v130
	v_sub_f32_e32 v131, v131, v151
	v_add_f32_e32 v136, v135, v136
	v_exp_f32_e32 v131, v131
	v_sub_f32_e32 v124, v124, v151
	v_add_f32_e32 v136, v128, v136
	v_exp_f32_e32 v124, v124
	v_sub_f32_e32 v125, v125, v151
	v_add_f32_e32 v136, v129, v136
	v_exp_f32_e32 v125, v125
	v_sub_f32_e32 v126, v126, v151
	v_add_f32_e32 v136, v130, v136
	v_exp_f32_e32 v126, v126
	v_sub_f32_e32 v127, v127, v151
	v_add_f32_e32 v136, v131, v136
	v_exp_f32_e32 v127, v127
	v_sub_f32_e32 v120, v120, v151
	v_add_f32_e32 v136, v124, v136
	v_exp_f32_e32 v120, v120
	v_sub_f32_e32 v121, v121, v151
	v_add_f32_e32 v136, v125, v136
	v_exp_f32_e32 v121, v121
	v_sub_f32_e32 v122, v122, v151
	v_add_f32_e32 v136, v126, v136
	v_exp_f32_e32 v122, v122
	v_sub_f32_e32 v123, v123, v151
	v_add_f32_e32 v136, v127, v136
	v_exp_f32_e32 v123, v123
	v_sub_f32_e32 v116, v116, v151
	v_add_f32_e32 v136, v120, v136
	v_exp_f32_e32 v116, v116
	v_sub_f32_e32 v117, v117, v151
	v_add_f32_e32 v136, v121, v136
	v_exp_f32_e32 v117, v117
	v_sub_f32_e32 v118, v118, v151
	v_add_f32_e32 v136, v122, v136
	v_exp_f32_e32 v118, v118
	v_sub_f32_e32 v119, v119, v151
	v_add_f32_e32 v136, v123, v136
	v_exp_f32_e32 v119, v119
	v_sub_f32_e32 v112, v112, v151
	v_add_f32_e32 v136, v116, v136
	v_exp_f32_e32 v112, v112
	v_sub_f32_e32 v113, v113, v151
	v_add_f32_e32 v136, v117, v136
	v_exp_f32_e32 v113, v113
	v_sub_f32_e32 v114, v114, v151
	v_add_f32_e32 v136, v118, v136
	v_exp_f32_e32 v114, v114
	v_sub_f32_e32 v115, v115, v151
	v_add_f32_e32 v136, v119, v136
	v_exp_f32_e32 v115, v115
	v_sub_f32_e32 v108, v108, v151
	v_add_f32_e32 v136, v112, v136
	v_exp_f32_e32 v108, v108
	v_sub_f32_e32 v109, v109, v151
	v_add_f32_e32 v136, v113, v136
	v_exp_f32_e32 v109, v109
	v_sub_f32_e32 v110, v110, v151
	v_add_f32_e32 v136, v114, v136
	v_exp_f32_e32 v110, v110
	v_sub_f32_e32 v111, v111, v151
	v_add_f32_e32 v136, v115, v136
	v_exp_f32_e32 v111, v111
	v_sub_f32_e32 v104, v104, v151
	v_add_f32_e32 v136, v108, v136
	v_exp_f32_e32 v104, v104
	v_sub_f32_e32 v105, v105, v151
	v_add_f32_e32 v136, v109, v136
	v_exp_f32_e32 v105, v105
	v_sub_f32_e32 v106, v106, v151
	v_add_f32_e32 v136, v110, v136
	v_exp_f32_e32 v106, v106
	v_sub_f32_e32 v107, v107, v151
	v_add_f32_e32 v136, v111, v136
	v_exp_f32_e32 v107, v107
	v_sub_f32_e32 v100, v100, v151
	v_add_f32_e32 v136, v104, v136
	v_exp_f32_e32 v100, v100
	v_sub_f32_e32 v101, v101, v151
	v_add_f32_e32 v136, v105, v136
	v_exp_f32_e32 v101, v101
	v_sub_f32_e32 v102, v102, v151
	v_add_f32_e32 v136, v106, v136
	v_exp_f32_e32 v102, v102
	v_sub_f32_e32 v103, v103, v151
	v_add_f32_e32 v136, v107, v136
	v_exp_f32_e32 v103, v103
	v_sub_f32_e32 v96, v96, v151
	v_add_f32_e32 v136, v100, v136
	v_exp_f32_e32 v96, v96
	v_sub_f32_e32 v97, v97, v151
	v_add_f32_e32 v136, v101, v136
	v_exp_f32_e32 v97, v97
	v_sub_f32_e32 v98, v98, v151
	v_add_f32_e32 v136, v102, v136
	v_exp_f32_e32 v98, v98
	v_sub_f32_e32 v99, v99, v151
	v_add_f32_e32 v136, v103, v136
	v_exp_f32_e32 v99, v99
	v_sub_f32_e32 v92, v92, v151
	v_add_f32_e32 v136, v96, v136
	v_exp_f32_e32 v137, v92
	v_add_f32_e32 v136, v97, v136
	v_add_f32_e32 v136, v98, v136
	v_add_f32_e32 v136, v99, v136
	v_sub_f32_e32 v93, v93, v151
	v_add_f32_e32 v92, v137, v136
	v_exp_f32_e32 v136, v93
	v_sub_f32_e32 v93, v94, v151
	v_exp_f32_e32 v138, v93
	v_sub_f32_e32 v93, v95, v151
	v_exp_f32_e32 v95, v93
	v_sub_f32_e32 v88, v88, v151
	v_exp_f32_e32 v139, v88
	v_sub_f32_e32 v89, v89, v151
	v_add_f32_e32 v92, v136, v92
	v_exp_f32_e32 v153, v89
	v_sub_f32_e32 v89, v90, v151
	v_add_f32_e32 v92, v138, v92
	v_exp_f32_e32 v155, v89
	v_sub_f32_e32 v89, v91, v151
	v_add_f32_e32 v92, v95, v92
	v_exp_f32_e32 v157, v89
	v_sub_f32_e32 v84, v84, v151
	v_add_f32_e32 v88, v139, v92
	v_exp_f32_e32 v159, v84
	v_sub_f32_e32 v85, v85, v151
	v_add_f32_e32 v88, v153, v88
	v_exp_f32_e32 v161, v85
	v_sub_f32_e32 v85, v86, v151
	v_add_f32_e32 v88, v155, v88
	v_exp_f32_e32 v163, v85
	v_sub_f32_e32 v85, v87, v151
	v_add_f32_e32 v88, v157, v88
	v_exp_f32_e32 v165, v85
	v_sub_f32_e32 v80, v80, v151
	v_add_f32_e32 v84, v159, v88
	v_exp_f32_e32 v167, v80
	v_sub_f32_e32 v81, v81, v151
	v_add_f32_e32 v84, v161, v84
	v_exp_f32_e32 v169, v81
	v_sub_f32_e32 v81, v82, v151
	v_add_f32_e32 v84, v163, v84
	v_exp_f32_e32 v171, v81
	v_sub_f32_e32 v81, v83, v151
	v_add_f32_e32 v84, v165, v84
	v_exp_f32_e32 v173, v81
	v_sub_f32_e32 v72, v72, v151
	v_add_f32_e32 v80, v167, v84
	v_exp_f32_e32 v176, v72
	v_sub_f32_e32 v73, v73, v151
	v_add_f32_e32 v80, v169, v80
	v_exp_f32_e32 v177, v73
	v_sub_f32_e32 v73, v74, v151
	v_add_f32_e32 v80, v171, v80
	v_exp_f32_e32 v178, v73
	v_sub_f32_e32 v73, v75, v151
	v_add_f32_e32 v80, v173, v80
	v_exp_f32_e32 v151, v73
	v_add_f32_e32 v72, v176, v80
	v_add_f32_e32 v72, v177, v72
	v_add_f32_e32 v72, v178, v72
	v_add_f32_e32 v72, v151, v72
	ds_bpermute_b32 v73, v145, v72
	v_cvt_pk_bf16_f32 v84, v76, v77
	v_cvt_pk_bf16_f32 v85, v78, v79
	v_cvt_pk_bf16_f32 v86, v132, v133
	v_cvt_pk_bf16_f32 v87, v134, v135
	s_waitcnt lgkmcnt(0)
; #define LAS __attribute__((address_space(3)))
; #define LAS __attribute__((address_space(3)))
; __device__ __forceinline__ unsigned pk2(float lo, float hi) { return pg8::cvt_pk_bf16(lo, hi); }
; __device__ __forceinline__ f32x4 mfma16(bf16x8 a, bf16x8 b, f32x4 c) { return __builtin_amdgcn_mfma_f32_16x16x32_bf16(a, b, c, 0, 0, 0); }
; template <int NKT, int VSTR, bool SINK>
; __device__ __forceinline__ void attn_core(LAS const unsigned char* kb_, LAS const unsigned char* vb_, bf16x8 q0, bf16x8 q1, float sk, unsigned mskbits, int fr, f32x4 (&o)[4]) {
;     ...
;     sum += __shfl_xor(sum, 16); sum += __shfl_xor(sum, 32);
;     if (SINK) sum += __builtin_amdgcn_exp2f(sk - mx);
;     const float inv = 1.0f / sum;
;     bf16x8 pf[NKT / 2];
; #pragma unroll
;     for (int kb = 0; kb < NKT / 2; ++kb) {
;         v4u w; w.x = pk2(S[2 * kb][0], S[2 * kb][1]); w.y = pk2(S[2 * kb][2], S[2 * kb][3]); w.z = pk2(S[2 * kb + 1][0], S[2 * kb + 1][1]); w.w = pk2(S[2 * kb + 1][2], S[2 * kb + 1][3]);
;         pf[kb] = __builtin_bit_cast(bf16x8, w);
;     }
; #pragma unroll
;     for (int dt = 0; dt < 4; ++dt) {
;         f32x4 acc = (f32x4){0.f, 0.f, 0.f, 0.f};
; #pragma unroll
;         for (int kb = 0; kb < NKT / 2; ++kb) {
;             const bf16x8 vf = *(LAS const bf16x8*)(vb_ + dt * 16 * VSTR + kb * 64);
;             acc = mfma16(vf, pf[kb], acc);
;         }
;         o[dt] = acc * inv;
;     }
	v_add_f32_e32 v72, v72, v73
	ds_bpermute_b32 v73, v147, v72
	v_cvt_pk_bf16_f32 v80, v128, v129
	v_cvt_pk_bf16_f32 v81, v130, v131
	v_cvt_pk_bf16_f32 v82, v124, v125
	v_cvt_pk_bf16_f32 v83, v126, v127
	s_waitcnt lgkmcnt(0)
	v_add_f32_e32 v179, v72, v73
	v_cvt_pk_bf16_f32 v76, v120, v121
	v_cvt_pk_bf16_f32 v77, v122, v123
	v_cvt_pk_bf16_f32 v78, v116, v117
	v_cvt_pk_bf16_f32 v79, v118, v119
	v_cvt_pk_bf16_f32 v72, v112, v113
	v_cvt_pk_bf16_f32 v73, v114, v115
	v_cvt_pk_bf16_f32 v74, v108, v109
	v_cvt_pk_bf16_f32 v75, v110, v111
	v_cvt_pk_bf16_f32 v88, v104, v105
	v_div_scale_f32 v104, s[0:1], v179, v179, 1.0
	v_rcp_f32_e32 v105, v104
	v_cvt_pk_bf16_f32 v89, v106, v107
	v_cvt_pk_bf16_f32 v90, v100, v101
	v_cvt_pk_bf16_f32 v91, v102, v103
	v_cvt_pk_bf16_f32 v92, v96, v97
	v_cvt_pk_bf16_f32 v93, v98, v99
	s_nop 0
	v_fma_f32 v106, -v104, v105, 1.0
	v_fmac_f32_e32 v105, v106, v105
	v_div_scale_f32 v106, vcc, 1.0, v179, 1.0
	v_mul_f32_e32 v107, v106, v105
	v_fma_f32 v108, -v104, v107, v106
	v_fmac_f32_e32 v107, v108, v105
	v_fma_f32 v104, -v104, v107, v106
	v_div_fmas_f32 v104, v104, v105, v107
	v_cvt_pk_bf16_f32 v94, v137, v136
	v_cvt_pk_bf16_f32 v95, v138, v95
	v_cvt_pk_bf16_f32 v96, v139, v153
	v_cvt_pk_bf16_f32 v97, v155, v157
	v_cvt_pk_bf16_f32 v98, v159, v161
	v_cvt_pk_bf16_f32 v99, v163, v165
	v_cvt_pk_bf16_f32 v100, v167, v169
	v_cvt_pk_bf16_f32 v101, v171, v173
	v_cvt_pk_bf16_f32 v102, v176, v177
	v_cvt_pk_bf16_f32 v103, v178, v151
	v_div_fixup_f32 v116, v104, v179, 1.0
	s_waitcnt lgkmcnt(0)
	ds_read_b128 v[196:199], v143
	ds_read_b128 v[200:203], v143 offset:64
	ds_read_b128 v[204:207], v143 offset:8512
	ds_read_b128 v[208:211], v143 offset:16960
	ds_read_b128 v[212:215], v143 offset:128
	ds_read_b128 v[228:231], v143 offset:192
	ds_read_b128 v[232:235], v143 offset:256
	ds_read_b128 v[236:239], v143 offset:320
	ds_read_b128 v[240:243], v143 offset:384
	ds_read_b128 v[244:247], v143 offset:448
	s_waitcnt lgkmcnt(9)
	v_mfma_f32_16x16x32_bf16 v[104:107], v[196:199], v[84:87], 0
	ds_read_b128 v[196:199], v143 offset:8448
	s_waitcnt lgkmcnt(9)
	v_mfma_f32_16x16x32_bf16 v[104:107], v[200:203], v[80:83], v[104:107]
	ds_read_b128 v[200:203], v143 offset:8576
	s_waitcnt lgkmcnt(7)
	v_mfma_f32_16x16x32_bf16 v[104:107], v[212:215], v[76:79], v[104:107]
	ds_read_b128 v[212:215], v143 offset:8640
	s_waitcnt lgkmcnt(7)
	v_mfma_f32_16x16x32_bf16 v[104:107], v[228:231], v[72:75], v[104:107]
	ds_read_b128 v[228:231], v143 offset:8704
	s_waitcnt lgkmcnt(7)
	v_mfma_f32_16x16x32_bf16 v[104:107], v[232:235], v[88:91], v[104:107]
	ds_read_b128 v[232:235], v143 offset:8768
	s_waitcnt lgkmcnt(7)
	v_mfma_f32_16x16x32_bf16 v[104:107], v[236:239], v[92:95], v[104:107]
	ds_read_b128 v[236:239], v143 offset:8832
	s_waitcnt lgkmcnt(7)
	v_mfma_f32_16x16x32_bf16 v[104:107], v[240:243], v[96:99], v[104:107]
	ds_read_b128 v[240:243], v143 offset:8896
	s_waitcnt lgkmcnt(7)
	v_mfma_f32_16x16x32_bf16 v[106:109], v[244:247], v[100:103], v[104:107]
	ds_read_b128 v[244:247], v143 offset:16896
	s_nop 7
	v_pk_mul_f32 v[104:105], v[108:109], v[116:117] op_sel_hi:[1,0]
	s_waitcnt lgkmcnt(7)
	v_mfma_f32_16x16x32_bf16 v[108:111], v[196:199], v[84:87], 0
	ds_read_b128 v[196:199], v143 offset:17024
	v_mul_f32_e64 v106, v106, v116
	v_mul_f32_e64 v107, v107, v116
	v_mfma_f32_16x16x32_bf16 v[108:111], v[204:207], v[80:83], v[108:111]
	ds_read_b128 v[204:207], v143 offset:17088
	s_waitcnt lgkmcnt(8)
	v_mfma_f32_16x16x32_bf16 v[108:111], v[200:203], v[76:79], v[108:111]
	ds_read_b128 v[200:203], v143 offset:17152
	s_waitcnt lgkmcnt(8)
	v_mfma_f32_16x16x32_bf16 v[108:111], v[212:215], v[72:75], v[108:111]
	ds_read_b128 v[212:215], v143 offset:17216
	s_waitcnt lgkmcnt(8)
	v_mfma_f32_16x16x32_bf16 v[108:111], v[228:231], v[88:91], v[108:111]
	ds_read_b128 v[228:231], v143 offset:17280
	s_waitcnt lgkmcnt(8)
	v_mfma_f32_16x16x32_bf16 v[108:111], v[232:235], v[92:95], v[108:111]
	ds_read_b128 v[232:235], v143 offset:17344
	s_waitcnt lgkmcnt(8)
	v_mfma_f32_16x16x32_bf16 v[108:111], v[236:239], v[96:99], v[108:111]
	ds_read_b128 v[236:239], v143 offset:25344
	s_waitcnt lgkmcnt(8)
	v_mfma_f32_16x16x32_bf16 v[110:113], v[240:243], v[100:103], v[108:111]
	s_nop 7
	v_pk_mul_f32 v[108:109], v[112:113], v[116:117] op_sel_hi:[1,0]
	ds_read_b128 v[240:243], v143 offset:25408
	s_waitcnt lgkmcnt(8)
	v_mfma_f32_16x16x32_bf16 v[112:115], v[244:247], v[84:87], 0
	v_mul_f32_e64 v110, v110, v116
	v_mul_f32_e64 v111, v111, v116
	v_mfma_f32_16x16x32_bf16 v[112:115], v[208:211], v[80:83], v[112:115]
	ds_read_b128 v[244:247], v143 offset:25472
	s_waitcnt lgkmcnt(8)
	v_mfma_f32_16x16x32_bf16 v[112:115], v[196:199], v[76:79], v[112:115]
	ds_read_b128 v[208:211], v143 offset:25536
	s_waitcnt lgkmcnt(8)
	v_mfma_f32_16x16x32_bf16 v[112:115], v[204:207], v[72:75], v[112:115]
	ds_read_b128 v[196:199], v143 offset:25600
	s_waitcnt lgkmcnt(8)
	v_mfma_f32_16x16x32_bf16 v[112:115], v[200:203], v[88:91], v[112:115]
	ds_read_b128 v[204:207], v143 offset:25664
	s_waitcnt lgkmcnt(8)
	v_mfma_f32_16x16x32_bf16 v[112:115], v[212:215], v[92:95], v[112:115]
	ds_read_b128 v[200:203], v143 offset:25728
	s_waitcnt lgkmcnt(8)
	v_mfma_f32_16x16x32_bf16 v[112:115], v[228:231], v[96:99], v[112:115]
	s_waitcnt lgkmcnt(7)
	v_mfma_f32_16x16x32_bf16 v[118:121], v[232:235], v[100:103], v[112:115]
	s_nop 7
	v_pk_mul_f32 v[112:113], v[116:117], v[120:121] op_sel_hi:[0,1]
	v_pk_mul_f32 v[114:115], v[116:117], v[118:119] op_sel_hi:[0,1]
	s_waitcnt lgkmcnt(6)
	v_mfma_f32_16x16x32_bf16 v[84:87], v[236:239], v[84:87], 0
	s_waitcnt lgkmcnt(5)
	v_mfma_f32_16x16x32_bf16 v[80:83], v[240:243], v[80:83], v[84:87]
	s_waitcnt lgkmcnt(4)
	v_mfma_f32_16x16x32_bf16 v[76:79], v[244:247], v[76:79], v[80:83]
	s_waitcnt lgkmcnt(3)
	v_mfma_f32_16x16x32_bf16 v[72:75], v[208:211], v[72:75], v[76:79]
	s_waitcnt lgkmcnt(2)
	v_mfma_f32_16x16x32_bf16 v[72:75], v[196:199], v[88:91], v[72:75]
	s_waitcnt lgkmcnt(1)
	v_mfma_f32_16x16x32_bf16 v[72:75], v[204:207], v[92:95], v[72:75]
	s_waitcnt lgkmcnt(0)
	v_mfma_f32_16x16x32_bf16 v[72:75], v[200:203], v[96:99], v[72:75]
	ds_read_b128 v[76:79], v143 offset:25792
	s_waitcnt lgkmcnt(0)
	s_barrier
; #define LAS __attribute__((address_space(3)))
; #define LAS __attribute__((address_space(3)))
; template <bool DO_SWA, bool DO_MEM>
; __device__ __forceinline__ void attn_unit(const Args& a, unsigned char* ws, LAS unsigned char* lds, int l, int tid_in, int lane_in, int wave, int unit) {
;     ...
;         __syncthreads();
;         if constexpr (DO_MEM)
; #pragma unroll
;         for (int i = 0; i < 8; ++i) {
;             const int chn = tid + 512 * i;
;             { const int key = chn >> 4, c16 = chn & 15; *(LAS v4u*)(lds + A_KS + ((c16 >> 3) * 256 + key) * 144 + (c16 & 7) * 16) = mkst[i]; }
;             { const int col = chn >> 5, kc = chn & 31; *(LAS v4u*)(lds + A_VT2 + col * 528 + kc * 16) = mvst[i]; }
;         }
;         __syncthreads();
;         if constexpr (DO_MEM) {
;             attn_core<16, 528, false>(lds + A_KS + g * 256 * 144 + fq * 16, lds + A_VT2 + (g * 64 + fr) * 528 + fq * 16, qmm[1][0], qmm[1][1], 0.f, 0u, fr, omem[1]);
	s_waitcnt vmcnt(11)
	ds_write_b128 v142, v[8:11]
	s_waitcnt vmcnt(10)
	ds_write_b128 v144, v[12:15]
	s_waitcnt vmcnt(9)
	ds_write_b128 v146, v[16:19]
	s_waitcnt vmcnt(8)
	ds_write_b128 v148, v[20:23]
	s_waitcnt vmcnt(7)
	ds_write_b128 v150, v[24:27]
	s_waitcnt vmcnt(6)
	ds_write_b128 v152, v[28:31]
	ds_write_b128 v154, v[32:35]
	ds_write_b128 v156, v[36:39]
	ds_write_b128 v158, v[40:43]
	ds_write_b128 v160, v[44:47]
	s_waitcnt vmcnt(5)
	ds_write_b128 v162, v[48:51]
	s_waitcnt vmcnt(4)
	ds_write_b128 v164, v[52:55]
	s_waitcnt vmcnt(3)
	ds_write_b128 v166, v[56:59]
	s_waitcnt vmcnt(2)
	ds_write_b128 v168, v[60:63]
	s_waitcnt vmcnt(1)
	ds_write_b128 v170, v[64:67]
	s_waitcnt vmcnt(0)
	ds_write_b128 v172, v[68:71]
	s_waitcnt lgkmcnt(0)
	s_barrier
	s_waitcnt lgkmcnt(0)
	ds_read_b128 v[80:83], v149
	ds_read_b128 v[84:87], v149 offset:64
	ds_read_b128 v[196:199], v149 offset:576
	ds_read_b128 v[200:203], v149 offset:640
	ds_read_b128 v[204:207], v149 offset:4608
	ds_read_b128 v[208:211], v149 offset:4672
	ds_read_b128 v[212:215], v149 offset:5184
	ds_read_b128 v[228:231], v149 offset:5248
	ds_read_b128 v[232:235], v149 offset:9216
	ds_read_b128 v[236:239], v149 offset:9280
	ds_read_b128 v[240:243], v149 offset:9792
	ds_read_b128 v[244:247], v149 offset:9856
	s_waitcnt lgkmcnt(11)
	v_mfma_f32_16x16x32_bf16 v[8:11], v[80:83], v[4:7], 0
	s_waitcnt lgkmcnt(10)
	v_mfma_f32_16x16x32_bf16 v[64:67], v[84:87], v[0:3], v[8:11]
	ds_read_b128 v[80:83], v149 offset:13824
	ds_read_b128 v[84:87], v149 offset:13888
	s_waitcnt lgkmcnt(11)
	v_mfma_f32_16x16x32_bf16 v[8:11], v[196:199], v[4:7], 0
	s_waitcnt lgkmcnt(10)
	v_mfma_f32_16x16x32_bf16 v[60:63], v[200:203], v[0:3], v[8:11]
	ds_read_b128 v[196:199], v149 offset:14400
	ds_read_b128 v[200:203], v149 offset:14464
	s_waitcnt lgkmcnt(11)
	v_mfma_f32_16x16x32_bf16 v[8:11], v[204:207], v[4:7], 0
	s_waitcnt lgkmcnt(10)
	v_mfma_f32_16x16x32_bf16 v[20:23], v[208:211], v[0:3], v[8:11]
	ds_read_b128 v[204:207], v149 offset:18432
	ds_read_b128 v[208:211], v149 offset:18496
	s_waitcnt lgkmcnt(11)
	v_mfma_f32_16x16x32_bf16 v[8:11], v[212:215], v[4:7], 0
	s_waitcnt lgkmcnt(10)
	v_mfma_f32_16x16x32_bf16 v[12:15], v[228:231], v[0:3], v[8:11]
	ds_read_b128 v[212:215], v149 offset:19008
	ds_read_b128 v[228:231], v149 offset:19072
	s_waitcnt lgkmcnt(11)
	v_mfma_f32_16x16x32_bf16 v[8:11], v[232:235], v[4:7], 0
	s_waitcnt lgkmcnt(10)
	v_mfma_f32_16x16x32_bf16 v[8:11], v[236:239], v[0:3], v[8:11]
	ds_read_b128 v[232:235], v149 offset:23040
	ds_read_b128 v[236:239], v149 offset:23104
	s_waitcnt lgkmcnt(11)
	v_mfma_f32_16x16x32_bf16 v[16:19], v[240:243], v[4:7], 0
	s_waitcnt lgkmcnt(10)
	v_mfma_f32_16x16x32_bf16 v[16:19], v[244:247], v[0:3], v[16:19]
	ds_read_b128 v[240:243], v149 offset:23616
	ds_read_b128 v[244:247], v149 offset:23680
	s_waitcnt lgkmcnt(11)
	v_mfma_f32_16x16x32_bf16 v[24:27], v[80:83], v[4:7], 0
	s_waitcnt lgkmcnt(10)
	v_mfma_f32_16x16x32_bf16 v[24:27], v[84:87], v[0:3], v[24:27]
	ds_read_b128 v[80:83], v149 offset:27648
	ds_read_b128 v[84:87], v149 offset:27712
	s_waitcnt lgkmcnt(11)
	v_mfma_f32_16x16x32_bf16 v[28:31], v[196:199], v[4:7], 0
	s_waitcnt lgkmcnt(10)
	v_mfma_f32_16x16x32_bf16 v[28:31], v[200:203], v[0:3], v[28:31]
	ds_read_b128 v[196:199], v149 offset:28224
	ds_read_b128 v[200:203], v149 offset:28288
	s_waitcnt lgkmcnt(11)
	v_mfma_f32_16x16x32_bf16 v[32:35], v[204:207], v[4:7], 0
	s_waitcnt lgkmcnt(10)
	v_mfma_f32_16x16x32_bf16 v[32:35], v[208:211], v[0:3], v[32:35]
	ds_read_b128 v[204:207], v149 offset:32256
	ds_read_b128 v[208:211], v149 offset:32320
	s_waitcnt lgkmcnt(11)
	v_mfma_f32_16x16x32_bf16 v[36:39], v[212:215], v[4:7], 0
	s_waitcnt lgkmcnt(10)
	v_mfma_f32_16x16x32_bf16 v[36:39], v[228:231], v[0:3], v[36:39]
	ds_read_b128 v[212:215], v149 offset:32832
	ds_read_b128 v[228:231], v149 offset:32896
	s_waitcnt lgkmcnt(11)
	v_mfma_f32_16x16x32_bf16 v[40:43], v[232:235], v[4:7], 0
	s_waitcnt lgkmcnt(10)
	v_mfma_f32_16x16x32_bf16 v[40:43], v[236:239], v[0:3], v[40:43]
	s_waitcnt lgkmcnt(9)
	v_mfma_f32_16x16x32_bf16 v[44:47], v[240:243], v[4:7], 0
	s_waitcnt lgkmcnt(8)
	v_mfma_f32_16x16x32_bf16 v[48:51], v[244:247], v[0:3], v[44:47]
	s_waitcnt lgkmcnt(7)
	v_mfma_f32_16x16x32_bf16 v[44:47], v[80:83], v[4:7], 0
	s_waitcnt lgkmcnt(6)
	v_mfma_f32_16x16x32_bf16 v[52:55], v[84:87], v[0:3], v[44:47]
	s_waitcnt lgkmcnt(5)
	v_mfma_f32_16x16x32_bf16 v[44:47], v[196:199], v[4:7], 0
	s_waitcnt lgkmcnt(4)
	v_mfma_f32_16x16x32_bf16 v[56:59], v[200:203], v[0:3], v[44:47]
	v_mfma_f32_16x16x32_bf16 v[74:77], v[76:79], v[100:103], v[72:75]
	s_waitcnt lgkmcnt(3)
	v_mfma_f32_16x16x32_bf16 v[44:47], v[204:207], v[4:7], 0
	s_waitcnt lgkmcnt(2)
	v_mfma_f32_16x16x32_bf16 v[44:47], v[208:211], v[0:3], v[44:47]
	s_nop 3
	v_mul_f32_e64 v72, v116, v76
	v_mul_f32_e64 v73, v116, v77
	v_pk_mul_f32 v[74:75], v[116:117], v[74:75] op_sel_hi:[0,1]
	s_waitcnt lgkmcnt(1)
	v_mfma_f32_16x16x32_bf16 v[4:7], v[212:215], v[4:7], 0
	s_waitcnt lgkmcnt(0)
; __device__ __forceinline__ unsigned pk2(float lo, float hi) { return pg8::cvt_pk_bf16(lo, hi); }
; template <int NKT, int VSTR, bool SINK>
; __device__ __forceinline__ void attn_core(LAS const unsigned char* kb_, LAS const unsigned char* vb_, bf16x8 q0, bf16x8 q1, float sk, unsigned mskbits, int fr, f32x4 (&o)[4]) {
;     ...
;     float mx = S[0][0];
; #pragma unroll
;     for (int kt = 0; kt < NKT; ++kt) mx = fmaxf(fmaxf(mx, fmaxf(S[kt][0], S[kt][1])), fmaxf(S[kt][2], S[kt][3]));
;     mx = fmaxf(mx, __shfl_xor(mx, 16)); mx = fmaxf(mx, __shfl_xor(mx, 32));
;     if (SINK) mx = fmaxf(mx, sk);
;     float sum = 0.f;
; #pragma unroll
;     for (int kt = 0; kt < NKT; ++kt)
; #pragma unroll
;         for (int r = 0; r < 4; ++r) { const float p = __builtin_amdgcn_exp2f(S[kt][r] - mx); S[kt][r] = p; sum += p; }
;     sum += __shfl_xor(sum, 16); sum += __shfl_xor(sum, 32);
;     if (SINK) sum += __builtin_amdgcn_exp2f(sk - mx);
;     const float inv = 1.0f / sum;
;     bf16x8 pf[NKT / 2];
; #pragma unroll
;     for (int kb = 0; kb < NKT / 2; ++kb) {
;         v4u w; w.x = pk2(S[2 * kb][0], S[2 * kb][1]); w.y = pk2(S[2 * kb][2], S[2 * kb][3]); w.z = pk2(S[2 * kb + 1][0], S[2 * kb + 1][1]); w.w = pk2(S[2 * kb + 1][2], S[2 * kb + 1][3]);
	v_mfma_f32_16x16x32_bf16 v[0:3], v[228:231], v[0:3], v[4:7]
	s_nop 5
	s_nop 0
	s_nop 0
	v_max_f32_e32 v4, v66, v67
	s_nop 0
	s_nop 0
	v_max_f32_e32 v5, v60, v61
	s_nop 0
	s_nop 0
	v_max3_f32 v4, v64, v65, v4
	v_max_f32_e32 v6, v62, v63
	v_max3_f32 v4, v4, v5, v6
	s_nop 0
	s_nop 0
	v_max_f32_e32 v5, v20, v21
	s_nop 0
	s_nop 0
	v_max_f32_e32 v6, v22, v23
	v_max3_f32 v4, v4, v5, v6
	s_nop 0
	s_nop 0
	v_max_f32_e32 v5, v12, v13
	s_nop 0
	s_nop 0
	v_max_f32_e32 v6, v14, v15
	v_max3_f32 v4, v4, v5, v6
	v_max_f32_e32 v5, v8, v9
	v_max_f32_e32 v6, v10, v11
	v_max3_f32 v4, v4, v5, v6
	v_max_f32_e32 v5, v16, v17
	v_max_f32_e32 v6, v18, v19
	v_max3_f32 v4, v4, v5, v6
	v_max_f32_e32 v5, v24, v25
	v_max_f32_e32 v6, v26, v27
	v_max3_f32 v4, v4, v5, v6
	v_max_f32_e32 v5, v28, v29
	v_max_f32_e32 v6, v30, v31
	v_max3_f32 v4, v4, v5, v6
	v_max_f32_e32 v5, v32, v33
	v_max_f32_e32 v6, v34, v35
	v_max3_f32 v4, v4, v5, v6
	v_max_f32_e32 v5, v36, v37
	v_max_f32_e32 v6, v38, v39
	v_max3_f32 v4, v4, v5, v6
	v_max_f32_e32 v5, v40, v41
	v_max_f32_e32 v6, v42, v43
	v_max3_f32 v4, v4, v5, v6
	v_max_f32_e32 v5, v48, v49
	v_max_f32_e32 v6, v50, v51
	v_max3_f32 v4, v4, v5, v6
	v_max_f32_e32 v5, v52, v53
	v_max_f32_e32 v6, v54, v55
	v_max3_f32 v4, v4, v5, v6
	v_max_f32_e32 v5, v56, v57
	v_max_f32_e32 v6, v58, v59
	v_max3_f32 v4, v4, v5, v6
	v_max_f32_e32 v5, v44, v45
	v_max_f32_e32 v6, v46, v47
	v_max3_f32 v4, v4, v5, v6
	v_max_f32_e32 v5, v0, v1
	v_max_f32_e32 v6, v2, v3
	v_max3_f32 v4, v4, v5, v6
	ds_bpermute_b32 v5, v145, v4
	s_waitcnt lgkmcnt(0)
	s_nop 0
	v_max_f32_e32 v4, v4, v5
	ds_bpermute_b32 v5, v147, v4
	s_waitcnt lgkmcnt(0)
	s_nop 0
	v_max_f32_e32 v7, v4, v5
	v_sub_f32_e32 v4, v64, v7
	v_exp_f32_e32 v4, v4
	v_sub_f32_e32 v5, v65, v7
	v_exp_f32_e32 v5, v5
	v_sub_f32_e32 v60, v60, v7
	v_add_f32_e32 v6, 0, v4
	v_exp_f32_e32 v60, v60
	v_add_f32_e32 v64, v5, v6
	v_sub_f32_e32 v6, v66, v7
	v_exp_f32_e32 v6, v6
	v_sub_f32_e32 v61, v61, v7
	v_exp_f32_e32 v61, v61
	v_sub_f32_e32 v62, v62, v7
	v_add_f32_e32 v65, v6, v64
	v_sub_f32_e32 v64, v67, v7
	v_exp_f32_e32 v64, v64
	v_exp_f32_e32 v62, v62
	v_sub_f32_e32 v63, v63, v7
	v_exp_f32_e32 v63, v63
	v_add_f32_e32 v65, v64, v65
	v_sub_f32_e32 v20, v20, v7
	v_add_f32_e32 v65, v60, v65
	v_exp_f32_e32 v20, v20
	v_sub_f32_e32 v21, v21, v7
	v_add_f32_e32 v65, v61, v65
	v_exp_f32_e32 v21, v21
	v_sub_f32_e32 v22, v22, v7
	v_add_f32_e32 v65, v62, v65
	v_exp_f32_e32 v22, v22
	v_sub_f32_e32 v23, v23, v7
	v_add_f32_e32 v65, v63, v65
	v_exp_f32_e32 v23, v23
	v_sub_f32_e32 v12, v12, v7
	v_add_f32_e32 v65, v20, v65
	v_exp_f32_e32 v12, v12
	v_sub_f32_e32 v13, v13, v7
	v_add_f32_e32 v65, v21, v65
	v_exp_f32_e32 v13, v13
	v_sub_f32_e32 v14, v14, v7
	v_add_f32_e32 v65, v22, v65
	v_exp_f32_e32 v14, v14
	v_sub_f32_e32 v15, v15, v7
	v_add_f32_e32 v65, v23, v65
	v_exp_f32_e32 v15, v15
	v_sub_f32_e32 v8, v8, v7
	v_add_f32_e32 v65, v12, v65
	v_exp_f32_e32 v8, v8
	v_sub_f32_e32 v9, v9, v7
	v_add_f32_e32 v65, v13, v65
	v_exp_f32_e32 v9, v9
	v_sub_f32_e32 v10, v10, v7
	v_add_f32_e32 v65, v14, v65
	v_exp_f32_e32 v10, v10
	v_sub_f32_e32 v11, v11, v7
	v_add_f32_e32 v65, v15, v65
	v_exp_f32_e32 v11, v11
	v_sub_f32_e32 v16, v16, v7
	v_add_f32_e32 v65, v8, v65
	v_exp_f32_e32 v16, v16
	v_sub_f32_e32 v17, v17, v7
	v_add_f32_e32 v65, v9, v65
	v_exp_f32_e32 v17, v17
	v_sub_f32_e32 v18, v18, v7
	v_add_f32_e32 v65, v10, v65
	v_exp_f32_e32 v18, v18
	v_sub_f32_e32 v19, v19, v7
	v_add_f32_e32 v65, v11, v65
	v_exp_f32_e32 v19, v19
	v_sub_f32_e32 v24, v24, v7
	v_add_f32_e32 v65, v16, v65
	v_exp_f32_e32 v66, v24
	v_add_f32_e32 v65, v17, v65
	v_add_f32_e32 v65, v18, v65
	v_add_f32_e32 v65, v19, v65
	v_sub_f32_e32 v25, v25, v7
	v_add_f32_e32 v24, v66, v65
	v_exp_f32_e32 v65, v25
	v_sub_f32_e32 v25, v26, v7
	v_exp_f32_e32 v67, v25
	v_sub_f32_e32 v25, v27, v7
	v_exp_f32_e32 v68, v25
	v_sub_f32_e32 v25, v28, v7
	v_exp_f32_e32 v69, v25
	v_sub_f32_e32 v25, v29, v7
	v_add_f32_e32 v24, v65, v24
	v_exp_f32_e32 v70, v25
	v_sub_f32_e32 v25, v30, v7
	v_add_f32_e32 v24, v67, v24
	v_exp_f32_e32 v71, v25
	v_sub_f32_e32 v25, v31, v7
	v_add_f32_e32 v24, v68, v24
	v_exp_f32_e32 v76, v25
	v_sub_f32_e32 v25, v32, v7
	v_add_f32_e32 v24, v69, v24
	v_exp_f32_e32 v32, v25
	v_sub_f32_e32 v25, v33, v7
	v_add_f32_e32 v24, v70, v24
	v_exp_f32_e32 v33, v25
	v_sub_f32_e32 v25, v34, v7
	v_add_f32_e32 v24, v71, v24
	v_exp_f32_e32 v34, v25
	v_sub_f32_e32 v25, v35, v7
	v_add_f32_e32 v24, v76, v24
	v_exp_f32_e32 v35, v25
	v_sub_f32_e32 v25, v36, v7
	v_add_f32_e32 v24, v32, v24
	v_exp_f32_e32 v36, v25
	v_sub_f32_e32 v25, v37, v7
	v_add_f32_e32 v24, v33, v24
	v_exp_f32_e32 v37, v25
	v_sub_f32_e32 v25, v38, v7
	v_add_f32_e32 v24, v34, v24
	v_exp_f32_e32 v38, v25
	v_sub_f32_e32 v25, v39, v7
	v_add_f32_e32 v24, v35, v24
	v_exp_f32_e32 v39, v25
	v_sub_f32_e32 v25, v40, v7
	v_add_f32_e32 v24, v36, v24
	v_exp_f32_e32 v40, v25
	v_sub_f32_e32 v25, v41, v7
	v_add_f32_e32 v24, v37, v24
	v_exp_f32_e32 v41, v25
	v_sub_f32_e32 v25, v42, v7
	v_add_f32_e32 v24, v38, v24
	v_exp_f32_e32 v42, v25
	v_sub_f32_e32 v25, v43, v7
	v_add_f32_e32 v24, v39, v24
	v_exp_f32_e32 v43, v25
	v_sub_f32_e32 v25, v48, v7
	v_add_f32_e32 v24, v40, v24
	v_exp_f32_e32 v48, v25
	v_sub_f32_e32 v25, v49, v7
	v_add_f32_e32 v24, v41, v24
	v_exp_f32_e32 v49, v25
	v_sub_f32_e32 v25, v50, v7
	v_add_f32_e32 v24, v42, v24
	v_exp_f32_e32 v50, v25
	v_sub_f32_e32 v25, v51, v7
	v_add_f32_e32 v24, v43, v24
	v_exp_f32_e32 v51, v25
	v_sub_f32_e32 v25, v52, v7
	v_add_f32_e32 v24, v48, v24
	v_exp_f32_e32 v52, v25
	v_sub_f32_e32 v25, v53, v7
	v_add_f32_e32 v24, v49, v24
	v_exp_f32_e32 v53, v25
	v_sub_f32_e32 v25, v54, v7
	v_add_f32_e32 v24, v50, v24
	v_exp_f32_e32 v54, v25
	v_sub_f32_e32 v25, v55, v7
	v_add_f32_e32 v24, v51, v24
	v_exp_f32_e32 v55, v25
	v_sub_f32_e32 v25, v56, v7
	v_add_f32_e32 v24, v52, v24
	v_exp_f32_e32 v56, v25
	v_sub_f32_e32 v25, v57, v7
	v_add_f32_e32 v24, v53, v24
	v_exp_f32_e32 v57, v25
	v_sub_f32_e32 v25, v58, v7
	v_add_f32_e32 v24, v54, v24
	v_exp_f32_e32 v58, v25
	v_sub_f32_e32 v25, v59, v7
	v_add_f32_e32 v24, v55, v24
	v_exp_f32_e32 v59, v25
	v_sub_f32_e32 v25, v44, v7
	v_add_f32_e32 v24, v56, v24
	v_exp_f32_e32 v44, v25
	v_sub_f32_e32 v25, v45, v7
	v_add_f32_e32 v24, v57, v24
	v_exp_f32_e32 v45, v25
	v_sub_f32_e32 v25, v46, v7
	v_add_f32_e32 v24, v58, v24
	v_exp_f32_e32 v46, v25
	v_sub_f32_e32 v25, v47, v7
	v_add_f32_e32 v24, v59, v24
	v_exp_f32_e32 v47, v25
	v_sub_f32_e32 v0, v0, v7
	v_add_f32_e32 v24, v44, v24
	v_exp_f32_e32 v77, v0
	v_sub_f32_e32 v1, v1, v7
	v_add_f32_e32 v24, v45, v24
	v_exp_f32_e32 v78, v1
	v_sub_f32_e32 v1, v2, v7
	v_add_f32_e32 v24, v46, v24
	v_exp_f32_e32 v79, v1
	v_sub_f32_e32 v1, v3, v7
	v_add_f32_e32 v24, v47, v24
	v_exp_f32_e32 v3, v1
	v_add_f32_e32 v0, v77, v24
	v_add_f32_e32 v0, v78, v0
	v_add_f32_e32 v0, v79, v0
	v_add_f32_e32 v0, v3, v0
	ds_bpermute_b32 v1, v145, v0
	v_cvt_pk_bf16_f32 v28, v4, v5
	v_cvt_pk_bf16_f32 v29, v6, v64
	v_cvt_pk_bf16_f32 v30, v60, v61
	v_cvt_pk_bf16_f32 v31, v62, v63
	s_waitcnt lgkmcnt(0)
; #define LAS __attribute__((address_space(3)))
; #define LAS __attribute__((address_space(3)))
; __device__ __forceinline__ unsigned pk2(float lo, float hi) { return pg8::cvt_pk_bf16(lo, hi); }
; __device__ __forceinline__ f32x4 mfma16(bf16x8 a, bf16x8 b, f32x4 c) { return __builtin_amdgcn_mfma_f32_16x16x32_bf16(a, b, c, 0, 0, 0); }
; template <int NKT, int VSTR, bool SINK>
; __device__ __forceinline__ void attn_core(LAS const unsigned char* kb_, LAS const unsigned char* vb_, bf16x8 q0, bf16x8 q1, float sk, unsigned mskbits, int fr, f32x4 (&o)[4]) {
;     ...
;     sum += __shfl_xor(sum, 16); sum += __shfl_xor(sum, 32);
;     if (SINK) sum += __builtin_amdgcn_exp2f(sk - mx);
;     const float inv = 1.0f / sum;
;     bf16x8 pf[NKT / 2];
; #pragma unroll
;     for (int kb = 0; kb < NKT / 2; ++kb) {
;         v4u w; w.x = pk2(S[2 * kb][0], S[2 * kb][1]); w.y = pk2(S[2 * kb][2], S[2 * kb][3]); w.z = pk2(S[2 * kb + 1][0], S[2 * kb + 1][1]); w.w = pk2(S[2 * kb + 1][2], S[2 * kb + 1][3]);
;         pf[kb] = __builtin_bit_cast(bf16x8, w);
;     }
; #pragma unroll
;     for (int dt = 0; dt < 4; ++dt) {
;         f32x4 acc = (f32x4){0.f, 0.f, 0.f, 0.f};
; #pragma unroll
;         for (int kb = 0; kb < NKT / 2; ++kb) {
;             const bf16x8 vf = *(LAS const bf16x8*)(vb_ + dt * 16 * VSTR + kb * 64);
;             acc = mfma16(vf, pf[kb], acc);
;         }
;         o[dt] = acc * inv;
;     }
	v_add_f32_e32 v0, v0, v1
	ds_bpermute_b32 v1, v147, v0
	v_cvt_pk_bf16_f32 v24, v20, v21
	v_cvt_pk_bf16_f32 v25, v22, v23
	v_cvt_pk_bf16_f32 v26, v12, v13
	v_cvt_pk_bf16_f32 v27, v14, v15
	s_waitcnt lgkmcnt(0)
	v_add_f32_e32 v80, v0, v1
	v_cvt_pk_bf16_f32 v20, v8, v9
	v_cvt_pk_bf16_f32 v21, v10, v11
	v_cvt_pk_bf16_f32 v22, v16, v17
	v_cvt_pk_bf16_f32 v23, v18, v19
	v_cvt_pk_bf16_f32 v16, v66, v65
	v_cvt_pk_bf16_f32 v17, v67, v68
	v_cvt_pk_bf16_f32 v18, v69, v70
	v_cvt_pk_bf16_f32 v19, v71, v76
	v_cvt_pk_bf16_f32 v12, v32, v33
	v_div_scale_f32 v32, s[0:1], v80, v80, 1.0
	v_rcp_f32_e32 v33, v32
	v_cvt_pk_bf16_f32 v13, v34, v35
	v_cvt_pk_bf16_f32 v14, v36, v37
	v_cvt_pk_bf16_f32 v15, v38, v39
	v_cvt_pk_bf16_f32 v8, v40, v41
	v_cvt_pk_bf16_f32 v9, v42, v43
	s_nop 0
	v_fma_f32 v34, -v32, v33, 1.0
	v_fmac_f32_e32 v33, v34, v33
	v_div_scale_f32 v34, vcc, 1.0, v80, 1.0
	v_mul_f32_e32 v35, v34, v33
	v_fma_f32 v36, -v32, v35, v34
	v_fmac_f32_e32 v35, v36, v33
	v_fma_f32 v32, -v32, v35, v34
	v_div_fmas_f32 v32, v32, v33, v35
	v_cvt_pk_bf16_f32 v10, v48, v49
	v_cvt_pk_bf16_f32 v11, v50, v51
	v_cvt_pk_bf16_f32 v4, v52, v53
	v_cvt_pk_bf16_f32 v5, v54, v55
	v_cvt_pk_bf16_f32 v6, v56, v57
	v_cvt_pk_bf16_f32 v7, v58, v59
	v_cvt_pk_bf16_f32 v0, v44, v45
	v_cvt_pk_bf16_f32 v1, v46, v47
	v_cvt_pk_bf16_f32 v2, v77, v78
	v_cvt_pk_bf16_f32 v3, v79, v3
	v_div_fixup_f32 v36, v32, v80, 1.0
	s_waitcnt lgkmcnt(0)
	ds_read_b128 v[60:63], v143
	ds_read_b128 v[64:67], v143 offset:64
	ds_read_b128 v[68:71], v143 offset:8512
	ds_read_b128 v[84:87], v143 offset:16960
	ds_read_b128 v[88:91], v143 offset:128
	ds_read_b128 v[92:95], v143 offset:192
	ds_read_b128 v[196:199], v143 offset:256
	ds_read_b128 v[200:203], v143 offset:320
	ds_read_b128 v[204:207], v143 offset:384
	ds_read_b128 v[208:211], v143 offset:448
	ds_read_b128 v[212:215], v143 offset:8448
	ds_read_b128 v[228:231], v143 offset:8576
	ds_read_b128 v[232:235], v143 offset:8640
	ds_read_b128 v[236:239], v143 offset:8704
	s_waitcnt lgkmcnt(13)
	v_mfma_f32_16x16x32_bf16 v[32:35], v[60:63], v[28:31], 0
	ds_read_b128 v[240:243], v143 offset:8768
	v_cmp_gt_u32_e32 vcc, 16, v175
	s_waitcnt lgkmcnt(13)
	v_mfma_f32_16x16x32_bf16 v[32:35], v[64:67], v[24:27], v[32:35]
	ds_read_b128 v[244:247], v143 offset:8832
	s_waitcnt lgkmcnt(11)
	v_mfma_f32_16x16x32_bf16 v[32:35], v[88:91], v[20:23], v[32:35]
	ds_read_b128 v[60:63], v143 offset:8896
	ds_read_b128 v[64:67], v143 offset:16896
	s_waitcnt lgkmcnt(12)
	v_mfma_f32_16x16x32_bf16 v[32:35], v[92:95], v[16:19], v[32:35]
	ds_read_b128 v[88:91], v143 offset:17024
	s_waitcnt lgkmcnt(12)
	v_mfma_f32_16x16x32_bf16 v[32:35], v[196:199], v[12:15], v[32:35]
	ds_read_b128 v[92:95], v143 offset:17088
	s_waitcnt lgkmcnt(12)
	v_mfma_f32_16x16x32_bf16 v[32:35], v[200:203], v[8:11], v[32:35]
	ds_read_b128 v[196:199], v143 offset:17152
	s_waitcnt lgkmcnt(12)
	v_mfma_f32_16x16x32_bf16 v[32:35], v[204:207], v[4:7], v[32:35]
	ds_read_b128 v[200:203], v143 offset:17216
	s_waitcnt lgkmcnt(12)
	v_mfma_f32_16x16x32_bf16 v[38:41], v[208:211], v[0:3], v[32:35]
	s_nop 7
	v_pk_mul_f32 v[32:33], v[40:41], v[36:37] op_sel_hi:[1,0]
	v_pk_mul_f32 v[34:35], v[38:39], v[36:37] op_sel_hi:[1,0]
	ds_read_b128 v[204:207], v143 offset:17280
	s_waitcnt lgkmcnt(12)
	v_mfma_f32_16x16x32_bf16 v[38:41], v[212:215], v[28:31], 0
	v_mfma_f32_16x16x32_bf16 v[38:41], v[68:71], v[24:27], v[38:41]
	ds_read_b128 v[208:211], v143 offset:17344
	s_waitcnt lgkmcnt(12)
	v_mfma_f32_16x16x32_bf16 v[38:41], v[228:231], v[20:23], v[38:41]
	ds_read_b128 v[212:215], v143 offset:25344
	s_waitcnt lgkmcnt(12)
	v_mfma_f32_16x16x32_bf16 v[38:41], v[232:235], v[16:19], v[38:41]
	ds_read_b128 v[68:71], v143 offset:25408
	s_waitcnt lgkmcnt(12)
	v_mfma_f32_16x16x32_bf16 v[38:41], v[236:239], v[12:15], v[38:41]
	ds_read_b128 v[228:231], v143 offset:25472
	s_waitcnt lgkmcnt(12)
; __device__ __forceinline__ float quad_sum(float s) { s += __shfl_xor(s, 16); s += __shfl_xor(s, 32); return s; }
; __device__ __forceinline__ float sq4(const f32x4 a) { return (a[0] * a[0] + a[1] * a[1]) + (a[2] * a[2] + a[3] * a[3]); }
; template <bool DO_SWA, bool DO_MEM>
; __device__ __forceinline__ void attn_unit(const Args& a, unsigned char* ws, LAS unsigned char* lds, int l, int tid_in, int lane_in, int wave, int unit) {
;     ...
;             float ssq = 0.f;
; #pragma unroll
;             for (int hp = 0; hp < 2; ++hp)
; #pragma unroll
;                 for (int dt = 0; dt < 4; ++dt) ssq += pg8::sq4(omem[hp][dt]);
;             ssq = pg8::quad_sum(ssq);
;             if (fq == 0) red_m[g * 64 + qs * 16 + fr] = ssq;
	v_mfma_f32_16x16x32_bf16 v[38:41], v[240:243], v[8:11], v[38:41]
	ds_read_b128 v[232:235], v143 offset:25536
	s_waitcnt lgkmcnt(12)
	v_mfma_f32_16x16x32_bf16 v[38:41], v[244:247], v[4:7], v[38:41]
	ds_read_b128 v[236:239], v143 offset:25600
	s_waitcnt lgkmcnt(12)
	v_mfma_f32_16x16x32_bf16 v[40:43], v[60:63], v[0:3], v[38:41]
	s_nop 7
	v_pk_mul_f32 v[38:39], v[42:43], v[36:37] op_sel_hi:[1,0]
	ds_read_b128 v[240:243], v143 offset:25664
	s_waitcnt lgkmcnt(12)
	v_mfma_f32_16x16x32_bf16 v[42:45], v[64:67], v[28:31], 0
	v_mul_f32_e64 v40, v40, v36
	v_mul_f32_e64 v41, v41, v36
	v_mfma_f32_16x16x32_bf16 v[42:45], v[84:87], v[24:27], v[42:45]
	ds_read_b128 v[244:247], v143 offset:25728
	s_waitcnt lgkmcnt(12)
	v_mfma_f32_16x16x32_bf16 v[42:45], v[88:91], v[20:23], v[42:45]
	ds_read_b128 v[60:63], v143 offset:25792
	s_waitcnt lgkmcnt(12)
	v_mfma_f32_16x16x32_bf16 v[42:45], v[92:95], v[16:19], v[42:45]
	s_waitcnt lgkmcnt(11)
	v_mfma_f32_16x16x32_bf16 v[42:45], v[196:199], v[12:15], v[42:45]
	s_waitcnt lgkmcnt(10)
	v_mfma_f32_16x16x32_bf16 v[42:45], v[200:203], v[8:11], v[42:45]
	s_waitcnt lgkmcnt(9)
	v_mfma_f32_16x16x32_bf16 v[42:45], v[204:207], v[4:7], v[42:45]
	s_waitcnt lgkmcnt(8)
	v_mfma_f32_16x16x32_bf16 v[44:47], v[208:211], v[0:3], v[42:45]
	s_nop 7
	v_pk_mul_f32 v[42:43], v[36:37], v[46:47] op_sel_hi:[0,1]
	s_waitcnt lgkmcnt(7)
	v_mfma_f32_16x16x32_bf16 v[28:31], v[212:215], v[28:31], 0
	v_pk_mul_f32 v[44:45], v[36:37], v[44:45] op_sel_hi:[0,1]
	s_waitcnt lgkmcnt(6)
	v_mfma_f32_16x16x32_bf16 v[24:27], v[68:71], v[24:27], v[28:31]
	s_waitcnt lgkmcnt(5)
	v_mfma_f32_16x16x32_bf16 v[20:23], v[228:231], v[20:23], v[24:27]
	s_waitcnt lgkmcnt(4)
	v_mfma_f32_16x16x32_bf16 v[16:19], v[232:235], v[16:19], v[20:23]
	s_waitcnt lgkmcnt(3)
	v_mfma_f32_16x16x32_bf16 v[12:15], v[236:239], v[12:15], v[16:19]
	s_waitcnt lgkmcnt(2)
	v_mfma_f32_16x16x32_bf16 v[8:11], v[240:243], v[8:11], v[12:15]
	s_waitcnt lgkmcnt(1)
	v_mfma_f32_16x16x32_bf16 v[4:7], v[244:247], v[4:7], v[8:11]
	s_waitcnt lgkmcnt(0)
	v_mfma_f32_16x16x32_bf16 v[2:5], v[60:63], v[0:3], v[4:7]
	s_nop 2
	v_mul_f32_e32 v6, v109, v109
	v_fmac_f32_e32 v6, v108, v108
	s_nop 2
	v_pk_mul_f32 v[0:1], v[36:37], v[4:5] op_sel_hi:[0,1]
	v_mul_f32_e32 v4, v107, v107
	v_mul_f32_e32 v5, v105, v105
	v_fmac_f32_e32 v4, v106, v106
	v_fmac_f32_e32 v5, v104, v104
	v_add_f32_e32 v4, v4, v5
	v_mul_f32_e32 v5, v111, v111
	v_fmac_f32_e32 v5, v110, v110
	v_add_f32_e32 v5, v5, v6
	v_add_f32_e32 v4, v4, v5
	v_mul_f32_e32 v5, v115, v115
	v_mul_f32_e32 v6, v113, v113
	v_fmac_f32_e32 v5, v114, v114
	v_fmac_f32_e32 v6, v112, v112
	v_add_f32_e32 v5, v5, v6
	v_add_f32_e32 v4, v4, v5
	v_mul_f32_e32 v5, v75, v75
	v_mul_f32_e32 v6, v73, v73
	v_fmac_f32_e32 v5, v74, v74
	v_fmac_f32_e32 v6, v72, v72
	v_add_f32_e32 v5, v5, v6
	v_add_f32_e32 v4, v4, v5
	v_mul_f32_e32 v5, v35, v35
	v_mul_f32_e32 v6, v33, v33
	v_fmac_f32_e32 v5, v34, v34
	v_fmac_f32_e32 v6, v32, v32
	v_add_f32_e32 v5, v5, v6
	v_add_f32_e32 v4, v4, v5
	v_mul_f32_e32 v5, v41, v41
	v_mul_f32_e32 v6, v39, v39
	v_fmac_f32_e32 v5, v40, v40
	v_fmac_f32_e32 v6, v38, v38
	v_add_f32_e32 v5, v5, v6
	v_add_f32_e32 v4, v5, v4
	v_mul_f32_e32 v5, v45, v45
	v_mul_f32_e32 v6, v43, v43
	v_fmac_f32_e32 v5, v44, v44
	v_fmac_f32_e32 v6, v42, v42
	v_pk_mul_f32 v[2:3], v[36:37], v[2:3] op_sel_hi:[0,1]
	v_add_f32_e32 v5, v5, v6
	v_add_f32_e32 v4, v4, v5
	v_mul_f32_e32 v5, v3, v3
	v_mul_f32_e32 v6, v1, v1
	v_fmac_f32_e32 v5, v2, v2
	v_fmac_f32_e32 v6, v0, v0
	v_add_f32_e32 v5, v5, v6
	v_add_f32_e32 v4, v4, v5
	ds_bpermute_b32 v5, v145, v4
	s_waitcnt lgkmcnt(0)
	v_add_f32_e32 v4, v4, v5
	ds_bpermute_b32 v5, v147, v4
	s_and_saveexec_b64 s[0:1], vcc
	s_cbranch_execz .LBB0_261
	v_readlane_b32 s2, v251, 26
	s_waitcnt lgkmcnt(0)
	v_add_f32_e32 v4, v4, v5
	v_lshl_add_u32 v6, v175, 2, s2
	ds_write_b32 v6, v4

; __device__ __forceinline__ unsigned pk2(float lo, float hi) { return pg8::cvt_pk_bf16(lo, hi); }
; template <bool DO_SWA, bool DO_MEM>
; __device__ __forceinline__ void attn_unit(const Args& a, unsigned char* ws, LAS unsigned char* lds, int l, int tid_in, int lane_in, int wave, int unit) {
;     ...
;         if constexpr (DO_SWA) {
;             float w0[8], w1[8], w2[8];
; #pragma unroll
;             for (int j = 0; j < 4; ++j) { w0[j] = cwv[0][j]; w0[4 + j] = cwv[1][j]; w1[j] = cwv[2][j]; w1[4 + j] = cwv[3][j]; w2[j] = cwv[4][j]; w2[4 + j] = cwv[5][j]; }
; #pragma unroll
;             for (int i = 0; i < 4; ++i) {
;                 float ua[8], ub_[8], uc[8], cbv[8], cy[8];
;                 unpack8(cu[i], ua); unpack8(cu[i + 1], ub_); unpack8(cu[i + 2], uc); unpack8(ccb[i], cbv);
;                 float ss = 0.f;
; #pragma unroll
;                 for (int j = 0; j < 8; ++j) { const float y = ua[j] * w0[j] + ub_[j] * w1[j] + uc[j] * w2[j]; cy[j] = cbv[j] * y; ss += cy[j] * cy[j]; }
;                 ss += __shfl_xor(ss, 1); ss += __shfl_xor(ss, 2); ss += __shfl_xor(ss, 4); ss += __shfl_xor(ss, 8); ss += __shfl_xor(ss, 16);
;                 const float rs = 1.0f / sqrtf(ss * (1.0f / 256.0f) + EPS);
;                 v4u o; o.x = pk2(cy[0] * rs, cy[1] * rs); o.y = pk2(cy[2] * rs, cy[3] * rs); o.z = pk2(cy[4] * rs, cy[5] * rs); o.w = pk2(cy[6] * rs, cy[7] * rs);
;                 *(v4u*)(MIX + (size_t)(row0 + t0 + i) * D + 512 + ch) = o;
.LBB0_272:
	s_or_b64 exec, exec, s[2:3]
	v_lshl_add_u64 v[108:109], v[104:105], 0, v[184:185]
	s_movk_i32 s0, 0x1000
	v_add_co_u32_e32 v110, vcc, s0, v108
	s_movk_i32 s0, 0x2000
	s_nop 0
	v_addc_co_u32_e32 v111, vcc, 0, v109, vcc
	v_add_co_u32_e32 v150, vcc, s0, v108
	v_ashrrev_i32_e32 v169, 31, v168
	s_nop 0
	v_addc_co_u32_e32 v151, vcc, 0, v109, vcc
	global_load_dwordx4 v[104:107], v[110:111], off offset:3328 nt
	global_load_dwordx4 v[116:119], v[110:111], off offset:2816
	global_load_dwordx4 v[124:127], v[110:111], off offset:512 nt
	global_load_dwordx4 v[176:179], v[110:111], off
	global_load_dwordx4 v[180:183], v[108:109], off offset:1792 nt
	global_load_dwordx4 v[146:149], v[108:109], off offset:1280
	global_load_dwordx4 v[112:115], v[150:151], off offset:1536
	s_nop 0
	global_load_dwordx4 v[108:111], v[150:151], off offset:2048 nt
	s_waitcnt vmcnt(0)
	v_lshlrev_b32_e32 v173, 16, v180
	v_lshlrev_b32_e32 v172, 16, v128
	v_mov_b32_e32 v174, v92
	v_mov_b32_e32 v175, v100
	v_pk_mul_f32 v[198:199], v[174:175], v[172:173]
	v_lshlrev_b32_e32 v155, 16, v182
	v_and_b32_e32 v151, 0xffff0000, v182
	v_lshlrev_b32_e32 v182, 16, v120
	v_lshlrev_b64 v[214:215], 11, v[168:169]
	v_fma_f32 v168, v96, v182, v198
	v_lshlrev_b32_e32 v190, 16, v146
	v_lshlrev_b32_e32 v217, 16, v147
	v_and_b32_e32 v220, 0xffff0000, v147
	v_lshlrev_b32_e32 v162, 16, v129
	v_and_b32_e32 v158, 0xffff0000, v129
	v_lshlrev_b32_e32 v147, 16, v183
	v_and_b32_e32 v129, 0xffff0000, v183
	v_lshlrev_b32_e32 v183, 16, v124
	v_add_f32_e32 v168, v168, v199
	v_and_b32_e32 v167, 0xffff0000, v180
	v_and_b32_e32 v166, 0xffff0000, v128
	v_mov_b32_e32 v170, v93
	v_mov_b32_e32 v171, v101
	v_mul_f32_e32 v190, v168, v190
	v_pk_mul_f32 v[168:169], v[174:175], v[182:183]
	v_and_b32_e32 v191, 0xffff0000, v146
	v_lshlrev_b32_e32 v223, 16, v148
	v_and_b32_e32 v224, 0xffff0000, v148
	v_lshlrev_b32_e32 v225, 16, v149
	v_and_b32_e32 v226, 0xffff0000, v149
	v_pk_mul_f32 v[200:201], v[170:171], v[166:167]
	v_lshlrev_b32_e32 v146, 16, v131
	v_mov_b32_e32 v148, v82
	v_mov_b32_e32 v149, v90
	v_fma_f32 v168, v96, v173, v168
	v_and_b32_e32 v180, 0xffff0000, v120
	v_lshlrev_b32_e32 v163, 16, v181
	v_and_b32_e32 v159, 0xffff0000, v181
	v_pk_mul_f32 v[210:211], v[148:149], v[146:147]
	v_lshlrev_b32_e32 v146, 16, v176
	v_add_f32_e32 v168, v168, v169
	v_and_b32_e32 v181, 0xffff0000, v124
	v_fma_f32 v120, v97, v180, v200
	v_mul_f32_e32 v146, v168, v146
	v_add_f32_e32 v120, v120, v201
	v_pk_mul_f32 v[168:169], v[170:171], v[180:181]
	v_mov_b32_e32 v164, v94
	v_mov_b32_e32 v165, v102
	v_lshlrev_b32_e32 v154, 16, v130
	v_mov_b32_e32 v156, v80
	v_mov_b32_e32 v157, v88
	v_mul_f32_e32 v182, v120, v191
	v_fma_f32 v120, v97, v167, v168
	v_pk_mul_f32 v[202:203], v[164:165], v[162:163]
	v_pk_mul_f32 v[206:207], v[156:157], v[154:155]
	v_and_b32_e32 v154, 0xffff0000, v176
	v_lshlrev_b32_e32 v227, 16, v178
	v_and_b32_e32 v228, 0xffff0000, v178
	v_add_f32_e32 v120, v120, v169
	v_lshlrev_b32_e32 v178, 16, v121
	v_lshlrev_b32_e32 v229, 16, v179
	v_and_b32_e32 v230, 0xffff0000, v179
	v_mul_f32_e32 v154, v120, v154
	v_lshlrev_b32_e32 v179, 16, v125
	v_fma_f32 v120, v98, v178, v202
	v_add_f32_e32 v120, v120, v203
	v_pk_mul_f32 v[168:169], v[164:165], v[178:179]
	v_mov_b32_e32 v160, v95
	v_mov_b32_e32 v161, v103
	v_mul_f32_e32 v200, v120, v217
	v_fma_f32 v120, v98, v163, v168
	v_pk_mul_f32 v[204:205], v[160:161], v[158:159]
	v_lshlrev_b32_e32 v162, 16, v177
	v_add_f32_e32 v120, v120, v169
	v_and_b32_e32 v176, 0xffff0000, v121
	v_mul_f32_e32 v162, v120, v162
	v_fma_f32 v120, v99, v176, v204
	v_add_f32_e32 v120, v120, v205
	v_lshlrev_b32_e32 v124, 16, v122
	v_and_b32_e32 v150, 0xffff0000, v130
	v_mov_b32_e32 v152, v81
	v_mov_b32_e32 v153, v89
	v_mul_f32_e32 v178, v120, v220
	v_fma_f32 v120, v84, v124, v206
	v_pk_mul_f32 v[208:209], v[152:153], v[150:151]
	v_and_b32_e32 v172, 0xffff0000, v177
	v_and_b32_e32 v177, 0xffff0000, v125
	v_add_f32_e32 v120, v120, v207
	v_and_b32_e32 v122, 0xffff0000, v122
	v_pk_mul_f32 v[198:199], v[160:161], v[176:177]
	v_mul_f32_e32 v176, v120, v223
	v_fma_f32 v120, v85, v122, v208
	v_mul_f32_e32 v191, v182, v182
	v_add_f32_e32 v120, v120, v209
	v_lshlrev_b32_e32 v168, 16, v123
	v_fmac_f32_e32 v191, v190, v190
	v_mul_f32_e32 v201, v120, v224
	v_fma_f32 v120, v86, v168, v210
	v_and_b32_e32 v128, 0xffff0000, v131
	v_mov_b32_e32 v130, v83
	v_mov_b32_e32 v131, v91
	v_fmac_f32_e32 v191, v200, v200
	v_add_f32_e32 v120, v120, v211
	v_and_b32_e32 v137, 64, v222
	v_pk_mul_f32 v[212:213], v[130:131], v[128:129]
	v_fmac_f32_e32 v191, v178, v178
	v_mul_f32_e32 v202, v120, v225
	v_and_b32_e32 v120, 0xffff0000, v123
	v_xor_b32_e32 v135, 1, v222
	v_add_u32_e32 v137, 64, v137
	v_fmac_f32_e32 v191, v176, v176
	v_fma_f32 v121, v87, v120, v212
	v_cmp_lt_i32_e32 vcc, v135, v137
	v_fmac_f32_e32 v191, v201, v201
	v_add_f32_e32 v121, v121, v213
	v_cndmask_b32_e32 v135, v222, v135, vcc
	v_fmac_f32_e32 v191, v202, v202
	v_mul_f32_e32 v203, v121, v226
	v_lshlrev_b32_e32 v145, 2, v135
	v_fmac_f32_e32 v191, v203, v203
	ds_bpermute_b32 v121, v145, v191
	v_xor_b32_e32 v135, 2, v222
	v_cmp_lt_i32_e32 vcc, v135, v137
	v_fma_f32 v123, v99, v159, v198
	v_add_f32_e32 v123, v123, v199
	v_cndmask_b32_e32 v135, v222, v135, vcc
	v_lshlrev_b32_e32 v143, 2, v135
	s_waitcnt lgkmcnt(0)
	v_add_f32_e32 v121, v191, v121
	v_mul_f32_e32 v172, v123, v172
	ds_bpermute_b32 v123, v143, v121
	v_xor_b32_e32 v135, 4, v222
	v_cmp_lt_i32_e32 vcc, v135, v137
	v_lshlrev_b32_e32 v125, 16, v126
	v_pk_mul_f32 v[198:199], v[156:157], v[124:125]
	v_cndmask_b32_e32 v135, v222, v135, vcc
	v_lshlrev_b32_e32 v141, 2, v135
	s_waitcnt lgkmcnt(0)
; __device__ __forceinline__ unsigned pk2(float lo, float hi) { return pg8::cvt_pk_bf16(lo, hi); }
; template <bool DO_SWA, bool DO_MEM>
; __device__ __forceinline__ void attn_unit(const Args& a, unsigned char* ws, LAS unsigned char* lds, int l, int tid_in, int lane_in, int wave, int unit) {
;     ...
; #pragma unroll
;             for (int i = 0; i < 4; ++i) {
;                 float ua[8], ub_[8], uc[8], cbv[8], cy[8];
;                 unpack8(cu[i], ua); unpack8(cu[i + 1], ub_); unpack8(cu[i + 2], uc); unpack8(ccb[i], cbv);
;                 float ss = 0.f;
; #pragma unroll
;                 for (int j = 0; j < 8; ++j) { const float y = ua[j] * w0[j] + ub_[j] * w1[j] + uc[j] * w2[j]; cy[j] = cbv[j] * y; ss += cy[j] * cy[j]; }
;                 ss += __shfl_xor(ss, 1); ss += __shfl_xor(ss, 2); ss += __shfl_xor(ss, 4); ss += __shfl_xor(ss, 8); ss += __shfl_xor(ss, 16);
;                 const float rs = 1.0f / sqrtf(ss * (1.0f / 256.0f) + EPS);
;                 v4u o; o.x = pk2(cy[0] * rs, cy[1] * rs); o.y = pk2(cy[2] * rs, cy[3] * rs); o.z = pk2(cy[4] * rs, cy[5] * rs); o.w = pk2(cy[6] * rs, cy[7] * rs);
;                 *(v4u*)(MIX + (size_t)(row0 + t0 + i) * D + 512 + ch) = o;
	v_add_f32_e32 v121, v121, v123
	ds_bpermute_b32 v169, v141, v121
	v_xor_b32_e32 v135, 8, v222
	v_cmp_lt_i32_e32 vcc, v135, v137
	v_fma_f32 v124, v84, v155, v198
	v_and_b32_e32 v123, 0xffff0000, v126
	v_cndmask_b32_e32 v135, v222, v135, vcc
	v_lshlrev_b32_e32 v139, 2, v135
	s_waitcnt lgkmcnt(0)
	v_add_f32_e32 v121, v121, v169
	v_add_f32_e32 v124, v124, v199
	v_pk_mul_f32 v[198:199], v[152:153], v[122:123]
	ds_bpermute_b32 v122, v139, v121
	v_xor_b32_e32 v135, 16, v222
	v_cmp_lt_i32_e32 vcc, v135, v137
	s_mov_b32 s2, 0xf800000
	v_fma_f32 v126, v85, v151, v198
	v_cndmask_b32_e32 v135, v222, v135, vcc
	v_lshlrev_b32_e32 v135, 2, v135
	s_waitcnt lgkmcnt(0)
	v_add_f32_e32 v121, v121, v122
	ds_bpermute_b32 v122, v135, v121
	v_lshlrev_b32_e32 v169, 16, v127
	v_add_f32_e32 v126, v126, v199
	v_pk_mul_f32 v[198:199], v[148:149], v[168:169]
	v_mul_f32_e32 v191, v126, v228
	s_waitcnt lgkmcnt(0)
	v_add_f32_e32 v121, v121, v122
	v_fmamk_f32 v121, v121, 0x3b800000, v218
	v_mul_f32_e32 v122, 0x4f800000, v121
	v_cmp_gt_f32_e32 vcc, s2, v121
	v_fma_f32 v126, v86, v147, v198
	v_add_f32_e32 v126, v126, v199
	v_cndmask_b32_e32 v122, v121, v122, vcc
	v_sqrt_f32_e32 v168, v122
	v_mul_f32_e32 v204, v126, v229
	v_and_b32_e32 v121, 0xffff0000, v127
	v_mul_f32_e32 v180, v154, v154
	v_add_u32_e32 v126, -1, v168
	v_fma_f32 v127, -v126, v168, v122
	v_cmp_ge_f32_e64 s[0:1], 0, v127
	v_add_u32_e32 v127, 1, v168
	v_fmac_f32_e32 v180, v146, v146
	v_cndmask_b32_e64 v126, v168, v126, s[0:1]
	v_fma_f32 v168, -v127, v168, v122
	v_cmp_lt_f32_e64 s[0:1], 0, v168
	v_fmac_f32_e32 v180, v162, v162
	v_fmac_f32_e32 v180, v172, v172
	v_cndmask_b32_e64 v126, v126, v127, s[0:1]
	v_mul_f32_e32 v127, 0x37800000, v126
	v_cndmask_b32_e32 v126, v126, v127, vcc
	v_cmp_class_f32_e32 vcc, v122, v219
	v_mul_f32_e32 v124, v124, v227
	v_fmac_f32_e32 v180, v124, v124
	v_cndmask_b32_e32 v122, v126, v122, vcc
	v_pk_mul_f32 v[126:127], v[130:131], v[120:121]
	v_fmac_f32_e32 v180, v191, v191
	v_fma_f32 v120, v87, v129, v126
	v_add_f32_e32 v120, v120, v127
	v_fmac_f32_e32 v180, v204, v204
	v_mul_f32_e32 v120, v120, v230
	v_fmac_f32_e32 v180, v120, v120
	ds_bpermute_b32 v199, v145, v180
	v_div_scale_f32 v168, s[0:1], v122, v122, 1.0
	v_rcp_f32_e32 v198, v168
	v_lshl_add_u64 v[126:127], s[20:21], 0, v[214:215]
	s_waitcnt lgkmcnt(0)
	v_add_f32_e32 v180, v180, v199
	ds_bpermute_b32 v199, v143, v180
	v_fma_f32 v205, -v168, v198, 1.0
	v_fmac_f32_e32 v198, v205, v198
	v_div_scale_f32 v205, vcc, 1.0, v122, 1.0
	s_waitcnt lgkmcnt(0)
	v_add_f32_e32 v180, v180, v199
	ds_bpermute_b32 v199, v141, v180
	v_mul_f32_e32 v206, v205, v198
	v_fma_f32 v207, -v168, v206, v205
	v_fmac_f32_e32 v206, v207, v198
	v_fma_f32 v168, -v168, v206, v205
	s_waitcnt lgkmcnt(0)
	v_add_f32_e32 v180, v180, v199
	ds_bpermute_b32 v199, v139, v180
	v_div_fmas_f32 v168, v168, v198, v206
	v_div_fixup_f32 v122, v168, v122, 1.0
	v_mul_f32_e32 v168, v190, v122
	v_mul_f32_e32 v182, v182, v122
	v_cvt_pk_bf16_f32 v198, v168, v182
	s_waitcnt lgkmcnt(0)
	v_add_f32_e32 v168, v180, v199
	ds_bpermute_b32 v180, v135, v168
	v_mul_f32_e32 v178, v178, v122
	v_mul_f32_e32 v182, v200, v122
	v_cvt_pk_bf16_f32 v199, v182, v178
	v_mul_f32_e32 v176, v176, v122
	s_waitcnt lgkmcnt(0)
	v_add_f32_e32 v168, v168, v180
	v_fmamk_f32 v168, v168, 0x3b800000, v218
	v_mul_f32_e32 v178, 0x4f800000, v168
	v_cmp_gt_f32_e32 vcc, s2, v168
	v_mul_f32_e32 v180, v201, v122
	v_cvt_pk_bf16_f32 v200, v176, v180
	v_mul_f32_e32 v176, v202, v122
	v_cndmask_b32_e32 v168, v168, v178, vcc
	v_sqrt_f32_e32 v178, v168
	v_mul_f32_e32 v122, v203, v122
	v_cvt_pk_bf16_f32 v201, v176, v122
	v_lshl_add_u64 v[126:127], v[126:127], 0, v[184:185]
	v_add_u32_e32 v180, -1, v178
	v_fma_f32 v182, -v180, v178, v168
	v_cmp_ge_f32_e64 s[0:1], 0, v182
	v_add_u32_e32 v182, 1, v178
	global_store_dwordx4 v[126:127], v[198:201], off offset:1024
	v_cndmask_b32_e64 v180, v178, v180, s[0:1]
	v_fma_f32 v178, -v182, v178, v168
	v_cmp_lt_f32_e64 s[0:1], 0, v178
	v_lshlrev_b32_e32 v176, 16, v114
	s_movk_i32 s3, 0x190
	v_cndmask_b32_e64 v178, v180, v182, s[0:1]
	v_mul_f32_e32 v180, 0x37800000, v178
	v_cndmask_b32_e32 v178, v178, v180, vcc
	v_cmp_class_f32_e32 vcc, v168, v219
	v_and_b32_e32 v182, 0xffff0000, v115
	s_nop 0
	v_cndmask_b32_e32 v168, v178, v168, vcc
	v_div_scale_f32 v178, s[0:1], v168, v168, 1.0
	v_rcp_f32_e32 v180, v178
	s_nop 0
	v_fma_f32 v122, -v178, v180, 1.0
	v_fmac_f32_e32 v180, v122, v180
	v_div_scale_f32 v122, vcc, 1.0, v168, 1.0
	v_mul_f32_e32 v126, v122, v180
	v_fma_f32 v127, -v178, v126, v122
	v_fmac_f32_e32 v126, v127, v180
	v_fma_f32 v122, -v178, v126, v122
	v_div_fmas_f32 v122, v122, v180, v126
	v_div_fixup_f32 v122, v122, v168, 1.0
	v_mul_f32_e32 v126, v146, v122
	v_mul_f32_e32 v127, v154, v122
	v_cvt_pk_bf16_f32 v198, v126, v127
	v_mul_f32_e32 v126, v162, v122
	v_mul_f32_e32 v127, v172, v122
	v_lshlrev_b32_e32 v154, 16, v112
	v_and_b32_e32 v162, 0xffff0000, v112
	v_lshlrev_b32_e32 v168, 16, v113
	v_and_b32_e32 v172, 0xffff0000, v113
	v_lshlrev_b32_e32 v112, 16, v104
	v_lshlrev_b32_e32 v113, 16, v108
	v_and_b32_e32 v178, 0xffff0000, v114
	v_lshlrev_b32_e32 v180, 16, v115
	v_pk_mov_b32 v[114:115], v[172:173], v[112:113] op_sel:[1,0]
	v_mul_f32_e32 v124, v124, v122
	v_pk_mul_f32 v[114:115], v[174:175], v[114:115]
	v_mul_f32_e32 v120, v120, v122
	v_fma_f32 v114, v96, v183, v114
	v_cvt_pk_bf16_f32 v199, v126, v127
	v_mul_f32_e32 v126, v191, v122
	v_cvt_pk_bf16_f32 v200, v124, v126
	v_mul_f32_e32 v124, v204, v122
	v_cvt_pk_bf16_f32 v201, v124, v120
	v_lshlrev_b32_e32 v120, 16, v116
	v_add_f32_e32 v114, v114, v115
	v_mul_f32_e32 v120, v114, v120
	v_mov_b32_e32 v114, v96
	v_mov_b32_e32 v115, v100
; __device__ __forceinline__ unsigned pk2(float lo, float hi) { return pg8::cvt_pk_bf16(lo, hi); }
; template <bool DO_SWA, bool DO_MEM>
; __device__ __forceinline__ void attn_unit(const Args& a, unsigned char* ws, LAS unsigned char* lds, int l, int tid_in, int lane_in, int wave, int unit) {
;     ...
; #pragma unroll
;             for (int i = 0; i < 4; ++i) {
;                 float ua[8], ub_[8], uc[8], cbv[8], cy[8];
;                 unpack8(cu[i], ua); unpack8(cu[i + 1], ub_); unpack8(cu[i + 2], uc); unpack8(ccb[i], cbv);
;                 float ss = 0.f;
; #pragma unroll
;                 for (int j = 0; j < 8; ++j) { const float y = ua[j] * w0[j] + ub_[j] * w1[j] + uc[j] * w2[j]; cy[j] = cbv[j] * y; ss += cy[j] * cy[j]; }
;                 ss += __shfl_xor(ss, 1); ss += __shfl_xor(ss, 2); ss += __shfl_xor(ss, 4); ss += __shfl_xor(ss, 8); ss += __shfl_xor(ss, 16);
;                 const float rs = 1.0f / sqrtf(ss * (1.0f / 256.0f) + EPS);
;                 v4u o; o.x = pk2(cy[0] * rs, cy[1] * rs); o.y = pk2(cy[2] * rs, cy[3] * rs); o.z = pk2(cy[4] * rs, cy[5] * rs); o.w = pk2(cy[6] * rs, cy[7] * rs);
;                 *(v4u*)(MIX + (size_t)(row0 + t0 + i) * D + 512 + ch) = o;
	v_pk_mul_f32 v[112:113], v[114:115], v[112:113]
	v_mov_b32_e32 v100, v97
	v_fma_f32 v92, v92, v183, v112
	v_add_f32_e32 v92, v92, v113
	v_and_b32_e32 v113, 0xffff0000, v108
	v_and_b32_e32 v112, 0xffff0000, v104
	v_pk_mov_b32 v[114:115], v[166:167], v[112:113] op_sel:[1,0]
	v_mul_f32_e32 v154, v92, v154
	v_pk_mul_f32 v[114:115], v[170:171], v[114:115]
	v_and_b32_e32 v122, 0xffff0000, v116
	v_fma_f32 v92, v97, v181, v114
	v_add_f32_e32 v92, v92, v115
	v_pk_mul_f32 v[96:97], v[100:101], v[112:113]
	v_mul_f32_e32 v104, v92, v122
	v_fma_f32 v92, v93, v181, v96
	v_add_f32_e32 v92, v92, v97
	v_mul_f32_e32 v112, v92, v162
	v_lshlrev_b32_e32 v92, 16, v105
	v_lshlrev_b32_e32 v93, 16, v109
	v_pk_mov_b32 v[96:97], v[162:163], v[92:93] op_sel:[1,0]
	v_lshlrev_b32_e32 v124, 16, v117
	v_pk_mul_f32 v[96:97], v[164:165], v[96:97]
	v_add_u32_e32 v126, -2, v144
	v_fma_f32 v96, v98, v179, v96
	v_add_f32_e32 v96, v96, v97
	v_mul_f32_e32 v114, v96, v124
	v_mov_b32_e32 v96, v98
	v_mov_b32_e32 v97, v102
	v_pk_mul_f32 v[92:93], v[96:97], v[92:93]
	v_ashrrev_i32_e32 v127, 31, v126
	v_fma_f32 v92, v94, v179, v92
	v_add_f32_e32 v92, v92, v93
	v_mul_f32_e32 v115, v92, v168
	v_and_b32_e32 v93, 0xffff0000, v109
	v_and_b32_e32 v92, 0xffff0000, v105
	v_lshlrev_b64 v[126:127], 11, v[126:127]
	v_pk_mov_b32 v[96:97], v[158:159], v[92:93] op_sel:[1,0]
	v_lshl_add_u64 v[126:127], s[20:21], 0, v[126:127]
	v_pk_mul_f32 v[96:97], v[160:161], v[96:97]
	v_lshl_add_u64 v[126:127], v[126:127], 0, v[184:185]
	v_fma_f32 v94, v99, v177, v96
	v_mov_b32_e32 v102, v99
	global_store_dwordx4 v[126:127], v[198:201], off offset:1024
	v_and_b32_e32 v126, 0xffff0000, v117
	v_add_f32_e32 v94, v94, v97
	v_pk_mul_f32 v[92:93], v[102:103], v[92:93]
	v_mul_f32_e32 v105, v94, v126
	v_fma_f32 v92, v95, v177, v92
	v_lshlrev_b32_e32 v94, 16, v106
	v_lshlrev_b32_e32 v95, 16, v110
	v_pk_mov_b32 v[96:97], v[154:155], v[94:95] op_sel:[1,0]
	v_lshlrev_b32_e32 v127, 16, v118
	v_pk_mul_f32 v[96:97], v[156:157], v[96:97]
	v_and_b32_e32 v118, 0xffff0000, v118
	v_fma_f32 v96, v84, v125, v96
	v_add_f32_e32 v96, v96, v97
	v_mul_f32_e32 v109, v96, v127
	v_and_b32_e32 v97, 0xffff0000, v110
	v_and_b32_e32 v96, 0xffff0000, v106
	v_pk_mov_b32 v[98:99], v[150:151], v[96:97] op_sel:[1,0]
	v_lshlrev_b32_e32 v146, 16, v119
	v_pk_mul_f32 v[98:99], v[152:153], v[98:99]
	v_mul_f32_e32 v108, v104, v104
	v_fma_f32 v98, v85, v123, v98
	v_add_f32_e32 v98, v98, v99
	v_mul_f32_e32 v106, v98, v118
	v_lshlrev_b32_e32 v98, 16, v107
	v_lshlrev_b32_e32 v99, 16, v111
	v_pk_mov_b32 v[100:101], v[146:147], v[98:99] op_sel:[1,0]
	v_fmac_f32_e32 v108, v120, v120
	v_pk_mul_f32 v[100:101], v[148:149], v[100:101]
	v_fmac_f32_e32 v108, v114, v114
	v_fma_f32 v100, v86, v169, v100
	v_add_f32_e32 v100, v100, v101
	v_mul_f32_e32 v110, v100, v146
	v_and_b32_e32 v101, 0xffff0000, v111
	v_and_b32_e32 v100, 0xffff0000, v107
	v_pk_mov_b32 v[102:103], v[128:129], v[100:101] op_sel:[1,0]
	v_fmac_f32_e32 v108, v105, v105
	v_pk_mul_f32 v[102:103], v[130:131], v[102:103]
	v_fmac_f32_e32 v108, v109, v109
	v_fma_f32 v102, v87, v121, v102
	v_and_b32_e32 v119, 0xffff0000, v119
	v_fmac_f32_e32 v108, v106, v106
	v_add_f32_e32 v102, v102, v103
	v_fmac_f32_e32 v108, v110, v110
	v_mul_f32_e32 v102, v102, v119
	v_fmac_f32_e32 v108, v102, v102
	ds_bpermute_b32 v103, v145, v108
	v_add_f32_e32 v92, v92, v93
	v_mul_f32_e32 v107, v92, v172
	v_mov_b32_e32 v92, v84
	v_mov_b32_e32 v93, v88
	s_waitcnt lgkmcnt(0)
	v_add_f32_e32 v84, v108, v103
	ds_bpermute_b32 v103, v143, v84
	v_pk_mul_f32 v[92:93], v[92:93], v[94:95]
	v_mov_b32_e32 v88, v85
	v_fma_f32 v80, v80, v125, v92
	v_add_f32_e32 v80, v80, v93
	s_waitcnt lgkmcnt(0)
	v_add_f32_e32 v92, v84, v103
	ds_bpermute_b32 v93, v141, v92
	v_mul_f32_e32 v94, v80, v176
	v_pk_mul_f32 v[84:85], v[88:89], v[96:97]
	v_mul_f32_e32 v113, v112, v112
	v_fma_f32 v81, v81, v123, v84
	s_waitcnt lgkmcnt(0)
	v_add_f32_e32 v80, v92, v93
	ds_bpermute_b32 v88, v139, v80
	v_add_f32_e32 v81, v81, v85
	v_mul_f32_e32 v89, v81, v178
	v_mov_b32_e32 v81, v90
	v_fmac_f32_e32 v113, v154, v154
	s_waitcnt lgkmcnt(0)
	v_add_f32_e32 v84, v80, v88
	ds_bpermute_b32 v85, v135, v84
	v_mov_b32_e32 v80, v86
	v_pk_mul_f32 v[80:81], v[80:81], v[98:99]
	v_fmac_f32_e32 v113, v115, v115
	v_fma_f32 v80, v82, v169, v80
	s_waitcnt lgkmcnt(0)
	v_add_f32_e32 v82, v84, v85
	v_fmamk_f32 v82, v82, 0x3b800000, v218
	v_mul_f32_e32 v84, 0x4f800000, v82
	v_cmp_gt_f32_e32 vcc, s2, v82
	v_add_f32_e32 v80, v80, v81
	v_mul_f32_e32 v86, v80, v180
	v_cndmask_b32_e32 v82, v82, v84, vcc
	v_sqrt_f32_e32 v84, v82
	v_mov_b32_e32 v90, v87
	v_fmac_f32_e32 v113, v107, v107
	v_fmac_f32_e32 v113, v94, v94
	v_add_u32_e32 v80, -1, v84
	v_fma_f32 v81, -v80, v84, v82
	v_cmp_ge_f32_e64 s[0:1], 0, v81
	v_add_u32_e32 v81, 1, v84
	v_fmac_f32_e32 v113, v89, v89
	v_cndmask_b32_e64 v80, v84, v80, s[0:1]
	v_fma_f32 v84, -v81, v84, v82
	v_cmp_lt_f32_e64 s[0:1], 0, v84
	v_fmac_f32_e32 v113, v86, v86
	v_add_u32_e32 v116, -1, v144
	v_cndmask_b32_e64 v80, v80, v81, s[0:1]
	v_mul_f32_e32 v81, 0x37800000, v80
	v_cndmask_b32_e32 v80, v80, v81, vcc
	v_cmp_class_f32_e32 vcc, v82, v219
	v_ashrrev_i32_e32 v117, 31, v116
	v_lshlrev_b64 v[116:117], 11, v[116:117]
	v_cndmask_b32_e32 v82, v80, v82, vcc
	v_pk_mul_f32 v[80:81], v[90:91], v[100:101]
	v_div_scale_f32 v88, s[0:1], v82, v82, 1.0
	v_fma_f32 v80, v83, v121, v80
	v_add_f32_e32 v80, v80, v81
	v_mul_f32_e32 v87, v80, v182
	v_fmac_f32_e32 v113, v87, v87
	v_rcp_f32_e32 v92, v88
	ds_bpermute_b32 v83, v145, v113
	v_lshl_add_u64 v[80:81], s[20:21], 0, v[116:117]
	v_lshl_add_u64 v[84:85], v[80:81], 0, v[184:185]
	v_fma_f32 v80, -v88, v92, 1.0
	v_fmac_f32_e32 v92, v80, v92
	s_waitcnt lgkmcnt(0)
; #define LAS __attribute__((address_space(3)))
; #define LAS __attribute__((address_space(3)))
; __device__ __forceinline__ unsigned pk2(float lo, float hi) { return pg8::cvt_pk_bf16(lo, hi); }
; template <bool DO_SWA, bool DO_MEM>
; __device__ __forceinline__ void attn_unit(const Args& a, unsigned char* ws, LAS unsigned char* lds, int l, int tid_in, int lane_in, int wave, int unit) {
;     ...
;                 ss += __shfl_xor(ss, 1); ss += __shfl_xor(ss, 2); ss += __shfl_xor(ss, 4); ss += __shfl_xor(ss, 8); ss += __shfl_xor(ss, 16);
;                 const float rs = 1.0f / sqrtf(ss * (1.0f / 256.0f) + EPS);
;                 v4u o; o.x = pk2(cy[0] * rs, cy[1] * rs); o.y = pk2(cy[2] * rs, cy[3] * rs); o.z = pk2(cy[4] * rs, cy[5] * rs); o.w = pk2(cy[6] * rs, cy[7] * rs);
;                 *(v4u*)(MIX + (size_t)(row0 + t0 + i) * D + 512 + ch) = o;
;             }
;         }
;         if constexpr (DO_SWA)
; #pragma unroll
;         for (int i = 0; i < 6; ++i) {
;             const int s = i >> 1, rem = tid + 512 * (i & 1);
;             { const int key = rem >> 4, c16 = rem & 15; *(LAS v4u*)(lds + A_KS + ((c16 >> 3) * 192 + s * 64 + key) * 144 + (c16 & 7) * 16) = kst[i]; }
;             { const int col = rem >> 3, kc = rem & 7; *(LAS v4u*)(lds + A_VT1 + col * 400 + (s * 64 + kc * 8) * 2) = vst[i]; }
;         }
;     ...
;             for (int hh = 0; hh < 4; ++hh) {
;                 const int h = g * 4 + hh;
;                 const float sk = a.in[12][l * 8 + h] * LOG2E;
;                 f32x4 o[4];
;                 attn_core<12, 400, true>(lds + A_KS + g * 192 * 144 + fq * 16, lds + A_VT1 + (g * 64 + fr) * 400 + fq * 16, qsw[hh][0], qsw[hh][1], sk, mskbits, fr, o);
	v_add_f32_e32 v80, v113, v83
	ds_bpermute_b32 v81, v143, v80
	v_div_scale_f32 v83, vcc, 1.0, v82, 1.0
	v_mul_f32_e32 v90, v83, v92
	v_fma_f32 v91, -v88, v90, v83
	s_waitcnt lgkmcnt(0)
	v_add_f32_e32 v80, v80, v81
	ds_bpermute_b32 v81, v141, v80
	v_fmac_f32_e32 v90, v91, v92
	v_fma_f32 v83, -v88, v90, v83
	v_div_fmas_f32 v83, v83, v92, v90
	v_div_fixup_f32 v83, v83, v82, 1.0
	s_waitcnt lgkmcnt(0)
	v_add_f32_e32 v81, v80, v81
	ds_bpermute_b32 v88, v139, v81
	v_mul_f32_e32 v80, v120, v83
	v_mul_f32_e32 v82, v104, v83
	v_cvt_pk_bf16_f32 v80, v80, v82
	v_mul_f32_e32 v90, v105, v83
	s_waitcnt lgkmcnt(0)
	v_add_f32_e32 v82, v81, v88
	ds_bpermute_b32 v88, v135, v82
	v_mul_f32_e32 v81, v114, v83
	v_cvt_pk_bf16_f32 v81, v81, v90
	v_mul_f32_e32 v90, v109, v83
	v_ashrrev_i32_e32 v145, 31, v144
	s_waitcnt lgkmcnt(0)
	v_add_f32_e32 v82, v82, v88
	v_fmamk_f32 v82, v82, 0x3b800000, v218
	v_mul_f32_e32 v88, 0x4f800000, v82
	v_cmp_gt_f32_e32 vcc, s2, v82
	s_movk_i32 s2, 0x90
	s_nop 0
	v_cndmask_b32_e32 v88, v82, v88, vcc
	v_sqrt_f32_e32 v91, v88
	v_mul_f32_e32 v82, v106, v83
	v_cvt_pk_bf16_f32 v82, v90, v82
	v_mul_f32_e32 v90, v110, v83
	v_add_u32_e32 v92, -1, v91
	v_fma_f32 v93, -v92, v91, v88
	v_cmp_ge_f32_e64 s[0:1], 0, v93
	v_add_u32_e32 v93, 1, v91
	v_mul_f32_e32 v83, v102, v83
	v_cndmask_b32_e64 v92, v91, v92, s[0:1]
	v_fma_f32 v91, -v93, v91, v88
	v_cmp_lt_f32_e64 s[0:1], 0, v91
	v_cvt_pk_bf16_f32 v83, v90, v83
	global_store_dwordx4 v[84:85], v[80:83], off offset:1024
	s_nop 0
	v_cndmask_b32_e64 v91, v92, v93, s[0:1]
	v_mul_f32_e32 v92, 0x37800000, v91
	v_cndmask_b32_e32 v91, v91, v92, vcc
	v_cmp_class_f32_e32 vcc, v88, v219
	s_nop 1
	v_cndmask_b32_e32 v88, v91, v88, vcc
	v_div_scale_f32 v91, s[0:1], v88, v88, 1.0
	v_rcp_f32_e32 v92, v91
	s_nop 0
	v_fma_f32 v80, -v91, v92, 1.0
	v_fmac_f32_e32 v92, v80, v92
	v_div_scale_f32 v80, vcc, 1.0, v88, 1.0
	v_mul_f32_e32 v81, v80, v92
	v_fma_f32 v82, -v91, v81, v80
	v_fmac_f32_e32 v81, v82, v92
	v_fma_f32 v80, -v91, v81, v80
	v_div_fmas_f32 v80, v80, v92, v81
	v_div_fixup_f32 v83, v80, v88, 1.0
	v_mul_f32_e32 v80, v154, v83
	v_mul_f32_e32 v81, v112, v83
	v_cvt_pk_bf16_f32 v80, v80, v81
	v_mul_f32_e32 v81, v115, v83
	v_mul_f32_e32 v82, v107, v83
	v_cvt_pk_bf16_f32 v81, v81, v82
	v_mul_f32_e32 v82, v94, v83
	v_mul_f32_e32 v84, v89, v83
	v_cvt_pk_bf16_f32 v82, v82, v84
	v_mul_f32_e32 v84, v86, v83
	v_mul_f32_e32 v83, v87, v83
	v_cvt_pk_bf16_f32 v83, v84, v83
	v_lshlrev_b64 v[84:85], 11, v[144:145]
	v_lshl_add_u64 v[84:85], s[20:21], 0, v[84:85]
	v_lshl_add_u64 v[84:85], v[84:85], 0, v[184:185]
	global_store_dwordx4 v[84:85], v[80:83], off offset:1024
	s_nop 1
	v_bfe_i32 v80, v196, 3, 1
	v_and_b32_e32 v81, 0xc0, v80
	v_and_b32_e32 v80, 0x70, v197
	v_add_u32_e32 v80, 0, v80
	v_add_u32_e32 v82, v81, v134
	v_mad_u64_u32 v[82:83], s[0:1], v82, s2, v[80:81]
	ds_write_b128 v82, v[36:39]
	v_mul_lo_u32 v36, v140, s3
	v_add3_u32 v36, 0, v36, v138
	ds_write_b128 v36, v[32:35] offset:55296
	v_add_u32_e32 v32, v81, v136
	v_mad_u64_u32 v[32:33], s[0:1], v32, s2, v[80:81]
	ds_write_b128 v32, v[56:59]
	v_mul_lo_u32 v32, v142, s3
	v_add_u32_e32 v35, 64, v81
	v_add3_u32 v34, 0, v32, v138
	v_add_u32_e32 v32, v35, v134
	v_mad_u64_u32 v[32:33], s[0:1], v32, s2, v[80:81]
	ds_write_b128 v34, v[68:71] offset:55296
	ds_write_b128 v32, v[52:55]
	ds_write_b128 v36, v[40:43] offset:55424
	v_add_u32_e32 v32, v35, v136
	v_mad_u64_u32 v[32:33], s[0:1], v32, s2, v[80:81]
	v_add_u32_e32 v35, 0x80, v81
	ds_write_b128 v32, v[44:47]
	ds_write_b128 v34, v[48:51] offset:55424
	v_add_u32_e32 v32, v35, v134
	v_mad_u64_u32 v[32:33], s[0:1], v32, s2, v[80:81]
	ds_write_b128 v32, v[60:63]
	ds_write_b128 v36, v[64:67] offset:55552
	v_add_u32_e32 v32, v35, v136
	v_mad_u64_u32 v[32:33], s[0:1], v32, s2, v[80:81]
	ds_write_b128 v32, v[72:75]
	ds_write_b128 v34, v[76:79] offset:55552
	v_readlane_b32 s0, v251, 22
	v_and_b32_e32 v32, -16, v133
	v_and_b32_e32 v34, 3, v133
	v_or_b32_e32 v33, s0, v195
	v_mul_lo_u32 v33, v33, s3
	v_add3_u32 v78, 0, v33, v32
	v_lshlrev_b32_e32 v33, 1, v195
	v_and_or_b32 v33, v33, 24, v34
	v_mul_u32_u24_e32 v33, 0x90, v33
	v_readlane_b32 s0, v251, 24
	s_waitcnt lgkmcnt(0)
	s_barrier
	v_add3_u32 v79, s0, v32, v33
	v_xor_b32_e32 v32, 32, v222
	v_cmp_lt_i32_e32 vcc, v32, v137
	v_mov_b32_e32 v80, s98
	s_nop 0
	v_cndmask_b32_e32 v32, v222, v32, vcc
	v_lshlrev_b32_e32 v76, 2, v32
	s_waitcnt lgkmcnt(0)
	ds_read_b128 v[92:95], v79
	ds_read_b128 v[196:199], v79 offset:64
	ds_read_b128 v[200:203], v79 offset:576
	ds_read_b128 v[204:207], v79 offset:640
	ds_read_b128 v[208:211], v79 offset:4608
	ds_read_b128 v[212:215], v79 offset:4672
	ds_read_b128 v[228:231], v79 offset:5184
	ds_read_b128 v[232:235], v79 offset:5248
	ds_read_b128 v[236:239], v79 offset:9216
	ds_read_b128 v[240:243], v79 offset:9280
	ds_read_b128 v[244:247], v79 offset:9792
	s_waitcnt lgkmcnt(10)
	v_mfma_f32_16x16x32_bf16 v[32:35], v[92:95], v[24:27], 0
	s_mov_b32 s2, 0x3fb8aa3b
	v_add_u32_e32 v77, 0xd800, v78

; #define LAS __attribute__((address_space(3)))
; #define LAS __attribute__((address_space(3)))
; __device__ __forceinline__ f32x4 mfma16(bf16x8 a, bf16x8 b, f32x4 c) { return __builtin_amdgcn_mfma_f32_16x16x32_bf16(a, b, c, 0, 0, 0); }
; template <int NKT, int VSTR, bool SINK>
; __device__ __forceinline__ void attn_core(LAS const unsigned char* kb_, LAS const unsigned char* vb_, bf16x8 q0, bf16x8 q1, float sk, unsigned mskbits, int fr, f32x4 (&o)[4]) {
;     ...
; #pragma unroll
;     for (int kt = 0; kt < NKT; ++kt) {
;         const int key = (kt >> 1) * 32 + ((kt & 1) << 2) + krow;
;         LAS const unsigned char* kp = kb_ + key * 144;
;         const bf16x8 a0 = *(LAS const bf16x8*)kp, a1 = *(LAS const bf16x8*)(kp + 64);
;         const float bias = ((mskbits >> (kt >> 2)) & 1u) ? -1e30f : 0.f;
;         f32x4 s = mfma16(a0, q0, (f32x4){bias, bias, bias, bias});
;         s = mfma16(a1, q1, s);
;         S[kt] = s;
;     }
;     float mx = S[0][0];
; #pragma unroll
;     for (int kt = 0; kt < NKT; ++kt) mx = fmaxf(fmaxf(mx, fmaxf(S[kt][0], S[kt][1])), fmaxf(S[kt][2], S[kt][3]));
;     mx = fmaxf(mx, __shfl_xor(mx, 16)); mx = fmaxf(mx, __shfl_xor(mx, 32));
;     if (SINK) mx = fmaxf(mx, sk);
;     float sum = 0.f;
; #pragma unroll
;     for (int kt = 0; kt < NKT; ++kt)
; #pragma unroll
;         for (int r = 0; r < 4; ++r) { const float p = __builtin_amdgcn_exp2f(S[kt][r] - mx); S[kt][r] = p; sum += p; }
;     sum += __shfl_xor(sum, 16); sum += __shfl_xor(sum, 32);
;     if (SINK) sum += __builtin_amdgcn_exp2f(sk - mx);
	v_mul_f32_e32 v81, 0x3fb8aa3b, v80
	s_waitcnt lgkmcnt(9)
	v_mfma_f32_16x16x32_bf16 v[72:75], v[196:199], v[28:31], v[32:35]
	ds_read_b128 v[92:95], v79 offset:9856
	ds_read_b128 v[196:199], v79 offset:13824
	s_waitcnt lgkmcnt(10)
	v_mfma_f32_16x16x32_bf16 v[32:35], v[200:203], v[24:27], 0
	s_waitcnt lgkmcnt(9)
	v_mfma_f32_16x16x32_bf16 v[68:71], v[204:207], v[28:31], v[32:35]
	ds_read_b128 v[200:203], v79 offset:13888
	ds_read_b128 v[204:207], v79 offset:14400
	s_waitcnt lgkmcnt(10)
	v_mfma_f32_16x16x32_bf16 v[32:35], v[208:211], v[24:27], 0
	s_waitcnt lgkmcnt(9)
	v_mfma_f32_16x16x32_bf16 v[64:67], v[212:215], v[28:31], v[32:35]
	ds_read_b128 v[208:211], v79 offset:14464
	ds_read_b128 v[212:215], v79 offset:18432
	s_waitcnt lgkmcnt(10)
	v_mfma_f32_16x16x32_bf16 v[32:35], v[228:231], v[24:27], 0
	s_waitcnt lgkmcnt(9)
	v_mfma_f32_16x16x32_bf16 v[60:63], v[232:235], v[28:31], v[32:35]
	ds_read_b128 v[228:231], v79 offset:18496
	ds_read_b128 v[232:235], v79 offset:19008
	s_waitcnt lgkmcnt(10)
	v_mfma_f32_16x16x32_bf16 v[32:35], v[236:239], v[24:27], 0
	s_waitcnt lgkmcnt(9)
	v_mfma_f32_16x16x32_bf16 v[56:59], v[240:243], v[28:31], v[32:35]
	ds_read_b128 v[236:239], v79 offset:19072
	ds_read_b128 v[240:243], v79 offset:23040
	s_waitcnt lgkmcnt(10)
	v_mfma_f32_16x16x32_bf16 v[32:35], v[244:247], v[24:27], 0
	s_waitcnt lgkmcnt(9)
	v_mfma_f32_16x16x32_bf16 v[52:55], v[92:95], v[28:31], v[32:35]
	ds_read_b128 v[244:247], v79 offset:23104
	ds_read_b128 v[92:95], v79 offset:23616
	s_waitcnt lgkmcnt(10)
	v_mfma_f32_16x16x32_bf16 v[32:35], v[196:199], v[24:27], 0
	s_waitcnt lgkmcnt(9)
	v_mfma_f32_16x16x32_bf16 v[48:51], v[200:203], v[28:31], v[32:35]
	ds_read_b128 v[196:199], v79 offset:23680
	s_waitcnt lgkmcnt(9)
	v_mfma_f32_16x16x32_bf16 v[32:35], v[204:207], v[24:27], 0
	s_waitcnt lgkmcnt(8)
	v_mfma_f32_16x16x32_bf16 v[44:47], v[208:211], v[28:31], v[32:35]
	s_waitcnt lgkmcnt(7)
	v_mfma_f32_16x16x32_bf16 v[32:35], v[212:215], v[24:27], 0
	s_waitcnt lgkmcnt(6)
	v_mfma_f32_16x16x32_bf16 v[40:43], v[228:231], v[28:31], v[32:35]
	s_waitcnt lgkmcnt(5)
	v_mfma_f32_16x16x32_bf16 v[32:35], v[232:235], v[24:27], 0
	s_waitcnt lgkmcnt(4)
	v_mfma_f32_16x16x32_bf16 v[36:39], v[236:239], v[28:31], v[32:35]
	s_waitcnt lgkmcnt(3)
	v_mfma_f32_16x16x32_bf16 v[32:35], v[240:243], v[24:27], 0
	s_waitcnt lgkmcnt(2)
	v_mfma_f32_16x16x32_bf16 v[32:35], v[244:247], v[28:31], v[32:35]
	s_waitcnt lgkmcnt(1)
	v_mfma_f32_16x16x32_bf16 v[24:27], v[92:95], v[24:27], 0
	s_waitcnt lgkmcnt(0)
	v_mfma_f32_16x16x32_bf16 v[24:27], v[196:199], v[28:31], v[24:27]
	s_nop 0
	s_nop 0
	v_max_f32_e32 v28, v74, v75
	s_nop 0
	s_nop 0
	v_max_f32_e32 v29, v68, v69
	s_nop 0
	s_nop 0
	v_max3_f32 v28, v72, v73, v28
	v_max_f32_e32 v30, v70, v71
	v_max3_f32 v28, v28, v29, v30
	s_nop 0
	s_nop 0
	v_max_f32_e32 v29, v64, v65
	s_nop 0
	s_nop 0
	v_max_f32_e32 v30, v66, v67
	v_max3_f32 v28, v28, v29, v30
	s_nop 0
	s_nop 0
	v_max_f32_e32 v29, v60, v61
	s_nop 0
	s_nop 0
	v_max_f32_e32 v30, v62, v63
	v_max3_f32 v28, v28, v29, v30
	v_max_f32_e32 v29, v56, v57
	v_max_f32_e32 v30, v58, v59
	v_max3_f32 v28, v28, v29, v30
	v_max_f32_e32 v29, v52, v53
	v_max_f32_e32 v30, v54, v55
	v_max3_f32 v28, v28, v29, v30
	v_max_f32_e32 v29, v48, v49
	v_max_f32_e32 v30, v50, v51
	v_max3_f32 v28, v28, v29, v30
	v_max_f32_e32 v29, v44, v45
	v_max_f32_e32 v30, v46, v47
	v_max3_f32 v28, v28, v29, v30
	v_max_f32_e32 v29, v40, v41
	v_max_f32_e32 v30, v42, v43
	v_max3_f32 v28, v28, v29, v30
	v_max_f32_e32 v29, v36, v37
	v_max_f32_e32 v30, v38, v39
	v_max3_f32 v28, v28, v29, v30
	v_max_f32_e32 v29, v32, v33
	v_max_f32_e32 v30, v34, v35
	v_max3_f32 v28, v28, v29, v30
	v_max_f32_e32 v29, v24, v25
	v_max_f32_e32 v30, v26, v27
	v_max3_f32 v28, v28, v29, v30
	ds_bpermute_b32 v29, v135, v28
	s_waitcnt lgkmcnt(0)
	s_nop 0
	v_max_f32_e32 v28, v28, v29
	ds_bpermute_b32 v29, v76, v28
	s_waitcnt lgkmcnt(0)
	v_max3_f32 v28, v28, v29, v81
	v_sub_f32_e32 v29, v72, v28
	v_exp_f32_e32 v29, v29
	v_sub_f32_e32 v31, v73, v28
	v_exp_f32_e32 v31, v31
	v_sub_f32_e32 v72, v74, v28
	v_exp_f32_e32 v72, v72
	v_sub_f32_e32 v73, v75, v28
	v_exp_f32_e32 v73, v73
	v_sub_f32_e32 v68, v68, v28
	v_add_f32_e32 v30, 0, v29
	v_exp_f32_e32 v68, v68
	v_sub_f32_e32 v69, v69, v28
	v_add_f32_e32 v30, v31, v30
	v_exp_f32_e32 v69, v69
	v_sub_f32_e32 v70, v70, v28
	v_add_f32_e32 v30, v72, v30
	v_exp_f32_e32 v70, v70
	v_sub_f32_e32 v71, v71, v28
	v_add_f32_e32 v30, v73, v30
	v_exp_f32_e32 v71, v71
	v_sub_f32_e32 v64, v64, v28
	v_add_f32_e32 v30, v68, v30
	v_exp_f32_e32 v64, v64
	v_sub_f32_e32 v65, v65, v28
	v_add_f32_e32 v30, v69, v30
	v_exp_f32_e32 v65, v65
	v_sub_f32_e32 v66, v66, v28
	v_add_f32_e32 v30, v70, v30
	v_exp_f32_e32 v66, v66
	v_sub_f32_e32 v67, v67, v28
	v_add_f32_e32 v30, v71, v30
	v_exp_f32_e32 v67, v67
	v_sub_f32_e32 v60, v60, v28
	v_add_f32_e32 v30, v64, v30
	v_exp_f32_e32 v60, v60
	v_sub_f32_e32 v61, v61, v28
	v_add_f32_e32 v30, v65, v30
	v_exp_f32_e32 v61, v61
	v_sub_f32_e32 v62, v62, v28
	v_add_f32_e32 v30, v66, v30
	v_exp_f32_e32 v62, v62
	v_sub_f32_e32 v63, v63, v28
	v_add_f32_e32 v30, v67, v30
	v_exp_f32_e32 v63, v63
	v_sub_f32_e32 v56, v56, v28
	v_add_f32_e32 v30, v60, v30
	v_exp_f32_e32 v56, v56
	v_sub_f32_e32 v57, v57, v28
	v_add_f32_e32 v30, v61, v30
	v_exp_f32_e32 v57, v57
	v_sub_f32_e32 v58, v58, v28
	v_add_f32_e32 v30, v62, v30
	v_exp_f32_e32 v58, v58
	v_sub_f32_e32 v59, v59, v28
	v_add_f32_e32 v30, v63, v30
	v_exp_f32_e32 v59, v59
	v_sub_f32_e32 v52, v52, v28
	v_add_f32_e32 v30, v56, v30
	v_exp_f32_e32 v52, v52
	v_sub_f32_e32 v53, v53, v28
	v_add_f32_e32 v30, v57, v30
	v_exp_f32_e32 v53, v53
	v_sub_f32_e32 v54, v54, v28
	v_add_f32_e32 v30, v58, v30
; #define LAS __attribute__((address_space(3)))
; #define LAS __attribute__((address_space(3)))
; __device__ __forceinline__ unsigned pk2(float lo, float hi) { return pg8::cvt_pk_bf16(lo, hi); }
; __device__ __forceinline__ f32x4 mfma16(bf16x8 a, bf16x8 b, f32x4 c) { return __builtin_amdgcn_mfma_f32_16x16x32_bf16(a, b, c, 0, 0, 0); }
; template <int NKT, int VSTR, bool SINK>
; __device__ __forceinline__ void attn_core(LAS const unsigned char* kb_, LAS const unsigned char* vb_, bf16x8 q0, bf16x8 q1, float sk, unsigned mskbits, int fr, f32x4 (&o)[4]) {
;     ...
;     for (int kt = 0; kt < NKT; ++kt)
; #pragma unroll
;         for (int r = 0; r < 4; ++r) { const float p = __builtin_amdgcn_exp2f(S[kt][r] - mx); S[kt][r] = p; sum += p; }
;     sum += __shfl_xor(sum, 16); sum += __shfl_xor(sum, 32);
;     if (SINK) sum += __builtin_amdgcn_exp2f(sk - mx);
;     const float inv = 1.0f / sum;
;     bf16x8 pf[NKT / 2];
; #pragma unroll
;     for (int kb = 0; kb < NKT / 2; ++kb) {
;         v4u w; w.x = pk2(S[2 * kb][0], S[2 * kb][1]); w.y = pk2(S[2 * kb][2], S[2 * kb][3]); w.z = pk2(S[2 * kb + 1][0], S[2 * kb + 1][1]); w.w = pk2(S[2 * kb + 1][2], S[2 * kb + 1][3]);
;         pf[kb] = __builtin_bit_cast(bf16x8, w);
;     }
; #pragma unroll
;     for (int dt = 0; dt < 4; ++dt) {
;         f32x4 acc = (f32x4){0.f, 0.f, 0.f, 0.f};
; #pragma unroll
;         for (int kb = 0; kb < NKT / 2; ++kb) {
;             const bf16x8 vf = *(LAS const bf16x8*)(vb_ + dt * 16 * VSTR + kb * 64);
;             acc = mfma16(vf, pf[kb], acc);
	v_exp_f32_e32 v54, v54
	v_sub_f32_e32 v55, v55, v28
	v_add_f32_e32 v30, v59, v30
	v_exp_f32_e32 v55, v55
	v_sub_f32_e32 v48, v48, v28
	v_add_f32_e32 v30, v52, v30
	v_exp_f32_e32 v48, v48
	v_sub_f32_e32 v49, v49, v28
	v_add_f32_e32 v30, v53, v30
	v_exp_f32_e32 v49, v49
	v_sub_f32_e32 v50, v50, v28
	v_add_f32_e32 v30, v54, v30
	v_exp_f32_e32 v50, v50
	v_sub_f32_e32 v51, v51, v28
	v_add_f32_e32 v30, v55, v30
	v_exp_f32_e32 v51, v51
	v_sub_f32_e32 v44, v44, v28
	v_add_f32_e32 v30, v48, v30
	v_exp_f32_e32 v74, v44
	v_sub_f32_e32 v44, v45, v28
	v_add_f32_e32 v30, v49, v30
	v_exp_f32_e32 v75, v44
	v_sub_f32_e32 v44, v46, v28
	v_add_f32_e32 v30, v50, v30
	v_exp_f32_e32 v81, v44
	v_sub_f32_e32 v44, v47, v28
	v_add_f32_e32 v30, v51, v30
	v_exp_f32_e32 v82, v44
	v_sub_f32_e32 v40, v40, v28
	v_add_f32_e32 v30, v74, v30
	v_exp_f32_e32 v83, v40
	v_sub_f32_e32 v40, v41, v28
	v_add_f32_e32 v30, v75, v30
	v_exp_f32_e32 v84, v40
	v_sub_f32_e32 v40, v42, v28
	v_add_f32_e32 v30, v81, v30
	v_exp_f32_e32 v85, v40
	v_sub_f32_e32 v40, v43, v28
	v_add_f32_e32 v30, v82, v30
	v_exp_f32_e32 v86, v40
	v_sub_f32_e32 v36, v36, v28
	v_add_f32_e32 v30, v83, v30
	v_exp_f32_e32 v87, v36
	v_sub_f32_e32 v36, v37, v28
	v_add_f32_e32 v30, v84, v30
	v_exp_f32_e32 v88, v36
	v_sub_f32_e32 v36, v38, v28
	v_add_f32_e32 v30, v85, v30
	v_exp_f32_e32 v89, v36
	v_sub_f32_e32 v36, v39, v28
	v_add_f32_e32 v30, v86, v30
	v_exp_f32_e32 v90, v36
	v_sub_f32_e32 v32, v32, v28
	v_add_f32_e32 v30, v87, v30
	v_exp_f32_e32 v91, v32
	v_sub_f32_e32 v32, v33, v28
	v_add_f32_e32 v30, v88, v30
	v_exp_f32_e32 v92, v32
	v_sub_f32_e32 v32, v34, v28
	v_add_f32_e32 v30, v89, v30
	v_exp_f32_e32 v93, v32
	v_sub_f32_e32 v32, v35, v28
	v_add_f32_e32 v30, v90, v30
	v_exp_f32_e32 v94, v32
	v_sub_f32_e32 v24, v24, v28
	v_add_f32_e32 v30, v91, v30
	v_exp_f32_e32 v95, v24
	v_sub_f32_e32 v25, v25, v28
	v_add_f32_e32 v30, v92, v30
	v_exp_f32_e32 v96, v25
	v_sub_f32_e32 v25, v26, v28
	v_add_f32_e32 v30, v93, v30
	v_exp_f32_e32 v97, v25
	v_sub_f32_e32 v25, v27, v28
	v_add_f32_e32 v30, v94, v30
	v_exp_f32_e32 v27, v25
	v_add_f32_e32 v24, v95, v30
	v_add_f32_e32 v24, v96, v24
	v_add_f32_e32 v24, v97, v24
	v_add_f32_e32 v24, v27, v24
	ds_bpermute_b32 v25, v135, v24
	v_cvt_pk_bf16_f32 v44, v29, v31
	v_cvt_pk_bf16_f32 v45, v72, v73
	v_cvt_pk_bf16_f32 v46, v68, v69
	v_cvt_pk_bf16_f32 v47, v70, v71
	s_waitcnt lgkmcnt(0)
	v_add_f32_e32 v24, v24, v25
	ds_bpermute_b32 v25, v76, v24
	v_cvt_pk_bf16_f32 v40, v64, v65
	v_cvt_pk_bf16_f32 v41, v66, v67
	v_cvt_pk_bf16_f32 v42, v60, v61
	v_cvt_pk_bf16_f32 v43, v62, v63
	s_waitcnt lgkmcnt(0)
	v_add_f32_e32 v24, v24, v25
	v_fma_f32 v25, v80, s2, -v28
	v_exp_f32_e32 v25, v25
	v_cvt_pk_bf16_f32 v36, v56, v57
	v_cvt_pk_bf16_f32 v37, v58, v59
	v_cvt_pk_bf16_f32 v38, v52, v53
	v_cvt_pk_bf16_f32 v39, v54, v55
	v_cvt_pk_bf16_f32 v32, v48, v49
	s_nop 0
	v_add_f32_e32 v80, v25, v24
	v_div_scale_f32 v48, s[0:1], v80, v80, 1.0
	v_rcp_f32_e32 v49, v48
	v_cvt_pk_bf16_f32 v33, v50, v51
	v_cvt_pk_bf16_f32 v34, v74, v75
	v_cvt_pk_bf16_f32 v35, v81, v82
	v_cvt_pk_bf16_f32 v28, v83, v84
	v_cvt_pk_bf16_f32 v29, v85, v86
	s_nop 0
	v_fma_f32 v50, -v48, v49, 1.0
	v_fmac_f32_e32 v49, v50, v49
	v_div_scale_f32 v50, vcc, 1.0, v80, 1.0
	v_mul_f32_e32 v51, v50, v49
	v_fma_f32 v52, -v48, v51, v50
	v_fmac_f32_e32 v51, v52, v49
	v_fma_f32 v48, -v48, v51, v50
	v_cvt_pk_bf16_f32 v30, v87, v88
	v_cvt_pk_bf16_f32 v31, v89, v90
	v_cvt_pk_bf16_f32 v24, v91, v92
	v_cvt_pk_bf16_f32 v25, v93, v94
	v_cvt_pk_bf16_f32 v26, v95, v96
	v_cvt_pk_bf16_f32 v27, v97, v27
	v_div_fmas_f32 v48, v48, v49, v51
	s_waitcnt lgkmcnt(0)
	ds_read_b128 v[196:199], v78 offset:55296
	ds_read_b128 v[200:203], v78 offset:55360
	ds_read_b128 v[204:207], v78 offset:61760
	ds_read_b128 v[208:211], v77 offset:12864
	ds_read_b128 v[212:215], v78 offset:55424
	ds_read_b128 v[228:231], v78 offset:55488
	ds_read_b128 v[232:235], v78 offset:55552
	ds_read_b128 v[236:239], v78 offset:55616
	ds_read_b128 v[240:243], v78 offset:61696
	ds_read_b128 v[244:247], v78 offset:61824
	s_waitcnt lgkmcnt(9)
	v_mfma_f32_16x16x32_bf16 v[50:53], v[196:199], v[44:47], 0
	ds_read_b128 v[196:199], v78 offset:61888
	v_div_fixup_f32 v48, v48, v80, 1.0
	s_waitcnt lgkmcnt(9)
	v_mfma_f32_16x16x32_bf16 v[50:53], v[200:203], v[40:43], v[50:53]
	ds_read_b128 v[200:203], v78 offset:61952
	s_waitcnt lgkmcnt(7)
; #define LAS __attribute__((address_space(3)))
; __device__ __forceinline__ float sq4(const f32x4 a) { return (a[0] * a[0] + a[1] * a[1]) + (a[2] * a[2] + a[3] * a[3]); }
; #define LAS __attribute__((address_space(3)))
; __device__ __forceinline__ unsigned pk2(float lo, float hi) { return pg8::cvt_pk_bf16(lo, hi); }
; __device__ __forceinline__ f32x4 mfma16(bf16x8 a, bf16x8 b, f32x4 c) { return __builtin_amdgcn_mfma_f32_16x16x32_bf16(a, b, c, 0, 0, 0); }
; template <int NKT, int VSTR, bool SINK>
; __device__ __forceinline__ void attn_core(LAS const unsigned char* kb_, LAS const unsigned char* vb_, bf16x8 q0, bf16x8 q1, float sk, unsigned mskbits, int fr, f32x4 (&o)[4]) {
;     ...
; #pragma unroll
;     for (int dt = 0; dt < 4; ++dt) {
;         f32x4 acc = (f32x4){0.f, 0.f, 0.f, 0.f};
; #pragma unroll
;         for (int kb = 0; kb < NKT / 2; ++kb) {
;             const bf16x8 vf = *(LAS const bf16x8*)(vb_ + dt * 16 * VSTR + kb * 64);
;             acc = mfma16(vf, pf[kb], acc);
;         }
;         o[dt] = acc * inv;
;     }
; template <bool DO_SWA, bool DO_MEM>
; __device__ __forceinline__ void attn_unit(const Args& a, unsigned char* ws, LAS unsigned char* lds, int l, int tid_in, int lane_in, int wave, int unit) {
;     ...
;                 attn_core<12, 400, true>(lds + A_KS + g * 192 * 144 + fq * 16, lds + A_VT1 + (g * 64 + fr) * 400 + fq * 16, qsw[hh][0], qsw[hh][1], sk, mskbits, fr, o);
; #pragma unroll
;                 for (int dt = 0; dt < 4; ++dt) { ssq += pg8::sq4(o[dt]); osv[hh][dt] = (v2u){pk2(o[dt][0], o[dt][1]), pk2(o[dt][2], o[dt][3])}; }
;             }
	v_mfma_f32_16x16x32_bf16 v[50:53], v[212:215], v[36:39], v[50:53]
	ds_read_b128 v[212:215], v78 offset:62016
	s_waitcnt lgkmcnt(7)
	v_mfma_f32_16x16x32_bf16 v[50:53], v[228:231], v[32:35], v[50:53]
	ds_read_b128 v[228:231], v77 offset:12800
	s_waitcnt lgkmcnt(7)
	v_mfma_f32_16x16x32_bf16 v[50:53], v[232:235], v[28:31], v[50:53]
	ds_read_b128 v[232:235], v77 offset:12928
	s_waitcnt lgkmcnt(7)
	v_mfma_f32_16x16x32_bf16 v[52:55], v[236:239], v[24:27], v[50:53]
	ds_read_b128 v[236:239], v77 offset:12992
	s_nop 7
	v_pk_mul_f32 v[50:51], v[54:55], v[48:49] op_sel_hi:[1,0]
	s_waitcnt lgkmcnt(7)
	v_mfma_f32_16x16x32_bf16 v[54:57], v[240:243], v[44:47], 0
	ds_read_b128 v[240:243], v77 offset:13056
	v_mul_f32_e64 v52, v52, v48
	v_mul_f32_e64 v53, v53, v48
	v_mfma_f32_16x16x32_bf16 v[54:57], v[204:207], v[40:43], v[54:57]
	ds_read_b128 v[204:207], v77 offset:13120
	s_waitcnt lgkmcnt(8)
	v_mfma_f32_16x16x32_bf16 v[54:57], v[244:247], v[36:39], v[54:57]
	ds_read_b128 v[244:247], v77 offset:19200
	s_waitcnt lgkmcnt(8)
	v_mfma_f32_16x16x32_bf16 v[54:57], v[196:199], v[32:35], v[54:57]
	ds_read_b128 v[196:199], v77 offset:19264
	s_waitcnt lgkmcnt(8)
	v_mfma_f32_16x16x32_bf16 v[54:57], v[200:203], v[28:31], v[54:57]
	ds_read_b128 v[200:203], v77 offset:19328
	s_waitcnt lgkmcnt(8)
	v_mfma_f32_16x16x32_bf16 v[56:59], v[212:215], v[24:27], v[54:57]
	s_nop 7
	v_pk_mul_f32 v[54:55], v[58:59], v[48:49] op_sel_hi:[1,0]
	ds_read_b128 v[212:215], v77 offset:19392
	s_waitcnt lgkmcnt(8)
	v_mfma_f32_16x16x32_bf16 v[58:61], v[228:231], v[44:47], 0
	v_mul_f32_e64 v56, v56, v48
	v_mul_f32_e64 v57, v57, v48
	v_mfma_f32_16x16x32_bf16 v[58:61], v[208:211], v[40:43], v[58:61]
	ds_read_b128 v[228:231], v77 offset:19456
	s_waitcnt lgkmcnt(8)
	v_mfma_f32_16x16x32_bf16 v[58:61], v[232:235], v[36:39], v[58:61]
	ds_read_b128 v[208:211], v77 offset:19520
	s_waitcnt lgkmcnt(8)
	v_mfma_f32_16x16x32_bf16 v[58:61], v[236:239], v[32:35], v[58:61]
	s_waitcnt lgkmcnt(7)
	v_mfma_f32_16x16x32_bf16 v[58:61], v[240:243], v[28:31], v[58:61]
	s_waitcnt lgkmcnt(6)
	v_mfma_f32_16x16x32_bf16 v[60:63], v[204:207], v[24:27], v[58:61]
	s_nop 7
	v_pk_mul_f32 v[58:59], v[48:49], v[62:63] op_sel_hi:[0,1]
	s_waitcnt lgkmcnt(5)
	v_mfma_f32_16x16x32_bf16 v[44:47], v[244:247], v[44:47], 0
	v_pk_mul_f32 v[60:61], v[48:49], v[60:61] op_sel_hi:[0,1]
	s_waitcnt lgkmcnt(4)
	v_mfma_f32_16x16x32_bf16 v[40:43], v[196:199], v[40:43], v[44:47]
	s_waitcnt lgkmcnt(3)
	v_mfma_f32_16x16x32_bf16 v[36:39], v[200:203], v[36:39], v[40:43]
	s_waitcnt lgkmcnt(2)
	v_mfma_f32_16x16x32_bf16 v[32:35], v[212:215], v[32:35], v[36:39]
	s_waitcnt lgkmcnt(1)
	v_mfma_f32_16x16x32_bf16 v[28:31], v[228:231], v[28:31], v[32:35]
	v_cvt_pk_bf16_f32 v69, v52, v53
	v_cvt_pk_bf16_f32 v68, v50, v51
	s_waitcnt lgkmcnt(0)
	v_mfma_f32_16x16x32_bf16 v[24:27], v[208:211], v[24:27], v[28:31]
	s_nop 2
	v_mul_f32_e32 v28, v53, v53
	v_mul_f32_e32 v29, v51, v51
	v_fmac_f32_e32 v28, v52, v52
	v_fmac_f32_e32 v29, v50, v50
	v_add_f32_e32 v28, v28, v29
	v_mul_f32_e32 v29, v57, v57
	v_mul_f32_e32 v30, v55, v55
	v_fmac_f32_e32 v29, v56, v56
	v_fmac_f32_e32 v30, v54, v54
	v_add_f32_e32 v29, v29, v30
	v_add_f32_e32 v28, v28, v29
	v_mul_f32_e32 v29, v61, v61
	v_mul_f32_e32 v30, v59, v59
	v_fmac_f32_e32 v29, v60, v60
	v_fmac_f32_e32 v30, v58, v58
	v_pk_mul_f32 v[26:27], v[48:49], v[26:27] op_sel_hi:[0,1]
	v_pk_mul_f32 v[24:25], v[48:49], v[24:25] op_sel_hi:[0,1]
	v_add_f32_e32 v29, v29, v30
	v_add_f32_e32 v28, v29, v28
	v_mul_f32_e32 v29, v25, v25
	v_mul_f32_e32 v30, v27, v27
	v_fmac_f32_e32 v29, v24, v24
	v_fmac_f32_e32 v30, v26, v26
	v_add_f32_e32 v29, v29, v30
	v_cvt_pk_bf16_f32 v71, v56, v57
	v_cvt_pk_bf16_f32 v70, v54, v55
	v_cvt_pk_bf16_f32 v73, v60, v61
	v_cvt_pk_bf16_f32 v72, v58, v59
	v_add_f32_e32 v80, v28, v29
	v_cvt_pk_bf16_f32 v75, v24, v25
	v_cvt_pk_bf16_f32 v74, v26, v27
	v_mov_b32_e32 v81, s99
	s_waitcnt lgkmcnt(0)
	ds_read_b128 v[92:95], v79
	ds_read_b128 v[196:199], v79 offset:64
	ds_read_b128 v[200:203], v79 offset:576
	ds_read_b128 v[204:207], v79 offset:640
	ds_read_b128 v[208:211], v79 offset:4608
	ds_read_b128 v[212:215], v79 offset:4672
	ds_read_b128 v[228:231], v79 offset:5184
	ds_read_b128 v[232:235], v79 offset:5248
	ds_read_b128 v[236:239], v79 offset:9216
	ds_read_b128 v[240:243], v79 offset:9280
	ds_read_b128 v[244:247], v79 offset:9792
	s_waitcnt lgkmcnt(10)
	v_mfma_f32_16x16x32_bf16 v[24:27], v[92:95], v[20:23], 0

; #define LAS __attribute__((address_space(3)))
; #define LAS __attribute__((address_space(3)))
; __device__ __forceinline__ f32x4 mfma16(bf16x8 a, bf16x8 b, f32x4 c) { return __builtin_amdgcn_mfma_f32_16x16x32_bf16(a, b, c, 0, 0, 0); }
; template <int NKT, int VSTR, bool SINK>
; __device__ __forceinline__ void attn_core(LAS const unsigned char* kb_, LAS const unsigned char* vb_, bf16x8 q0, bf16x8 q1, float sk, unsigned mskbits, int fr, f32x4 (&o)[4]) {
;     ...
; #pragma unroll
;     for (int kt = 0; kt < NKT; ++kt) {
;         const int key = (kt >> 1) * 32 + ((kt & 1) << 2) + krow;
;         LAS const unsigned char* kp = kb_ + key * 144;
;         const bf16x8 a0 = *(LAS const bf16x8*)kp, a1 = *(LAS const bf16x8*)(kp + 64);
;         const float bias = ((mskbits >> (kt >> 2)) & 1u) ? -1e30f : 0.f;
;         f32x4 s = mfma16(a0, q0, (f32x4){bias, bias, bias, bias});
;         s = mfma16(a1, q1, s);
;         S[kt] = s;
;     }
;     float mx = S[0][0];
; #pragma unroll
;     for (int kt = 0; kt < NKT; ++kt) mx = fmaxf(fmaxf(mx, fmaxf(S[kt][0], S[kt][1])), fmaxf(S[kt][2], S[kt][3]));
;     mx = fmaxf(mx, __shfl_xor(mx, 16)); mx = fmaxf(mx, __shfl_xor(mx, 32));
;     if (SINK) mx = fmaxf(mx, sk);
;     float sum = 0.f;
; #pragma unroll
;     for (int kt = 0; kt < NKT; ++kt)
; #pragma unroll
;         for (int r = 0; r < 4; ++r) { const float p = __builtin_amdgcn_exp2f(S[kt][r] - mx); S[kt][r] = p; sum += p; }
;     sum += __shfl_xor(sum, 16); sum += __shfl_xor(sum, 32);
;     if (SINK) sum += __builtin_amdgcn_exp2f(sk - mx);
	v_mul_f32_e32 v90, 0x3fb8aa3b, v81
	s_waitcnt lgkmcnt(9)
	v_mfma_f32_16x16x32_bf16 v[64:67], v[196:199], v[16:19], v[24:27]
	ds_read_b128 v[92:95], v79 offset:9856
	ds_read_b128 v[196:199], v79 offset:13824
	s_waitcnt lgkmcnt(10)
	v_mfma_f32_16x16x32_bf16 v[24:27], v[200:203], v[20:23], 0
	s_waitcnt lgkmcnt(9)
	v_mfma_f32_16x16x32_bf16 v[60:63], v[204:207], v[16:19], v[24:27]
	ds_read_b128 v[200:203], v79 offset:13888
	ds_read_b128 v[204:207], v79 offset:14400
	s_waitcnt lgkmcnt(10)
	v_mfma_f32_16x16x32_bf16 v[24:27], v[208:211], v[20:23], 0
	s_waitcnt lgkmcnt(9)
	v_mfma_f32_16x16x32_bf16 v[56:59], v[212:215], v[16:19], v[24:27]
	ds_read_b128 v[208:211], v79 offset:14464
	ds_read_b128 v[212:215], v79 offset:18432
	s_waitcnt lgkmcnt(10)
	v_mfma_f32_16x16x32_bf16 v[24:27], v[228:231], v[20:23], 0
	s_waitcnt lgkmcnt(9)
	v_mfma_f32_16x16x32_bf16 v[52:55], v[232:235], v[16:19], v[24:27]
	ds_read_b128 v[228:231], v79 offset:18496
	ds_read_b128 v[232:235], v79 offset:19008
	s_waitcnt lgkmcnt(10)
	v_mfma_f32_16x16x32_bf16 v[24:27], v[236:239], v[20:23], 0
	s_waitcnt lgkmcnt(9)
	v_mfma_f32_16x16x32_bf16 v[48:51], v[240:243], v[16:19], v[24:27]
	ds_read_b128 v[236:239], v79 offset:19072
	ds_read_b128 v[240:243], v79 offset:23040
	s_waitcnt lgkmcnt(10)
	v_mfma_f32_16x16x32_bf16 v[24:27], v[244:247], v[20:23], 0
	s_waitcnt lgkmcnt(9)
	v_mfma_f32_16x16x32_bf16 v[44:47], v[92:95], v[16:19], v[24:27]
	ds_read_b128 v[244:247], v79 offset:23104
	ds_read_b128 v[92:95], v79 offset:23616
	s_waitcnt lgkmcnt(10)
	v_mfma_f32_16x16x32_bf16 v[24:27], v[196:199], v[20:23], 0
	s_waitcnt lgkmcnt(9)
	v_mfma_f32_16x16x32_bf16 v[40:43], v[200:203], v[16:19], v[24:27]
	ds_read_b128 v[196:199], v79 offset:23680
	s_waitcnt lgkmcnt(9)
	v_mfma_f32_16x16x32_bf16 v[24:27], v[204:207], v[20:23], 0
	s_waitcnt lgkmcnt(8)
	v_mfma_f32_16x16x32_bf16 v[36:39], v[208:211], v[16:19], v[24:27]
	s_waitcnt lgkmcnt(7)
	v_mfma_f32_16x16x32_bf16 v[24:27], v[212:215], v[20:23], 0
	s_waitcnt lgkmcnt(6)
	v_mfma_f32_16x16x32_bf16 v[32:35], v[228:231], v[16:19], v[24:27]
	s_waitcnt lgkmcnt(5)
	v_mfma_f32_16x16x32_bf16 v[24:27], v[232:235], v[20:23], 0
	s_waitcnt lgkmcnt(4)
	v_mfma_f32_16x16x32_bf16 v[28:31], v[236:239], v[16:19], v[24:27]
	s_waitcnt lgkmcnt(3)
	v_mfma_f32_16x16x32_bf16 v[24:27], v[240:243], v[20:23], 0
	s_waitcnt lgkmcnt(2)
	v_mfma_f32_16x16x32_bf16 v[24:27], v[244:247], v[16:19], v[24:27]
	s_waitcnt lgkmcnt(1)
	v_mfma_f32_16x16x32_bf16 v[20:23], v[92:95], v[20:23], 0
	s_waitcnt lgkmcnt(0)
	v_mfma_f32_16x16x32_bf16 v[16:19], v[196:199], v[16:19], v[20:23]
	s_nop 5
	s_nop 0
	s_nop 0
	v_max_f32_e32 v20, v66, v67
	s_nop 0
	s_nop 0
	v_max_f32_e32 v21, v60, v61
	s_nop 0
	s_nop 0
	v_max3_f32 v20, v64, v65, v20
	v_max_f32_e32 v22, v62, v63
	v_max3_f32 v20, v20, v21, v22
	s_nop 0
	s_nop 0
	v_max_f32_e32 v21, v56, v57
	s_nop 0
	s_nop 0
	v_max_f32_e32 v22, v58, v59
	v_max3_f32 v20, v20, v21, v22
	s_nop 0
	s_nop 0
	v_max_f32_e32 v21, v52, v53
	s_nop 0
	s_nop 0
	v_max_f32_e32 v22, v54, v55
	v_max3_f32 v20, v20, v21, v22
	v_max_f32_e32 v21, v48, v49
	v_max_f32_e32 v22, v50, v51
	v_max3_f32 v20, v20, v21, v22
	v_max_f32_e32 v21, v44, v45
	v_max_f32_e32 v22, v46, v47
	v_max3_f32 v20, v20, v21, v22
	v_max_f32_e32 v21, v40, v41
	v_max_f32_e32 v22, v42, v43
	v_max3_f32 v20, v20, v21, v22
	v_max_f32_e32 v21, v36, v37
	v_max_f32_e32 v22, v38, v39
	v_max3_f32 v20, v20, v21, v22
	v_max_f32_e32 v21, v32, v33
	v_max_f32_e32 v22, v34, v35
	v_max3_f32 v20, v20, v21, v22
	v_max_f32_e32 v21, v28, v29
	v_max_f32_e32 v22, v30, v31
	v_max3_f32 v20, v20, v21, v22
	v_max_f32_e32 v21, v24, v25
	v_max_f32_e32 v22, v26, v27
	v_max3_f32 v20, v20, v21, v22
	v_max_f32_e32 v21, v16, v17
	v_max_f32_e32 v22, v18, v19
	v_max3_f32 v20, v20, v21, v22
	ds_bpermute_b32 v21, v135, v20
	s_waitcnt lgkmcnt(0)
	s_nop 0
	v_max_f32_e32 v20, v20, v21
	ds_bpermute_b32 v21, v76, v20
	s_waitcnt lgkmcnt(0)
	v_max3_f32 v20, v20, v21, v90
	v_sub_f32_e32 v21, v64, v20
	v_exp_f32_e32 v21, v21
	v_sub_f32_e32 v23, v65, v20
	v_exp_f32_e32 v23, v23
	v_sub_f32_e32 v64, v66, v20
	v_exp_f32_e32 v64, v64
	v_sub_f32_e32 v65, v67, v20
	v_exp_f32_e32 v65, v65
	v_sub_f32_e32 v60, v60, v20
	v_add_f32_e32 v22, 0, v21
	v_exp_f32_e32 v60, v60
	v_sub_f32_e32 v61, v61, v20
	v_add_f32_e32 v22, v23, v22
	v_exp_f32_e32 v61, v61
	v_sub_f32_e32 v62, v62, v20
	v_add_f32_e32 v22, v64, v22
	v_exp_f32_e32 v62, v62
	v_sub_f32_e32 v63, v63, v20
	v_add_f32_e32 v22, v65, v22
	v_exp_f32_e32 v63, v63
	v_sub_f32_e32 v56, v56, v20
	v_add_f32_e32 v22, v60, v22
	v_exp_f32_e32 v56, v56
	v_sub_f32_e32 v57, v57, v20
	v_add_f32_e32 v22, v61, v22
	v_exp_f32_e32 v57, v57
	v_sub_f32_e32 v58, v58, v20
	v_add_f32_e32 v22, v62, v22
	v_exp_f32_e32 v58, v58
	v_sub_f32_e32 v59, v59, v20
	v_add_f32_e32 v22, v63, v22
	v_exp_f32_e32 v59, v59
	v_sub_f32_e32 v52, v52, v20
	v_add_f32_e32 v22, v56, v22
	v_exp_f32_e32 v52, v52
	v_sub_f32_e32 v53, v53, v20
	v_add_f32_e32 v22, v57, v22
	v_exp_f32_e32 v53, v53
	v_sub_f32_e32 v54, v54, v20
	v_add_f32_e32 v22, v58, v22
	v_exp_f32_e32 v54, v54
	v_sub_f32_e32 v55, v55, v20
	v_add_f32_e32 v22, v59, v22
	v_exp_f32_e32 v55, v55
	v_sub_f32_e32 v48, v48, v20
	v_add_f32_e32 v22, v52, v22
	v_exp_f32_e32 v48, v48
	v_sub_f32_e32 v49, v49, v20
	v_add_f32_e32 v22, v53, v22
	v_exp_f32_e32 v49, v49
	v_sub_f32_e32 v50, v50, v20
	v_add_f32_e32 v22, v54, v22
	v_exp_f32_e32 v50, v50
	v_sub_f32_e32 v51, v51, v20
	v_add_f32_e32 v22, v55, v22
	v_exp_f32_e32 v51, v51
	v_sub_f32_e32 v44, v44, v20
	v_add_f32_e32 v22, v48, v22
	v_exp_f32_e32 v44, v44
	v_sub_f32_e32 v45, v45, v20
	v_add_f32_e32 v22, v49, v22
	v_exp_f32_e32 v45, v45
	v_sub_f32_e32 v46, v46, v20
; #define LAS __attribute__((address_space(3)))
; #define LAS __attribute__((address_space(3)))
; __device__ __forceinline__ unsigned pk2(float lo, float hi) { return pg8::cvt_pk_bf16(lo, hi); }
; __device__ __forceinline__ f32x4 mfma16(bf16x8 a, bf16x8 b, f32x4 c) { return __builtin_amdgcn_mfma_f32_16x16x32_bf16(a, b, c, 0, 0, 0); }
; template <int NKT, int VSTR, bool SINK>
; __device__ __forceinline__ void attn_core(LAS const unsigned char* kb_, LAS const unsigned char* vb_, bf16x8 q0, bf16x8 q1, float sk, unsigned mskbits, int fr, f32x4 (&o)[4]) {
;     ...
;     for (int kt = 0; kt < NKT; ++kt)
; #pragma unroll
;         for (int r = 0; r < 4; ++r) { const float p = __builtin_amdgcn_exp2f(S[kt][r] - mx); S[kt][r] = p; sum += p; }
;     sum += __shfl_xor(sum, 16); sum += __shfl_xor(sum, 32);
;     if (SINK) sum += __builtin_amdgcn_exp2f(sk - mx);
;     const float inv = 1.0f / sum;
;     bf16x8 pf[NKT / 2];
; #pragma unroll
;     for (int kb = 0; kb < NKT / 2; ++kb) {
;         v4u w; w.x = pk2(S[2 * kb][0], S[2 * kb][1]); w.y = pk2(S[2 * kb][2], S[2 * kb][3]); w.z = pk2(S[2 * kb + 1][0], S[2 * kb + 1][1]); w.w = pk2(S[2 * kb + 1][2], S[2 * kb + 1][3]);
;         pf[kb] = __builtin_bit_cast(bf16x8, w);
;     }
; #pragma unroll
;     for (int dt = 0; dt < 4; ++dt) {
;         f32x4 acc = (f32x4){0.f, 0.f, 0.f, 0.f};
; #pragma unroll
;         for (int kb = 0; kb < NKT / 2; ++kb) {
;             const bf16x8 vf = *(LAS const bf16x8*)(vb_ + dt * 16 * VSTR + kb * 64);
;             acc = mfma16(vf, pf[kb], acc);
	v_add_f32_e32 v22, v50, v22
	v_exp_f32_e32 v46, v46
	v_sub_f32_e32 v47, v47, v20
	v_add_f32_e32 v22, v51, v22
	v_exp_f32_e32 v47, v47
	v_sub_f32_e32 v40, v40, v20
	v_add_f32_e32 v22, v44, v22
	v_exp_f32_e32 v40, v40
	v_sub_f32_e32 v41, v41, v20
	v_add_f32_e32 v22, v45, v22
	v_exp_f32_e32 v41, v41
	v_sub_f32_e32 v42, v42, v20
	v_add_f32_e32 v22, v46, v22
	v_exp_f32_e32 v42, v42
	v_sub_f32_e32 v43, v43, v20
	v_add_f32_e32 v22, v47, v22
	v_exp_f32_e32 v43, v43
	v_sub_f32_e32 v36, v36, v20
	v_add_f32_e32 v22, v40, v22
	v_exp_f32_e32 v66, v36
	v_sub_f32_e32 v36, v37, v20
	v_add_f32_e32 v22, v41, v22
	v_exp_f32_e32 v67, v36
	v_sub_f32_e32 v36, v38, v20
	v_add_f32_e32 v22, v42, v22
	v_exp_f32_e32 v82, v36
	v_sub_f32_e32 v36, v39, v20
	v_add_f32_e32 v22, v43, v22
	v_exp_f32_e32 v83, v36
	v_sub_f32_e32 v32, v32, v20
	v_add_f32_e32 v22, v66, v22
	v_exp_f32_e32 v84, v32
	v_sub_f32_e32 v32, v33, v20
	v_add_f32_e32 v22, v67, v22
	v_exp_f32_e32 v85, v32
	v_sub_f32_e32 v32, v34, v20
	v_add_f32_e32 v22, v82, v22
	v_exp_f32_e32 v86, v32
	v_sub_f32_e32 v32, v35, v20
	v_add_f32_e32 v22, v83, v22
	v_exp_f32_e32 v87, v32
	v_sub_f32_e32 v28, v28, v20
	v_add_f32_e32 v22, v84, v22
	v_exp_f32_e32 v88, v28
	v_sub_f32_e32 v28, v29, v20
	v_add_f32_e32 v22, v85, v22
	v_exp_f32_e32 v89, v28
	v_sub_f32_e32 v28, v30, v20
	v_add_f32_e32 v22, v86, v22
	v_exp_f32_e32 v90, v28
	v_sub_f32_e32 v28, v31, v20
	v_add_f32_e32 v22, v87, v22
	v_exp_f32_e32 v91, v28
	v_sub_f32_e32 v24, v24, v20
	v_add_f32_e32 v22, v88, v22
	v_exp_f32_e32 v92, v24
	v_sub_f32_e32 v24, v25, v20
	v_add_f32_e32 v22, v89, v22
	v_exp_f32_e32 v93, v24
	v_sub_f32_e32 v24, v26, v20
	v_add_f32_e32 v22, v90, v22
	v_exp_f32_e32 v94, v24
	v_sub_f32_e32 v24, v27, v20
	v_add_f32_e32 v22, v91, v22
	v_exp_f32_e32 v95, v24
	v_sub_f32_e32 v16, v16, v20
	v_add_f32_e32 v22, v92, v22
	v_exp_f32_e32 v96, v16
	v_sub_f32_e32 v17, v17, v20
	v_add_f32_e32 v22, v93, v22
	v_exp_f32_e32 v97, v17
	v_sub_f32_e32 v17, v18, v20
	v_add_f32_e32 v22, v94, v22
	v_exp_f32_e32 v98, v17
	v_sub_f32_e32 v17, v19, v20
	v_add_f32_e32 v22, v95, v22
	v_exp_f32_e32 v19, v17
	v_add_f32_e32 v16, v96, v22
	v_add_f32_e32 v16, v97, v16
	v_add_f32_e32 v16, v98, v16
	v_add_f32_e32 v16, v19, v16
	ds_bpermute_b32 v17, v135, v16
	v_cvt_pk_bf16_f32 v36, v21, v23
	v_cvt_pk_bf16_f32 v37, v64, v65
	v_cvt_pk_bf16_f32 v38, v60, v61
	v_cvt_pk_bf16_f32 v39, v62, v63
	s_waitcnt lgkmcnt(0)
	v_add_f32_e32 v16, v16, v17
	ds_bpermute_b32 v17, v76, v16
	v_cvt_pk_bf16_f32 v32, v56, v57
	v_cvt_pk_bf16_f32 v33, v58, v59
	v_cvt_pk_bf16_f32 v34, v52, v53
	v_cvt_pk_bf16_f32 v35, v54, v55
	s_waitcnt lgkmcnt(0)
	v_add_f32_e32 v16, v16, v17
	v_fma_f32 v17, v81, s2, -v20
	v_exp_f32_e32 v17, v17
	v_cvt_pk_bf16_f32 v28, v48, v49
	v_cvt_pk_bf16_f32 v29, v50, v51
	v_cvt_pk_bf16_f32 v30, v44, v45
	v_cvt_pk_bf16_f32 v31, v46, v47
	v_cvt_pk_bf16_f32 v24, v40, v41
	s_nop 0
	v_add_f32_e32 v81, v17, v16
	v_div_scale_f32 v40, s[0:1], v81, v81, 1.0
	v_rcp_f32_e32 v41, v40
	v_cvt_pk_bf16_f32 v25, v42, v43
	v_cvt_pk_bf16_f32 v26, v66, v67
	v_cvt_pk_bf16_f32 v27, v82, v83
	v_cvt_pk_bf16_f32 v20, v84, v85
	v_cvt_pk_bf16_f32 v21, v86, v87
	s_nop 0
	v_fma_f32 v42, -v40, v41, 1.0
	v_fmac_f32_e32 v41, v42, v41
	v_div_scale_f32 v42, vcc, 1.0, v81, 1.0
	v_mul_f32_e32 v43, v42, v41
	v_fma_f32 v44, -v40, v43, v42
	v_fmac_f32_e32 v43, v44, v41
	v_fma_f32 v40, -v40, v43, v42
	v_cvt_pk_bf16_f32 v22, v88, v89
	v_cvt_pk_bf16_f32 v23, v90, v91
	v_cvt_pk_bf16_f32 v16, v92, v93
	v_cvt_pk_bf16_f32 v17, v94, v95
	v_cvt_pk_bf16_f32 v18, v96, v97
	v_cvt_pk_bf16_f32 v19, v98, v19
	v_div_fmas_f32 v40, v40, v41, v43
	s_waitcnt lgkmcnt(0)
	ds_read_b128 v[196:199], v78 offset:55296
	ds_read_b128 v[200:203], v78 offset:55360
	ds_read_b128 v[204:207], v78 offset:61760
	ds_read_b128 v[208:211], v77 offset:12864
	ds_read_b128 v[212:215], v78 offset:55424
	ds_read_b128 v[228:231], v78 offset:55488
	ds_read_b128 v[232:235], v78 offset:55552
	ds_read_b128 v[236:239], v78 offset:55616
	ds_read_b128 v[240:243], v78 offset:61696
	ds_read_b128 v[244:247], v78 offset:61824
	s_waitcnt lgkmcnt(9)
	v_mfma_f32_16x16x32_bf16 v[42:45], v[196:199], v[36:39], 0
	ds_read_b128 v[196:199], v78 offset:61888
	v_div_fixup_f32 v40, v40, v81, 1.0
	s_waitcnt lgkmcnt(9)
	v_mfma_f32_16x16x32_bf16 v[42:45], v[200:203], v[32:35], v[42:45]
	ds_read_b128 v[200:203], v78 offset:61952
	s_waitcnt lgkmcnt(7)
; #define LAS __attribute__((address_space(3)))
; __device__ __forceinline__ float sq4(const f32x4 a) { return (a[0] * a[0] + a[1] * a[1]) + (a[2] * a[2] + a[3] * a[3]); }
; #define LAS __attribute__((address_space(3)))
; __device__ __forceinline__ unsigned pk2(float lo, float hi) { return pg8::cvt_pk_bf16(lo, hi); }
; __device__ __forceinline__ f32x4 mfma16(bf16x8 a, bf16x8 b, f32x4 c) { return __builtin_amdgcn_mfma_f32_16x16x32_bf16(a, b, c, 0, 0, 0); }
; template <int NKT, int VSTR, bool SINK>
; __device__ __forceinline__ void attn_core(LAS const unsigned char* kb_, LAS const unsigned char* vb_, bf16x8 q0, bf16x8 q1, float sk, unsigned mskbits, int fr, f32x4 (&o)[4]) {
;     ...
; #pragma unroll
;     for (int dt = 0; dt < 4; ++dt) {
;         f32x4 acc = (f32x4){0.f, 0.f, 0.f, 0.f};
; #pragma unroll
;         for (int kb = 0; kb < NKT / 2; ++kb) {
;             const bf16x8 vf = *(LAS const bf16x8*)(vb_ + dt * 16 * VSTR + kb * 64);
;             acc = mfma16(vf, pf[kb], acc);
;         }
;         o[dt] = acc * inv;
;     }
; template <bool DO_SWA, bool DO_MEM>
; __device__ __forceinline__ void attn_unit(const Args& a, unsigned char* ws, LAS unsigned char* lds, int l, int tid_in, int lane_in, int wave, int unit) {
;     ...
;                 attn_core<12, 400, true>(lds + A_KS + g * 192 * 144 + fq * 16, lds + A_VT1 + (g * 64 + fr) * 400 + fq * 16, qsw[hh][0], qsw[hh][1], sk, mskbits, fr, o);
; #pragma unroll
;                 for (int dt = 0; dt < 4; ++dt) { ssq += pg8::sq4(o[dt]); osv[hh][dt] = (v2u){pk2(o[dt][0], o[dt][1]), pk2(o[dt][2], o[dt][3])}; }
;             }
	v_mfma_f32_16x16x32_bf16 v[42:45], v[212:215], v[28:31], v[42:45]
	ds_read_b128 v[212:215], v78 offset:62016
	s_waitcnt lgkmcnt(7)
	v_mfma_f32_16x16x32_bf16 v[42:45], v[228:231], v[24:27], v[42:45]
	ds_read_b128 v[228:231], v77 offset:12800
	s_waitcnt lgkmcnt(7)
	v_mfma_f32_16x16x32_bf16 v[42:45], v[232:235], v[20:23], v[42:45]
	ds_read_b128 v[232:235], v77 offset:12928
	s_waitcnt lgkmcnt(7)
	v_mfma_f32_16x16x32_bf16 v[44:47], v[236:239], v[16:19], v[42:45]
	ds_read_b128 v[236:239], v77 offset:12992
	s_nop 7
	v_pk_mul_f32 v[42:43], v[46:47], v[40:41] op_sel_hi:[1,0]
	s_waitcnt lgkmcnt(7)
	v_mfma_f32_16x16x32_bf16 v[46:49], v[240:243], v[36:39], 0
	ds_read_b128 v[240:243], v77 offset:13056
	v_mul_f32_e64 v44, v44, v40
	v_mul_f32_e64 v45, v45, v40
	v_mfma_f32_16x16x32_bf16 v[46:49], v[204:207], v[32:35], v[46:49]
	ds_read_b128 v[204:207], v77 offset:13120
	s_waitcnt lgkmcnt(8)
	v_mfma_f32_16x16x32_bf16 v[46:49], v[244:247], v[28:31], v[46:49]
	ds_read_b128 v[244:247], v77 offset:19200
	s_waitcnt lgkmcnt(8)
	v_mfma_f32_16x16x32_bf16 v[46:49], v[196:199], v[24:27], v[46:49]
	ds_read_b128 v[196:199], v77 offset:19264
	s_waitcnt lgkmcnt(8)
	v_mfma_f32_16x16x32_bf16 v[46:49], v[200:203], v[20:23], v[46:49]
	ds_read_b128 v[200:203], v77 offset:19328
	s_waitcnt lgkmcnt(8)
	v_mfma_f32_16x16x32_bf16 v[48:51], v[212:215], v[16:19], v[46:49]
	s_nop 7
	v_pk_mul_f32 v[46:47], v[50:51], v[40:41] op_sel_hi:[1,0]
	ds_read_b128 v[212:215], v77 offset:19392
	s_waitcnt lgkmcnt(8)
	v_mfma_f32_16x16x32_bf16 v[50:53], v[228:231], v[36:39], 0
	v_mul_f32_e64 v48, v48, v40
	v_mul_f32_e64 v49, v49, v40
	v_mfma_f32_16x16x32_bf16 v[50:53], v[208:211], v[32:35], v[50:53]
	ds_read_b128 v[228:231], v77 offset:19456
	s_waitcnt lgkmcnt(8)
	v_mfma_f32_16x16x32_bf16 v[50:53], v[232:235], v[28:31], v[50:53]
	ds_read_b128 v[208:211], v77 offset:19520
	s_waitcnt lgkmcnt(8)
	v_mfma_f32_16x16x32_bf16 v[50:53], v[236:239], v[24:27], v[50:53]
	s_waitcnt lgkmcnt(7)
	v_mfma_f32_16x16x32_bf16 v[50:53], v[240:243], v[20:23], v[50:53]
	s_waitcnt lgkmcnt(6)
	v_mfma_f32_16x16x32_bf16 v[52:55], v[204:207], v[16:19], v[50:53]
	s_nop 7
	v_pk_mul_f32 v[50:51], v[40:41], v[54:55] op_sel_hi:[0,1]
	s_waitcnt lgkmcnt(5)
	v_mfma_f32_16x16x32_bf16 v[36:39], v[244:247], v[36:39], 0
	v_pk_mul_f32 v[52:53], v[40:41], v[52:53] op_sel_hi:[0,1]
	s_waitcnt lgkmcnt(4)
	v_mfma_f32_16x16x32_bf16 v[32:35], v[196:199], v[32:35], v[36:39]
	s_waitcnt lgkmcnt(3)
	v_mfma_f32_16x16x32_bf16 v[28:31], v[200:203], v[28:31], v[32:35]
	s_waitcnt lgkmcnt(2)
	v_mfma_f32_16x16x32_bf16 v[24:27], v[212:215], v[24:27], v[28:31]
	s_waitcnt lgkmcnt(1)
	v_mfma_f32_16x16x32_bf16 v[20:23], v[228:231], v[20:23], v[24:27]
	v_cvt_pk_bf16_f32 v61, v44, v45
	v_cvt_pk_bf16_f32 v60, v42, v43
	s_waitcnt lgkmcnt(0)
	v_mfma_f32_16x16x32_bf16 v[16:19], v[208:211], v[16:19], v[20:23]
	s_nop 2
	v_mul_f32_e32 v20, v45, v45
	v_mul_f32_e32 v21, v43, v43
	v_fmac_f32_e32 v20, v44, v44
	v_fmac_f32_e32 v21, v42, v42
	v_add_f32_e32 v20, v20, v21
	v_mul_f32_e32 v21, v49, v49
	v_mul_f32_e32 v22, v47, v47
	v_fmac_f32_e32 v21, v48, v48
	v_fmac_f32_e32 v22, v46, v46
	v_add_f32_e32 v20, v80, v20
	v_add_f32_e32 v21, v21, v22
	v_add_f32_e32 v20, v21, v20
	v_mul_f32_e32 v21, v53, v53
	v_mul_f32_e32 v22, v51, v51
	v_fmac_f32_e32 v21, v52, v52
	v_fmac_f32_e32 v22, v50, v50
	v_pk_mul_f32 v[18:19], v[40:41], v[18:19] op_sel_hi:[0,1]
	v_pk_mul_f32 v[16:17], v[40:41], v[16:17] op_sel_hi:[0,1]
	v_add_f32_e32 v21, v21, v22
	v_add_f32_e32 v20, v21, v20
	v_mul_f32_e32 v21, v17, v17
	v_mul_f32_e32 v22, v19, v19
	v_fmac_f32_e32 v21, v16, v16
	v_fmac_f32_e32 v22, v18, v18
	v_add_f32_e32 v21, v21, v22
	v_cvt_pk_bf16_f32 v63, v48, v49
	v_cvt_pk_bf16_f32 v62, v46, v47
	v_cvt_pk_bf16_f32 v65, v52, v53
	v_cvt_pk_bf16_f32 v64, v50, v51
	v_add_f32_e32 v80, v20, v21
	v_cvt_pk_bf16_f32 v67, v16, v17
	v_cvt_pk_bf16_f32 v66, v18, v19
	v_mov_b32_e32 v81, s100
	s_waitcnt lgkmcnt(0)
	ds_read_b128 v[92:95], v79
	ds_read_b128 v[196:199], v79 offset:64
	ds_read_b128 v[200:203], v79 offset:576
	ds_read_b128 v[204:207], v79 offset:640
	ds_read_b128 v[208:211], v79 offset:4608
	ds_read_b128 v[212:215], v79 offset:4672
	ds_read_b128 v[228:231], v79 offset:5184
	ds_read_b128 v[232:235], v79 offset:5248
	ds_read_b128 v[236:239], v79 offset:9216
	ds_read_b128 v[240:243], v79 offset:9280
	ds_read_b128 v[244:247], v79 offset:9792
	s_waitcnt lgkmcnt(10)
	v_mfma_f32_16x16x32_bf16 v[16:19], v[92:95], v[12:15], 0

; #define LAS __attribute__((address_space(3)))
; #define LAS __attribute__((address_space(3)))
; __device__ __forceinline__ f32x4 mfma16(bf16x8 a, bf16x8 b, f32x4 c) { return __builtin_amdgcn_mfma_f32_16x16x32_bf16(a, b, c, 0, 0, 0); }
; template <int NKT, int VSTR, bool SINK>
; __device__ __forceinline__ void attn_core(LAS const unsigned char* kb_, LAS const unsigned char* vb_, bf16x8 q0, bf16x8 q1, float sk, unsigned mskbits, int fr, f32x4 (&o)[4]) {
;     ...
; #pragma unroll
;     for (int kt = 0; kt < NKT; ++kt) {
;         const int key = (kt >> 1) * 32 + ((kt & 1) << 2) + krow;
;         LAS const unsigned char* kp = kb_ + key * 144;
;         const bf16x8 a0 = *(LAS const bf16x8*)kp, a1 = *(LAS const bf16x8*)(kp + 64);
;         const float bias = ((mskbits >> (kt >> 2)) & 1u) ? -1e30f : 0.f;
;         f32x4 s = mfma16(a0, q0, (f32x4){bias, bias, bias, bias});
;         s = mfma16(a1, q1, s);
;         S[kt] = s;
;     }
;     float mx = S[0][0];
; #pragma unroll
;     for (int kt = 0; kt < NKT; ++kt) mx = fmaxf(fmaxf(mx, fmaxf(S[kt][0], S[kt][1])), fmaxf(S[kt][2], S[kt][3]));
;     mx = fmaxf(mx, __shfl_xor(mx, 16)); mx = fmaxf(mx, __shfl_xor(mx, 32));
;     if (SINK) mx = fmaxf(mx, sk);
;     float sum = 0.f;
; #pragma unroll
;     for (int kt = 0; kt < NKT; ++kt)
; #pragma unroll
;         for (int r = 0; r < 4; ++r) { const float p = __builtin_amdgcn_exp2f(S[kt][r] - mx); S[kt][r] = p; sum += p; }
;     sum += __shfl_xor(sum, 16); sum += __shfl_xor(sum, 32);
;     if (SINK) sum += __builtin_amdgcn_exp2f(sk - mx);
	v_mul_f32_e32 v90, 0x3fb8aa3b, v81
	s_waitcnt lgkmcnt(9)
	v_mfma_f32_16x16x32_bf16 v[56:59], v[196:199], v[8:11], v[16:19]
	ds_read_b128 v[92:95], v79 offset:9856
	ds_read_b128 v[196:199], v79 offset:13824
	s_waitcnt lgkmcnt(10)
	v_mfma_f32_16x16x32_bf16 v[16:19], v[200:203], v[12:15], 0
	s_waitcnt lgkmcnt(9)
	v_mfma_f32_16x16x32_bf16 v[52:55], v[204:207], v[8:11], v[16:19]
	ds_read_b128 v[200:203], v79 offset:13888
	ds_read_b128 v[204:207], v79 offset:14400
	s_waitcnt lgkmcnt(10)
	v_mfma_f32_16x16x32_bf16 v[16:19], v[208:211], v[12:15], 0
	s_waitcnt lgkmcnt(9)
	v_mfma_f32_16x16x32_bf16 v[48:51], v[212:215], v[8:11], v[16:19]
	ds_read_b128 v[208:211], v79 offset:14464
	ds_read_b128 v[212:215], v79 offset:18432
	s_waitcnt lgkmcnt(10)
	v_mfma_f32_16x16x32_bf16 v[16:19], v[228:231], v[12:15], 0
	s_waitcnt lgkmcnt(9)
	v_mfma_f32_16x16x32_bf16 v[44:47], v[232:235], v[8:11], v[16:19]
	ds_read_b128 v[228:231], v79 offset:18496
	ds_read_b128 v[232:235], v79 offset:19008
	s_waitcnt lgkmcnt(10)
	v_mfma_f32_16x16x32_bf16 v[16:19], v[236:239], v[12:15], 0
	s_waitcnt lgkmcnt(9)
	v_mfma_f32_16x16x32_bf16 v[40:43], v[240:243], v[8:11], v[16:19]
	ds_read_b128 v[236:239], v79 offset:19072
	ds_read_b128 v[240:243], v79 offset:23040
	s_waitcnt lgkmcnt(10)
	v_mfma_f32_16x16x32_bf16 v[16:19], v[244:247], v[12:15], 0
	s_waitcnt lgkmcnt(9)
	v_mfma_f32_16x16x32_bf16 v[36:39], v[92:95], v[8:11], v[16:19]
	ds_read_b128 v[244:247], v79 offset:23104
	ds_read_b128 v[92:95], v79 offset:23616
	s_waitcnt lgkmcnt(10)
	v_mfma_f32_16x16x32_bf16 v[16:19], v[196:199], v[12:15], 0
	s_waitcnt lgkmcnt(9)
	v_mfma_f32_16x16x32_bf16 v[32:35], v[200:203], v[8:11], v[16:19]
	ds_read_b128 v[196:199], v79 offset:23680
	s_waitcnt lgkmcnt(9)
	v_mfma_f32_16x16x32_bf16 v[16:19], v[204:207], v[12:15], 0
	s_waitcnt lgkmcnt(8)
	v_mfma_f32_16x16x32_bf16 v[28:31], v[208:211], v[8:11], v[16:19]
	s_waitcnt lgkmcnt(7)
	v_mfma_f32_16x16x32_bf16 v[16:19], v[212:215], v[12:15], 0
	s_waitcnt lgkmcnt(6)
	v_mfma_f32_16x16x32_bf16 v[24:27], v[228:231], v[8:11], v[16:19]
	s_waitcnt lgkmcnt(5)
	v_mfma_f32_16x16x32_bf16 v[16:19], v[232:235], v[12:15], 0
	s_waitcnt lgkmcnt(4)
	v_mfma_f32_16x16x32_bf16 v[20:23], v[236:239], v[8:11], v[16:19]
	s_waitcnt lgkmcnt(3)
	v_mfma_f32_16x16x32_bf16 v[16:19], v[240:243], v[12:15], 0
	s_waitcnt lgkmcnt(2)
	v_mfma_f32_16x16x32_bf16 v[16:19], v[244:247], v[8:11], v[16:19]
	s_waitcnt lgkmcnt(1)
	v_mfma_f32_16x16x32_bf16 v[12:15], v[92:95], v[12:15], 0
	s_waitcnt lgkmcnt(0)
	v_mfma_f32_16x16x32_bf16 v[8:11], v[196:199], v[8:11], v[12:15]
	s_nop 5
	s_nop 0
	s_nop 0
	v_max_f32_e32 v12, v58, v59
	s_nop 0
	s_nop 0
	v_max_f32_e32 v13, v52, v53
	s_nop 0
	s_nop 0
	v_max3_f32 v12, v56, v57, v12
	v_max_f32_e32 v14, v54, v55
	v_max3_f32 v12, v12, v13, v14
	s_nop 0
	s_nop 0
	v_max_f32_e32 v13, v48, v49
	s_nop 0
	s_nop 0
	v_max_f32_e32 v14, v50, v51
	v_max3_f32 v12, v12, v13, v14
	s_nop 0
	s_nop 0
	v_max_f32_e32 v13, v44, v45
	s_nop 0
	s_nop 0
	v_max_f32_e32 v14, v46, v47
	v_max3_f32 v12, v12, v13, v14
	v_max_f32_e32 v13, v40, v41
	v_max_f32_e32 v14, v42, v43
	v_max3_f32 v12, v12, v13, v14
	v_max_f32_e32 v13, v36, v37
	v_max_f32_e32 v14, v38, v39
	v_max3_f32 v12, v12, v13, v14
	v_max_f32_e32 v13, v32, v33
	v_max_f32_e32 v14, v34, v35
	v_max3_f32 v12, v12, v13, v14
	v_max_f32_e32 v13, v28, v29
	v_max_f32_e32 v14, v30, v31
	v_max3_f32 v12, v12, v13, v14
	v_max_f32_e32 v13, v24, v25
	v_max_f32_e32 v14, v26, v27
	v_max3_f32 v12, v12, v13, v14
	v_max_f32_e32 v13, v20, v21
	v_max_f32_e32 v14, v22, v23
	v_max3_f32 v12, v12, v13, v14
	v_max_f32_e32 v13, v16, v17
	v_max_f32_e32 v14, v18, v19
	v_max3_f32 v12, v12, v13, v14
	v_max_f32_e32 v13, v8, v9
	v_max_f32_e32 v14, v10, v11
	v_max3_f32 v12, v12, v13, v14
	ds_bpermute_b32 v13, v135, v12
	s_waitcnt lgkmcnt(0)
	s_nop 0
	v_max_f32_e32 v12, v12, v13
	ds_bpermute_b32 v13, v76, v12
	s_waitcnt lgkmcnt(0)
	v_max3_f32 v12, v12, v13, v90
	v_sub_f32_e32 v13, v56, v12
	v_exp_f32_e32 v13, v13
	v_sub_f32_e32 v15, v57, v12
	v_exp_f32_e32 v15, v15
	v_sub_f32_e32 v56, v58, v12
	v_exp_f32_e32 v56, v56
	v_sub_f32_e32 v57, v59, v12
	v_exp_f32_e32 v57, v57
	v_sub_f32_e32 v52, v52, v12
	v_add_f32_e32 v14, 0, v13
	v_exp_f32_e32 v52, v52
	v_sub_f32_e32 v53, v53, v12
	v_add_f32_e32 v14, v15, v14
	v_exp_f32_e32 v53, v53
	v_sub_f32_e32 v54, v54, v12
	v_add_f32_e32 v14, v56, v14
	v_exp_f32_e32 v54, v54
	v_sub_f32_e32 v55, v55, v12
	v_add_f32_e32 v14, v57, v14
	v_exp_f32_e32 v55, v55
	v_sub_f32_e32 v48, v48, v12
	v_add_f32_e32 v14, v52, v14
	v_exp_f32_e32 v48, v48
	v_sub_f32_e32 v49, v49, v12
	v_add_f32_e32 v14, v53, v14
	v_exp_f32_e32 v49, v49
	v_sub_f32_e32 v50, v50, v12
	v_add_f32_e32 v14, v54, v14
	v_exp_f32_e32 v50, v50
	v_sub_f32_e32 v51, v51, v12
	v_add_f32_e32 v14, v55, v14
	v_exp_f32_e32 v51, v51
	v_sub_f32_e32 v44, v44, v12
	v_add_f32_e32 v14, v48, v14
	v_exp_f32_e32 v44, v44
	v_sub_f32_e32 v45, v45, v12
	v_add_f32_e32 v14, v49, v14
	v_exp_f32_e32 v45, v45
	v_sub_f32_e32 v46, v46, v12
	v_add_f32_e32 v14, v50, v14
	v_exp_f32_e32 v46, v46
	v_sub_f32_e32 v47, v47, v12
	v_add_f32_e32 v14, v51, v14
	v_exp_f32_e32 v47, v47
	v_sub_f32_e32 v40, v40, v12
	v_add_f32_e32 v14, v44, v14
	v_exp_f32_e32 v40, v40
	v_sub_f32_e32 v41, v41, v12
	v_add_f32_e32 v14, v45, v14
	v_exp_f32_e32 v41, v41
	v_sub_f32_e32 v42, v42, v12
	v_add_f32_e32 v14, v46, v14
	v_exp_f32_e32 v42, v42
	v_sub_f32_e32 v43, v43, v12
	v_add_f32_e32 v14, v47, v14
	v_exp_f32_e32 v43, v43
	v_sub_f32_e32 v36, v36, v12
	v_add_f32_e32 v14, v40, v14
	v_exp_f32_e32 v36, v36
	v_sub_f32_e32 v37, v37, v12
	v_add_f32_e32 v14, v41, v14
	v_exp_f32_e32 v37, v37
	v_sub_f32_e32 v38, v38, v12
	v_add_f32_e32 v14, v42, v14
; #define LAS __attribute__((address_space(3)))
; #define LAS __attribute__((address_space(3)))
; __device__ __forceinline__ unsigned pk2(float lo, float hi) { return pg8::cvt_pk_bf16(lo, hi); }
; __device__ __forceinline__ f32x4 mfma16(bf16x8 a, bf16x8 b, f32x4 c) { return __builtin_amdgcn_mfma_f32_16x16x32_bf16(a, b, c, 0, 0, 0); }
; template <int NKT, int VSTR, bool SINK>
; __device__ __forceinline__ void attn_core(LAS const unsigned char* kb_, LAS const unsigned char* vb_, bf16x8 q0, bf16x8 q1, float sk, unsigned mskbits, int fr, f32x4 (&o)[4]) {
;     ...
;     for (int kt = 0; kt < NKT; ++kt)
; #pragma unroll
;         for (int r = 0; r < 4; ++r) { const float p = __builtin_amdgcn_exp2f(S[kt][r] - mx); S[kt][r] = p; sum += p; }
;     sum += __shfl_xor(sum, 16); sum += __shfl_xor(sum, 32);
;     if (SINK) sum += __builtin_amdgcn_exp2f(sk - mx);
;     const float inv = 1.0f / sum;
;     bf16x8 pf[NKT / 2];
; #pragma unroll
;     for (int kb = 0; kb < NKT / 2; ++kb) {
;         v4u w; w.x = pk2(S[2 * kb][0], S[2 * kb][1]); w.y = pk2(S[2 * kb][2], S[2 * kb][3]); w.z = pk2(S[2 * kb + 1][0], S[2 * kb + 1][1]); w.w = pk2(S[2 * kb + 1][2], S[2 * kb + 1][3]);
;         pf[kb] = __builtin_bit_cast(bf16x8, w);
;     }
; #pragma unroll
;     for (int dt = 0; dt < 4; ++dt) {
;         f32x4 acc = (f32x4){0.f, 0.f, 0.f, 0.f};
; #pragma unroll
;         for (int kb = 0; kb < NKT / 2; ++kb) {
;             const bf16x8 vf = *(LAS const bf16x8*)(vb_ + dt * 16 * VSTR + kb * 64);
;             acc = mfma16(vf, pf[kb], acc);
	v_exp_f32_e32 v38, v38
	v_sub_f32_e32 v39, v39, v12
	v_add_f32_e32 v14, v43, v14
	v_exp_f32_e32 v39, v39
	v_sub_f32_e32 v32, v32, v12
	v_add_f32_e32 v14, v36, v14
	v_exp_f32_e32 v32, v32
	v_sub_f32_e32 v33, v33, v12
	v_add_f32_e32 v14, v37, v14
	v_exp_f32_e32 v33, v33
	v_sub_f32_e32 v34, v34, v12
	v_add_f32_e32 v14, v38, v14
	v_exp_f32_e32 v34, v34
	v_sub_f32_e32 v35, v35, v12
	v_add_f32_e32 v14, v39, v14
	v_exp_f32_e32 v35, v35
	v_sub_f32_e32 v28, v28, v12
	v_add_f32_e32 v14, v32, v14
	v_exp_f32_e32 v58, v28
	v_sub_f32_e32 v28, v29, v12
	v_add_f32_e32 v14, v33, v14
	v_exp_f32_e32 v59, v28
	v_sub_f32_e32 v28, v30, v12
	v_add_f32_e32 v14, v34, v14
	v_exp_f32_e32 v82, v28
	v_sub_f32_e32 v28, v31, v12
	v_add_f32_e32 v14, v35, v14
	v_exp_f32_e32 v83, v28
	v_sub_f32_e32 v24, v24, v12
	v_add_f32_e32 v14, v58, v14
	v_exp_f32_e32 v84, v24
	v_sub_f32_e32 v24, v25, v12
	v_add_f32_e32 v14, v59, v14
	v_exp_f32_e32 v85, v24
	v_sub_f32_e32 v24, v26, v12
	v_add_f32_e32 v14, v82, v14
	v_exp_f32_e32 v86, v24
	v_sub_f32_e32 v24, v27, v12
	v_add_f32_e32 v14, v83, v14
	v_exp_f32_e32 v87, v24
	v_sub_f32_e32 v20, v20, v12
	v_add_f32_e32 v14, v84, v14
	v_exp_f32_e32 v88, v20
	v_sub_f32_e32 v20, v21, v12
	v_add_f32_e32 v14, v85, v14
	v_exp_f32_e32 v89, v20
	v_sub_f32_e32 v20, v22, v12
	v_add_f32_e32 v14, v86, v14
	v_exp_f32_e32 v90, v20
	v_sub_f32_e32 v20, v23, v12
	v_add_f32_e32 v14, v87, v14
	v_exp_f32_e32 v91, v20
	v_sub_f32_e32 v16, v16, v12
	v_add_f32_e32 v14, v88, v14
	v_exp_f32_e32 v92, v16
	v_sub_f32_e32 v16, v17, v12
	v_add_f32_e32 v14, v89, v14
	v_exp_f32_e32 v93, v16
	v_sub_f32_e32 v16, v18, v12
	v_add_f32_e32 v14, v90, v14
	v_exp_f32_e32 v94, v16
	v_sub_f32_e32 v16, v19, v12
	v_add_f32_e32 v14, v91, v14
	v_exp_f32_e32 v95, v16
	v_sub_f32_e32 v8, v8, v12
	v_add_f32_e32 v14, v92, v14
	v_exp_f32_e32 v96, v8
	v_sub_f32_e32 v9, v9, v12
	v_add_f32_e32 v14, v93, v14
	v_exp_f32_e32 v97, v9
	v_sub_f32_e32 v9, v10, v12
	v_add_f32_e32 v14, v94, v14
	v_exp_f32_e32 v98, v9
	v_sub_f32_e32 v9, v11, v12
	v_add_f32_e32 v14, v95, v14
	v_exp_f32_e32 v11, v9
	v_add_f32_e32 v8, v96, v14
	v_add_f32_e32 v8, v97, v8
	v_add_f32_e32 v8, v98, v8
	v_add_f32_e32 v8, v11, v8
	ds_bpermute_b32 v9, v135, v8
	v_cvt_pk_bf16_f32 v28, v13, v15
	v_cvt_pk_bf16_f32 v29, v56, v57
	v_cvt_pk_bf16_f32 v30, v52, v53
	v_cvt_pk_bf16_f32 v31, v54, v55
	s_waitcnt lgkmcnt(0)
	v_add_f32_e32 v8, v8, v9
	ds_bpermute_b32 v9, v76, v8
	v_cvt_pk_bf16_f32 v24, v48, v49
	v_cvt_pk_bf16_f32 v25, v50, v51
	v_cvt_pk_bf16_f32 v26, v44, v45
	v_cvt_pk_bf16_f32 v27, v46, v47
	s_waitcnt lgkmcnt(0)
	v_add_f32_e32 v8, v8, v9
	v_fma_f32 v9, v81, s2, -v12
	v_exp_f32_e32 v9, v9
	v_cvt_pk_bf16_f32 v20, v40, v41
	v_cvt_pk_bf16_f32 v21, v42, v43
	v_cvt_pk_bf16_f32 v22, v36, v37
	v_cvt_pk_bf16_f32 v23, v38, v39
	v_cvt_pk_bf16_f32 v16, v32, v33
	s_nop 0
	v_add_f32_e32 v81, v9, v8
	v_div_scale_f32 v32, s[0:1], v81, v81, 1.0
	v_rcp_f32_e32 v33, v32
	v_cvt_pk_bf16_f32 v17, v34, v35
	v_cvt_pk_bf16_f32 v18, v58, v59
	v_cvt_pk_bf16_f32 v19, v82, v83
	v_cvt_pk_bf16_f32 v12, v84, v85
	v_cvt_pk_bf16_f32 v13, v86, v87
	s_nop 0
	v_fma_f32 v34, -v32, v33, 1.0
	v_fmac_f32_e32 v33, v34, v33
	v_div_scale_f32 v34, vcc, 1.0, v81, 1.0
	v_mul_f32_e32 v35, v34, v33
	v_fma_f32 v36, -v32, v35, v34
	v_fmac_f32_e32 v35, v36, v33
	v_fma_f32 v32, -v32, v35, v34
	v_cvt_pk_bf16_f32 v14, v88, v89
	v_cvt_pk_bf16_f32 v15, v90, v91
	v_cvt_pk_bf16_f32 v8, v92, v93
	v_cvt_pk_bf16_f32 v9, v94, v95
	v_cvt_pk_bf16_f32 v10, v96, v97
	v_cvt_pk_bf16_f32 v11, v98, v11
	v_div_fmas_f32 v32, v32, v33, v35
	s_waitcnt lgkmcnt(0)
	ds_read_b128 v[196:199], v78 offset:55296
	ds_read_b128 v[200:203], v78 offset:55360
	ds_read_b128 v[204:207], v78 offset:61760
	ds_read_b128 v[208:211], v77 offset:12864
	ds_read_b128 v[212:215], v78 offset:55424
	ds_read_b128 v[228:231], v78 offset:55488
	ds_read_b128 v[232:235], v78 offset:55552
	ds_read_b128 v[236:239], v78 offset:55616
	ds_read_b128 v[240:243], v78 offset:61696
	ds_read_b128 v[244:247], v78 offset:61824
	s_waitcnt lgkmcnt(9)
	v_mfma_f32_16x16x32_bf16 v[34:37], v[196:199], v[28:31], 0
	ds_read_b128 v[196:199], v78 offset:61888
	v_div_fixup_f32 v32, v32, v81, 1.0
	s_waitcnt lgkmcnt(9)
	v_mfma_f32_16x16x32_bf16 v[34:37], v[200:203], v[24:27], v[34:37]
	ds_read_b128 v[200:203], v78 offset:61952
	s_waitcnt lgkmcnt(7)
; #define LAS __attribute__((address_space(3)))
; __device__ __forceinline__ float sq4(const f32x4 a) { return (a[0] * a[0] + a[1] * a[1]) + (a[2] * a[2] + a[3] * a[3]); }
; #define LAS __attribute__((address_space(3)))
; __device__ __forceinline__ unsigned pk2(float lo, float hi) { return pg8::cvt_pk_bf16(lo, hi); }
; __device__ __forceinline__ f32x4 mfma16(bf16x8 a, bf16x8 b, f32x4 c) { return __builtin_amdgcn_mfma_f32_16x16x32_bf16(a, b, c, 0, 0, 0); }
; template <int NKT, int VSTR, bool SINK>
; __device__ __forceinline__ void attn_core(LAS const unsigned char* kb_, LAS const unsigned char* vb_, bf16x8 q0, bf16x8 q1, float sk, unsigned mskbits, int fr, f32x4 (&o)[4]) {
;     ...
; #pragma unroll
;     for (int dt = 0; dt < 4; ++dt) {
;         f32x4 acc = (f32x4){0.f, 0.f, 0.f, 0.f};
; #pragma unroll
;         for (int kb = 0; kb < NKT / 2; ++kb) {
;             const bf16x8 vf = *(LAS const bf16x8*)(vb_ + dt * 16 * VSTR + kb * 64);
;             acc = mfma16(vf, pf[kb], acc);
;         }
;         o[dt] = acc * inv;
;     }
; template <bool DO_SWA, bool DO_MEM>
; __device__ __forceinline__ void attn_unit(const Args& a, unsigned char* ws, LAS unsigned char* lds, int l, int tid_in, int lane_in, int wave, int unit) {
;     ...
;                 attn_core<12, 400, true>(lds + A_KS + g * 192 * 144 + fq * 16, lds + A_VT1 + (g * 64 + fr) * 400 + fq * 16, qsw[hh][0], qsw[hh][1], sk, mskbits, fr, o);
; #pragma unroll
;                 for (int dt = 0; dt < 4; ++dt) { ssq += pg8::sq4(o[dt]); osv[hh][dt] = (v2u){pk2(o[dt][0], o[dt][1]), pk2(o[dt][2], o[dt][3])}; }
;             }
	v_mfma_f32_16x16x32_bf16 v[34:37], v[212:215], v[20:23], v[34:37]
	ds_read_b128 v[212:215], v78 offset:62016
	s_waitcnt lgkmcnt(7)
	v_mfma_f32_16x16x32_bf16 v[34:37], v[228:231], v[16:19], v[34:37]
	ds_read_b128 v[228:231], v77 offset:12800
	s_waitcnt lgkmcnt(7)
	v_mfma_f32_16x16x32_bf16 v[34:37], v[232:235], v[12:15], v[34:37]
	ds_read_b128 v[232:235], v77 offset:12928
	s_waitcnt lgkmcnt(7)
	v_mfma_f32_16x16x32_bf16 v[36:39], v[236:239], v[8:11], v[34:37]
	ds_read_b128 v[236:239], v77 offset:12992
	s_nop 7
	v_pk_mul_f32 v[34:35], v[38:39], v[32:33] op_sel_hi:[1,0]
	s_waitcnt lgkmcnt(7)
	v_mfma_f32_16x16x32_bf16 v[38:41], v[240:243], v[28:31], 0
	ds_read_b128 v[240:243], v77 offset:13056
	v_mul_f32_e64 v36, v36, v32
	v_mul_f32_e64 v37, v37, v32
	v_mfma_f32_16x16x32_bf16 v[38:41], v[204:207], v[24:27], v[38:41]
	ds_read_b128 v[204:207], v77 offset:13120
	s_waitcnt lgkmcnt(8)
	v_mfma_f32_16x16x32_bf16 v[38:41], v[244:247], v[20:23], v[38:41]
	ds_read_b128 v[244:247], v77 offset:19200
	s_waitcnt lgkmcnt(8)
	v_mfma_f32_16x16x32_bf16 v[38:41], v[196:199], v[16:19], v[38:41]
	ds_read_b128 v[196:199], v77 offset:19264
	s_waitcnt lgkmcnt(8)
	v_mfma_f32_16x16x32_bf16 v[38:41], v[200:203], v[12:15], v[38:41]
	ds_read_b128 v[200:203], v77 offset:19328
	s_waitcnt lgkmcnt(8)
	v_mfma_f32_16x16x32_bf16 v[40:43], v[212:215], v[8:11], v[38:41]
	s_nop 7
	v_pk_mul_f32 v[38:39], v[42:43], v[32:33] op_sel_hi:[1,0]
	ds_read_b128 v[212:215], v77 offset:19392
	s_waitcnt lgkmcnt(8)
	v_mfma_f32_16x16x32_bf16 v[42:45], v[228:231], v[28:31], 0
	v_mul_f32_e64 v40, v40, v32
	v_mul_f32_e64 v41, v41, v32
	v_mfma_f32_16x16x32_bf16 v[42:45], v[208:211], v[24:27], v[42:45]
	ds_read_b128 v[228:231], v77 offset:19456
	s_waitcnt lgkmcnt(8)
	v_mfma_f32_16x16x32_bf16 v[42:45], v[232:235], v[20:23], v[42:45]
	ds_read_b128 v[208:211], v77 offset:19520
	s_waitcnt lgkmcnt(8)
	v_mfma_f32_16x16x32_bf16 v[42:45], v[236:239], v[16:19], v[42:45]
	s_waitcnt lgkmcnt(7)
	v_mfma_f32_16x16x32_bf16 v[42:45], v[240:243], v[12:15], v[42:45]
	s_waitcnt lgkmcnt(6)
	v_mfma_f32_16x16x32_bf16 v[44:47], v[204:207], v[8:11], v[42:45]
	s_nop 7
	v_pk_mul_f32 v[42:43], v[32:33], v[46:47] op_sel_hi:[0,1]
	s_waitcnt lgkmcnt(5)
	v_mfma_f32_16x16x32_bf16 v[28:31], v[244:247], v[28:31], 0
	v_pk_mul_f32 v[44:45], v[32:33], v[44:45] op_sel_hi:[0,1]
	s_waitcnt lgkmcnt(4)
	v_mfma_f32_16x16x32_bf16 v[24:27], v[196:199], v[24:27], v[28:31]
	s_waitcnt lgkmcnt(3)
	v_mfma_f32_16x16x32_bf16 v[20:23], v[200:203], v[20:23], v[24:27]
	s_waitcnt lgkmcnt(2)
	v_mfma_f32_16x16x32_bf16 v[16:19], v[212:215], v[16:19], v[20:23]
	s_waitcnt lgkmcnt(1)
	v_mfma_f32_16x16x32_bf16 v[12:15], v[228:231], v[12:15], v[16:19]
	v_cvt_pk_bf16_f32 v53, v36, v37
	v_cvt_pk_bf16_f32 v52, v34, v35
	s_waitcnt lgkmcnt(0)
	v_mfma_f32_16x16x32_bf16 v[8:11], v[208:211], v[8:11], v[12:15]
	s_nop 2
	v_mul_f32_e32 v12, v37, v37
	v_mul_f32_e32 v13, v35, v35
	v_fmac_f32_e32 v12, v36, v36
	v_fmac_f32_e32 v13, v34, v34
	v_add_f32_e32 v12, v12, v13
	v_mul_f32_e32 v13, v41, v41
	v_mul_f32_e32 v14, v39, v39
	v_fmac_f32_e32 v13, v40, v40
	v_fmac_f32_e32 v14, v38, v38
	v_add_f32_e32 v12, v80, v12
	v_add_f32_e32 v13, v13, v14
	v_add_f32_e32 v12, v13, v12
	v_mul_f32_e32 v13, v45, v45
	v_mul_f32_e32 v14, v43, v43
	v_fmac_f32_e32 v13, v44, v44
	v_fmac_f32_e32 v14, v42, v42
	v_pk_mul_f32 v[10:11], v[32:33], v[10:11] op_sel_hi:[0,1]
	v_pk_mul_f32 v[8:9], v[32:33], v[8:9] op_sel_hi:[0,1]
	v_add_f32_e32 v13, v13, v14
	v_add_f32_e32 v12, v13, v12
	v_mul_f32_e32 v13, v9, v9
	v_mul_f32_e32 v14, v11, v11
	v_fmac_f32_e32 v13, v8, v8
	v_fmac_f32_e32 v14, v10, v10
	v_add_f32_e32 v13, v13, v14
	v_cvt_pk_bf16_f32 v55, v40, v41
	v_cvt_pk_bf16_f32 v54, v38, v39
	v_cvt_pk_bf16_f32 v57, v44, v45
	v_cvt_pk_bf16_f32 v56, v42, v43
	v_add_f32_e32 v80, v12, v13
	v_cvt_pk_bf16_f32 v59, v8, v9
	v_cvt_pk_bf16_f32 v58, v10, v11
	v_mov_b32_e32 v81, s101
	s_waitcnt lgkmcnt(0)
	ds_read_b128 v[92:95], v79
	ds_read_b128 v[196:199], v79 offset:64
	ds_read_b128 v[200:203], v79 offset:576
	ds_read_b128 v[204:207], v79 offset:640
	ds_read_b128 v[208:211], v79 offset:4608
	ds_read_b128 v[212:215], v79 offset:4672
	ds_read_b128 v[228:231], v79 offset:5184
	ds_read_b128 v[232:235], v79 offset:5248
	ds_read_b128 v[236:239], v79 offset:9216
	ds_read_b128 v[240:243], v79 offset:9280
	ds_read_b128 v[244:247], v79 offset:9792
	s_waitcnt lgkmcnt(10)
	v_mfma_f32_16x16x32_bf16 v[8:11], v[92:95], v[4:7], 0

; #define LAS __attribute__((address_space(3)))
; #define LAS __attribute__((address_space(3)))
; __device__ __forceinline__ f32x4 mfma16(bf16x8 a, bf16x8 b, f32x4 c) { return __builtin_amdgcn_mfma_f32_16x16x32_bf16(a, b, c, 0, 0, 0); }
; template <int NKT, int VSTR, bool SINK>
; __device__ __forceinline__ void attn_core(LAS const unsigned char* kb_, LAS const unsigned char* vb_, bf16x8 q0, bf16x8 q1, float sk, unsigned mskbits, int fr, f32x4 (&o)[4]) {
;     ...
; #pragma unroll
;     for (int kt = 0; kt < NKT; ++kt) {
;         const int key = (kt >> 1) * 32 + ((kt & 1) << 2) + krow;
;         LAS const unsigned char* kp = kb_ + key * 144;
;         const bf16x8 a0 = *(LAS const bf16x8*)kp, a1 = *(LAS const bf16x8*)(kp + 64);
;         const float bias = ((mskbits >> (kt >> 2)) & 1u) ? -1e30f : 0.f;
;         f32x4 s = mfma16(a0, q0, (f32x4){bias, bias, bias, bias});
;         s = mfma16(a1, q1, s);
;         S[kt] = s;
;     }
;     float mx = S[0][0];
; #pragma unroll
;     for (int kt = 0; kt < NKT; ++kt) mx = fmaxf(fmaxf(mx, fmaxf(S[kt][0], S[kt][1])), fmaxf(S[kt][2], S[kt][3]));
;     mx = fmaxf(mx, __shfl_xor(mx, 16)); mx = fmaxf(mx, __shfl_xor(mx, 32));
;     if (SINK) mx = fmaxf(mx, sk);
;     float sum = 0.f;
; #pragma unroll
;     for (int kt = 0; kt < NKT; ++kt)
; #pragma unroll
;         for (int r = 0; r < 4; ++r) { const float p = __builtin_amdgcn_exp2f(S[kt][r] - mx); S[kt][r] = p; sum += p; }
;     sum += __shfl_xor(sum, 16); sum += __shfl_xor(sum, 32);
;     if (SINK) sum += __builtin_amdgcn_exp2f(sk - mx);
	v_mul_f32_e32 v82, 0x3fb8aa3b, v81
	s_waitcnt lgkmcnt(9)
	v_mfma_f32_16x16x32_bf16 v[36:39], v[196:199], v[0:3], v[8:11]
	ds_read_b128 v[92:95], v79 offset:9856
	ds_read_b128 v[196:199], v79 offset:13824
	s_waitcnt lgkmcnt(10)
	v_mfma_f32_16x16x32_bf16 v[8:11], v[200:203], v[4:7], 0
	s_waitcnt lgkmcnt(9)
	v_mfma_f32_16x16x32_bf16 v[28:31], v[204:207], v[0:3], v[8:11]
	ds_read_b128 v[200:203], v79 offset:13888
	ds_read_b128 v[204:207], v79 offset:14400
	s_waitcnt lgkmcnt(10)
	v_mfma_f32_16x16x32_bf16 v[8:11], v[208:211], v[4:7], 0
	s_waitcnt lgkmcnt(9)
	v_mfma_f32_16x16x32_bf16 v[20:23], v[212:215], v[0:3], v[8:11]
	ds_read_b128 v[208:211], v79 offset:14464
	ds_read_b128 v[212:215], v79 offset:18432
	s_waitcnt lgkmcnt(10)
	v_mfma_f32_16x16x32_bf16 v[8:11], v[228:231], v[4:7], 0
	s_waitcnt lgkmcnt(9)
	v_mfma_f32_16x16x32_bf16 v[12:15], v[232:235], v[0:3], v[8:11]
	ds_read_b128 v[228:231], v79 offset:18496
	ds_read_b128 v[232:235], v79 offset:19008
	s_waitcnt lgkmcnt(10)
	v_mfma_f32_16x16x32_bf16 v[8:11], v[236:239], v[4:7], 0
	s_waitcnt lgkmcnt(9)
	v_mfma_f32_16x16x32_bf16 v[8:11], v[240:243], v[0:3], v[8:11]
	ds_read_b128 v[236:239], v79 offset:19072
	ds_read_b128 v[240:243], v79 offset:23040
	s_waitcnt lgkmcnt(10)
	v_mfma_f32_16x16x32_bf16 v[16:19], v[244:247], v[4:7], 0
	s_waitcnt lgkmcnt(9)
	v_mfma_f32_16x16x32_bf16 v[16:19], v[92:95], v[0:3], v[16:19]
	ds_read_b128 v[244:247], v79 offset:23104
	ds_read_b128 v[92:95], v79 offset:23616
	s_waitcnt lgkmcnt(10)
	v_mfma_f32_16x16x32_bf16 v[24:27], v[196:199], v[4:7], 0
	s_waitcnt lgkmcnt(9)
	v_mfma_f32_16x16x32_bf16 v[24:27], v[200:203], v[0:3], v[24:27]
	ds_read_b128 v[196:199], v79 offset:23680
	s_waitcnt lgkmcnt(9)
	v_mfma_f32_16x16x32_bf16 v[32:35], v[204:207], v[4:7], 0
	s_waitcnt lgkmcnt(8)
	v_mfma_f32_16x16x32_bf16 v[32:35], v[208:211], v[0:3], v[32:35]
	s_waitcnt lgkmcnt(7)
	v_mfma_f32_16x16x32_bf16 v[40:43], v[212:215], v[4:7], 0
	s_waitcnt lgkmcnt(6)
	v_mfma_f32_16x16x32_bf16 v[40:43], v[228:231], v[0:3], v[40:43]
	s_waitcnt lgkmcnt(5)
	v_mfma_f32_16x16x32_bf16 v[44:47], v[232:235], v[4:7], 0
	s_waitcnt lgkmcnt(4)
	v_mfma_f32_16x16x32_bf16 v[44:47], v[236:239], v[0:3], v[44:47]
	s_waitcnt lgkmcnt(3)
	v_mfma_f32_16x16x32_bf16 v[48:51], v[240:243], v[4:7], 0
	s_waitcnt lgkmcnt(2)
	v_mfma_f32_16x16x32_bf16 v[48:51], v[244:247], v[0:3], v[48:51]
	s_waitcnt lgkmcnt(1)
	v_mfma_f32_16x16x32_bf16 v[4:7], v[92:95], v[4:7], 0
	s_waitcnt lgkmcnt(0)
	v_mfma_f32_16x16x32_bf16 v[0:3], v[196:199], v[0:3], v[4:7]
	s_nop 5
	s_nop 0
	s_nop 0
	v_max_f32_e32 v4, v38, v39
	s_nop 0
	s_nop 0
	v_max_f32_e32 v5, v28, v29
	s_nop 0
	s_nop 0
	v_max3_f32 v4, v36, v37, v4
	v_max_f32_e32 v6, v30, v31
	v_max3_f32 v4, v4, v5, v6
	s_nop 0
	s_nop 0
	v_max_f32_e32 v5, v20, v21
	s_nop 0
	s_nop 0
	v_max_f32_e32 v6, v22, v23
	v_max3_f32 v4, v4, v5, v6
	s_nop 0
	s_nop 0
	v_max_f32_e32 v5, v12, v13
	s_nop 0
	s_nop 0
	v_max_f32_e32 v6, v14, v15
	v_max3_f32 v4, v4, v5, v6
	v_max_f32_e32 v5, v8, v9
	v_max_f32_e32 v6, v10, v11
	v_max3_f32 v4, v4, v5, v6
	v_max_f32_e32 v5, v16, v17
	v_max_f32_e32 v6, v18, v19
	v_max3_f32 v4, v4, v5, v6
	v_max_f32_e32 v5, v24, v25
	v_max_f32_e32 v6, v26, v27
	v_max3_f32 v4, v4, v5, v6
	v_max_f32_e32 v5, v32, v33
	v_max_f32_e32 v6, v34, v35
	v_max3_f32 v4, v4, v5, v6
	v_max_f32_e32 v5, v40, v41
	v_max_f32_e32 v6, v42, v43
	v_max3_f32 v4, v4, v5, v6
	v_max_f32_e32 v5, v44, v45
	v_max_f32_e32 v6, v46, v47
	v_max3_f32 v4, v4, v5, v6
	v_max_f32_e32 v5, v48, v49
	v_max_f32_e32 v6, v50, v51
	v_max3_f32 v4, v4, v5, v6
	v_max_f32_e32 v5, v0, v1
	v_max_f32_e32 v6, v2, v3
	v_max3_f32 v4, v4, v5, v6
	ds_bpermute_b32 v5, v135, v4
	s_waitcnt lgkmcnt(0)
	s_nop 0
	v_max_f32_e32 v4, v4, v5
	ds_bpermute_b32 v5, v76, v4
	s_waitcnt lgkmcnt(0)
	v_max3_f32 v4, v4, v5, v82
	v_sub_f32_e32 v5, v36, v4
	v_exp_f32_e32 v5, v5
	v_sub_f32_e32 v7, v37, v4
	v_exp_f32_e32 v7, v7
	v_sub_f32_e32 v36, v38, v4
	v_exp_f32_e32 v36, v36
	v_sub_f32_e32 v37, v39, v4
	v_exp_f32_e32 v37, v37
	v_sub_f32_e32 v28, v28, v4
	v_add_f32_e32 v6, 0, v5
	v_exp_f32_e32 v28, v28
	v_sub_f32_e32 v29, v29, v4
	v_add_f32_e32 v6, v7, v6
	v_exp_f32_e32 v29, v29
	v_sub_f32_e32 v30, v30, v4
	v_add_f32_e32 v6, v36, v6
	v_exp_f32_e32 v30, v30
	v_sub_f32_e32 v31, v31, v4
	v_add_f32_e32 v6, v37, v6
	v_exp_f32_e32 v31, v31
	v_sub_f32_e32 v20, v20, v4
	v_add_f32_e32 v6, v28, v6
	v_exp_f32_e32 v38, v20
	v_sub_f32_e32 v20, v21, v4
	v_add_f32_e32 v6, v29, v6
	v_exp_f32_e32 v39, v20
	v_sub_f32_e32 v20, v22, v4
	v_add_f32_e32 v6, v30, v6
	v_exp_f32_e32 v79, v20
	v_sub_f32_e32 v20, v23, v4
	v_add_f32_e32 v6, v31, v6
	v_exp_f32_e32 v82, v20
	v_sub_f32_e32 v12, v12, v4
	v_add_f32_e32 v6, v38, v6
	v_exp_f32_e32 v12, v12
	v_sub_f32_e32 v13, v13, v4
	v_add_f32_e32 v6, v39, v6
	v_exp_f32_e32 v13, v13
	v_sub_f32_e32 v14, v14, v4
	v_add_f32_e32 v6, v79, v6
	v_exp_f32_e32 v14, v14
	v_sub_f32_e32 v15, v15, v4
	v_add_f32_e32 v6, v82, v6
	v_exp_f32_e32 v15, v15
	v_sub_f32_e32 v8, v8, v4
	v_add_f32_e32 v6, v12, v6
	v_exp_f32_e32 v8, v8
	v_sub_f32_e32 v9, v9, v4
	v_add_f32_e32 v6, v13, v6
	v_exp_f32_e32 v9, v9
	v_sub_f32_e32 v10, v10, v4
	v_add_f32_e32 v6, v14, v6
	v_exp_f32_e32 v10, v10
	v_sub_f32_e32 v11, v11, v4
	v_add_f32_e32 v6, v15, v6
	v_exp_f32_e32 v11, v11
	v_sub_f32_e32 v16, v16, v4
	v_add_f32_e32 v6, v8, v6
	v_exp_f32_e32 v83, v16
	v_sub_f32_e32 v16, v17, v4
	v_add_f32_e32 v6, v9, v6
	v_exp_f32_e32 v84, v16
	v_sub_f32_e32 v16, v18, v4
	v_add_f32_e32 v6, v10, v6
	v_exp_f32_e32 v85, v16
	v_sub_f32_e32 v16, v19, v4
	v_add_f32_e32 v6, v11, v6
	v_exp_f32_e32 v86, v16
	v_sub_f32_e32 v16, v24, v4
	v_add_f32_e32 v6, v83, v6
	v_exp_f32_e32 v24, v16
	v_sub_f32_e32 v16, v25, v4
; #define LAS __attribute__((address_space(3)))
; #define LAS __attribute__((address_space(3)))
; __device__ __forceinline__ unsigned pk2(float lo, float hi) { return pg8::cvt_pk_bf16(lo, hi); }
; __device__ __forceinline__ f32x4 mfma16(bf16x8 a, bf16x8 b, f32x4 c) { return __builtin_amdgcn_mfma_f32_16x16x32_bf16(a, b, c, 0, 0, 0); }
; template <int NKT, int VSTR, bool SINK>
; __device__ __forceinline__ void attn_core(LAS const unsigned char* kb_, LAS const unsigned char* vb_, bf16x8 q0, bf16x8 q1, float sk, unsigned mskbits, int fr, f32x4 (&o)[4]) {
;     ...
;     for (int kt = 0; kt < NKT; ++kt)
; #pragma unroll
;         for (int r = 0; r < 4; ++r) { const float p = __builtin_amdgcn_exp2f(S[kt][r] - mx); S[kt][r] = p; sum += p; }
;     sum += __shfl_xor(sum, 16); sum += __shfl_xor(sum, 32);
;     if (SINK) sum += __builtin_amdgcn_exp2f(sk - mx);
;     const float inv = 1.0f / sum;
;     bf16x8 pf[NKT / 2];
; #pragma unroll
;     for (int kb = 0; kb < NKT / 2; ++kb) {
;         v4u w; w.x = pk2(S[2 * kb][0], S[2 * kb][1]); w.y = pk2(S[2 * kb][2], S[2 * kb][3]); w.z = pk2(S[2 * kb + 1][0], S[2 * kb + 1][1]); w.w = pk2(S[2 * kb + 1][2], S[2 * kb + 1][3]);
;         pf[kb] = __builtin_bit_cast(bf16x8, w);
;     }
; #pragma unroll
;     for (int dt = 0; dt < 4; ++dt) {
;         f32x4 acc = (f32x4){0.f, 0.f, 0.f, 0.f};
; #pragma unroll
;         for (int kb = 0; kb < NKT / 2; ++kb) {
;             const bf16x8 vf = *(LAS const bf16x8*)(vb_ + dt * 16 * VSTR + kb * 64);
;             acc = mfma16(vf, pf[kb], acc);
	v_add_f32_e32 v6, v84, v6
	v_exp_f32_e32 v25, v16
	v_sub_f32_e32 v16, v26, v4
	v_add_f32_e32 v6, v85, v6
	v_exp_f32_e32 v26, v16
	v_sub_f32_e32 v16, v27, v4
	v_add_f32_e32 v6, v86, v6
	v_exp_f32_e32 v27, v16
	v_sub_f32_e32 v16, v32, v4
	v_add_f32_e32 v6, v24, v6
	v_exp_f32_e32 v32, v16
	v_sub_f32_e32 v16, v33, v4
	v_add_f32_e32 v6, v25, v6
	v_exp_f32_e32 v33, v16
	v_sub_f32_e32 v16, v34, v4
	v_add_f32_e32 v6, v26, v6
	v_exp_f32_e32 v34, v16
	v_sub_f32_e32 v16, v35, v4
	v_add_f32_e32 v6, v27, v6
	v_exp_f32_e32 v35, v16
	v_sub_f32_e32 v16, v40, v4
	v_add_f32_e32 v6, v32, v6
	v_exp_f32_e32 v40, v16
	v_sub_f32_e32 v16, v41, v4
	v_add_f32_e32 v6, v33, v6
	v_exp_f32_e32 v41, v16
	v_sub_f32_e32 v16, v42, v4
	v_add_f32_e32 v6, v34, v6
	v_exp_f32_e32 v42, v16
	v_sub_f32_e32 v16, v43, v4
	v_add_f32_e32 v6, v35, v6
	v_exp_f32_e32 v43, v16
	v_sub_f32_e32 v16, v44, v4
	v_add_f32_e32 v6, v40, v6
	v_exp_f32_e32 v44, v16
	v_sub_f32_e32 v16, v45, v4
	v_add_f32_e32 v6, v41, v6
	v_exp_f32_e32 v45, v16
	v_sub_f32_e32 v16, v46, v4
	v_add_f32_e32 v6, v42, v6
	v_exp_f32_e32 v46, v16
	v_sub_f32_e32 v16, v47, v4
	v_add_f32_e32 v6, v43, v6
	v_exp_f32_e32 v47, v16
	v_sub_f32_e32 v16, v48, v4
	v_add_f32_e32 v6, v44, v6
	v_exp_f32_e32 v48, v16
	v_sub_f32_e32 v16, v49, v4
	v_add_f32_e32 v6, v45, v6
	v_exp_f32_e32 v49, v16
	v_sub_f32_e32 v16, v50, v4
	v_add_f32_e32 v6, v46, v6
	v_exp_f32_e32 v50, v16
	v_sub_f32_e32 v16, v51, v4
	v_add_f32_e32 v6, v47, v6
	v_exp_f32_e32 v51, v16
	v_sub_f32_e32 v0, v0, v4
	v_add_f32_e32 v6, v48, v6
	v_exp_f32_e32 v87, v0
	v_sub_f32_e32 v1, v1, v4
	v_add_f32_e32 v6, v49, v6
	v_exp_f32_e32 v88, v1
	v_sub_f32_e32 v1, v2, v4
	v_add_f32_e32 v6, v50, v6
	v_exp_f32_e32 v89, v1
	v_sub_f32_e32 v1, v3, v4
	v_add_f32_e32 v6, v51, v6
	v_exp_f32_e32 v3, v1
	v_add_f32_e32 v0, v87, v6
	v_add_f32_e32 v0, v88, v0
	v_add_f32_e32 v0, v89, v0
	v_add_f32_e32 v0, v3, v0
	ds_bpermute_b32 v1, v135, v0
	v_cvt_pk_bf16_f32 v20, v5, v7
	v_cvt_pk_bf16_f32 v21, v36, v37
	v_cvt_pk_bf16_f32 v22, v28, v29
	v_cvt_pk_bf16_f32 v23, v30, v31
	s_waitcnt lgkmcnt(0)
	v_add_f32_e32 v0, v0, v1
	ds_bpermute_b32 v1, v76, v0
	v_cvt_pk_bf16_f32 v16, v38, v39
	v_cvt_pk_bf16_f32 v17, v79, v82
	v_cvt_pk_bf16_f32 v18, v12, v13
	v_cvt_pk_bf16_f32 v19, v14, v15
	s_waitcnt lgkmcnt(0)
	v_add_f32_e32 v0, v0, v1
	v_fma_f32 v1, v81, s2, -v4
	v_exp_f32_e32 v1, v1
	v_cvt_pk_bf16_f32 v12, v8, v9
	v_cvt_pk_bf16_f32 v13, v10, v11
	v_cvt_pk_bf16_f32 v14, v83, v84
	v_cvt_pk_bf16_f32 v15, v85, v86
	v_cvt_pk_bf16_f32 v8, v24, v25
	s_nop 0
	v_add_f32_e32 v81, v1, v0
	v_div_scale_f32 v24, s[0:1], v81, v81, 1.0
	v_rcp_f32_e32 v25, v24
	v_cvt_pk_bf16_f32 v9, v26, v27
	v_cvt_pk_bf16_f32 v10, v32, v33
	v_cvt_pk_bf16_f32 v11, v34, v35
	v_cvt_pk_bf16_f32 v4, v40, v41
	v_cvt_pk_bf16_f32 v5, v42, v43
	s_nop 0
	v_fma_f32 v26, -v24, v25, 1.0
	v_fmac_f32_e32 v25, v26, v25
	v_div_scale_f32 v26, vcc, 1.0, v81, 1.0
	v_mul_f32_e32 v27, v26, v25
	v_fma_f32 v28, -v24, v27, v26
	v_fmac_f32_e32 v27, v28, v25
	v_fma_f32 v24, -v24, v27, v26
	v_cvt_pk_bf16_f32 v6, v44, v45
	v_cvt_pk_bf16_f32 v7, v46, v47
	v_cvt_pk_bf16_f32 v0, v48, v49
	v_cvt_pk_bf16_f32 v1, v50, v51
	v_cvt_pk_bf16_f32 v2, v87, v88
	v_cvt_pk_bf16_f32 v3, v89, v3
	v_div_fmas_f32 v24, v24, v25, v27
	s_waitcnt lgkmcnt(0)
	ds_read_b128 v[92:95], v78 offset:55296
	ds_read_b128 v[196:199], v78 offset:55360
	ds_read_b128 v[200:203], v78 offset:61760
	ds_read_b128 v[204:207], v77 offset:12864
	ds_read_b128 v[208:211], v78 offset:55424
	ds_read_b128 v[212:215], v78 offset:55488
	ds_read_b128 v[228:231], v78 offset:55552
	ds_read_b128 v[232:235], v78 offset:55616
	ds_read_b128 v[236:239], v78 offset:61696
	ds_read_b128 v[240:243], v78 offset:61824
	ds_read_b128 v[244:247], v78 offset:61888
	s_waitcnt lgkmcnt(10)
	v_mfma_f32_16x16x32_bf16 v[26:29], v[92:95], v[20:23], 0
	ds_read_b128 v[92:95], v78 offset:61952
	v_div_fixup_f32 v24, v24, v81, 1.0
	s_waitcnt lgkmcnt(10)
	v_mfma_f32_16x16x32_bf16 v[26:29], v[196:199], v[16:19], v[26:29]
	ds_read_b128 v[196:199], v78 offset:62016
	v_cmp_gt_u32_e32 vcc, 16, v133
	s_waitcnt lgkmcnt(8)
; #define LAS __attribute__((address_space(3)))
; __device__ __forceinline__ float quad_sum(float s) { s += __shfl_xor(s, 16); s += __shfl_xor(s, 32); return s; }
; __device__ __forceinline__ float sq4(const f32x4 a) { return (a[0] * a[0] + a[1] * a[1]) + (a[2] * a[2] + a[3] * a[3]); }
; #define LAS __attribute__((address_space(3)))
; __device__ __forceinline__ unsigned pk2(float lo, float hi) { return pg8::cvt_pk_bf16(lo, hi); }
; __device__ __forceinline__ f32x4 mfma16(bf16x8 a, bf16x8 b, f32x4 c) { return __builtin_amdgcn_mfma_f32_16x16x32_bf16(a, b, c, 0, 0, 0); }
; template <int NKT, int VSTR, bool SINK>
; __device__ __forceinline__ void attn_core(LAS const unsigned char* kb_, LAS const unsigned char* vb_, bf16x8 q0, bf16x8 q1, float sk, unsigned mskbits, int fr, f32x4 (&o)[4]) {
;     ...
; #pragma unroll
;     for (int dt = 0; dt < 4; ++dt) {
;         f32x4 acc = (f32x4){0.f, 0.f, 0.f, 0.f};
; #pragma unroll
;         for (int kb = 0; kb < NKT / 2; ++kb) {
;             const bf16x8 vf = *(LAS const bf16x8*)(vb_ + dt * 16 * VSTR + kb * 64);
;             acc = mfma16(vf, pf[kb], acc);
;         }
;         o[dt] = acc * inv;
;     }
; template <bool DO_SWA, bool DO_MEM>
; __device__ __forceinline__ void attn_unit(const Args& a, unsigned char* ws, LAS unsigned char* lds, int l, int tid_in, int lane_in, int wave, int unit) {
;     ...
; #pragma unroll
;                 for (int dt = 0; dt < 4; ++dt) { ssq += pg8::sq4(o[dt]); osv[hh][dt] = (v2u){pk2(o[dt][0], o[dt][1]), pk2(o[dt][2], o[dt][3])}; }
;             }
;             ssq = pg8::quad_sum(ssq);
;             if (fq == 0) red_a[g * 64 + qs * 16 + fr] = ssq;
	v_mfma_f32_16x16x32_bf16 v[26:29], v[208:211], v[12:15], v[26:29]
	ds_read_b128 v[208:211], v77 offset:12800
	s_waitcnt lgkmcnt(8)
	v_mfma_f32_16x16x32_bf16 v[26:29], v[212:215], v[8:11], v[26:29]
	ds_read_b128 v[212:215], v77 offset:12928
	s_waitcnt lgkmcnt(8)
	v_mfma_f32_16x16x32_bf16 v[26:29], v[228:231], v[4:7], v[26:29]
	ds_read_b128 v[228:231], v77 offset:12992
	s_waitcnt lgkmcnt(8)
	v_mfma_f32_16x16x32_bf16 v[28:31], v[232:235], v[0:3], v[26:29]
	ds_read_b128 v[232:235], v77 offset:13056
	s_nop 7
	v_pk_mul_f32 v[26:27], v[30:31], v[24:25] op_sel_hi:[1,0]
	s_waitcnt lgkmcnt(8)
	v_mfma_f32_16x16x32_bf16 v[30:33], v[236:239], v[20:23], 0
	ds_read_b128 v[236:239], v77 offset:13120
	v_mul_f32_e64 v28, v28, v24
	v_mul_f32_e64 v29, v29, v24
	v_mfma_f32_16x16x32_bf16 v[30:33], v[200:203], v[16:19], v[30:33]
	ds_read_b128 v[200:203], v77 offset:19200
	s_waitcnt lgkmcnt(9)
	v_mfma_f32_16x16x32_bf16 v[30:33], v[240:243], v[12:15], v[30:33]
	ds_read_b128 v[240:243], v77 offset:19264
	s_waitcnt lgkmcnt(9)
	v_mfma_f32_16x16x32_bf16 v[30:33], v[244:247], v[8:11], v[30:33]
	ds_read_b128 v[244:247], v77 offset:19328
	s_waitcnt lgkmcnt(9)
	v_mfma_f32_16x16x32_bf16 v[30:33], v[92:95], v[4:7], v[30:33]
	ds_read_b128 v[92:95], v77 offset:19392
	s_waitcnt lgkmcnt(9)
	v_mfma_f32_16x16x32_bf16 v[32:35], v[196:199], v[0:3], v[30:33]
	s_nop 7
	v_pk_mul_f32 v[30:31], v[34:35], v[24:25] op_sel_hi:[1,0]
	ds_read_b128 v[196:199], v77 offset:19456
	s_waitcnt lgkmcnt(9)
	v_mfma_f32_16x16x32_bf16 v[34:37], v[208:211], v[20:23], 0
	v_mul_f32_e64 v32, v32, v24
	v_mul_f32_e64 v33, v33, v24
	v_mfma_f32_16x16x32_bf16 v[34:37], v[204:207], v[16:19], v[34:37]
	ds_read_b128 v[208:211], v77 offset:19520
	s_waitcnt lgkmcnt(9)
	v_mfma_f32_16x16x32_bf16 v[34:37], v[212:215], v[12:15], v[34:37]
	s_waitcnt lgkmcnt(8)
	v_mfma_f32_16x16x32_bf16 v[34:37], v[228:231], v[8:11], v[34:37]
	s_waitcnt lgkmcnt(7)
	v_mfma_f32_16x16x32_bf16 v[34:37], v[232:235], v[4:7], v[34:37]
	s_waitcnt lgkmcnt(6)
	v_mfma_f32_16x16x32_bf16 v[34:37], v[236:239], v[0:3], v[34:37]
	s_nop 7
	v_pk_mul_f32 v[38:39], v[24:25], v[36:37] op_sel_hi:[0,1]
	v_pk_mul_f32 v[40:41], v[24:25], v[34:35] op_sel_hi:[0,1]
	s_waitcnt lgkmcnt(5)
	v_mfma_f32_16x16x32_bf16 v[20:23], v[200:203], v[20:23], 0
	s_waitcnt lgkmcnt(4)
	v_mfma_f32_16x16x32_bf16 v[16:19], v[240:243], v[16:19], v[20:23]
	s_waitcnt lgkmcnt(3)
	v_mfma_f32_16x16x32_bf16 v[12:15], v[244:247], v[12:15], v[16:19]
	s_waitcnt lgkmcnt(2)
	v_mfma_f32_16x16x32_bf16 v[8:11], v[92:95], v[8:11], v[12:15]
	s_waitcnt lgkmcnt(1)
	v_mfma_f32_16x16x32_bf16 v[4:7], v[196:199], v[4:7], v[8:11]
	s_waitcnt lgkmcnt(0)
	v_mfma_f32_16x16x32_bf16 v[0:3], v[208:211], v[0:3], v[4:7]
	s_nop 2
	v_mul_f32_e32 v4, v31, v31
	v_fmac_f32_e32 v4, v30, v30
	v_mul_f32_e32 v5, v41, v41
	s_nop 1
	v_pk_mul_f32 v[6:7], v[24:25], v[0:1] op_sel_hi:[0,1]
	v_mul_f32_e32 v0, v29, v29
	v_mul_f32_e32 v1, v27, v27
	v_pk_mul_f32 v[8:9], v[24:25], v[2:3] op_sel_hi:[0,1]
	v_fmac_f32_e32 v0, v28, v28
	v_fmac_f32_e32 v1, v26, v26
	v_mul_f32_e32 v3, v33, v33
	v_add_f32_e32 v0, v0, v1
	v_fmac_f32_e32 v3, v32, v32
	v_mul_f32_e32 v10, v39, v39
	v_add_f32_e32 v2, v80, v0
	v_add_f32_e32 v3, v3, v4
	v_fmac_f32_e32 v5, v40, v40
	v_fmac_f32_e32 v10, v38, v38
	v_mul_f32_e32 v11, v7, v7
	v_mul_f32_e32 v12, v9, v9
	v_add_f32_e32 v4, v3, v2
	v_add_f32_e32 v5, v5, v10
	v_fmac_f32_e32 v11, v6, v6
	v_fmac_f32_e32 v12, v8, v8
	v_add_f32_e32 v10, v5, v4
	v_add_f32_e32 v11, v11, v12
	v_add_f32_e32 v10, v10, v11
	v_cvt_pk_bf16_f32 v1, v28, v29
	v_cvt_pk_bf16_f32 v0, v26, v27
	v_cvt_pk_bf16_f32 v3, v32, v33
	v_cvt_pk_bf16_f32 v2, v30, v31
	v_cvt_pk_bf16_f32 v5, v40, v41
	v_cvt_pk_bf16_f32 v4, v38, v39
	v_cvt_pk_bf16_f32 v7, v6, v7
	v_cvt_pk_bf16_f32 v6, v8, v9
	ds_bpermute_b32 v8, v135, v10
	s_waitcnt lgkmcnt(0)
	v_add_f32_e32 v8, v10, v8
	ds_bpermute_b32 v9, v76, v8
	s_and_saveexec_b64 s[0:1], vcc
	s_cbranch_execz .LBB0_274
	v_readlane_b32 s2, v251, 30
	s_waitcnt lgkmcnt(0)
	v_add_f32_e32 v8, v8, v9
	v_lshl_add_u32 v10, v133, 2, s2
	ds_write_b32 v10, v8

; __device__ __forceinline__ unsigned pk2(float lo, float hi) { return pg8::cvt_pk_bf16(lo, hi); }
; template <bool DO_SWA, bool DO_MEM>
; __device__ __forceinline__ void attn_unit(const Args& a, unsigned char* ws, LAS unsigned char* lds, int l, int tid_in, int lane_in, int wave, int unit) {
;     ...
;             const bf16* ub = UB + (size_t)(row0 + t0) * UBW;
; #pragma unroll
;             for (int r = 0; r < 6; ++r) {
;                 if (r >= 2 || tg > 0 || !first) cu[r] = __builtin_nontemporal_load((const v4u*)(ub + (ptrdiff_t)(r - 2) * UBW + 896 + ch));
;                 else if (is_s) { const float* sp = a.in[5] + (size_t)(l * NBS + sb) * 512 + r * 256 + ch; const f32x4 s0 = *(const f32x4*)sp, s1 = *(const f32x4*)(sp + 4);
;                                  cu[r] = (v4u){pk2(s0[0], s0[1]), pk2(s0[2], s0[3]), pk2(s1[0], s1[1]), pk2(s1[2], s1[3])}; }
;                 else cu[r] = zero4;
;             }
; #pragma unroll
;             for (int i = 0; i < 4; ++i) ccb[i] = __builtin_nontemporal_load((const v4u*)(ub + (size_t)i * UBW + 640 + ch));
;         }
;         __builtin_amdgcn_sched_barrier(0);
;         if constexpr (DO_SWA) {
;             float w0[8], w1[8], w2[8];
; #pragma unroll
;             for (int j = 0; j < 4; ++j) { w0[j] = cwv[0][j]; w0[4 + j] = cwv[1][j]; w1[j] = cwv[2][j]; w1[4 + j] = cwv[3][j]; w2[j] = cwv[4][j]; w2[4 + j] = cwv[5][j]; }
; #pragma unroll
;             for (int i = 0; i < 4; ++i) {
;                 float ua[8], ub_[8], uc[8], cbv[8], cy[8];
;                 unpack8(cu[i], ua); unpack8(cu[i + 1], ub_); unpack8(cu[i + 2], uc); unpack8(ccb[i], cbv);
;                 float ss = 0.f;
; #pragma unroll
;                 for (int j = 0; j < 8; ++j) { const float y = ua[j] * w0[j] + ub_[j] * w1[j] + uc[j] * w2[j]; cy[j] = cbv[j] * y; ss += cy[j] * cy[j]; }
;                 ss += __shfl_xor(ss, 1); ss += __shfl_xor(ss, 2); ss += __shfl_xor(ss, 4); ss += __shfl_xor(ss, 8); ss += __shfl_xor(ss, 16);
;                 const float rs = 1.0f / sqrtf(ss * (1.0f / 256.0f) + EPS);
;                 v4u o; o.x = pk2(cy[0] * rs, cy[1] * rs); o.y = pk2(cy[2] * rs, cy[3] * rs); o.z = pk2(cy[4] * rs, cy[5] * rs); o.w = pk2(cy[6] * rs, cy[7] * rs);
;                 *(v4u*)(MIX + (size_t)(row0 + t0 + i) * D + 512 + ch) = o;
.LBB0_290:
	s_or_b64 exec, exec, s[4:5]
	v_lshl_add_u64 v[124:125], v[124:125], 0, v[184:185]
	s_movk_i32 s0, 0x1000
	v_add_co_u32_e32 v128, vcc, s0, v124
	s_movk_i32 s0, 0x2000
	s_nop 0
	v_addc_co_u32_e32 v129, vcc, 0, v125, vcc
	v_add_co_u32_e32 v132, vcc, s0, v124
	v_ashrrev_i32_e32 v153, 31, v152
	s_nop 0
	v_addc_co_u32_e32 v133, vcc, 0, v125, vcc
	global_load_dwordx4 v[202:205], v[124:125], off offset:1792 nt
	global_load_dwordx4 v[162:165], v[124:125], off offset:1280 nt
	global_load_dwordx4 v[140:143], v[128:129], off offset:512 nt
	global_load_dwordx4 v[206:209], v[128:129], off nt
	s_nop 0
	global_load_dwordx4 v[124:127], v[128:129], off offset:3328 nt
	global_load_dwordx4 v[136:139], v[128:129], off offset:2816 nt
	s_nop 0
	global_load_dwordx4 v[128:131], v[132:133], off offset:2048 nt
	s_nop 0
	global_load_dwordx4 v[132:135], v[132:133], off offset:1536 nt
	v_ashrrev_i32_e32 v149, 31, v148
	v_ashrrev_i32_e32 v161, 31, v160
	s_waitcnt vmcnt(0)
	v_lshlrev_b32_e32 v199, 16, v202
	v_lshlrev_b32_e32 v198, 16, v144
	v_mov_b32_e32 v200, v112
	v_mov_b32_e32 v201, v120
	v_pk_mul_f32 v[194:195], v[200:201], v[198:199]
	v_lshlrev_b32_e32 v198, 16, v208
	v_and_b32_e32 v220, 0xffff0000, v208
	v_lshlrev_b32_e32 v208, 16, v108
	v_and_b32_e32 v151, 64, v222
	v_fma_f32 v194, v116, v208, v194
	v_xor_b32_e32 v159, 1, v222
	v_add_u32_e32 v151, 64, v151
	v_lshlrev_b32_e32 v226, 16, v162
	v_lshlrev_b32_e32 v190, 16, v209
	v_and_b32_e32 v191, 0xffff0000, v209
	v_lshlrev_b32_e32 v209, 16, v140
	v_add_f32_e32 v194, v194, v195
	v_cmp_lt_i32_e32 vcc, v159, v151
	v_and_b32_e32 v246, 0xffff0000, v162
	v_lshlrev_b32_e32 v247, 16, v163
	v_and_b32_e32 v248, 0xffff0000, v163
	v_lshlrev_b32_e32 v249, 16, v164
	v_and_b32_e32 v223, 0xffff0000, v164
	v_lshlrev_b32_e32 v250, 16, v165
	v_and_b32_e32 v217, 0xffff0000, v165
	v_and_b32_e32 v183, 0xffff0000, v202
	v_and_b32_e32 v182, 0xffff0000, v144
	v_mov_b32_e32 v196, v113
	v_mov_b32_e32 v197, v121
	v_lshlrev_b32_e32 v163, 16, v205
	v_lshlrev_b32_e32 v162, 16, v147
	v_mov_b32_e32 v164, v98
	v_mov_b32_e32 v165, v106
	v_mul_f32_e32 v226, v194, v226
	v_pk_mul_f32 v[194:195], v[200:201], v[208:209]
	v_cndmask_b32_e32 v159, v222, v159, vcc
	v_pk_mul_f32 v[224:225], v[196:197], v[182:183]
	v_lshlrev_b32_e32 v179, 16, v203
	v_lshlrev_b32_e32 v178, 16, v145
	v_mov_b32_e32 v180, v114
	v_mov_b32_e32 v181, v122
	v_lshlrev_b32_e32 v171, 16, v204
	v_lshlrev_b32_e32 v170, 16, v146
	v_mov_b32_e32 v172, v96
	v_mov_b32_e32 v173, v104
	v_pk_mul_f32 v[240:241], v[164:165], v[162:163]
	v_lshlrev_b64 v[244:245], 11, v[160:161]
	v_lshlrev_b32_e32 v161, 16, v206
	v_and_b32_e32 v162, 0xffff0000, v206
	v_fma_f32 v194, v116, v199, v194
	v_and_b32_e32 v206, 0xffff0000, v108
	v_lshlrev_b32_e32 v231, 2, v159
	v_xor_b32_e32 v159, 2, v222
	v_pk_mul_f32 v[232:233], v[180:181], v[178:179]
	v_pk_mul_f32 v[236:237], v[172:173], v[170:171]
	v_lshlrev_b32_e32 v170, 16, v207
	v_and_b32_e32 v178, 0xffff0000, v207
	v_add_f32_e32 v194, v194, v195
	v_and_b32_e32 v207, 0xffff0000, v140
	v_fma_f32 v108, v117, v206, v224
	v_cmp_lt_i32_e32 vcc, v159, v151
	v_mul_f32_e32 v161, v194, v161
	v_add_f32_e32 v108, v108, v225
	v_pk_mul_f32 v[194:195], v[196:197], v[206:207]
	v_cndmask_b32_e32 v159, v222, v159, vcc
	v_mul_f32_e32 v208, v108, v246
	v_fma_f32 v108, v117, v183, v194
	v_lshlrev_b32_e32 v230, 2, v159
	v_xor_b32_e32 v159, 4, v222
	v_and_b32_e32 v167, 0xffff0000, v204
	v_add_f32_e32 v108, v108, v195
	v_lshlrev_b32_e32 v204, 16, v109
	v_cmp_lt_i32_e32 vcc, v159, v151
	v_and_b32_e32 v174, 0xffff0000, v145
	v_and_b32_e32 v145, 0xffff0000, v205
	v_mul_f32_e32 v162, v108, v162
	v_lshlrev_b32_e32 v205, 16, v141
	v_fma_f32 v108, v118, v204, v232
	v_cndmask_b32_e32 v159, v222, v159, vcc
	v_add_f32_e32 v108, v108, v233
	v_pk_mul_f32 v[194:195], v[180:181], v[204:205]
	v_lshlrev_b32_e32 v229, 2, v159
	v_xor_b32_e32 v159, 8, v222
	v_and_b32_e32 v175, 0xffff0000, v203
	v_mov_b32_e32 v176, v115
	v_mov_b32_e32 v177, v123
	v_mul_f32_e32 v233, v108, v247
	v_fma_f32 v108, v118, v179, v194
	v_cmp_lt_i32_e32 vcc, v159, v151
	v_xor_b32_e32 v166, 16, v222
	v_pk_mul_f32 v[234:235], v[176:177], v[174:175]
	v_add_f32_e32 v108, v108, v195
	v_and_b32_e32 v202, 0xffff0000, v109
	v_cndmask_b32_e32 v159, v222, v159, vcc
	v_cmp_lt_i32_e32 vcc, v166, v151
	v_mul_f32_e32 v170, v108, v170
	v_fma_f32 v108, v119, v202, v234
	v_cndmask_b32_e32 v166, v222, v166, vcc
	v_add_f32_e32 v108, v108, v235
	v_lshlrev_b32_e32 v140, 16, v110
	v_lshlrev_b32_e32 v212, 2, v166
	v_and_b32_e32 v166, 0xffff0000, v146
	v_mov_b32_e32 v168, v97
	v_mov_b32_e32 v169, v105
	v_mul_f32_e32 v204, v108, v248
	v_fma_f32 v108, v100, v140, v236
	v_pk_mul_f32 v[238:239], v[168:169], v[166:167]
	v_and_b32_e32 v203, 0xffff0000, v141
	v_add_f32_e32 v108, v108, v237
	v_and_b32_e32 v110, 0xffff0000, v110
	v_pk_mul_f32 v[224:225], v[176:177], v[202:203]
	v_mul_f32_e32 v202, v108, v249
	v_fma_f32 v108, v101, v110, v238
	v_mul_f32_e32 v246, v208, v208
	v_add_f32_e32 v108, v108, v239
	v_lshlrev_b32_e32 v194, 16, v111
	v_fmac_f32_e32 v246, v226, v226
	v_mul_f32_e32 v223, v108, v223
	v_fma_f32 v108, v102, v194, v240
	v_and_b32_e32 v144, 0xffff0000, v147
	v_mov_b32_e32 v146, v99
	v_mov_b32_e32 v147, v107
	v_fmac_f32_e32 v246, v233, v233
	v_add_f32_e32 v108, v108, v241
	v_pk_mul_f32 v[242:243], v[146:147], v[144:145]
	v_fmac_f32_e32 v246, v204, v204
	v_mul_f32_e32 v235, v108, v250
	v_and_b32_e32 v108, 0xffff0000, v111
	v_fmac_f32_e32 v246, v202, v202
	v_fma_f32 v109, v103, v108, v242
	v_fmac_f32_e32 v246, v223, v223
	v_add_f32_e32 v109, v109, v243
	v_fmac_f32_e32 v246, v235, v235
	v_mul_f32_e32 v217, v109, v217
	v_fmac_f32_e32 v246, v217, v217
	ds_bpermute_b32 v109, v231, v246
	v_fma_f32 v111, v119, v175, v224
	v_add_f32_e32 v111, v111, v225
	v_mul_f32_e32 v178, v111, v178
	v_lshlrev_b32_e32 v141, 16, v142
	s_waitcnt lgkmcnt(0)
; __device__ __forceinline__ unsigned pk2(float lo, float hi) { return pg8::cvt_pk_bf16(lo, hi); }
; template <bool DO_SWA, bool DO_MEM>
; __device__ __forceinline__ void attn_unit(const Args& a, unsigned char* ws, LAS unsigned char* lds, int l, int tid_in, int lane_in, int wave, int unit) {
;     ...
;             for (int i = 0; i < 4; ++i) {
;                 float ua[8], ub_[8], uc[8], cbv[8], cy[8];
;                 unpack8(cu[i], ua); unpack8(cu[i + 1], ub_); unpack8(cu[i + 2], uc); unpack8(ccb[i], cbv);
;                 float ss = 0.f;
; #pragma unroll
;                 for (int j = 0; j < 8; ++j) { const float y = ua[j] * w0[j] + ub_[j] * w1[j] + uc[j] * w2[j]; cy[j] = cbv[j] * y; ss += cy[j] * cy[j]; }
;                 ss += __shfl_xor(ss, 1); ss += __shfl_xor(ss, 2); ss += __shfl_xor(ss, 4); ss += __shfl_xor(ss, 8); ss += __shfl_xor(ss, 16);
;                 const float rs = 1.0f / sqrtf(ss * (1.0f / 256.0f) + EPS);
;                 v4u o; o.x = pk2(cy[0] * rs, cy[1] * rs); o.y = pk2(cy[2] * rs, cy[3] * rs); o.z = pk2(cy[4] * rs, cy[5] * rs); o.w = pk2(cy[6] * rs, cy[7] * rs);
;                 *(v4u*)(MIX + (size_t)(row0 + t0 + i) * D + 512 + ch) = o;
	v_add_f32_e32 v109, v246, v109
	ds_bpermute_b32 v111, v230, v109
	v_pk_mul_f32 v[224:225], v[172:173], v[140:141]
	v_lshlrev_b32_e32 v159, 2, v159
	v_fma_f32 v140, v100, v171, v224
	v_add_f32_e32 v140, v140, v225
	s_waitcnt lgkmcnt(0)
	v_add_f32_e32 v109, v109, v111
	ds_bpermute_b32 v195, v229, v109
	v_and_b32_e32 v111, 0xffff0000, v142
	v_pk_mul_f32 v[224:225], v[168:169], v[110:111]
	s_mov_b32 s4, 0xf800000
	v_fma_f32 v142, v101, v167, v224
	s_waitcnt lgkmcnt(0)
	v_add_f32_e32 v109, v109, v195
	ds_bpermute_b32 v110, v159, v109
	v_lshlrev_b32_e32 v195, 16, v143
	v_add_f32_e32 v142, v142, v225
	v_pk_mul_f32 v[224:225], v[164:165], v[194:195]
	v_mul_f32_e32 v140, v140, v198
	s_waitcnt lgkmcnt(0)
	v_add_f32_e32 v109, v109, v110
	ds_bpermute_b32 v110, v212, v109
	v_mul_f32_e32 v198, v142, v220
	v_fma_f32 v142, v102, v163, v224
	v_add_f32_e32 v142, v142, v225
	v_mul_f32_e32 v190, v142, v190
	s_waitcnt lgkmcnt(0)
	v_add_f32_e32 v109, v109, v110
	v_fmamk_f32 v109, v109, 0x3b800000, v218
	v_mul_f32_e32 v110, 0x4f800000, v109
	v_cmp_gt_f32_e32 vcc, s4, v109
	v_mul_f32_e32 v206, v162, v162
	v_fmac_f32_e32 v206, v161, v161
	v_cndmask_b32_e32 v110, v109, v110, vcc
	v_sqrt_f32_e32 v194, v110
	v_and_b32_e32 v109, 0xffff0000, v143
	v_fmac_f32_e32 v206, v170, v170
	v_fmac_f32_e32 v206, v178, v178
	v_add_u32_e32 v142, -1, v194
	v_fma_f32 v143, -v142, v194, v110
	v_cmp_ge_f32_e64 s[0:1], 0, v143
	v_add_u32_e32 v143, 1, v194
	v_fmac_f32_e32 v206, v140, v140
	v_cndmask_b32_e64 v142, v194, v142, s[0:1]
	v_fma_f32 v194, -v143, v194, v110
	v_cmp_lt_f32_e64 s[0:1], 0, v194
	v_fmac_f32_e32 v206, v198, v198
	v_fmac_f32_e32 v206, v190, v190
	v_cndmask_b32_e64 v142, v142, v143, s[0:1]
	v_mul_f32_e32 v143, 0x37800000, v142
	v_cndmask_b32_e32 v142, v142, v143, vcc
	v_cmp_class_f32_e32 vcc, v110, v219
	s_movk_i32 s5, 0x190
	s_nop 0
	v_cndmask_b32_e32 v110, v142, v110, vcc
	v_pk_mul_f32 v[142:143], v[146:147], v[108:109]
	v_div_scale_f32 v194, s[0:1], v110, v110, 1.0
	v_fma_f32 v108, v103, v145, v142
	v_add_f32_e32 v108, v108, v143
	v_mul_f32_e32 v108, v108, v191
	v_fmac_f32_e32 v206, v108, v108
	ds_bpermute_b32 v191, v231, v206
	v_rcp_f32_e32 v220, v194
	v_lshl_add_u64 v[142:143], s[20:21], 0, v[244:245]
	v_lshl_add_u64 v[142:143], v[142:143], 0, v[184:185]
	s_waitcnt lgkmcnt(0)
	v_add_f32_e32 v191, v206, v191
	ds_bpermute_b32 v206, v230, v191
	v_fma_f32 v224, -v194, v220, 1.0
	v_fmac_f32_e32 v220, v224, v220
	v_div_scale_f32 v224, vcc, 1.0, v110, 1.0
	s_waitcnt lgkmcnt(0)
	v_add_f32_e32 v191, v191, v206
	ds_bpermute_b32 v206, v229, v191
	v_mul_f32_e32 v225, v224, v220
	v_fma_f32 v232, -v194, v225, v224
	v_fmac_f32_e32 v225, v232, v220
	v_fma_f32 v194, -v194, v225, v224
	s_waitcnt lgkmcnt(0)
	v_add_f32_e32 v191, v191, v206
	ds_bpermute_b32 v206, v159, v191
	v_div_fmas_f32 v194, v194, v220, v225
	v_div_fixup_f32 v110, v194, v110, 1.0
	v_mul_f32_e32 v194, v226, v110
	v_mul_f32_e32 v208, v208, v110
	s_waitcnt lgkmcnt(0)
	v_add_f32_e32 v191, v191, v206
	v_cvt_pk_bf16_f32 v232, v194, v208
	ds_bpermute_b32 v194, v212, v191
	v_mul_f32_e32 v204, v204, v110
	v_mul_f32_e32 v206, v233, v110
	v_cvt_pk_bf16_f32 v233, v206, v204
	v_mul_f32_e32 v204, v223, v110
	s_waitcnt lgkmcnt(0)
	v_add_f32_e32 v191, v191, v194
	v_fmamk_f32 v191, v191, 0x3b800000, v218
	v_mul_f32_e32 v194, 0x4f800000, v191
	v_cmp_gt_f32_e32 vcc, s4, v191
	v_mul_f32_e32 v202, v202, v110
	v_cvt_pk_bf16_f32 v234, v202, v204
	v_mul_f32_e32 v202, v235, v110
	v_cndmask_b32_e32 v191, v191, v194, vcc
	v_sqrt_f32_e32 v194, v191
	v_mul_f32_e32 v110, v217, v110
	v_cvt_pk_bf16_f32 v235, v202, v110
	global_store_dwordx4 v[142:143], v[232:235], off offset:1024
	v_add_u32_e32 v204, -1, v194
	v_fma_f32 v206, -v204, v194, v191
	v_cmp_ge_f32_e64 s[0:1], 0, v206
	v_add_u32_e32 v206, 1, v194
	v_and_b32_e32 v202, 0xffff0000, v135
	v_cndmask_b32_e64 v204, v194, v204, s[0:1]
	v_fma_f32 v194, -v206, v194, v191
	v_cmp_lt_f32_e64 s[0:1], 0, v194
	s_nop 1
	v_cndmask_b32_e64 v194, v204, v206, s[0:1]
	v_mul_f32_e32 v204, 0x37800000, v194
	v_cndmask_b32_e32 v194, v194, v204, vcc
	v_cmp_class_f32_e32 vcc, v191, v219
	s_nop 1
	v_cndmask_b32_e32 v191, v194, v191, vcc
	v_div_scale_f32 v194, s[0:1], v191, v191, 1.0
	v_rcp_f32_e32 v204, v194
	s_nop 0
	v_fma_f32 v110, -v194, v204, 1.0
	v_fmac_f32_e32 v204, v110, v204
	v_div_scale_f32 v110, vcc, 1.0, v191, 1.0
	v_mul_f32_e32 v142, v110, v204
	v_fma_f32 v143, -v194, v142, v110
	v_fmac_f32_e32 v142, v143, v204
	v_fma_f32 v110, -v194, v142, v110
	v_div_fmas_f32 v110, v110, v204, v142
	v_div_fixup_f32 v110, v110, v191, 1.0
	v_mul_f32_e32 v142, v161, v110
	v_mul_f32_e32 v143, v162, v110
	v_cvt_pk_bf16_f32 v232, v142, v143
	v_mul_f32_e32 v142, v170, v110
	v_mul_f32_e32 v140, v140, v110
	v_mul_f32_e32 v143, v178, v110
	v_cvt_pk_bf16_f32 v233, v142, v143
	v_mul_f32_e32 v142, v198, v110
	v_cvt_pk_bf16_f32 v234, v140, v142
	v_mul_f32_e32 v140, v190, v110
	v_lshlrev_b32_e32 v162, 16, v132
	v_and_b32_e32 v170, 0xffff0000, v132
	v_lshlrev_b32_e32 v178, 16, v133
	v_and_b32_e32 v190, 0xffff0000, v133
	v_lshlrev_b32_e32 v198, 16, v135
	v_lshlrev_b32_e32 v132, 16, v124
	v_lshlrev_b32_e32 v133, 16, v128
	v_lshlrev_b32_e32 v191, 16, v134
	v_and_b32_e32 v194, 0xffff0000, v134
	v_pk_mov_b32 v[134:135], v[198:199], v[132:133] op_sel:[1,0]
	v_mul_f32_e32 v108, v108, v110
	v_pk_mul_f32 v[134:135], v[200:201], v[134:135]
	v_cvt_pk_bf16_f32 v235, v140, v108
	v_lshlrev_b32_e32 v108, 16, v136
	v_fma_f32 v134, v116, v209, v134
	v_add_f32_e32 v134, v134, v135
	v_mul_f32_e32 v108, v134, v108
	v_mov_b32_e32 v134, v116
	v_mov_b32_e32 v135, v120
	v_pk_mul_f32 v[132:133], v[134:135], v[132:133]
	v_mov_b32_e32 v120, v117
; __device__ __forceinline__ unsigned pk2(float lo, float hi) { return pg8::cvt_pk_bf16(lo, hi); }
; template <bool DO_SWA, bool DO_MEM>
; __device__ __forceinline__ void attn_unit(const Args& a, unsigned char* ws, LAS unsigned char* lds, int l, int tid_in, int lane_in, int wave, int unit) {
;     ...
;             for (int i = 0; i < 4; ++i) {
;                 float ua[8], ub_[8], uc[8], cbv[8], cy[8];
;                 unpack8(cu[i], ua); unpack8(cu[i + 1], ub_); unpack8(cu[i + 2], uc); unpack8(ccb[i], cbv);
;                 float ss = 0.f;
; #pragma unroll
;                 for (int j = 0; j < 8; ++j) { const float y = ua[j] * w0[j] + ub_[j] * w1[j] + uc[j] * w2[j]; cy[j] = cbv[j] * y; ss += cy[j] * cy[j]; }
;                 ss += __shfl_xor(ss, 1); ss += __shfl_xor(ss, 2); ss += __shfl_xor(ss, 4); ss += __shfl_xor(ss, 8); ss += __shfl_xor(ss, 16);
;                 const float rs = 1.0f / sqrtf(ss * (1.0f / 256.0f) + EPS);
;                 v4u o; o.x = pk2(cy[0] * rs, cy[1] * rs); o.y = pk2(cy[2] * rs, cy[3] * rs); o.z = pk2(cy[4] * rs, cy[5] * rs); o.w = pk2(cy[6] * rs, cy[7] * rs);
;                 *(v4u*)(MIX + (size_t)(row0 + t0 + i) * D + 512 + ch) = o;
	v_fma_f32 v112, v112, v209, v132
	v_add_f32_e32 v112, v112, v133
	v_and_b32_e32 v133, 0xffff0000, v128
	v_and_b32_e32 v132, 0xffff0000, v124
	v_pk_mov_b32 v[134:135], v[182:183], v[132:133] op_sel:[1,0]
	v_mul_f32_e32 v162, v112, v162
	v_pk_mul_f32 v[134:135], v[196:197], v[134:135]
	v_and_b32_e32 v110, 0xffff0000, v136
	v_fma_f32 v112, v117, v207, v134
	v_add_f32_e32 v112, v112, v135
	v_pk_mul_f32 v[116:117], v[120:121], v[132:133]
	v_mul_f32_e32 v110, v112, v110
	v_fma_f32 v112, v113, v207, v116
	v_add_f32_e32 v112, v112, v117
	v_mul_f32_e32 v128, v112, v170
	v_lshlrev_b32_e32 v112, 16, v125
	v_lshlrev_b32_e32 v113, 16, v129
	v_pk_mov_b32 v[116:117], v[178:179], v[112:113] op_sel:[1,0]
	v_lshlrev_b32_e32 v140, 16, v137
	v_pk_mul_f32 v[116:117], v[180:181], v[116:117]
	v_or_b32_e32 v142, 1, v160
	v_fma_f32 v116, v118, v205, v116
	v_add_f32_e32 v116, v116, v117
	v_mul_f32_e32 v133, v116, v140
	v_mov_b32_e32 v116, v118
	v_mov_b32_e32 v117, v122
	v_pk_mul_f32 v[112:113], v[116:117], v[112:113]
	v_ashrrev_i32_e32 v143, 31, v142
	v_fma_f32 v112, v114, v205, v112
	v_add_f32_e32 v112, v112, v113
	v_mul_f32_e32 v134, v112, v178
	v_and_b32_e32 v113, 0xffff0000, v129
	v_and_b32_e32 v112, 0xffff0000, v125
	v_lshlrev_b64 v[142:143], 11, v[142:143]
	v_pk_mov_b32 v[116:117], v[174:175], v[112:113] op_sel:[1,0]
	v_lshl_add_u64 v[142:143], s[20:21], 0, v[142:143]
	v_pk_mul_f32 v[116:117], v[176:177], v[116:117]
	v_lshl_add_u64 v[142:143], v[142:143], 0, v[184:185]
	v_fma_f32 v114, v119, v203, v116
	v_mov_b32_e32 v122, v119
	global_store_dwordx4 v[142:143], v[232:235], off offset:1024
	v_and_b32_e32 v142, 0xffff0000, v137
	v_add_f32_e32 v114, v114, v117
	v_pk_mul_f32 v[112:113], v[122:123], v[112:113]
	v_mul_f32_e32 v125, v114, v142
	v_fma_f32 v112, v115, v203, v112
	v_lshlrev_b32_e32 v114, 16, v126
	v_lshlrev_b32_e32 v115, 16, v130
	v_pk_mov_b32 v[116:117], v[170:171], v[114:115] op_sel:[1,0]
	v_lshlrev_b32_e32 v143, 16, v138
	v_pk_mul_f32 v[116:117], v[172:173], v[116:117]
	v_and_b32_e32 v138, 0xffff0000, v138
	v_fma_f32 v116, v100, v141, v116
	v_add_f32_e32 v116, v116, v117
	v_mul_f32_e32 v129, v116, v143
	v_and_b32_e32 v117, 0xffff0000, v130
	v_and_b32_e32 v116, 0xffff0000, v126
	v_pk_mov_b32 v[118:119], v[166:167], v[116:117] op_sel:[1,0]
	v_lshlrev_b32_e32 v161, 16, v139
	v_pk_mul_f32 v[118:119], v[168:169], v[118:119]
	v_mul_f32_e32 v124, v110, v110
	v_fma_f32 v118, v101, v111, v118
	v_add_f32_e32 v118, v118, v119
	v_mul_f32_e32 v126, v118, v138
	v_lshlrev_b32_e32 v118, 16, v127
	v_lshlrev_b32_e32 v119, 16, v131
	v_pk_mov_b32 v[120:121], v[162:163], v[118:119] op_sel:[1,0]
	v_fmac_f32_e32 v124, v108, v108
	v_pk_mul_f32 v[120:121], v[164:165], v[120:121]
	v_fmac_f32_e32 v124, v133, v133
	v_fma_f32 v120, v102, v195, v120
	v_add_f32_e32 v120, v120, v121
	v_mul_f32_e32 v130, v120, v161
	v_and_b32_e32 v121, 0xffff0000, v131
	v_and_b32_e32 v120, 0xffff0000, v127
	v_pk_mov_b32 v[122:123], v[144:145], v[120:121] op_sel:[1,0]
	v_fmac_f32_e32 v124, v125, v125
	v_pk_mul_f32 v[122:123], v[146:147], v[122:123]
	v_fmac_f32_e32 v124, v129, v129
	v_fma_f32 v122, v103, v109, v122
	v_and_b32_e32 v139, 0xffff0000, v139
	v_fmac_f32_e32 v124, v126, v126
	v_add_f32_e32 v122, v122, v123
	v_fmac_f32_e32 v124, v130, v130
	v_mul_f32_e32 v122, v122, v139
	v_fmac_f32_e32 v124, v122, v122
	ds_bpermute_b32 v123, v231, v124
	v_add_f32_e32 v112, v112, v113
	v_mul_f32_e32 v127, v112, v190
	v_mov_b32_e32 v112, v100
	v_mov_b32_e32 v113, v104
	s_waitcnt lgkmcnt(0)
	v_add_f32_e32 v100, v124, v123
	ds_bpermute_b32 v123, v230, v100
	v_pk_mul_f32 v[112:113], v[112:113], v[114:115]
	v_mov_b32_e32 v104, v101
	v_fma_f32 v96, v96, v141, v112
	v_add_f32_e32 v96, v96, v113
	s_waitcnt lgkmcnt(0)
	v_add_f32_e32 v112, v100, v123
	ds_bpermute_b32 v113, v229, v112
	v_mul_f32_e32 v114, v96, v191
	v_pk_mul_f32 v[100:101], v[104:105], v[116:117]
	v_mul_f32_e32 v132, v128, v128
	v_fma_f32 v97, v97, v111, v100
	s_waitcnt lgkmcnt(0)
	v_add_f32_e32 v96, v112, v113
	ds_bpermute_b32 v104, v159, v96
	v_add_f32_e32 v97, v97, v101
	v_mul_f32_e32 v105, v97, v194
	v_mov_b32_e32 v97, v106
	v_fmac_f32_e32 v132, v162, v162
	s_waitcnt lgkmcnt(0)
	v_add_f32_e32 v100, v96, v104
	ds_bpermute_b32 v101, v212, v100
	v_mov_b32_e32 v96, v102
	v_pk_mul_f32 v[96:97], v[96:97], v[118:119]
	v_fmac_f32_e32 v132, v134, v134
	v_fma_f32 v96, v98, v195, v96
	s_waitcnt lgkmcnt(0)
	v_add_f32_e32 v98, v100, v101
	v_fmamk_f32 v98, v98, 0x3b800000, v218
	v_mul_f32_e32 v100, 0x4f800000, v98
	v_cmp_gt_f32_e32 vcc, s4, v98
	v_add_f32_e32 v96, v96, v97
	v_mul_f32_e32 v102, v96, v198
	v_cndmask_b32_e32 v98, v98, v100, vcc
	v_sqrt_f32_e32 v100, v98
	v_mov_b32_e32 v106, v103
	v_fmac_f32_e32 v132, v127, v127
	v_fmac_f32_e32 v132, v114, v114
	v_add_u32_e32 v96, -1, v100
	v_fma_f32 v97, -v96, v100, v98
	v_cmp_ge_f32_e64 s[0:1], 0, v97
	v_add_u32_e32 v97, 1, v100
	v_fmac_f32_e32 v132, v105, v105
	v_cndmask_b32_e64 v96, v100, v96, s[0:1]
	v_fma_f32 v100, -v97, v100, v98
	v_cmp_lt_f32_e64 s[0:1], 0, v100
	v_fmac_f32_e32 v132, v102, v102
	v_or_b32_e32 v136, 2, v160
	v_cndmask_b32_e64 v96, v96, v97, s[0:1]
	v_mul_f32_e32 v97, 0x37800000, v96
	v_cndmask_b32_e32 v96, v96, v97, vcc
	v_cmp_class_f32_e32 vcc, v98, v219
	v_ashrrev_i32_e32 v137, 31, v136
	v_lshlrev_b64 v[136:137], 11, v[136:137]
	v_cndmask_b32_e32 v98, v96, v98, vcc
	v_pk_mul_f32 v[96:97], v[106:107], v[120:121]
	v_div_scale_f32 v104, s[0:1], v98, v98, 1.0
	v_fma_f32 v96, v99, v109, v96
	v_add_f32_e32 v96, v96, v97
	v_mul_f32_e32 v103, v96, v202
	v_fmac_f32_e32 v132, v103, v103
	v_rcp_f32_e32 v111, v104
	ds_bpermute_b32 v99, v231, v132
	v_lshl_add_u64 v[96:97], s[20:21], 0, v[136:137]
	v_lshl_add_u64 v[100:101], v[96:97], 0, v[184:185]
	v_fma_f32 v96, -v104, v111, 1.0
	v_fmac_f32_e32 v111, v96, v111
	s_waitcnt lgkmcnt(0)
; #define LAS __attribute__((address_space(3)))
; #define LAS __attribute__((address_space(3)))
; __device__ __forceinline__ f32x4 mfma16(bf16x8 a, bf16x8 b, f32x4 c) { return __builtin_amdgcn_mfma_f32_16x16x32_bf16(a, b, c, 0, 0, 0); }
; template <int NKT, int VSTR, bool SINK>
; __device__ __forceinline__ void attn_core(LAS const unsigned char* kb_, LAS const unsigned char* vb_, bf16x8 q0, bf16x8 q1, float sk, unsigned mskbits, int fr, f32x4 (&o)[4]) {
;     ...
; #pragma unroll
;     for (int kt = 0; kt < NKT; ++kt) {
;         const int key = (kt >> 1) * 32 + ((kt & 1) << 2) + krow;
;         LAS const unsigned char* kp = kb_ + key * 144;
;         const bf16x8 a0 = *(LAS const bf16x8*)kp, a1 = *(LAS const bf16x8*)(kp + 64);
;         const float bias = ((mskbits >> (kt >> 2)) & 1u) ? -1e30f : 0.f;
;         f32x4 s = mfma16(a0, q0, (f32x4){bias, bias, bias, bias});
; template <bool DO_SWA, bool DO_MEM>
; __device__ __forceinline__ void attn_unit(const Args& a, unsigned char* ws, LAS unsigned char* lds, int l, int tid_in, int lane_in, int wave, int unit) {
;     ...
;         if constexpr (DO_SWA)
; #pragma unroll
;         for (int i = 0; i < 6; ++i) {
;             const int s = i >> 1, rem = tid + 512 * (i & 1);
;             { const int key = rem >> 4, c16 = rem & 15; *(LAS v4u*)(lds + A_KS + ((c16 >> 3) * 192 + s * 64 + key) * 144 + (c16 & 7) * 16) = kst[i]; }
;             { const int col = rem >> 3, kc = rem & 7; *(LAS v4u*)(lds + A_VT1 + col * 400 + (s * 64 + kc * 8) * 2) = vst[i]; }
;         }
;         const bf16* MKb = (const bf16*)(ws + WS_MK) + (size_t)(l * 40 + bb) * 65536;
;         const bf16* MVTb = (const bf16*)(ws + WS_MVT) + (size_t)(l * 40 + bb) * 65536;
;         v4u mkst[8], mvst[8];
;         __builtin_amdgcn_sched_barrier(0);
;         __syncthreads();
;         v2u osv[4][4];
;         if constexpr (DO_SWA) {
;             float ssq = 0.f;
; #pragma unroll
;             for (int hh = 0; hh < 4; ++hh) {
;                 const int h = g * 4 + hh;
;                 const float sk = a.in[12][l * 8 + h] * LOG2E;
;                 f32x4 o[4];
;                 attn_core<12, 400, true>(lds + A_KS + g * 192 * 144 + fq * 16, lds + A_VT1 + (g * 64 + fr) * 400 + fq * 16, qsw[hh][0], qsw[hh][1], sk, mskbits, fr, o);
	v_add_f32_e32 v96, v132, v99
	ds_bpermute_b32 v97, v230, v96
	v_div_scale_f32 v99, vcc, 1.0, v98, 1.0
	v_mul_f32_e32 v106, v99, v111
	v_fma_f32 v107, -v104, v106, v99
	s_waitcnt lgkmcnt(0)
	v_add_f32_e32 v96, v96, v97
	ds_bpermute_b32 v97, v229, v96
	v_fmac_f32_e32 v106, v107, v111
	v_fma_f32 v99, -v104, v106, v99
	v_div_fmas_f32 v99, v99, v111, v106
	v_div_fixup_f32 v99, v99, v98, 1.0
	s_waitcnt lgkmcnt(0)
	v_add_f32_e32 v97, v96, v97
	ds_bpermute_b32 v104, v159, v97
	v_mul_f32_e32 v96, v108, v99
	v_mul_f32_e32 v98, v110, v99
	v_cvt_pk_bf16_f32 v96, v96, v98
	v_mul_f32_e32 v106, v125, v99
	s_waitcnt lgkmcnt(0)
	v_add_f32_e32 v98, v97, v104
	ds_bpermute_b32 v104, v212, v98
	v_mul_f32_e32 v97, v133, v99
	v_cvt_pk_bf16_f32 v97, v97, v106
	v_mul_f32_e32 v106, v129, v99
	s_waitcnt lgkmcnt(0)
	v_add_f32_e32 v98, v98, v104
	v_fmamk_f32 v98, v98, 0x3b800000, v218
	v_mul_f32_e32 v104, 0x4f800000, v98
	v_cmp_gt_f32_e32 vcc, s4, v98
	s_movk_i32 s4, 0x90
	s_nop 0
	v_cndmask_b32_e32 v104, v98, v104, vcc
	v_sqrt_f32_e32 v107, v104
	v_mul_f32_e32 v98, v126, v99
	v_cvt_pk_bf16_f32 v98, v106, v98
	v_mul_f32_e32 v106, v130, v99
	v_add_u32_e32 v108, -1, v107
	v_fma_f32 v109, -v108, v107, v104
	v_cmp_ge_f32_e64 s[0:1], 0, v109
	v_add_u32_e32 v109, 1, v107
	v_mul_f32_e32 v99, v122, v99
	v_cndmask_b32_e64 v108, v107, v108, s[0:1]
	v_fma_f32 v107, -v109, v107, v104
	v_cmp_lt_f32_e64 s[0:1], 0, v107
	v_cvt_pk_bf16_f32 v99, v106, v99
	global_store_dwordx4 v[100:101], v[96:99], off offset:1024
	s_nop 0
	v_cndmask_b32_e64 v107, v108, v109, s[0:1]
	v_mul_f32_e32 v108, 0x37800000, v107
	v_cndmask_b32_e32 v107, v107, v108, vcc
	v_cmp_class_f32_e32 vcc, v104, v219
	s_nop 1
	v_cndmask_b32_e32 v104, v107, v104, vcc
	v_div_scale_f32 v107, s[0:1], v104, v104, 1.0
	v_rcp_f32_e32 v108, v107
	s_nop 0
	v_fma_f32 v96, -v107, v108, 1.0
	v_fmac_f32_e32 v108, v96, v108
	v_div_scale_f32 v96, vcc, 1.0, v104, 1.0
	v_mul_f32_e32 v97, v96, v108
	v_fma_f32 v98, -v107, v97, v96
	v_fmac_f32_e32 v97, v98, v108
	v_fma_f32 v96, -v107, v97, v96
	v_div_fmas_f32 v96, v96, v108, v97
	v_div_fixup_f32 v99, v96, v104, 1.0
	v_mul_f32_e32 v96, v162, v99
	v_mul_f32_e32 v97, v128, v99
	v_cvt_pk_bf16_f32 v96, v96, v97
	v_mul_f32_e32 v97, v134, v99
	v_mul_f32_e32 v98, v127, v99
	v_cvt_pk_bf16_f32 v97, v97, v98
	v_mul_f32_e32 v98, v114, v99
	v_mul_f32_e32 v100, v105, v99
	v_cvt_pk_bf16_f32 v98, v98, v100
	v_mul_f32_e32 v100, v102, v99
	v_mul_f32_e32 v99, v103, v99
	v_cvt_pk_bf16_f32 v99, v100, v99
	v_or_b32_e32 v100, 3, v160
	v_ashrrev_i32_e32 v101, 31, v100
	v_lshlrev_b64 v[100:101], 11, v[100:101]
	v_lshl_add_u64 v[100:101], s[20:21], 0, v[100:101]
	v_lshl_add_u64 v[100:101], v[100:101], 0, v[184:185]
	global_store_dwordx4 v[100:101], v[96:99], off offset:1024
	v_lshlrev_b32_e32 v104, 4, v213
	s_nop 0
	v_bfe_i32 v96, v213, 3, 1
	v_and_b32_e32 v98, 0xc0, v96
	v_and_b32_e32 v96, 0x70, v104
	v_add_u32_e32 v100, 0, v96
	v_add_u32_e32 v96, v98, v148
	v_mad_u64_u32 v[96:97], s[0:1], v96, s4, v[100:101]
	ds_write_b128 v96, v[28:31]
	v_mul_lo_u32 v28, v157, s5
	v_add3_u32 v28, 0, v28, v158
	ds_write_b128 v28, v[24:27] offset:55296
	v_add_u32_e32 v24, v98, v152
	v_mad_u64_u32 v[24:25], s[0:1], v24, s4, v[100:101]
	ds_write_b128 v24, v[60:63]
	v_mul_lo_u32 v24, v227, s5
	v_add_u32_e32 v27, 64, v98
	v_add3_u32 v26, 0, v24, v158
	v_add_u32_e32 v24, v27, v148
	v_mad_u64_u32 v[24:25], s[0:1], v24, s4, v[100:101]
	ds_write_b128 v26, v[56:59] offset:55296
	ds_write_b128 v24, v[68:71]
	ds_write_b128 v28, v[64:67] offset:55424
	v_add_u32_e32 v24, v27, v152
	v_mad_u64_u32 v[24:25], s[0:1], v24, s4, v[100:101]
	v_add_u32_e32 v27, 0x80, v98
	ds_write_b128 v24, v[72:75]
	ds_write_b128 v26, v[76:79] offset:55424
	v_add_u32_e32 v24, v27, v148
	v_mad_u64_u32 v[24:25], s[0:1], v24, s4, v[100:101]
	ds_write_b128 v24, v[80:83]
	ds_write_b128 v28, v[84:87] offset:55552
	v_add_u32_e32 v24, v27, v152
	v_mad_u64_u32 v[24:25], s[0:1], v24, s4, v[100:101]
	ds_write_b128 v24, v[88:91]
	ds_write_b128 v26, v[92:95] offset:55552
	v_readlane_b32 s0, v251, 22
	v_and_b32_e32 v101, -16, v210
	v_and_b32_e32 v25, 3, v210
	v_or_b32_e32 v102, s0, v228
	v_mul_lo_u32 v24, v102, s5
	v_add3_u32 v106, 0, v24, v101
	v_lshlrev_b32_e32 v24, 1, v228
	v_and_or_b32 v24, v24, 24, v25
	v_xor_b32_e32 v56, 32, v222
	v_mul_u32_u24_e32 v103, 0x90, v24
	v_readlane_b32 s0, v251, 24
	v_cmp_lt_i32_e32 vcc, v56, v151
	s_waitcnt lgkmcnt(0)
	v_add3_u32 v107, s0, v101, v103
	v_cndmask_b32_e32 v56, v222, v56, vcc
	s_barrier
	v_lshlrev_b32_e32 v176, 2, v56
	v_mov_b32_e32 v108, s98
	s_waitcnt lgkmcnt(0)
	ds_read_b128 v[120:123], v107
	ds_read_b128 v[124:127], v107 offset:64
	ds_read_b128 v[128:131], v107 offset:576
	ds_read_b128 v[132:135], v107 offset:640
	ds_read_b128 v[136:139], v107 offset:4608
	ds_read_b128 v[140:143], v107 offset:4672
	ds_read_b128 v[144:147], v107 offset:5184
	ds_read_b128 v[160:163], v107 offset:5248
	ds_read_b128 v[164:167], v107 offset:9216
	ds_read_b128 v[168:171], v107 offset:9280
	ds_read_b128 v[172:175], v107 offset:9792
	ds_read_b128 v[180:183], v107 offset:9856
	ds_read_b128 v[196:199], v107 offset:13824
	ds_read_b128 v[200:203], v107 offset:13888
	v_mov_b32_e32 v24, 0xf149f2ca
	v_cndmask_b32_e64 v28, v24, 0, s[2:3]
	v_mov_b32_e32 v29, v28
	v_mov_b32_e32 v30, v28
	v_mov_b32_e32 v31, v28
	v_cndmask_b32_e64 v24, 0, v24, s[36:37]
	v_mov_b32_e32 v25, v24
	s_waitcnt lgkmcnt(13)
	v_mfma_f32_16x16x32_bf16 v[56:59], v[120:123], v[48:51], v[28:31]
	v_mov_b32_e32 v26, v24
	v_mov_b32_e32 v27, v24
	s_mov_b32 s2, 0x3fb8aa3b
	s_waitcnt lgkmcnt(12)
	v_mfma_f32_16x16x32_bf16 v[96:99], v[124:127], v[52:55], v[56:59]
	ds_read_b128 v[204:207], v107 offset:14400
	ds_read_b128 v[224:227], v107 offset:14464
	v_add_u32_e32 v105, 0xd800, v106
	v_cmp_gt_u32_e64 s[36:37], 16, v210
	s_waitcnt lgkmcnt(13)
	v_mfma_f32_16x16x32_bf16 v[56:59], v[128:131], v[48:51], v[28:31]

; #define LAS __attribute__((address_space(3)))
; #define LAS __attribute__((address_space(3)))
; __device__ __forceinline__ f32x4 mfma16(bf16x8 a, bf16x8 b, f32x4 c) { return __builtin_amdgcn_mfma_f32_16x16x32_bf16(a, b, c, 0, 0, 0); }
; template <int NKT, int VSTR, bool SINK>
; __device__ __forceinline__ void attn_core(LAS const unsigned char* kb_, LAS const unsigned char* vb_, bf16x8 q0, bf16x8 q1, float sk, unsigned mskbits, int fr, f32x4 (&o)[4]) {
;     ...
; #pragma unroll
;     for (int kt = 0; kt < NKT; ++kt) {
;         const int key = (kt >> 1) * 32 + ((kt & 1) << 2) + krow;
;         LAS const unsigned char* kp = kb_ + key * 144;
;         const bf16x8 a0 = *(LAS const bf16x8*)kp, a1 = *(LAS const bf16x8*)(kp + 64);
;         const float bias = ((mskbits >> (kt >> 2)) & 1u) ? -1e30f : 0.f;
;         f32x4 s = mfma16(a0, q0, (f32x4){bias, bias, bias, bias});
;         s = mfma16(a1, q1, s);
;         S[kt] = s;
;     }
;     float mx = S[0][0];
; #pragma unroll
;     for (int kt = 0; kt < NKT; ++kt) mx = fmaxf(fmaxf(mx, fmaxf(S[kt][0], S[kt][1])), fmaxf(S[kt][2], S[kt][3]));
;     mx = fmaxf(mx, __shfl_xor(mx, 16)); mx = fmaxf(mx, __shfl_xor(mx, 32));
;     if (SINK) mx = fmaxf(mx, sk);
;     float sum = 0.f;
; #pragma unroll
;     for (int kt = 0; kt < NKT; ++kt)
; #pragma unroll
;         for (int r = 0; r < 4; ++r) { const float p = __builtin_amdgcn_exp2f(S[kt][r] - mx); S[kt][r] = p; sum += p; }
;     sum += __shfl_xor(sum, 16); sum += __shfl_xor(sum, 32);
;     if (SINK) sum += __builtin_amdgcn_exp2f(sk - mx);
	v_mul_f32_e32 v109, 0x3fb8aa3b, v108
	s_waitcnt lgkmcnt(12)
	v_mfma_f32_16x16x32_bf16 v[92:95], v[132:135], v[52:55], v[56:59]
	ds_read_b128 v[232:235], v107 offset:18432
	ds_read_b128 v[236:239], v107 offset:18496
	s_waitcnt lgkmcnt(13)
	v_mfma_f32_16x16x32_bf16 v[56:59], v[136:139], v[48:51], v[28:31]
	s_waitcnt lgkmcnt(12)
	v_mfma_f32_16x16x32_bf16 v[88:91], v[140:143], v[52:55], v[56:59]
	ds_read_b128 v[240:243], v107 offset:19008
	ds_read_b128 v[244:247], v107 offset:19072
	s_waitcnt lgkmcnt(13)
	v_mfma_f32_16x16x32_bf16 v[56:59], v[144:147], v[48:51], v[28:31]
	s_waitcnt lgkmcnt(12)
	v_mfma_f32_16x16x32_bf16 v[84:87], v[160:163], v[52:55], v[56:59]
	ds_read_b128 v[120:123], v107 offset:23040
	ds_read_b128 v[124:127], v107 offset:23104
	s_waitcnt lgkmcnt(13)
	v_mfma_f32_16x16x32_bf16 v[56:59], v[164:167], v[48:51], v[24:27]
	s_waitcnt lgkmcnt(12)
	v_mfma_f32_16x16x32_bf16 v[80:83], v[168:171], v[52:55], v[56:59]
	ds_read_b128 v[128:131], v107 offset:23616
	ds_read_b128 v[132:135], v107 offset:23680
	s_waitcnt lgkmcnt(13)
	v_mfma_f32_16x16x32_bf16 v[56:59], v[172:175], v[48:51], v[24:27]
	s_waitcnt lgkmcnt(12)
	v_mfma_f32_16x16x32_bf16 v[76:79], v[180:183], v[52:55], v[56:59]
	s_waitcnt lgkmcnt(11)
	v_mfma_f32_16x16x32_bf16 v[56:59], v[196:199], v[48:51], v[24:27]
	s_waitcnt lgkmcnt(10)
	v_mfma_f32_16x16x32_bf16 v[72:75], v[200:203], v[52:55], v[56:59]
	s_waitcnt lgkmcnt(9)
	v_mfma_f32_16x16x32_bf16 v[56:59], v[204:207], v[48:51], v[24:27]
	s_waitcnt lgkmcnt(8)
	v_mfma_f32_16x16x32_bf16 v[68:71], v[224:227], v[52:55], v[56:59]
	s_waitcnt lgkmcnt(7)
	v_mfma_f32_16x16x32_bf16 v[56:59], v[232:235], v[48:51], 0
	s_waitcnt lgkmcnt(6)
	v_mfma_f32_16x16x32_bf16 v[64:67], v[236:239], v[52:55], v[56:59]
	s_waitcnt lgkmcnt(5)
	v_mfma_f32_16x16x32_bf16 v[56:59], v[240:243], v[48:51], 0
	s_waitcnt lgkmcnt(4)
	v_mfma_f32_16x16x32_bf16 v[60:63], v[244:247], v[52:55], v[56:59]
	s_waitcnt lgkmcnt(3)
	v_mfma_f32_16x16x32_bf16 v[56:59], v[120:123], v[48:51], 0
	s_waitcnt lgkmcnt(2)
	v_mfma_f32_16x16x32_bf16 v[56:59], v[124:127], v[52:55], v[56:59]
	s_waitcnt lgkmcnt(1)
	v_mfma_f32_16x16x32_bf16 v[48:51], v[128:131], v[48:51], 0
	s_waitcnt lgkmcnt(0)
	v_mfma_f32_16x16x32_bf16 v[48:51], v[132:135], v[52:55], v[48:51]
	s_nop 0
	s_nop 0
	v_max_f32_e32 v52, v98, v99
	s_nop 0
	s_nop 0
	v_max_f32_e32 v53, v92, v93
	s_nop 0
	s_nop 0
	v_max3_f32 v52, v96, v97, v52
	v_max_f32_e32 v54, v94, v95
	v_max3_f32 v52, v52, v53, v54
	s_nop 0
	s_nop 0
	v_max_f32_e32 v53, v88, v89
	s_nop 0
	s_nop 0
	v_max_f32_e32 v54, v90, v91
	v_max3_f32 v52, v52, v53, v54
	s_nop 0
	s_nop 0
	v_max_f32_e32 v53, v84, v85
	s_nop 0
	s_nop 0
	v_max_f32_e32 v54, v86, v87
	v_max3_f32 v52, v52, v53, v54
	v_max_f32_e32 v53, v80, v81
	v_max_f32_e32 v54, v82, v83
	v_max3_f32 v52, v52, v53, v54
	v_max_f32_e32 v53, v76, v77
	v_max_f32_e32 v54, v78, v79
	v_max3_f32 v52, v52, v53, v54
	v_max_f32_e32 v53, v72, v73
	v_max_f32_e32 v54, v74, v75
	v_max3_f32 v52, v52, v53, v54
	v_max_f32_e32 v53, v68, v69
	v_max_f32_e32 v54, v70, v71
	v_max3_f32 v52, v52, v53, v54
	v_max_f32_e32 v53, v64, v65
	v_max_f32_e32 v54, v66, v67
	v_max3_f32 v52, v52, v53, v54
	v_max_f32_e32 v53, v60, v61
	v_max_f32_e32 v54, v62, v63
	v_max3_f32 v52, v52, v53, v54
	v_max_f32_e32 v53, v56, v57
	v_max_f32_e32 v54, v58, v59
	v_max3_f32 v52, v52, v53, v54
	v_max_f32_e32 v53, v48, v49
	v_max_f32_e32 v54, v50, v51
	v_max3_f32 v52, v52, v53, v54
	ds_bpermute_b32 v53, v212, v52
	s_waitcnt lgkmcnt(0)
	s_nop 0
	v_max_f32_e32 v52, v52, v53
	ds_bpermute_b32 v53, v176, v52
	s_waitcnt lgkmcnt(0)
	v_max3_f32 v52, v52, v53, v109
	v_sub_f32_e32 v53, v96, v52
	v_exp_f32_e32 v53, v53
	v_sub_f32_e32 v55, v97, v52
	v_exp_f32_e32 v55, v55
	v_sub_f32_e32 v96, v98, v52
	v_exp_f32_e32 v96, v96
	v_sub_f32_e32 v97, v99, v52
	v_exp_f32_e32 v97, v97
	v_sub_f32_e32 v92, v92, v52
	v_add_f32_e32 v54, 0, v53
	v_exp_f32_e32 v92, v92
	v_sub_f32_e32 v93, v93, v52
	v_add_f32_e32 v54, v55, v54
	v_exp_f32_e32 v93, v93
	v_sub_f32_e32 v94, v94, v52
	v_add_f32_e32 v54, v96, v54
	v_exp_f32_e32 v94, v94
	v_sub_f32_e32 v95, v95, v52
	v_add_f32_e32 v54, v97, v54
	v_exp_f32_e32 v95, v95
	v_sub_f32_e32 v88, v88, v52
	v_add_f32_e32 v54, v92, v54
	v_exp_f32_e32 v88, v88
	v_sub_f32_e32 v89, v89, v52
	v_add_f32_e32 v54, v93, v54
	v_exp_f32_e32 v89, v89
	v_sub_f32_e32 v90, v90, v52
	v_add_f32_e32 v54, v94, v54
	v_exp_f32_e32 v90, v90
	v_sub_f32_e32 v91, v91, v52
	v_add_f32_e32 v54, v95, v54
	v_exp_f32_e32 v91, v91
	v_sub_f32_e32 v84, v84, v52
	v_add_f32_e32 v54, v88, v54
	v_exp_f32_e32 v84, v84
	v_sub_f32_e32 v85, v85, v52
	v_add_f32_e32 v54, v89, v54
	v_exp_f32_e32 v85, v85
	v_sub_f32_e32 v86, v86, v52
	v_add_f32_e32 v54, v90, v54
	v_exp_f32_e32 v86, v86
	v_sub_f32_e32 v87, v87, v52
	v_add_f32_e32 v54, v91, v54
	v_exp_f32_e32 v87, v87
	v_sub_f32_e32 v80, v80, v52
	v_add_f32_e32 v54, v84, v54
	v_exp_f32_e32 v80, v80
	v_sub_f32_e32 v81, v81, v52
	v_add_f32_e32 v54, v85, v54
	v_exp_f32_e32 v81, v81
	v_sub_f32_e32 v82, v82, v52
	v_add_f32_e32 v54, v86, v54
	v_exp_f32_e32 v82, v82
	v_sub_f32_e32 v83, v83, v52
	v_add_f32_e32 v54, v87, v54
	v_exp_f32_e32 v83, v83
	v_sub_f32_e32 v76, v76, v52
	v_add_f32_e32 v54, v80, v54
	v_exp_f32_e32 v76, v76
	v_sub_f32_e32 v77, v77, v52
	v_add_f32_e32 v54, v81, v54
	v_exp_f32_e32 v77, v77
	v_sub_f32_e32 v78, v78, v52
	v_add_f32_e32 v54, v82, v54
	v_exp_f32_e32 v78, v78
	v_sub_f32_e32 v79, v79, v52
	v_add_f32_e32 v54, v83, v54
	v_exp_f32_e32 v79, v79
	v_sub_f32_e32 v72, v72, v52
	v_add_f32_e32 v54, v76, v54
	v_exp_f32_e32 v72, v72
	v_sub_f32_e32 v73, v73, v52
	v_add_f32_e32 v54, v77, v54
	v_exp_f32_e32 v73, v73
	v_sub_f32_e32 v74, v74, v52
; #define LAS __attribute__((address_space(3)))
; #define LAS __attribute__((address_space(3)))
; __device__ __forceinline__ unsigned pk2(float lo, float hi) { return pg8::cvt_pk_bf16(lo, hi); }
; __device__ __forceinline__ f32x4 mfma16(bf16x8 a, bf16x8 b, f32x4 c) { return __builtin_amdgcn_mfma_f32_16x16x32_bf16(a, b, c, 0, 0, 0); }
; template <int NKT, int VSTR, bool SINK>
; __device__ __forceinline__ void attn_core(LAS const unsigned char* kb_, LAS const unsigned char* vb_, bf16x8 q0, bf16x8 q1, float sk, unsigned mskbits, int fr, f32x4 (&o)[4]) {
;     ...
;     for (int kt = 0; kt < NKT; ++kt)
; #pragma unroll
;         for (int r = 0; r < 4; ++r) { const float p = __builtin_amdgcn_exp2f(S[kt][r] - mx); S[kt][r] = p; sum += p; }
;     sum += __shfl_xor(sum, 16); sum += __shfl_xor(sum, 32);
;     if (SINK) sum += __builtin_amdgcn_exp2f(sk - mx);
;     const float inv = 1.0f / sum;
;     bf16x8 pf[NKT / 2];
; #pragma unroll
;     for (int kb = 0; kb < NKT / 2; ++kb) {
;         v4u w; w.x = pk2(S[2 * kb][0], S[2 * kb][1]); w.y = pk2(S[2 * kb][2], S[2 * kb][3]); w.z = pk2(S[2 * kb + 1][0], S[2 * kb + 1][1]); w.w = pk2(S[2 * kb + 1][2], S[2 * kb + 1][3]);
;         pf[kb] = __builtin_bit_cast(bf16x8, w);
;     }
; #pragma unroll
;     for (int dt = 0; dt < 4; ++dt) {
;         f32x4 acc = (f32x4){0.f, 0.f, 0.f, 0.f};
; #pragma unroll
;         for (int kb = 0; kb < NKT / 2; ++kb) {
;             const bf16x8 vf = *(LAS const bf16x8*)(vb_ + dt * 16 * VSTR + kb * 64);
;             acc = mfma16(vf, pf[kb], acc);
	v_add_f32_e32 v54, v78, v54
	v_exp_f32_e32 v74, v74
	v_sub_f32_e32 v75, v75, v52
	v_add_f32_e32 v54, v79, v54
	v_exp_f32_e32 v75, v75
	v_sub_f32_e32 v68, v68, v52
	v_add_f32_e32 v54, v72, v54
	v_exp_f32_e32 v98, v68
	v_sub_f32_e32 v68, v69, v52
	v_add_f32_e32 v54, v73, v54
	v_exp_f32_e32 v99, v68
	v_sub_f32_e32 v68, v70, v52
	v_add_f32_e32 v54, v74, v54
	v_exp_f32_e32 v109, v68
	v_sub_f32_e32 v68, v71, v52
	v_add_f32_e32 v54, v75, v54
	v_exp_f32_e32 v110, v68
	v_sub_f32_e32 v64, v64, v52
	v_add_f32_e32 v54, v98, v54
	v_exp_f32_e32 v111, v64
	v_sub_f32_e32 v64, v65, v52
	v_add_f32_e32 v54, v99, v54
	v_exp_f32_e32 v112, v64
	v_sub_f32_e32 v64, v66, v52
	v_add_f32_e32 v54, v109, v54
	v_exp_f32_e32 v113, v64
	v_sub_f32_e32 v64, v67, v52
	v_add_f32_e32 v54, v110, v54
	v_exp_f32_e32 v114, v64
	v_sub_f32_e32 v60, v60, v52
	v_add_f32_e32 v54, v111, v54
	v_exp_f32_e32 v115, v60
	v_sub_f32_e32 v60, v61, v52
	v_add_f32_e32 v54, v112, v54
	v_exp_f32_e32 v116, v60
	v_sub_f32_e32 v60, v62, v52
	v_add_f32_e32 v54, v113, v54
	v_exp_f32_e32 v117, v60
	v_sub_f32_e32 v60, v63, v52
	v_add_f32_e32 v54, v114, v54
	v_exp_f32_e32 v118, v60
	v_sub_f32_e32 v56, v56, v52
	v_add_f32_e32 v54, v115, v54
	v_exp_f32_e32 v119, v56
	v_sub_f32_e32 v56, v57, v52
	v_add_f32_e32 v54, v116, v54
	v_exp_f32_e32 v120, v56
	v_sub_f32_e32 v56, v58, v52
	v_add_f32_e32 v54, v117, v54
	v_exp_f32_e32 v121, v56
	v_sub_f32_e32 v56, v59, v52
	v_add_f32_e32 v54, v118, v54
	v_exp_f32_e32 v122, v56
	v_sub_f32_e32 v48, v48, v52
	v_add_f32_e32 v54, v119, v54
	v_exp_f32_e32 v123, v48
	v_sub_f32_e32 v49, v49, v52
	v_add_f32_e32 v54, v120, v54
	v_exp_f32_e32 v124, v49
	v_sub_f32_e32 v49, v50, v52
	v_add_f32_e32 v54, v121, v54
	v_exp_f32_e32 v125, v49
	v_sub_f32_e32 v49, v51, v52
	v_add_f32_e32 v54, v122, v54
	v_exp_f32_e32 v51, v49
	v_add_f32_e32 v48, v123, v54
	v_add_f32_e32 v48, v124, v48
	v_add_f32_e32 v48, v125, v48
	v_add_f32_e32 v48, v51, v48
	ds_bpermute_b32 v49, v212, v48
	v_cvt_pk_bf16_f32 v68, v53, v55
	v_cvt_pk_bf16_f32 v69, v96, v97
	v_cvt_pk_bf16_f32 v70, v92, v93
	v_cvt_pk_bf16_f32 v71, v94, v95
	s_waitcnt lgkmcnt(0)
	v_add_f32_e32 v48, v48, v49
	ds_bpermute_b32 v49, v176, v48
	v_cvt_pk_bf16_f32 v64, v88, v89
	v_cvt_pk_bf16_f32 v65, v90, v91
	v_cvt_pk_bf16_f32 v66, v84, v85
	v_cvt_pk_bf16_f32 v67, v86, v87
	s_waitcnt lgkmcnt(0)
	v_add_f32_e32 v48, v48, v49
	v_fma_f32 v49, v108, s2, -v52
	v_exp_f32_e32 v49, v49
	v_cvt_pk_bf16_f32 v60, v80, v81
	v_cvt_pk_bf16_f32 v61, v82, v83
	v_cvt_pk_bf16_f32 v62, v76, v77
	v_cvt_pk_bf16_f32 v63, v78, v79
	v_cvt_pk_bf16_f32 v56, v72, v73
	s_nop 0
	v_add_f32_e32 v108, v49, v48
	v_div_scale_f32 v72, s[0:1], v108, v108, 1.0
	v_rcp_f32_e32 v73, v72
	v_cvt_pk_bf16_f32 v57, v74, v75
	v_cvt_pk_bf16_f32 v58, v98, v99
	v_cvt_pk_bf16_f32 v59, v109, v110
	v_cvt_pk_bf16_f32 v52, v111, v112
	v_cvt_pk_bf16_f32 v53, v113, v114
	s_nop 0
	v_fma_f32 v74, -v72, v73, 1.0
	v_fmac_f32_e32 v73, v74, v73
	v_div_scale_f32 v74, vcc, 1.0, v108, 1.0
	v_mul_f32_e32 v75, v74, v73
	v_fma_f32 v76, -v72, v75, v74
	v_fmac_f32_e32 v75, v76, v73
	v_fma_f32 v72, -v72, v75, v74
	v_cvt_pk_bf16_f32 v54, v115, v116
	v_cvt_pk_bf16_f32 v55, v117, v118
	v_cvt_pk_bf16_f32 v48, v119, v120
	v_cvt_pk_bf16_f32 v49, v121, v122
	v_cvt_pk_bf16_f32 v50, v123, v124
	v_cvt_pk_bf16_f32 v51, v125, v51
	v_div_fmas_f32 v72, v72, v73, v75
	s_waitcnt lgkmcnt(0)
	ds_read_b128 v[128:131], v106 offset:55296
	ds_read_b128 v[132:135], v106 offset:55360
	ds_read_b128 v[136:139], v106 offset:61760
	ds_read_b128 v[140:143], v105 offset:12864
	ds_read_b128 v[144:147], v106 offset:55424
	ds_read_b128 v[160:163], v106 offset:55488
	ds_read_b128 v[164:167], v106 offset:55552
	ds_read_b128 v[168:171], v106 offset:55616
	ds_read_b128 v[172:175], v106 offset:61696
	ds_read_b128 v[180:183], v106 offset:61824
	ds_read_b128 v[196:199], v106 offset:61888
	ds_read_b128 v[200:203], v106 offset:61952
	ds_read_b128 v[204:207], v106 offset:62016
	ds_read_b128 v[224:227], v105 offset:12800
	s_waitcnt lgkmcnt(13)
	v_mfma_f32_16x16x32_bf16 v[74:77], v[128:131], v[68:71], 0
	ds_read_b128 v[228:231], v105 offset:12928
	v_div_fixup_f32 v72, v72, v108, 1.0
	s_waitcnt lgkmcnt(13)
	v_mfma_f32_16x16x32_bf16 v[74:77], v[132:135], v[64:67], v[74:77]
	ds_read_b128 v[232:235], v105 offset:12992
	s_waitcnt lgkmcnt(11)
; #define LAS __attribute__((address_space(3)))
; __device__ __forceinline__ float sq4(const f32x4 a) { return (a[0] * a[0] + a[1] * a[1]) + (a[2] * a[2] + a[3] * a[3]); }
; #define LAS __attribute__((address_space(3)))
; __device__ __forceinline__ unsigned pk2(float lo, float hi) { return pg8::cvt_pk_bf16(lo, hi); }
; __device__ __forceinline__ f32x4 mfma16(bf16x8 a, bf16x8 b, f32x4 c) { return __builtin_amdgcn_mfma_f32_16x16x32_bf16(a, b, c, 0, 0, 0); }
; template <int NKT, int VSTR, bool SINK>
; __device__ __forceinline__ void attn_core(LAS const unsigned char* kb_, LAS const unsigned char* vb_, bf16x8 q0, bf16x8 q1, float sk, unsigned mskbits, int fr, f32x4 (&o)[4]) {
;     ...
; #pragma unroll
;     for (int dt = 0; dt < 4; ++dt) {
;         f32x4 acc = (f32x4){0.f, 0.f, 0.f, 0.f};
; #pragma unroll
;         for (int kb = 0; kb < NKT / 2; ++kb) {
;             const bf16x8 vf = *(LAS const bf16x8*)(vb_ + dt * 16 * VSTR + kb * 64);
;             acc = mfma16(vf, pf[kb], acc);
;         }
;         o[dt] = acc * inv;
;     }
; template <bool DO_SWA, bool DO_MEM>
; __device__ __forceinline__ void attn_unit(const Args& a, unsigned char* ws, LAS unsigned char* lds, int l, int tid_in, int lane_in, int wave, int unit) {
;     ...
;                 attn_core<12, 400, true>(lds + A_KS + g * 192 * 144 + fq * 16, lds + A_VT1 + (g * 64 + fr) * 400 + fq * 16, qsw[hh][0], qsw[hh][1], sk, mskbits, fr, o);
; #pragma unroll
;                 for (int dt = 0; dt < 4; ++dt) { ssq += pg8::sq4(o[dt]); osv[hh][dt] = (v2u){pk2(o[dt][0], o[dt][1]), pk2(o[dt][2], o[dt][3])}; }
;             }
	v_mfma_f32_16x16x32_bf16 v[74:77], v[144:147], v[60:63], v[74:77]
	ds_read_b128 v[236:239], v105 offset:13056
	ds_read_b128 v[240:243], v105 offset:13120
	s_waitcnt lgkmcnt(12)
	v_mfma_f32_16x16x32_bf16 v[74:77], v[160:163], v[56:59], v[74:77]
	ds_read_b128 v[244:247], v105 offset:19200
	s_waitcnt lgkmcnt(12)
	v_mfma_f32_16x16x32_bf16 v[74:77], v[164:167], v[52:55], v[74:77]
	ds_read_b128 v[128:131], v105 offset:19264
	s_waitcnt lgkmcnt(12)
	v_mfma_f32_16x16x32_bf16 v[76:79], v[168:171], v[48:51], v[74:77]
	s_nop 7
	v_pk_mul_f32 v[74:75], v[78:79], v[72:73] op_sel_hi:[1,0]
	ds_read_b128 v[132:135], v105 offset:19328
	s_waitcnt lgkmcnt(12)
	v_mfma_f32_16x16x32_bf16 v[78:81], v[172:175], v[68:71], 0
	v_mul_f32_e64 v76, v76, v72
	v_mul_f32_e64 v77, v77, v72
	v_mfma_f32_16x16x32_bf16 v[78:81], v[136:139], v[64:67], v[78:81]
	ds_read_b128 v[144:147], v105 offset:19392
	s_waitcnt lgkmcnt(12)
	v_mfma_f32_16x16x32_bf16 v[78:81], v[180:183], v[60:63], v[78:81]
	ds_read_b128 v[160:163], v105 offset:19456
	s_waitcnt lgkmcnt(12)
	v_mfma_f32_16x16x32_bf16 v[78:81], v[196:199], v[56:59], v[78:81]
	ds_read_b128 v[164:167], v105 offset:19520
	s_waitcnt lgkmcnt(12)
	v_mfma_f32_16x16x32_bf16 v[78:81], v[200:203], v[52:55], v[78:81]
	s_waitcnt lgkmcnt(11)
	v_mfma_f32_16x16x32_bf16 v[80:83], v[204:207], v[48:51], v[78:81]
	s_nop 7
	v_pk_mul_f32 v[78:79], v[82:83], v[72:73] op_sel_hi:[1,0]
	s_waitcnt lgkmcnt(10)
	v_mfma_f32_16x16x32_bf16 v[82:85], v[224:227], v[68:71], 0
	v_mul_f32_e64 v80, v80, v72
	v_mul_f32_e64 v81, v81, v72
	v_mfma_f32_16x16x32_bf16 v[82:85], v[140:143], v[64:67], v[82:85]
	s_waitcnt lgkmcnt(9)
	v_mfma_f32_16x16x32_bf16 v[82:85], v[228:231], v[60:63], v[82:85]
	s_waitcnt lgkmcnt(8)
	v_mfma_f32_16x16x32_bf16 v[82:85], v[232:235], v[56:59], v[82:85]
	s_waitcnt lgkmcnt(7)
	v_mfma_f32_16x16x32_bf16 v[82:85], v[236:239], v[52:55], v[82:85]
	s_waitcnt lgkmcnt(6)
	v_mfma_f32_16x16x32_bf16 v[84:87], v[240:243], v[48:51], v[82:85]
	s_nop 7
	v_pk_mul_f32 v[82:83], v[72:73], v[86:87] op_sel_hi:[0,1]
	s_waitcnt lgkmcnt(5)
	v_mfma_f32_16x16x32_bf16 v[68:71], v[244:247], v[68:71], 0
	v_pk_mul_f32 v[84:85], v[72:73], v[84:85] op_sel_hi:[0,1]
	s_waitcnt lgkmcnt(4)
	v_mfma_f32_16x16x32_bf16 v[64:67], v[128:131], v[64:67], v[68:71]
	s_waitcnt lgkmcnt(3)
	v_mfma_f32_16x16x32_bf16 v[60:63], v[132:135], v[60:63], v[64:67]
	s_waitcnt lgkmcnt(2)
	v_mfma_f32_16x16x32_bf16 v[56:59], v[144:147], v[56:59], v[60:63]
	s_waitcnt lgkmcnt(1)
	v_mfma_f32_16x16x32_bf16 v[52:55], v[160:163], v[52:55], v[56:59]
	v_cvt_pk_bf16_f32 v93, v76, v77
	v_cvt_pk_bf16_f32 v92, v74, v75
	s_waitcnt lgkmcnt(0)
	v_mfma_f32_16x16x32_bf16 v[48:51], v[164:167], v[48:51], v[52:55]
	s_nop 2
	v_mul_f32_e32 v52, v77, v77
	v_mul_f32_e32 v53, v75, v75
	v_fmac_f32_e32 v52, v76, v76
	v_fmac_f32_e32 v53, v74, v74
	v_add_f32_e32 v52, v52, v53
	v_mul_f32_e32 v53, v81, v81
	v_mul_f32_e32 v54, v79, v79
	v_fmac_f32_e32 v53, v80, v80
	v_fmac_f32_e32 v54, v78, v78
	v_add_f32_e32 v53, v53, v54
	v_add_f32_e32 v52, v52, v53
	v_mul_f32_e32 v53, v85, v85
	v_mul_f32_e32 v54, v83, v83
	v_fmac_f32_e32 v53, v84, v84
	v_fmac_f32_e32 v54, v82, v82
	v_pk_mul_f32 v[50:51], v[72:73], v[50:51] op_sel_hi:[0,1]
	v_pk_mul_f32 v[48:49], v[72:73], v[48:49] op_sel_hi:[0,1]
	v_add_f32_e32 v53, v53, v54
	v_add_f32_e32 v52, v53, v52
	v_mul_f32_e32 v53, v49, v49
	v_mul_f32_e32 v54, v51, v51
	v_fmac_f32_e32 v53, v48, v48
	v_fmac_f32_e32 v54, v50, v50
	v_add_f32_e32 v53, v53, v54
	v_cvt_pk_bf16_f32 v95, v80, v81
	v_cvt_pk_bf16_f32 v94, v78, v79
	v_cvt_pk_bf16_f32 v97, v84, v85
	v_cvt_pk_bf16_f32 v96, v82, v83
	v_add_f32_e32 v108, v52, v53
	v_cvt_pk_bf16_f32 v99, v48, v49
	v_cvt_pk_bf16_f32 v98, v50, v51
	v_mov_b32_e32 v109, s99
	s_waitcnt lgkmcnt(0)
	ds_read_b128 v[120:123], v107
	ds_read_b128 v[124:127], v107 offset:64
	ds_read_b128 v[128:131], v107 offset:576
	ds_read_b128 v[132:135], v107 offset:640
	ds_read_b128 v[136:139], v107 offset:4608
	ds_read_b128 v[140:143], v107 offset:4672
	ds_read_b128 v[144:147], v107 offset:5184
	ds_read_b128 v[160:163], v107 offset:5248
	ds_read_b128 v[164:167], v107 offset:9216
	ds_read_b128 v[168:171], v107 offset:9280
	ds_read_b128 v[172:175], v107 offset:9792
	ds_read_b128 v[180:183], v107 offset:9856
	ds_read_b128 v[196:199], v107 offset:13824
	ds_read_b128 v[200:203], v107 offset:13888
	s_waitcnt lgkmcnt(13)
	v_mfma_f32_16x16x32_bf16 v[48:51], v[120:123], v[44:47], v[28:31]

; #define LAS __attribute__((address_space(3)))
; #define LAS __attribute__((address_space(3)))
; __device__ __forceinline__ f32x4 mfma16(bf16x8 a, bf16x8 b, f32x4 c) { return __builtin_amdgcn_mfma_f32_16x16x32_bf16(a, b, c, 0, 0, 0); }
; template <int NKT, int VSTR, bool SINK>
; __device__ __forceinline__ void attn_core(LAS const unsigned char* kb_, LAS const unsigned char* vb_, bf16x8 q0, bf16x8 q1, float sk, unsigned mskbits, int fr, f32x4 (&o)[4]) {
;     ...
; #pragma unroll
;     for (int kt = 0; kt < NKT; ++kt) {
;         const int key = (kt >> 1) * 32 + ((kt & 1) << 2) + krow;
;         LAS const unsigned char* kp = kb_ + key * 144;
;         const bf16x8 a0 = *(LAS const bf16x8*)kp, a1 = *(LAS const bf16x8*)(kp + 64);
;         const float bias = ((mskbits >> (kt >> 2)) & 1u) ? -1e30f : 0.f;
;         f32x4 s = mfma16(a0, q0, (f32x4){bias, bias, bias, bias});
;         s = mfma16(a1, q1, s);
;         S[kt] = s;
;     }
;     float mx = S[0][0];
; #pragma unroll
;     for (int kt = 0; kt < NKT; ++kt) mx = fmaxf(fmaxf(mx, fmaxf(S[kt][0], S[kt][1])), fmaxf(S[kt][2], S[kt][3]));
;     mx = fmaxf(mx, __shfl_xor(mx, 16)); mx = fmaxf(mx, __shfl_xor(mx, 32));
;     if (SINK) mx = fmaxf(mx, sk);
;     float sum = 0.f;
; #pragma unroll
;     for (int kt = 0; kt < NKT; ++kt)
; #pragma unroll
;         for (int r = 0; r < 4; ++r) { const float p = __builtin_amdgcn_exp2f(S[kt][r] - mx); S[kt][r] = p; sum += p; }
;     sum += __shfl_xor(sum, 16); sum += __shfl_xor(sum, 32);
;     if (SINK) sum += __builtin_amdgcn_exp2f(sk - mx);
	v_mul_f32_e32 v118, 0x3fb8aa3b, v109
	s_waitcnt lgkmcnt(12)
	v_mfma_f32_16x16x32_bf16 v[88:91], v[124:127], v[40:43], v[48:51]
	ds_read_b128 v[204:207], v107 offset:14400
	ds_read_b128 v[224:227], v107 offset:14464
	s_waitcnt lgkmcnt(13)
	v_mfma_f32_16x16x32_bf16 v[48:51], v[128:131], v[44:47], v[28:31]
	s_waitcnt lgkmcnt(12)
	v_mfma_f32_16x16x32_bf16 v[84:87], v[132:135], v[40:43], v[48:51]
	ds_read_b128 v[228:231], v107 offset:18432
	ds_read_b128 v[232:235], v107 offset:18496
	s_waitcnt lgkmcnt(13)
	v_mfma_f32_16x16x32_bf16 v[48:51], v[136:139], v[44:47], v[28:31]
	s_waitcnt lgkmcnt(12)
	v_mfma_f32_16x16x32_bf16 v[80:83], v[140:143], v[40:43], v[48:51]
	ds_read_b128 v[236:239], v107 offset:19008
	ds_read_b128 v[240:243], v107 offset:19072
	s_waitcnt lgkmcnt(13)
	v_mfma_f32_16x16x32_bf16 v[48:51], v[144:147], v[44:47], v[28:31]
	s_waitcnt lgkmcnt(12)
	v_mfma_f32_16x16x32_bf16 v[76:79], v[160:163], v[40:43], v[48:51]
	ds_read_b128 v[244:247], v107 offset:23040
	ds_read_b128 v[120:123], v107 offset:23104
	s_waitcnt lgkmcnt(13)
	v_mfma_f32_16x16x32_bf16 v[48:51], v[164:167], v[44:47], v[24:27]
	s_waitcnt lgkmcnt(12)
	v_mfma_f32_16x16x32_bf16 v[72:75], v[168:171], v[40:43], v[48:51]
	ds_read_b128 v[124:127], v107 offset:23616
	ds_read_b128 v[128:131], v107 offset:23680
	s_waitcnt lgkmcnt(13)
	v_mfma_f32_16x16x32_bf16 v[48:51], v[172:175], v[44:47], v[24:27]
	s_waitcnt lgkmcnt(12)
	v_mfma_f32_16x16x32_bf16 v[68:71], v[180:183], v[40:43], v[48:51]
	s_waitcnt lgkmcnt(11)
	v_mfma_f32_16x16x32_bf16 v[48:51], v[196:199], v[44:47], v[24:27]
	s_waitcnt lgkmcnt(10)
	v_mfma_f32_16x16x32_bf16 v[64:67], v[200:203], v[40:43], v[48:51]
	s_waitcnt lgkmcnt(9)
	v_mfma_f32_16x16x32_bf16 v[48:51], v[204:207], v[44:47], v[24:27]
	s_waitcnt lgkmcnt(8)
	v_mfma_f32_16x16x32_bf16 v[60:63], v[224:227], v[40:43], v[48:51]
	s_waitcnt lgkmcnt(7)
	v_mfma_f32_16x16x32_bf16 v[48:51], v[228:231], v[44:47], 0
	s_waitcnt lgkmcnt(6)
	v_mfma_f32_16x16x32_bf16 v[56:59], v[232:235], v[40:43], v[48:51]
	s_waitcnt lgkmcnt(5)
	v_mfma_f32_16x16x32_bf16 v[48:51], v[236:239], v[44:47], 0
	s_waitcnt lgkmcnt(4)
	v_mfma_f32_16x16x32_bf16 v[52:55], v[240:243], v[40:43], v[48:51]
	s_waitcnt lgkmcnt(3)
	v_mfma_f32_16x16x32_bf16 v[48:51], v[244:247], v[44:47], 0
	s_waitcnt lgkmcnt(2)
	v_mfma_f32_16x16x32_bf16 v[48:51], v[120:123], v[40:43], v[48:51]
	s_waitcnt lgkmcnt(1)
	v_mfma_f32_16x16x32_bf16 v[44:47], v[124:127], v[44:47], 0
	s_waitcnt lgkmcnt(0)
	v_mfma_f32_16x16x32_bf16 v[40:43], v[128:131], v[40:43], v[44:47]
	s_nop 5
	s_nop 0
	s_nop 0
	v_max_f32_e32 v44, v90, v91
	s_nop 0
	s_nop 0
	v_max_f32_e32 v45, v84, v85
	s_nop 0
	s_nop 0
	v_max3_f32 v44, v88, v89, v44
	v_max_f32_e32 v46, v86, v87
	v_max3_f32 v44, v44, v45, v46
	s_nop 0
	s_nop 0
	v_max_f32_e32 v45, v80, v81
	s_nop 0
	s_nop 0
	v_max_f32_e32 v46, v82, v83
	v_max3_f32 v44, v44, v45, v46
	s_nop 0
	s_nop 0
	v_max_f32_e32 v45, v76, v77
	s_nop 0
	s_nop 0
	v_max_f32_e32 v46, v78, v79
	v_max3_f32 v44, v44, v45, v46
	v_max_f32_e32 v45, v72, v73
	v_max_f32_e32 v46, v74, v75
	v_max3_f32 v44, v44, v45, v46
	v_max_f32_e32 v45, v68, v69
	v_max_f32_e32 v46, v70, v71
	v_max3_f32 v44, v44, v45, v46
	v_max_f32_e32 v45, v64, v65
	v_max_f32_e32 v46, v66, v67
	v_max3_f32 v44, v44, v45, v46
	v_max_f32_e32 v45, v60, v61
	v_max_f32_e32 v46, v62, v63
	v_max3_f32 v44, v44, v45, v46
	v_max_f32_e32 v45, v56, v57
	v_max_f32_e32 v46, v58, v59
	v_max3_f32 v44, v44, v45, v46
	v_max_f32_e32 v45, v52, v53
	v_max_f32_e32 v46, v54, v55
	v_max3_f32 v44, v44, v45, v46
	v_max_f32_e32 v45, v48, v49
	v_max_f32_e32 v46, v50, v51
	v_max3_f32 v44, v44, v45, v46
	v_max_f32_e32 v45, v40, v41
	v_max_f32_e32 v46, v42, v43
	v_max3_f32 v44, v44, v45, v46
	ds_bpermute_b32 v45, v212, v44
	s_waitcnt lgkmcnt(0)
	s_nop 0
	v_max_f32_e32 v44, v44, v45
	ds_bpermute_b32 v45, v176, v44
	s_waitcnt lgkmcnt(0)
	v_max3_f32 v44, v44, v45, v118
	v_sub_f32_e32 v45, v88, v44
	v_exp_f32_e32 v45, v45
	v_sub_f32_e32 v47, v89, v44
	v_exp_f32_e32 v47, v47
	v_sub_f32_e32 v88, v90, v44
	v_exp_f32_e32 v88, v88
	v_sub_f32_e32 v89, v91, v44
	v_exp_f32_e32 v89, v89
	v_sub_f32_e32 v84, v84, v44
	v_add_f32_e32 v46, 0, v45
	v_exp_f32_e32 v84, v84
	v_sub_f32_e32 v85, v85, v44
	v_add_f32_e32 v46, v47, v46
	v_exp_f32_e32 v85, v85
	v_sub_f32_e32 v86, v86, v44
	v_add_f32_e32 v46, v88, v46
	v_exp_f32_e32 v86, v86
	v_sub_f32_e32 v87, v87, v44
	v_add_f32_e32 v46, v89, v46
	v_exp_f32_e32 v87, v87
	v_sub_f32_e32 v80, v80, v44
	v_add_f32_e32 v46, v84, v46
	v_exp_f32_e32 v80, v80
	v_sub_f32_e32 v81, v81, v44
	v_add_f32_e32 v46, v85, v46
	v_exp_f32_e32 v81, v81
	v_sub_f32_e32 v82, v82, v44
	v_add_f32_e32 v46, v86, v46
	v_exp_f32_e32 v82, v82
	v_sub_f32_e32 v83, v83, v44
	v_add_f32_e32 v46, v87, v46
	v_exp_f32_e32 v83, v83
	v_sub_f32_e32 v76, v76, v44
	v_add_f32_e32 v46, v80, v46
	v_exp_f32_e32 v76, v76
	v_sub_f32_e32 v77, v77, v44
	v_add_f32_e32 v46, v81, v46
	v_exp_f32_e32 v77, v77
	v_sub_f32_e32 v78, v78, v44
	v_add_f32_e32 v46, v82, v46
	v_exp_f32_e32 v78, v78
	v_sub_f32_e32 v79, v79, v44
	v_add_f32_e32 v46, v83, v46
	v_exp_f32_e32 v79, v79
	v_sub_f32_e32 v72, v72, v44
	v_add_f32_e32 v46, v76, v46
	v_exp_f32_e32 v72, v72
	v_sub_f32_e32 v73, v73, v44
	v_add_f32_e32 v46, v77, v46
	v_exp_f32_e32 v73, v73
	v_sub_f32_e32 v74, v74, v44
	v_add_f32_e32 v46, v78, v46
	v_exp_f32_e32 v74, v74
	v_sub_f32_e32 v75, v75, v44
	v_add_f32_e32 v46, v79, v46
	v_exp_f32_e32 v75, v75
	v_sub_f32_e32 v68, v68, v44
	v_add_f32_e32 v46, v72, v46
	v_exp_f32_e32 v68, v68
	v_sub_f32_e32 v69, v69, v44
	v_add_f32_e32 v46, v73, v46
	v_exp_f32_e32 v69, v69
	v_sub_f32_e32 v70, v70, v44
	v_add_f32_e32 v46, v74, v46
	v_exp_f32_e32 v70, v70
; #define LAS __attribute__((address_space(3)))
; #define LAS __attribute__((address_space(3)))
; __device__ __forceinline__ unsigned pk2(float lo, float hi) { return pg8::cvt_pk_bf16(lo, hi); }
; __device__ __forceinline__ f32x4 mfma16(bf16x8 a, bf16x8 b, f32x4 c) { return __builtin_amdgcn_mfma_f32_16x16x32_bf16(a, b, c, 0, 0, 0); }
; template <int NKT, int VSTR, bool SINK>
; __device__ __forceinline__ void attn_core(LAS const unsigned char* kb_, LAS const unsigned char* vb_, bf16x8 q0, bf16x8 q1, float sk, unsigned mskbits, int fr, f32x4 (&o)[4]) {
;     ...
;     for (int kt = 0; kt < NKT; ++kt)
; #pragma unroll
;         for (int r = 0; r < 4; ++r) { const float p = __builtin_amdgcn_exp2f(S[kt][r] - mx); S[kt][r] = p; sum += p; }
;     sum += __shfl_xor(sum, 16); sum += __shfl_xor(sum, 32);
;     if (SINK) sum += __builtin_amdgcn_exp2f(sk - mx);
;     const float inv = 1.0f / sum;
;     bf16x8 pf[NKT / 2];
; #pragma unroll
;     for (int kb = 0; kb < NKT / 2; ++kb) {
;         v4u w; w.x = pk2(S[2 * kb][0], S[2 * kb][1]); w.y = pk2(S[2 * kb][2], S[2 * kb][3]); w.z = pk2(S[2 * kb + 1][0], S[2 * kb + 1][1]); w.w = pk2(S[2 * kb + 1][2], S[2 * kb + 1][3]);
;         pf[kb] = __builtin_bit_cast(bf16x8, w);
;     }
; #pragma unroll
;     for (int dt = 0; dt < 4; ++dt) {
;         f32x4 acc = (f32x4){0.f, 0.f, 0.f, 0.f};
; #pragma unroll
;         for (int kb = 0; kb < NKT / 2; ++kb) {
;             const bf16x8 vf = *(LAS const bf16x8*)(vb_ + dt * 16 * VSTR + kb * 64);
;             acc = mfma16(vf, pf[kb], acc);
	v_sub_f32_e32 v71, v71, v44
	v_add_f32_e32 v46, v75, v46
	v_exp_f32_e32 v71, v71
	v_sub_f32_e32 v64, v64, v44
	v_add_f32_e32 v46, v68, v46
	v_exp_f32_e32 v64, v64
	v_sub_f32_e32 v65, v65, v44
	v_add_f32_e32 v46, v69, v46
	v_exp_f32_e32 v65, v65
	v_sub_f32_e32 v66, v66, v44
	v_add_f32_e32 v46, v70, v46
	v_exp_f32_e32 v66, v66
	v_sub_f32_e32 v67, v67, v44
	v_add_f32_e32 v46, v71, v46
	v_exp_f32_e32 v67, v67
	v_sub_f32_e32 v60, v60, v44
	v_add_f32_e32 v46, v64, v46
	v_exp_f32_e32 v90, v60
	v_sub_f32_e32 v60, v61, v44
	v_add_f32_e32 v46, v65, v46
	v_exp_f32_e32 v91, v60
	v_sub_f32_e32 v60, v62, v44
	v_add_f32_e32 v46, v66, v46
	v_exp_f32_e32 v110, v60
	v_sub_f32_e32 v60, v63, v44
	v_add_f32_e32 v46, v67, v46
	v_exp_f32_e32 v111, v60
	v_sub_f32_e32 v56, v56, v44
	v_add_f32_e32 v46, v90, v46
	v_exp_f32_e32 v112, v56
	v_sub_f32_e32 v56, v57, v44
	v_add_f32_e32 v46, v91, v46
	v_exp_f32_e32 v113, v56
	v_sub_f32_e32 v56, v58, v44
	v_add_f32_e32 v46, v110, v46
	v_exp_f32_e32 v114, v56
	v_sub_f32_e32 v56, v59, v44
	v_add_f32_e32 v46, v111, v46
	v_exp_f32_e32 v115, v56
	v_sub_f32_e32 v52, v52, v44
	v_add_f32_e32 v46, v112, v46
	v_exp_f32_e32 v116, v52
	v_sub_f32_e32 v52, v53, v44
	v_add_f32_e32 v46, v113, v46
	v_exp_f32_e32 v117, v52
	v_sub_f32_e32 v52, v54, v44
	v_add_f32_e32 v46, v114, v46
	v_exp_f32_e32 v118, v52
	v_sub_f32_e32 v52, v55, v44
	v_add_f32_e32 v46, v115, v46
	v_exp_f32_e32 v119, v52
	v_sub_f32_e32 v48, v48, v44
	v_add_f32_e32 v46, v116, v46
	v_exp_f32_e32 v120, v48
	v_sub_f32_e32 v48, v49, v44
	v_add_f32_e32 v46, v117, v46
	v_exp_f32_e32 v121, v48
	v_sub_f32_e32 v48, v50, v44
	v_add_f32_e32 v46, v118, v46
	v_exp_f32_e32 v122, v48
	v_sub_f32_e32 v48, v51, v44
	v_add_f32_e32 v46, v119, v46
	v_exp_f32_e32 v123, v48
	v_sub_f32_e32 v40, v40, v44
	v_add_f32_e32 v46, v120, v46
	v_exp_f32_e32 v124, v40
	v_sub_f32_e32 v41, v41, v44
	v_add_f32_e32 v46, v121, v46
	v_exp_f32_e32 v125, v41
	v_sub_f32_e32 v41, v42, v44
	v_add_f32_e32 v46, v122, v46
	v_exp_f32_e32 v126, v41
	v_sub_f32_e32 v41, v43, v44
	v_add_f32_e32 v46, v123, v46
	v_exp_f32_e32 v43, v41
	v_add_f32_e32 v40, v124, v46
	v_add_f32_e32 v40, v125, v40
	v_add_f32_e32 v40, v126, v40
	v_add_f32_e32 v40, v43, v40
	ds_bpermute_b32 v41, v212, v40
	v_cvt_pk_bf16_f32 v60, v45, v47
	v_cvt_pk_bf16_f32 v61, v88, v89
	v_cvt_pk_bf16_f32 v62, v84, v85
	v_cvt_pk_bf16_f32 v63, v86, v87
	s_waitcnt lgkmcnt(0)
	v_add_f32_e32 v40, v40, v41
	ds_bpermute_b32 v41, v176, v40
	v_cvt_pk_bf16_f32 v56, v80, v81
	v_cvt_pk_bf16_f32 v57, v82, v83
	v_cvt_pk_bf16_f32 v58, v76, v77
	v_cvt_pk_bf16_f32 v59, v78, v79
	s_waitcnt lgkmcnt(0)
	v_add_f32_e32 v40, v40, v41
	v_fma_f32 v41, v109, s2, -v44
	v_exp_f32_e32 v41, v41
	v_cvt_pk_bf16_f32 v52, v72, v73
	v_cvt_pk_bf16_f32 v53, v74, v75
	v_cvt_pk_bf16_f32 v54, v68, v69
	v_cvt_pk_bf16_f32 v55, v70, v71
	v_cvt_pk_bf16_f32 v48, v64, v65
	s_nop 0
	v_add_f32_e32 v109, v41, v40
	v_div_scale_f32 v64, s[0:1], v109, v109, 1.0
	v_rcp_f32_e32 v65, v64
	v_cvt_pk_bf16_f32 v49, v66, v67
	v_cvt_pk_bf16_f32 v50, v90, v91
	v_cvt_pk_bf16_f32 v51, v110, v111
	v_cvt_pk_bf16_f32 v44, v112, v113
	v_cvt_pk_bf16_f32 v45, v114, v115
	s_nop 0
	v_fma_f32 v66, -v64, v65, 1.0
	v_fmac_f32_e32 v65, v66, v65
	v_div_scale_f32 v66, vcc, 1.0, v109, 1.0
	v_mul_f32_e32 v67, v66, v65
	v_fma_f32 v68, -v64, v67, v66
	v_fmac_f32_e32 v67, v68, v65
	v_fma_f32 v64, -v64, v67, v66
	v_cvt_pk_bf16_f32 v46, v116, v117
	v_cvt_pk_bf16_f32 v47, v118, v119
	v_cvt_pk_bf16_f32 v40, v120, v121
	v_cvt_pk_bf16_f32 v41, v122, v123
	v_cvt_pk_bf16_f32 v42, v124, v125
	v_cvt_pk_bf16_f32 v43, v126, v43
	v_div_fmas_f32 v64, v64, v65, v67
	s_waitcnt lgkmcnt(0)
	ds_read_b128 v[128:131], v106 offset:55296
	ds_read_b128 v[132:135], v106 offset:55360
	ds_read_b128 v[136:139], v106 offset:61760
	ds_read_b128 v[140:143], v105 offset:12864
	ds_read_b128 v[144:147], v106 offset:55424
	ds_read_b128 v[160:163], v106 offset:55488
	ds_read_b128 v[164:167], v106 offset:55552
	ds_read_b128 v[168:171], v106 offset:55616
	ds_read_b128 v[172:175], v106 offset:61696
	ds_read_b128 v[180:183], v106 offset:61824
	ds_read_b128 v[196:199], v106 offset:61888
	ds_read_b128 v[200:203], v106 offset:61952
	ds_read_b128 v[204:207], v106 offset:62016
	ds_read_b128 v[224:227], v105 offset:12800
	s_waitcnt lgkmcnt(13)
	v_mfma_f32_16x16x32_bf16 v[66:69], v[128:131], v[60:63], 0
	ds_read_b128 v[228:231], v105 offset:12928
	v_div_fixup_f32 v64, v64, v109, 1.0
	s_waitcnt lgkmcnt(13)
	v_mfma_f32_16x16x32_bf16 v[66:69], v[132:135], v[56:59], v[66:69]
	ds_read_b128 v[232:235], v105 offset:12992
	s_waitcnt lgkmcnt(11)
; #define LAS __attribute__((address_space(3)))
; __device__ __forceinline__ float sq4(const f32x4 a) { return (a[0] * a[0] + a[1] * a[1]) + (a[2] * a[2] + a[3] * a[3]); }
; #define LAS __attribute__((address_space(3)))
; __device__ __forceinline__ unsigned pk2(float lo, float hi) { return pg8::cvt_pk_bf16(lo, hi); }
; __device__ __forceinline__ f32x4 mfma16(bf16x8 a, bf16x8 b, f32x4 c) { return __builtin_amdgcn_mfma_f32_16x16x32_bf16(a, b, c, 0, 0, 0); }
; template <int NKT, int VSTR, bool SINK>
; __device__ __forceinline__ void attn_core(LAS const unsigned char* kb_, LAS const unsigned char* vb_, bf16x8 q0, bf16x8 q1, float sk, unsigned mskbits, int fr, f32x4 (&o)[4]) {
;     ...
; #pragma unroll
;     for (int dt = 0; dt < 4; ++dt) {
;         f32x4 acc = (f32x4){0.f, 0.f, 0.f, 0.f};
; #pragma unroll
;         for (int kb = 0; kb < NKT / 2; ++kb) {
;             const bf16x8 vf = *(LAS const bf16x8*)(vb_ + dt * 16 * VSTR + kb * 64);
;             acc = mfma16(vf, pf[kb], acc);
;         }
;         o[dt] = acc * inv;
;     }
; template <bool DO_SWA, bool DO_MEM>
; __device__ __forceinline__ void attn_unit(const Args& a, unsigned char* ws, LAS unsigned char* lds, int l, int tid_in, int lane_in, int wave, int unit) {
;     ...
;                 attn_core<12, 400, true>(lds + A_KS + g * 192 * 144 + fq * 16, lds + A_VT1 + (g * 64 + fr) * 400 + fq * 16, qsw[hh][0], qsw[hh][1], sk, mskbits, fr, o);
; #pragma unroll
;                 for (int dt = 0; dt < 4; ++dt) { ssq += pg8::sq4(o[dt]); osv[hh][dt] = (v2u){pk2(o[dt][0], o[dt][1]), pk2(o[dt][2], o[dt][3])}; }
;             }
	v_mfma_f32_16x16x32_bf16 v[66:69], v[144:147], v[52:55], v[66:69]
	ds_read_b128 v[236:239], v105 offset:13056
	ds_read_b128 v[240:243], v105 offset:13120
	s_waitcnt lgkmcnt(12)
	v_mfma_f32_16x16x32_bf16 v[66:69], v[160:163], v[48:51], v[66:69]
	ds_read_b128 v[244:247], v105 offset:19200
	s_waitcnt lgkmcnt(12)
	v_mfma_f32_16x16x32_bf16 v[66:69], v[164:167], v[44:47], v[66:69]
	ds_read_b128 v[128:131], v105 offset:19264
	s_waitcnt lgkmcnt(12)
	v_mfma_f32_16x16x32_bf16 v[68:71], v[168:171], v[40:43], v[66:69]
	s_nop 7
	v_pk_mul_f32 v[66:67], v[70:71], v[64:65] op_sel_hi:[1,0]
	ds_read_b128 v[132:135], v105 offset:19328
	s_waitcnt lgkmcnt(12)
	v_mfma_f32_16x16x32_bf16 v[70:73], v[172:175], v[60:63], 0
	v_mul_f32_e64 v68, v68, v64
	v_mul_f32_e64 v69, v69, v64
	v_mfma_f32_16x16x32_bf16 v[70:73], v[136:139], v[56:59], v[70:73]
	ds_read_b128 v[144:147], v105 offset:19392
	s_waitcnt lgkmcnt(12)
	v_mfma_f32_16x16x32_bf16 v[70:73], v[180:183], v[52:55], v[70:73]
	ds_read_b128 v[160:163], v105 offset:19456
	s_waitcnt lgkmcnt(12)
	v_mfma_f32_16x16x32_bf16 v[70:73], v[196:199], v[48:51], v[70:73]
	ds_read_b128 v[164:167], v105 offset:19520
	s_waitcnt lgkmcnt(12)
	v_mfma_f32_16x16x32_bf16 v[70:73], v[200:203], v[44:47], v[70:73]
	s_waitcnt lgkmcnt(11)
	v_mfma_f32_16x16x32_bf16 v[72:75], v[204:207], v[40:43], v[70:73]
	s_nop 7
	v_pk_mul_f32 v[70:71], v[74:75], v[64:65] op_sel_hi:[1,0]
	s_waitcnt lgkmcnt(10)
	v_mfma_f32_16x16x32_bf16 v[74:77], v[224:227], v[60:63], 0
	v_mul_f32_e64 v72, v72, v64
	v_mul_f32_e64 v73, v73, v64
	v_mfma_f32_16x16x32_bf16 v[74:77], v[140:143], v[56:59], v[74:77]
	s_waitcnt lgkmcnt(9)
	v_mfma_f32_16x16x32_bf16 v[74:77], v[228:231], v[52:55], v[74:77]
	s_waitcnt lgkmcnt(8)
	v_mfma_f32_16x16x32_bf16 v[74:77], v[232:235], v[48:51], v[74:77]
	s_waitcnt lgkmcnt(7)
	v_mfma_f32_16x16x32_bf16 v[74:77], v[236:239], v[44:47], v[74:77]
	s_waitcnt lgkmcnt(6)
	v_mfma_f32_16x16x32_bf16 v[76:79], v[240:243], v[40:43], v[74:77]
	s_nop 7
	v_pk_mul_f32 v[74:75], v[64:65], v[78:79] op_sel_hi:[0,1]
	s_waitcnt lgkmcnt(5)
	v_mfma_f32_16x16x32_bf16 v[60:63], v[244:247], v[60:63], 0
	v_pk_mul_f32 v[76:77], v[64:65], v[76:77] op_sel_hi:[0,1]
	s_waitcnt lgkmcnt(4)
	v_mfma_f32_16x16x32_bf16 v[56:59], v[128:131], v[56:59], v[60:63]
	s_waitcnt lgkmcnt(3)
	v_mfma_f32_16x16x32_bf16 v[52:55], v[132:135], v[52:55], v[56:59]
	s_waitcnt lgkmcnt(2)
	v_mfma_f32_16x16x32_bf16 v[48:51], v[144:147], v[48:51], v[52:55]
	s_waitcnt lgkmcnt(1)
	v_mfma_f32_16x16x32_bf16 v[44:47], v[160:163], v[44:47], v[48:51]
	v_cvt_pk_bf16_f32 v85, v68, v69
	v_cvt_pk_bf16_f32 v84, v66, v67
	s_waitcnt lgkmcnt(0)
	v_mfma_f32_16x16x32_bf16 v[40:43], v[164:167], v[40:43], v[44:47]
	s_nop 2
	v_mul_f32_e32 v44, v69, v69
	v_mul_f32_e32 v45, v67, v67
	v_fmac_f32_e32 v44, v68, v68
	v_fmac_f32_e32 v45, v66, v66
	v_add_f32_e32 v44, v44, v45
	v_mul_f32_e32 v45, v73, v73
	v_mul_f32_e32 v46, v71, v71
	v_fmac_f32_e32 v45, v72, v72
	v_fmac_f32_e32 v46, v70, v70
	v_add_f32_e32 v44, v108, v44
	v_add_f32_e32 v45, v45, v46
	v_add_f32_e32 v44, v45, v44
	v_mul_f32_e32 v45, v77, v77
	v_mul_f32_e32 v46, v75, v75
	v_fmac_f32_e32 v45, v76, v76
	v_fmac_f32_e32 v46, v74, v74
	v_pk_mul_f32 v[42:43], v[64:65], v[42:43] op_sel_hi:[0,1]
	v_pk_mul_f32 v[40:41], v[64:65], v[40:41] op_sel_hi:[0,1]
	v_add_f32_e32 v45, v45, v46
	v_add_f32_e32 v44, v45, v44
	v_mul_f32_e32 v45, v41, v41
	v_mul_f32_e32 v46, v43, v43
	v_fmac_f32_e32 v45, v40, v40
	v_fmac_f32_e32 v46, v42, v42
	v_add_f32_e32 v45, v45, v46
	v_cvt_pk_bf16_f32 v87, v72, v73
	v_cvt_pk_bf16_f32 v86, v70, v71
	v_cvt_pk_bf16_f32 v89, v76, v77
	v_cvt_pk_bf16_f32 v88, v74, v75
	v_add_f32_e32 v108, v44, v45
	v_cvt_pk_bf16_f32 v91, v40, v41
	v_cvt_pk_bf16_f32 v90, v42, v43
	v_mov_b32_e32 v109, s100
	s_waitcnt lgkmcnt(0)
	ds_read_b128 v[120:123], v107
	ds_read_b128 v[124:127], v107 offset:64
	ds_read_b128 v[128:131], v107 offset:576
	ds_read_b128 v[132:135], v107 offset:640
	ds_read_b128 v[136:139], v107 offset:4608
	ds_read_b128 v[140:143], v107 offset:4672
	ds_read_b128 v[144:147], v107 offset:5184
	ds_read_b128 v[160:163], v107 offset:5248
	ds_read_b128 v[164:167], v107 offset:9216
	ds_read_b128 v[168:171], v107 offset:9280
	ds_read_b128 v[172:175], v107 offset:9792
	ds_read_b128 v[180:183], v107 offset:9856
	ds_read_b128 v[196:199], v107 offset:13824
	ds_read_b128 v[200:203], v107 offset:13888
	s_waitcnt lgkmcnt(13)
	v_mfma_f32_16x16x32_bf16 v[40:43], v[120:123], v[36:39], v[28:31]

; #define LAS __attribute__((address_space(3)))
; #define LAS __attribute__((address_space(3)))
; __device__ __forceinline__ f32x4 mfma16(bf16x8 a, bf16x8 b, f32x4 c) { return __builtin_amdgcn_mfma_f32_16x16x32_bf16(a, b, c, 0, 0, 0); }
; template <int NKT, int VSTR, bool SINK>
; __device__ __forceinline__ void attn_core(LAS const unsigned char* kb_, LAS const unsigned char* vb_, bf16x8 q0, bf16x8 q1, float sk, unsigned mskbits, int fr, f32x4 (&o)[4]) {
;     ...
;     for (int kt = 0; kt < NKT; ++kt) {
;         const int key = (kt >> 1) * 32 + ((kt & 1) << 2) + krow;
;         LAS const unsigned char* kp = kb_ + key * 144;
;         const bf16x8 a0 = *(LAS const bf16x8*)kp, a1 = *(LAS const bf16x8*)(kp + 64);
;         const float bias = ((mskbits >> (kt >> 2)) & 1u) ? -1e30f : 0.f;
;         f32x4 s = mfma16(a0, q0, (f32x4){bias, bias, bias, bias});
;         s = mfma16(a1, q1, s);
;         S[kt] = s;
;     }
;     float mx = S[0][0];
; #pragma unroll
;     for (int kt = 0; kt < NKT; ++kt) mx = fmaxf(fmaxf(mx, fmaxf(S[kt][0], S[kt][1])), fmaxf(S[kt][2], S[kt][3]));
;     mx = fmaxf(mx, __shfl_xor(mx, 16)); mx = fmaxf(mx, __shfl_xor(mx, 32));
;     if (SINK) mx = fmaxf(mx, sk);
;     float sum = 0.f;
; #pragma unroll
;     for (int kt = 0; kt < NKT; ++kt)
; #pragma unroll
;         for (int r = 0; r < 4; ++r) { const float p = __builtin_amdgcn_exp2f(S[kt][r] - mx); S[kt][r] = p; sum += p; }
	v_mul_f32_e32 v118, 0x3fb8aa3b, v109
	s_waitcnt lgkmcnt(12)
	v_mfma_f32_16x16x32_bf16 v[80:83], v[124:127], v[32:35], v[40:43]
	ds_read_b128 v[204:207], v107 offset:14400
	ds_read_b128 v[224:227], v107 offset:14464
	s_waitcnt lgkmcnt(13)
	v_mfma_f32_16x16x32_bf16 v[40:43], v[128:131], v[36:39], v[28:31]
	s_waitcnt lgkmcnt(12)
	v_mfma_f32_16x16x32_bf16 v[76:79], v[132:135], v[32:35], v[40:43]
	ds_read_b128 v[228:231], v107 offset:18432
	ds_read_b128 v[232:235], v107 offset:18496
	s_waitcnt lgkmcnt(13)
	v_mfma_f32_16x16x32_bf16 v[40:43], v[136:139], v[36:39], v[28:31]
	s_waitcnt lgkmcnt(12)
	v_mfma_f32_16x16x32_bf16 v[72:75], v[140:143], v[32:35], v[40:43]
	ds_read_b128 v[236:239], v107 offset:19008
	ds_read_b128 v[240:243], v107 offset:19072
	s_waitcnt lgkmcnt(13)
	v_mfma_f32_16x16x32_bf16 v[40:43], v[144:147], v[36:39], v[28:31]
	s_waitcnt lgkmcnt(12)
	v_mfma_f32_16x16x32_bf16 v[68:71], v[160:163], v[32:35], v[40:43]
	ds_read_b128 v[244:247], v107 offset:23040
	ds_read_b128 v[120:123], v107 offset:23104
	s_waitcnt lgkmcnt(13)
	v_mfma_f32_16x16x32_bf16 v[40:43], v[164:167], v[36:39], v[24:27]
	s_waitcnt lgkmcnt(12)
	v_mfma_f32_16x16x32_bf16 v[64:67], v[168:171], v[32:35], v[40:43]
	ds_read_b128 v[124:127], v107 offset:23616
	ds_read_b128 v[128:131], v107 offset:23680
	s_waitcnt lgkmcnt(13)
	v_mfma_f32_16x16x32_bf16 v[40:43], v[172:175], v[36:39], v[24:27]
	s_waitcnt lgkmcnt(12)
	v_mfma_f32_16x16x32_bf16 v[60:63], v[180:183], v[32:35], v[40:43]
	s_waitcnt lgkmcnt(11)
	v_mfma_f32_16x16x32_bf16 v[40:43], v[196:199], v[36:39], v[24:27]
	s_waitcnt lgkmcnt(10)
	v_mfma_f32_16x16x32_bf16 v[56:59], v[200:203], v[32:35], v[40:43]
	s_waitcnt lgkmcnt(9)
	v_mfma_f32_16x16x32_bf16 v[40:43], v[204:207], v[36:39], v[24:27]
	s_waitcnt lgkmcnt(8)
	v_mfma_f32_16x16x32_bf16 v[52:55], v[224:227], v[32:35], v[40:43]
	s_waitcnt lgkmcnt(7)
	v_mfma_f32_16x16x32_bf16 v[40:43], v[228:231], v[36:39], 0
	s_waitcnt lgkmcnt(6)
	v_mfma_f32_16x16x32_bf16 v[48:51], v[232:235], v[32:35], v[40:43]
	s_waitcnt lgkmcnt(5)
	v_mfma_f32_16x16x32_bf16 v[40:43], v[236:239], v[36:39], 0
	s_waitcnt lgkmcnt(4)
	v_mfma_f32_16x16x32_bf16 v[44:47], v[240:243], v[32:35], v[40:43]
	s_waitcnt lgkmcnt(3)
	v_mfma_f32_16x16x32_bf16 v[40:43], v[244:247], v[36:39], 0
	s_waitcnt lgkmcnt(2)
	v_mfma_f32_16x16x32_bf16 v[40:43], v[120:123], v[32:35], v[40:43]
	s_waitcnt lgkmcnt(1)
	v_mfma_f32_16x16x32_bf16 v[36:39], v[124:127], v[36:39], 0
	s_waitcnt lgkmcnt(0)
	v_mfma_f32_16x16x32_bf16 v[32:35], v[128:131], v[32:35], v[36:39]
	s_nop 5
	s_nop 0
	s_nop 0
	v_max_f32_e32 v36, v82, v83
	s_nop 0
	s_nop 0
	v_max_f32_e32 v37, v76, v77
	s_nop 0
	s_nop 0
	v_max3_f32 v36, v80, v81, v36
	v_max_f32_e32 v38, v78, v79
	v_max3_f32 v36, v36, v37, v38
	s_nop 0
	s_nop 0
	v_max_f32_e32 v37, v72, v73
	s_nop 0
	s_nop 0
	v_max_f32_e32 v38, v74, v75
	v_max3_f32 v36, v36, v37, v38
	s_nop 0
	s_nop 0
	v_max_f32_e32 v37, v68, v69
	s_nop 0
	s_nop 0
	v_max_f32_e32 v38, v70, v71
	v_max3_f32 v36, v36, v37, v38
	v_max_f32_e32 v37, v64, v65
	v_max_f32_e32 v38, v66, v67
	v_max3_f32 v36, v36, v37, v38
	v_max_f32_e32 v37, v60, v61
	v_max_f32_e32 v38, v62, v63
	v_max3_f32 v36, v36, v37, v38
	v_max_f32_e32 v37, v56, v57
	v_max_f32_e32 v38, v58, v59
	v_max3_f32 v36, v36, v37, v38
	v_max_f32_e32 v37, v52, v53
	v_max_f32_e32 v38, v54, v55
	v_max3_f32 v36, v36, v37, v38
	v_max_f32_e32 v37, v48, v49
	v_max_f32_e32 v38, v50, v51
	v_max3_f32 v36, v36, v37, v38
	v_max_f32_e32 v37, v44, v45
	v_max_f32_e32 v38, v46, v47
	v_max3_f32 v36, v36, v37, v38
	v_max_f32_e32 v37, v40, v41
	v_max_f32_e32 v38, v42, v43
	v_max3_f32 v36, v36, v37, v38
	v_max_f32_e32 v37, v32, v33
	v_max_f32_e32 v38, v34, v35
	v_max3_f32 v36, v36, v37, v38
	ds_bpermute_b32 v37, v212, v36
	s_waitcnt lgkmcnt(0)
	s_nop 0
	v_max_f32_e32 v36, v36, v37
	ds_bpermute_b32 v37, v176, v36
	s_waitcnt lgkmcnt(0)
	v_max3_f32 v36, v36, v37, v118
	v_sub_f32_e32 v37, v80, v36
	v_exp_f32_e32 v37, v37
	v_sub_f32_e32 v39, v81, v36
	v_exp_f32_e32 v39, v39
	v_sub_f32_e32 v80, v82, v36
	v_exp_f32_e32 v80, v80
	v_sub_f32_e32 v81, v83, v36
	v_exp_f32_e32 v81, v81
	v_sub_f32_e32 v76, v76, v36
	v_add_f32_e32 v38, 0, v37
	v_exp_f32_e32 v76, v76
	v_sub_f32_e32 v77, v77, v36
	v_add_f32_e32 v38, v39, v38
	v_exp_f32_e32 v77, v77
	v_sub_f32_e32 v78, v78, v36
	v_add_f32_e32 v38, v80, v38
	v_exp_f32_e32 v78, v78
	v_sub_f32_e32 v79, v79, v36
	v_add_f32_e32 v38, v81, v38
	v_exp_f32_e32 v79, v79
	v_sub_f32_e32 v72, v72, v36
	v_add_f32_e32 v38, v76, v38
	v_exp_f32_e32 v72, v72
	v_sub_f32_e32 v73, v73, v36
	v_add_f32_e32 v38, v77, v38
	v_exp_f32_e32 v73, v73
	v_sub_f32_e32 v74, v74, v36
	v_add_f32_e32 v38, v78, v38
	v_exp_f32_e32 v74, v74
	v_sub_f32_e32 v75, v75, v36
	v_add_f32_e32 v38, v79, v38
	v_exp_f32_e32 v75, v75
	v_sub_f32_e32 v68, v68, v36
	v_add_f32_e32 v38, v72, v38
	v_exp_f32_e32 v68, v68
	v_sub_f32_e32 v69, v69, v36
	v_add_f32_e32 v38, v73, v38
	v_exp_f32_e32 v69, v69
	v_sub_f32_e32 v70, v70, v36
	v_add_f32_e32 v38, v74, v38
	v_exp_f32_e32 v70, v70
	v_sub_f32_e32 v71, v71, v36
	v_add_f32_e32 v38, v75, v38
	v_exp_f32_e32 v71, v71
	v_sub_f32_e32 v64, v64, v36
	v_add_f32_e32 v38, v68, v38
	v_exp_f32_e32 v64, v64
	v_sub_f32_e32 v65, v65, v36
	v_add_f32_e32 v38, v69, v38
	v_exp_f32_e32 v65, v65
	v_sub_f32_e32 v66, v66, v36
	v_add_f32_e32 v38, v70, v38
	v_exp_f32_e32 v66, v66
	v_sub_f32_e32 v67, v67, v36
	v_add_f32_e32 v38, v71, v38
	v_exp_f32_e32 v67, v67
	v_sub_f32_e32 v60, v60, v36
	v_add_f32_e32 v38, v64, v38
	v_exp_f32_e32 v60, v60
	v_sub_f32_e32 v61, v61, v36
	v_add_f32_e32 v38, v65, v38
	v_exp_f32_e32 v61, v61
	v_sub_f32_e32 v62, v62, v36
	v_add_f32_e32 v38, v66, v38
	v_exp_f32_e32 v62, v62
; #define LAS __attribute__((address_space(3)))
; #define LAS __attribute__((address_space(3)))
; __device__ __forceinline__ unsigned pk2(float lo, float hi) { return pg8::cvt_pk_bf16(lo, hi); }
; __device__ __forceinline__ f32x4 mfma16(bf16x8 a, bf16x8 b, f32x4 c) { return __builtin_amdgcn_mfma_f32_16x16x32_bf16(a, b, c, 0, 0, 0); }
; template <int NKT, int VSTR, bool SINK>
; __device__ __forceinline__ void attn_core(LAS const unsigned char* kb_, LAS const unsigned char* vb_, bf16x8 q0, bf16x8 q1, float sk, unsigned mskbits, int fr, f32x4 (&o)[4]) {
;     ...
; #pragma unroll
;     for (int kt = 0; kt < NKT; ++kt)
; #pragma unroll
;         for (int r = 0; r < 4; ++r) { const float p = __builtin_amdgcn_exp2f(S[kt][r] - mx); S[kt][r] = p; sum += p; }
;     sum += __shfl_xor(sum, 16); sum += __shfl_xor(sum, 32);
;     if (SINK) sum += __builtin_amdgcn_exp2f(sk - mx);
;     const float inv = 1.0f / sum;
;     bf16x8 pf[NKT / 2];
; #pragma unroll
;     for (int kb = 0; kb < NKT / 2; ++kb) {
;         v4u w; w.x = pk2(S[2 * kb][0], S[2 * kb][1]); w.y = pk2(S[2 * kb][2], S[2 * kb][3]); w.z = pk2(S[2 * kb + 1][0], S[2 * kb + 1][1]); w.w = pk2(S[2 * kb + 1][2], S[2 * kb + 1][3]);
;         pf[kb] = __builtin_bit_cast(bf16x8, w);
;     }
; #pragma unroll
;     for (int dt = 0; dt < 4; ++dt) {
;         f32x4 acc = (f32x4){0.f, 0.f, 0.f, 0.f};
; #pragma unroll
;         for (int kb = 0; kb < NKT / 2; ++kb) {
;             const bf16x8 vf = *(LAS const bf16x8*)(vb_ + dt * 16 * VSTR + kb * 64);
;             acc = mfma16(vf, pf[kb], acc);
;         }
;         o[dt] = acc * inv;
	v_sub_f32_e32 v63, v63, v36
	v_add_f32_e32 v38, v67, v38
	v_exp_f32_e32 v63, v63
	v_sub_f32_e32 v56, v56, v36
	v_add_f32_e32 v38, v60, v38
	v_exp_f32_e32 v56, v56
	v_sub_f32_e32 v57, v57, v36
	v_add_f32_e32 v38, v61, v38
	v_exp_f32_e32 v57, v57
	v_sub_f32_e32 v58, v58, v36
	v_add_f32_e32 v38, v62, v38
	v_exp_f32_e32 v58, v58
	v_sub_f32_e32 v59, v59, v36
	v_add_f32_e32 v38, v63, v38
	v_exp_f32_e32 v59, v59
	v_sub_f32_e32 v52, v52, v36
	v_add_f32_e32 v38, v56, v38
	v_exp_f32_e32 v82, v52
	v_sub_f32_e32 v52, v53, v36
	v_add_f32_e32 v38, v57, v38
	v_exp_f32_e32 v83, v52
	v_sub_f32_e32 v52, v54, v36
	v_add_f32_e32 v38, v58, v38
	v_exp_f32_e32 v110, v52
	v_sub_f32_e32 v52, v55, v36
	v_add_f32_e32 v38, v59, v38
	v_exp_f32_e32 v111, v52
	v_sub_f32_e32 v48, v48, v36
	v_add_f32_e32 v38, v82, v38
	v_exp_f32_e32 v112, v48
	v_sub_f32_e32 v48, v49, v36
	v_add_f32_e32 v38, v83, v38
	v_exp_f32_e32 v113, v48
	v_sub_f32_e32 v48, v50, v36
	v_add_f32_e32 v38, v110, v38
	v_exp_f32_e32 v114, v48
	v_sub_f32_e32 v48, v51, v36
	v_add_f32_e32 v38, v111, v38
	v_exp_f32_e32 v115, v48
	v_sub_f32_e32 v44, v44, v36
	v_add_f32_e32 v38, v112, v38
	v_exp_f32_e32 v116, v44
	v_sub_f32_e32 v44, v45, v36
	v_add_f32_e32 v38, v113, v38
	v_exp_f32_e32 v117, v44
	v_sub_f32_e32 v44, v46, v36
	v_add_f32_e32 v38, v114, v38
	v_exp_f32_e32 v118, v44
	v_sub_f32_e32 v44, v47, v36
	v_add_f32_e32 v38, v115, v38
	v_exp_f32_e32 v119, v44
	v_sub_f32_e32 v40, v40, v36
	v_add_f32_e32 v38, v116, v38
	v_exp_f32_e32 v120, v40
	v_sub_f32_e32 v40, v41, v36
	v_add_f32_e32 v38, v117, v38
	v_exp_f32_e32 v121, v40
	v_sub_f32_e32 v40, v42, v36
	v_add_f32_e32 v38, v118, v38
	v_exp_f32_e32 v122, v40
	v_sub_f32_e32 v40, v43, v36
	v_add_f32_e32 v38, v119, v38
	v_exp_f32_e32 v123, v40
	v_sub_f32_e32 v32, v32, v36
	v_add_f32_e32 v38, v120, v38
	v_exp_f32_e32 v124, v32
	v_sub_f32_e32 v33, v33, v36
	v_add_f32_e32 v38, v121, v38
	v_exp_f32_e32 v125, v33
	v_sub_f32_e32 v33, v34, v36
	v_add_f32_e32 v38, v122, v38
	v_exp_f32_e32 v126, v33
	v_sub_f32_e32 v33, v35, v36
	v_add_f32_e32 v38, v123, v38
	v_exp_f32_e32 v35, v33
	v_add_f32_e32 v32, v124, v38
	v_add_f32_e32 v32, v125, v32
	v_add_f32_e32 v32, v126, v32
	v_add_f32_e32 v32, v35, v32
	ds_bpermute_b32 v33, v212, v32
	v_cvt_pk_bf16_f32 v52, v37, v39
	v_cvt_pk_bf16_f32 v53, v80, v81
	v_cvt_pk_bf16_f32 v54, v76, v77
	v_cvt_pk_bf16_f32 v55, v78, v79
	s_waitcnt lgkmcnt(0)
	v_add_f32_e32 v32, v32, v33
	ds_bpermute_b32 v33, v176, v32
	v_cvt_pk_bf16_f32 v48, v72, v73
	v_cvt_pk_bf16_f32 v49, v74, v75
	v_cvt_pk_bf16_f32 v50, v68, v69
	v_cvt_pk_bf16_f32 v51, v70, v71
	s_waitcnt lgkmcnt(0)
	v_add_f32_e32 v32, v32, v33
	v_fma_f32 v33, v109, s2, -v36
	v_exp_f32_e32 v33, v33
	v_cvt_pk_bf16_f32 v44, v64, v65
	v_cvt_pk_bf16_f32 v45, v66, v67
	v_cvt_pk_bf16_f32 v46, v60, v61
	v_cvt_pk_bf16_f32 v47, v62, v63
	v_cvt_pk_bf16_f32 v40, v56, v57
	s_nop 0
	v_add_f32_e32 v109, v33, v32
	v_div_scale_f32 v56, s[0:1], v109, v109, 1.0
	v_rcp_f32_e32 v57, v56
	v_cvt_pk_bf16_f32 v41, v58, v59
	v_cvt_pk_bf16_f32 v42, v82, v83
	v_cvt_pk_bf16_f32 v43, v110, v111
	v_cvt_pk_bf16_f32 v36, v112, v113
	v_cvt_pk_bf16_f32 v37, v114, v115
	s_nop 0
	v_fma_f32 v58, -v56, v57, 1.0
	v_fmac_f32_e32 v57, v58, v57
	v_div_scale_f32 v58, vcc, 1.0, v109, 1.0
	v_mul_f32_e32 v59, v58, v57
	v_fma_f32 v60, -v56, v59, v58
	v_fmac_f32_e32 v59, v60, v57
	v_fma_f32 v56, -v56, v59, v58
	v_cvt_pk_bf16_f32 v38, v116, v117
	v_cvt_pk_bf16_f32 v39, v118, v119
	v_cvt_pk_bf16_f32 v32, v120, v121
	v_cvt_pk_bf16_f32 v33, v122, v123
	v_cvt_pk_bf16_f32 v34, v124, v125
	v_cvt_pk_bf16_f32 v35, v126, v35
	v_div_fmas_f32 v56, v56, v57, v59
	s_waitcnt lgkmcnt(0)
	ds_read_b128 v[76:79], v106 offset:55296
	ds_read_b128 v[128:131], v106 offset:55360
	ds_read_b128 v[132:135], v106 offset:61760
	ds_read_b128 v[136:139], v105 offset:12864
	ds_read_b128 v[140:143], v106 offset:55424
	ds_read_b128 v[144:147], v106 offset:55488
	ds_read_b128 v[160:163], v106 offset:55552
	ds_read_b128 v[164:167], v106 offset:55616
	ds_read_b128 v[168:171], v106 offset:61696
	ds_read_b128 v[172:175], v106 offset:61824
	ds_read_b128 v[180:183], v106 offset:61888
	ds_read_b128 v[196:199], v106 offset:61952
	ds_read_b128 v[200:203], v106 offset:62016
	ds_read_b128 v[204:207], v105 offset:12800
	s_waitcnt lgkmcnt(13)
	v_mfma_f32_16x16x32_bf16 v[58:61], v[76:79], v[52:55], 0
	ds_read_b128 v[224:227], v105 offset:12928
	v_div_fixup_f32 v56, v56, v109, 1.0
	s_waitcnt lgkmcnt(13)
	v_mfma_f32_16x16x32_bf16 v[58:61], v[128:131], v[48:51], v[58:61]
	ds_read_b128 v[228:231], v105 offset:12992
	s_waitcnt lgkmcnt(11)
; #define LAS __attribute__((address_space(3)))
; __device__ __forceinline__ float sq4(const f32x4 a) { return (a[0] * a[0] + a[1] * a[1]) + (a[2] * a[2] + a[3] * a[3]); }
; #define LAS __attribute__((address_space(3)))
; __device__ __forceinline__ unsigned pk2(float lo, float hi) { return pg8::cvt_pk_bf16(lo, hi); }
; __device__ __forceinline__ f32x4 mfma16(bf16x8 a, bf16x8 b, f32x4 c) { return __builtin_amdgcn_mfma_f32_16x16x32_bf16(a, b, c, 0, 0, 0); }
; template <int NKT, int VSTR, bool SINK>
; __device__ __forceinline__ void attn_core(LAS const unsigned char* kb_, LAS const unsigned char* vb_, bf16x8 q0, bf16x8 q1, float sk, unsigned mskbits, int fr, f32x4 (&o)[4]) {
;     ...
; #pragma unroll
;     for (int dt = 0; dt < 4; ++dt) {
;         f32x4 acc = (f32x4){0.f, 0.f, 0.f, 0.f};
; #pragma unroll
;         for (int kb = 0; kb < NKT / 2; ++kb) {
;             const bf16x8 vf = *(LAS const bf16x8*)(vb_ + dt * 16 * VSTR + kb * 64);
;             acc = mfma16(vf, pf[kb], acc);
;         }
;         o[dt] = acc * inv;
;     }
; template <bool DO_SWA, bool DO_MEM>
; __device__ __forceinline__ void attn_unit(const Args& a, unsigned char* ws, LAS unsigned char* lds, int l, int tid_in, int lane_in, int wave, int unit) {
;     ...
;                 attn_core<12, 400, true>(lds + A_KS + g * 192 * 144 + fq * 16, lds + A_VT1 + (g * 64 + fr) * 400 + fq * 16, qsw[hh][0], qsw[hh][1], sk, mskbits, fr, o);
; #pragma unroll
;                 for (int dt = 0; dt < 4; ++dt) { ssq += pg8::sq4(o[dt]); osv[hh][dt] = (v2u){pk2(o[dt][0], o[dt][1]), pk2(o[dt][2], o[dt][3])}; }
;             }
	v_mfma_f32_16x16x32_bf16 v[58:61], v[140:143], v[44:47], v[58:61]
	ds_read_b128 v[232:235], v105 offset:13056
	ds_read_b128 v[236:239], v105 offset:13120
	s_waitcnt lgkmcnt(12)
	v_mfma_f32_16x16x32_bf16 v[58:61], v[144:147], v[40:43], v[58:61]
	ds_read_b128 v[240:243], v105 offset:19200
	s_waitcnt lgkmcnt(12)
	v_mfma_f32_16x16x32_bf16 v[58:61], v[160:163], v[36:39], v[58:61]
	ds_read_b128 v[244:247], v105 offset:19264
	s_waitcnt lgkmcnt(12)
	v_mfma_f32_16x16x32_bf16 v[60:63], v[164:167], v[32:35], v[58:61]
	s_nop 7
	v_pk_mul_f32 v[58:59], v[62:63], v[56:57] op_sel_hi:[1,0]
	ds_read_b128 v[76:79], v105 offset:19328
	s_waitcnt lgkmcnt(12)
	v_mfma_f32_16x16x32_bf16 v[62:65], v[168:171], v[52:55], 0
	v_mul_f32_e64 v60, v60, v56
	v_mul_f32_e64 v61, v61, v56
	v_mfma_f32_16x16x32_bf16 v[62:65], v[132:135], v[48:51], v[62:65]
	ds_read_b128 v[128:131], v105 offset:19392
	s_waitcnt lgkmcnt(12)
	v_mfma_f32_16x16x32_bf16 v[62:65], v[172:175], v[44:47], v[62:65]
	ds_read_b128 v[140:143], v105 offset:19456
	s_waitcnt lgkmcnt(12)
	v_mfma_f32_16x16x32_bf16 v[62:65], v[180:183], v[40:43], v[62:65]
	ds_read_b128 v[144:147], v105 offset:19520
	s_waitcnt lgkmcnt(12)
	v_mfma_f32_16x16x32_bf16 v[62:65], v[196:199], v[36:39], v[62:65]
	s_waitcnt lgkmcnt(11)
	v_mfma_f32_16x16x32_bf16 v[64:67], v[200:203], v[32:35], v[62:65]
	s_nop 7
	v_pk_mul_f32 v[62:63], v[66:67], v[56:57] op_sel_hi:[1,0]
	s_waitcnt lgkmcnt(10)
	v_mfma_f32_16x16x32_bf16 v[66:69], v[204:207], v[52:55], 0
	v_mul_f32_e64 v64, v64, v56
	v_mul_f32_e64 v65, v65, v56
	v_mfma_f32_16x16x32_bf16 v[66:69], v[136:139], v[48:51], v[66:69]
	s_waitcnt lgkmcnt(9)
	v_mfma_f32_16x16x32_bf16 v[66:69], v[224:227], v[44:47], v[66:69]
	s_waitcnt lgkmcnt(8)
	v_mfma_f32_16x16x32_bf16 v[66:69], v[228:231], v[40:43], v[66:69]
	s_waitcnt lgkmcnt(7)
	v_mfma_f32_16x16x32_bf16 v[66:69], v[232:235], v[36:39], v[66:69]
	s_waitcnt lgkmcnt(6)
	v_mfma_f32_16x16x32_bf16 v[68:71], v[236:239], v[32:35], v[66:69]
	s_nop 7
	v_pk_mul_f32 v[66:67], v[56:57], v[70:71] op_sel_hi:[0,1]
	s_waitcnt lgkmcnt(5)
	v_mfma_f32_16x16x32_bf16 v[52:55], v[240:243], v[52:55], 0
	v_pk_mul_f32 v[68:69], v[56:57], v[68:69] op_sel_hi:[0,1]
	s_waitcnt lgkmcnt(4)
	v_mfma_f32_16x16x32_bf16 v[48:51], v[244:247], v[48:51], v[52:55]
	s_waitcnt lgkmcnt(3)
	v_mfma_f32_16x16x32_bf16 v[44:47], v[76:79], v[44:47], v[48:51]
	s_waitcnt lgkmcnt(2)
	v_mfma_f32_16x16x32_bf16 v[40:43], v[128:131], v[40:43], v[44:47]
	s_waitcnt lgkmcnt(1)
	v_mfma_f32_16x16x32_bf16 v[36:39], v[140:143], v[36:39], v[40:43]
	v_cvt_pk_bf16_f32 v81, v60, v61
	v_cvt_pk_bf16_f32 v80, v58, v59
	s_waitcnt lgkmcnt(0)
	v_mfma_f32_16x16x32_bf16 v[32:35], v[144:147], v[32:35], v[36:39]
	s_nop 2
	v_mul_f32_e32 v36, v61, v61
	v_mul_f32_e32 v37, v59, v59
	v_fmac_f32_e32 v36, v60, v60
	v_fmac_f32_e32 v37, v58, v58
	v_add_f32_e32 v36, v36, v37
	v_mul_f32_e32 v37, v65, v65
	v_mul_f32_e32 v38, v63, v63
	v_fmac_f32_e32 v37, v64, v64
	v_fmac_f32_e32 v38, v62, v62
	v_add_f32_e32 v36, v108, v36
	v_add_f32_e32 v37, v37, v38
	v_add_f32_e32 v36, v37, v36
	v_mul_f32_e32 v37, v69, v69
	v_mul_f32_e32 v38, v67, v67
	v_fmac_f32_e32 v37, v68, v68
	v_fmac_f32_e32 v38, v66, v66
	v_pk_mul_f32 v[34:35], v[56:57], v[34:35] op_sel_hi:[0,1]
	v_pk_mul_f32 v[32:33], v[56:57], v[32:33] op_sel_hi:[0,1]
	v_add_f32_e32 v37, v37, v38
	v_add_f32_e32 v36, v37, v36
	v_mul_f32_e32 v37, v33, v33
	v_mul_f32_e32 v38, v35, v35
	v_fmac_f32_e32 v37, v32, v32
	v_fmac_f32_e32 v38, v34, v34
	v_add_f32_e32 v37, v37, v38
	v_cvt_pk_bf16_f32 v83, v64, v65
	v_cvt_pk_bf16_f32 v82, v62, v63
	v_cvt_pk_bf16_f32 v109, v68, v69
	v_cvt_pk_bf16_f32 v108, v66, v67
	v_add_f32_e32 v68, v36, v37
	v_cvt_pk_bf16_f32 v111, v32, v33
	v_cvt_pk_bf16_f32 v110, v34, v35
	v_mov_b32_e32 v69, s101
	s_waitcnt lgkmcnt(0)
	ds_read_b128 v[112:115], v107
	ds_read_b128 v[116:119], v107 offset:64
	ds_read_b128 v[120:123], v107 offset:576
	ds_read_b128 v[124:127], v107 offset:640
	ds_read_b128 v[128:131], v107 offset:4608
	ds_read_b128 v[132:135], v107 offset:4672
	ds_read_b128 v[136:139], v107 offset:5184
	ds_read_b128 v[140:143], v107 offset:5248
	ds_read_b128 v[144:147], v107 offset:9216
	ds_read_b128 v[160:163], v107 offset:9280
	ds_read_b128 v[164:167], v107 offset:9792
	ds_read_b128 v[168:171], v107 offset:9856
	ds_read_b128 v[172:175], v107 offset:13824
	ds_read_b128 v[180:183], v107 offset:13888
	s_waitcnt lgkmcnt(13)
	v_mfma_f32_16x16x32_bf16 v[32:35], v[112:115], v[20:23], v[28:31]

; #define LAS __attribute__((address_space(3)))
; #define LAS __attribute__((address_space(3)))
; __device__ __forceinline__ f32x4 mfma16(bf16x8 a, bf16x8 b, f32x4 c) { return __builtin_amdgcn_mfma_f32_16x16x32_bf16(a, b, c, 0, 0, 0); }
; template <int NKT, int VSTR, bool SINK>
; __device__ __forceinline__ void attn_core(LAS const unsigned char* kb_, LAS const unsigned char* vb_, bf16x8 q0, bf16x8 q1, float sk, unsigned mskbits, int fr, f32x4 (&o)[4]) {
;     ...
;     for (int kt = 0; kt < NKT; ++kt) {
;         const int key = (kt >> 1) * 32 + ((kt & 1) << 2) + krow;
;         LAS const unsigned char* kp = kb_ + key * 144;
;         const bf16x8 a0 = *(LAS const bf16x8*)kp, a1 = *(LAS const bf16x8*)(kp + 64);
;         const float bias = ((mskbits >> (kt >> 2)) & 1u) ? -1e30f : 0.f;
;         f32x4 s = mfma16(a0, q0, (f32x4){bias, bias, bias, bias});
;         s = mfma16(a1, q1, s);
;         S[kt] = s;
;     }
;     float mx = S[0][0];
; #pragma unroll
;     for (int kt = 0; kt < NKT; ++kt) mx = fmaxf(fmaxf(mx, fmaxf(S[kt][0], S[kt][1])), fmaxf(S[kt][2], S[kt][3]));
;     mx = fmaxf(mx, __shfl_xor(mx, 16)); mx = fmaxf(mx, __shfl_xor(mx, 32));
;     if (SINK) mx = fmaxf(mx, sk);
;     float sum = 0.f;
; #pragma unroll
;     for (int kt = 0; kt < NKT; ++kt)
; #pragma unroll
;         for (int r = 0; r < 4; ++r) { const float p = __builtin_amdgcn_exp2f(S[kt][r] - mx); S[kt][r] = p; sum += p; }
	v_mul_f32_e32 v70, 0x3fb8aa3b, v69
	s_waitcnt lgkmcnt(12)
	v_mfma_f32_16x16x32_bf16 v[52:55], v[116:119], v[16:19], v[32:35]
	ds_read_b128 v[196:199], v107 offset:14400
	ds_read_b128 v[200:203], v107 offset:14464
	s_waitcnt lgkmcnt(13)
	v_mfma_f32_16x16x32_bf16 v[32:35], v[120:123], v[20:23], v[28:31]
	s_waitcnt lgkmcnt(12)
	v_mfma_f32_16x16x32_bf16 v[48:51], v[124:127], v[16:19], v[32:35]
	ds_read_b128 v[204:207], v107 offset:18432
	ds_read_b128 v[224:227], v107 offset:18496
	s_waitcnt lgkmcnt(13)
	v_mfma_f32_16x16x32_bf16 v[32:35], v[128:131], v[20:23], v[28:31]
	s_waitcnt lgkmcnt(12)
	v_mfma_f32_16x16x32_bf16 v[40:43], v[132:135], v[16:19], v[32:35]
	ds_read_b128 v[228:231], v107 offset:19008
	ds_read_b128 v[232:235], v107 offset:19072
	s_waitcnt lgkmcnt(13)
	v_mfma_f32_16x16x32_bf16 v[28:31], v[136:139], v[20:23], v[28:31]
	s_waitcnt lgkmcnt(12)
	v_mfma_f32_16x16x32_bf16 v[32:35], v[140:143], v[16:19], v[28:31]
	ds_read_b128 v[236:239], v107 offset:23040
	ds_read_b128 v[240:243], v107 offset:23104
	s_waitcnt lgkmcnt(13)
	v_mfma_f32_16x16x32_bf16 v[28:31], v[144:147], v[20:23], v[24:27]
	s_waitcnt lgkmcnt(12)
	v_mfma_f32_16x16x32_bf16 v[28:31], v[160:163], v[16:19], v[28:31]
	ds_read_b128 v[244:247], v107 offset:23616
	ds_read_b128 v[112:115], v107 offset:23680
	s_waitcnt lgkmcnt(13)
	v_mfma_f32_16x16x32_bf16 v[36:39], v[164:167], v[20:23], v[24:27]
	s_waitcnt lgkmcnt(12)
	v_mfma_f32_16x16x32_bf16 v[36:39], v[168:171], v[16:19], v[36:39]
	s_waitcnt lgkmcnt(11)
	v_mfma_f32_16x16x32_bf16 v[44:47], v[172:175], v[20:23], v[24:27]
	s_waitcnt lgkmcnt(10)
	v_mfma_f32_16x16x32_bf16 v[44:47], v[180:183], v[16:19], v[44:47]
	s_waitcnt lgkmcnt(9)
	v_mfma_f32_16x16x32_bf16 v[24:27], v[196:199], v[20:23], v[24:27]
	s_waitcnt lgkmcnt(8)
	v_mfma_f32_16x16x32_bf16 v[24:27], v[200:203], v[16:19], v[24:27]
	s_waitcnt lgkmcnt(7)
	v_mfma_f32_16x16x32_bf16 v[56:59], v[204:207], v[20:23], 0
	s_waitcnt lgkmcnt(6)
	v_mfma_f32_16x16x32_bf16 v[56:59], v[224:227], v[16:19], v[56:59]
	s_waitcnt lgkmcnt(5)
	v_mfma_f32_16x16x32_bf16 v[60:63], v[228:231], v[20:23], 0
	s_waitcnt lgkmcnt(4)
	v_mfma_f32_16x16x32_bf16 v[60:63], v[232:235], v[16:19], v[60:63]
	s_waitcnt lgkmcnt(3)
	v_mfma_f32_16x16x32_bf16 v[64:67], v[236:239], v[20:23], 0
	s_waitcnt lgkmcnt(2)
	v_mfma_f32_16x16x32_bf16 v[64:67], v[240:243], v[16:19], v[64:67]
	s_waitcnt lgkmcnt(1)
	v_mfma_f32_16x16x32_bf16 v[20:23], v[244:247], v[20:23], 0
	s_waitcnt lgkmcnt(0)
	v_mfma_f32_16x16x32_bf16 v[16:19], v[112:115], v[16:19], v[20:23]
	s_nop 5
	s_nop 0
	s_nop 0
	v_max_f32_e32 v20, v54, v55
	s_nop 0
	s_nop 0
	v_max_f32_e32 v21, v48, v49
	s_nop 0
	s_nop 0
	v_max3_f32 v20, v52, v53, v20
	v_max_f32_e32 v22, v50, v51
	v_max3_f32 v20, v20, v21, v22
	s_nop 0
	s_nop 0
	v_max_f32_e32 v21, v40, v41
	s_nop 0
	s_nop 0
	v_max_f32_e32 v22, v42, v43
	v_max3_f32 v20, v20, v21, v22
	s_nop 0
	s_nop 0
	v_max_f32_e32 v21, v32, v33
	s_nop 0
	s_nop 0
	v_max_f32_e32 v22, v34, v35
	v_max3_f32 v20, v20, v21, v22
	v_max_f32_e32 v21, v28, v29
	v_max_f32_e32 v22, v30, v31
	v_max3_f32 v20, v20, v21, v22
	v_max_f32_e32 v21, v36, v37
	v_max_f32_e32 v22, v38, v39
	v_max3_f32 v20, v20, v21, v22
	v_max_f32_e32 v21, v44, v45
	v_max_f32_e32 v22, v46, v47
	v_max3_f32 v20, v20, v21, v22
	v_max_f32_e32 v21, v24, v25
	v_max_f32_e32 v22, v26, v27
	v_max3_f32 v20, v20, v21, v22
	v_max_f32_e32 v21, v56, v57
	v_max_f32_e32 v22, v58, v59
	v_max3_f32 v20, v20, v21, v22
	v_max_f32_e32 v21, v60, v61
	v_max_f32_e32 v22, v62, v63
	v_max3_f32 v20, v20, v21, v22
	v_max_f32_e32 v21, v64, v65
	v_max_f32_e32 v22, v66, v67
	v_max3_f32 v20, v20, v21, v22
	v_max_f32_e32 v21, v16, v17
	v_max_f32_e32 v22, v18, v19
	v_max3_f32 v20, v20, v21, v22
	ds_bpermute_b32 v21, v212, v20
	s_waitcnt lgkmcnt(0)
	s_nop 0
	v_max_f32_e32 v20, v20, v21
	ds_bpermute_b32 v21, v176, v20
	s_waitcnt lgkmcnt(0)
	v_max3_f32 v20, v20, v21, v70
	v_sub_f32_e32 v21, v52, v20
	v_exp_f32_e32 v21, v21
	v_sub_f32_e32 v23, v53, v20
	v_exp_f32_e32 v23, v23
	v_sub_f32_e32 v52, v54, v20
	v_exp_f32_e32 v52, v52
	v_sub_f32_e32 v53, v55, v20
	v_exp_f32_e32 v53, v53
	v_sub_f32_e32 v48, v48, v20
	v_add_f32_e32 v22, 0, v21
	v_exp_f32_e32 v48, v48
	v_sub_f32_e32 v49, v49, v20
	v_add_f32_e32 v22, v23, v22
	v_exp_f32_e32 v49, v49
	v_sub_f32_e32 v50, v50, v20
	v_add_f32_e32 v22, v52, v22
	v_exp_f32_e32 v50, v50
	v_sub_f32_e32 v51, v51, v20
	v_add_f32_e32 v22, v53, v22
	v_exp_f32_e32 v51, v51
	v_sub_f32_e32 v40, v40, v20
	v_add_f32_e32 v22, v48, v22
	v_exp_f32_e32 v40, v40
	v_sub_f32_e32 v41, v41, v20
	v_add_f32_e32 v22, v49, v22
	v_exp_f32_e32 v41, v41
	v_sub_f32_e32 v42, v42, v20
	v_add_f32_e32 v22, v50, v22
	v_exp_f32_e32 v42, v42
	v_sub_f32_e32 v43, v43, v20
	v_add_f32_e32 v22, v51, v22
	v_exp_f32_e32 v43, v43
	v_sub_f32_e32 v32, v32, v20
	v_add_f32_e32 v22, v40, v22
	v_exp_f32_e32 v54, v32
	v_sub_f32_e32 v32, v33, v20
	v_add_f32_e32 v22, v41, v22
	v_exp_f32_e32 v55, v32
	v_sub_f32_e32 v32, v34, v20
	v_add_f32_e32 v22, v42, v22
	v_exp_f32_e32 v70, v32
	v_sub_f32_e32 v32, v35, v20
	v_add_f32_e32 v22, v43, v22
	v_exp_f32_e32 v35, v32
	v_sub_f32_e32 v28, v28, v20
	v_add_f32_e32 v22, v54, v22
	v_exp_f32_e32 v28, v28
	v_sub_f32_e32 v29, v29, v20
	v_add_f32_e32 v22, v55, v22
	v_exp_f32_e32 v29, v29
	v_sub_f32_e32 v30, v30, v20
	v_add_f32_e32 v22, v70, v22
	v_exp_f32_e32 v30, v30
	v_sub_f32_e32 v31, v31, v20
	v_add_f32_e32 v22, v35, v22
	v_exp_f32_e32 v31, v31
	v_sub_f32_e32 v32, v36, v20
	v_add_f32_e32 v22, v28, v22
	v_exp_f32_e32 v71, v32
	v_sub_f32_e32 v32, v37, v20
	v_add_f32_e32 v22, v29, v22
	v_exp_f32_e32 v72, v32
	v_sub_f32_e32 v32, v38, v20
	v_add_f32_e32 v22, v30, v22
	v_exp_f32_e32 v73, v32
; #define LAS __attribute__((address_space(3)))
; #define LAS __attribute__((address_space(3)))
; __device__ __forceinline__ unsigned pk2(float lo, float hi) { return pg8::cvt_pk_bf16(lo, hi); }
; __device__ __forceinline__ f32x4 mfma16(bf16x8 a, bf16x8 b, f32x4 c) { return __builtin_amdgcn_mfma_f32_16x16x32_bf16(a, b, c, 0, 0, 0); }
; template <int NKT, int VSTR, bool SINK>
; __device__ __forceinline__ void attn_core(LAS const unsigned char* kb_, LAS const unsigned char* vb_, bf16x8 q0, bf16x8 q1, float sk, unsigned mskbits, int fr, f32x4 (&o)[4]) {
;     ...
; #pragma unroll
;     for (int kt = 0; kt < NKT; ++kt)
; #pragma unroll
;         for (int r = 0; r < 4; ++r) { const float p = __builtin_amdgcn_exp2f(S[kt][r] - mx); S[kt][r] = p; sum += p; }
;     sum += __shfl_xor(sum, 16); sum += __shfl_xor(sum, 32);
;     if (SINK) sum += __builtin_amdgcn_exp2f(sk - mx);
;     const float inv = 1.0f / sum;
;     bf16x8 pf[NKT / 2];
; #pragma unroll
;     for (int kb = 0; kb < NKT / 2; ++kb) {
;         v4u w; w.x = pk2(S[2 * kb][0], S[2 * kb][1]); w.y = pk2(S[2 * kb][2], S[2 * kb][3]); w.z = pk2(S[2 * kb + 1][0], S[2 * kb + 1][1]); w.w = pk2(S[2 * kb + 1][2], S[2 * kb + 1][3]);
;         pf[kb] = __builtin_bit_cast(bf16x8, w);
;     }
; #pragma unroll
;     for (int dt = 0; dt < 4; ++dt) {
;         f32x4 acc = (f32x4){0.f, 0.f, 0.f, 0.f};
; #pragma unroll
;         for (int kb = 0; kb < NKT / 2; ++kb) {
;             const bf16x8 vf = *(LAS const bf16x8*)(vb_ + dt * 16 * VSTR + kb * 64);
;             acc = mfma16(vf, pf[kb], acc);
;         }
;         o[dt] = acc * inv;
	v_sub_f32_e32 v32, v39, v20
	v_add_f32_e32 v22, v31, v22
	v_exp_f32_e32 v74, v32
	v_sub_f32_e32 v32, v44, v20
	v_add_f32_e32 v22, v71, v22
	v_exp_f32_e32 v44, v32
	v_sub_f32_e32 v32, v45, v20
	v_add_f32_e32 v22, v72, v22
	v_exp_f32_e32 v45, v32
	v_sub_f32_e32 v32, v46, v20
	v_add_f32_e32 v22, v73, v22
	v_exp_f32_e32 v46, v32
	v_sub_f32_e32 v32, v47, v20
	v_add_f32_e32 v22, v74, v22
	v_exp_f32_e32 v47, v32
	v_sub_f32_e32 v24, v24, v20
	v_add_f32_e32 v22, v44, v22
	v_exp_f32_e32 v75, v24
	v_sub_f32_e32 v24, v25, v20
	v_add_f32_e32 v22, v45, v22
	v_exp_f32_e32 v76, v24
	v_sub_f32_e32 v24, v26, v20
	v_add_f32_e32 v22, v46, v22
	v_exp_f32_e32 v77, v24
	v_sub_f32_e32 v24, v27, v20
	v_add_f32_e32 v22, v47, v22
	v_exp_f32_e32 v27, v24
	v_sub_f32_e32 v24, v56, v20
	v_add_f32_e32 v22, v75, v22
	v_exp_f32_e32 v56, v24
	v_sub_f32_e32 v24, v57, v20
	v_add_f32_e32 v22, v76, v22
	v_exp_f32_e32 v57, v24
	v_sub_f32_e32 v24, v58, v20
	v_add_f32_e32 v22, v77, v22
	v_exp_f32_e32 v58, v24
	v_sub_f32_e32 v24, v59, v20
	v_add_f32_e32 v22, v27, v22
	v_exp_f32_e32 v59, v24
	v_sub_f32_e32 v24, v60, v20
	v_add_f32_e32 v22, v56, v22
	v_exp_f32_e32 v60, v24
	v_sub_f32_e32 v24, v61, v20
	v_add_f32_e32 v22, v57, v22
	v_exp_f32_e32 v61, v24
	v_sub_f32_e32 v24, v62, v20
	v_add_f32_e32 v22, v58, v22
	v_exp_f32_e32 v62, v24
	v_sub_f32_e32 v24, v63, v20
	v_add_f32_e32 v22, v59, v22
	v_exp_f32_e32 v63, v24
	v_sub_f32_e32 v24, v64, v20
	v_add_f32_e32 v22, v60, v22
	v_exp_f32_e32 v64, v24
	v_sub_f32_e32 v24, v65, v20
	v_add_f32_e32 v22, v61, v22
	v_exp_f32_e32 v65, v24
	v_sub_f32_e32 v24, v66, v20
	v_add_f32_e32 v22, v62, v22
	v_exp_f32_e32 v66, v24
	v_sub_f32_e32 v24, v67, v20
	v_add_f32_e32 v22, v63, v22
	v_exp_f32_e32 v67, v24
	v_sub_f32_e32 v16, v16, v20
	v_add_f32_e32 v22, v64, v22
	v_exp_f32_e32 v78, v16
	v_sub_f32_e32 v17, v17, v20
	v_add_f32_e32 v22, v65, v22
	v_exp_f32_e32 v79, v17
	v_sub_f32_e32 v17, v18, v20
	v_add_f32_e32 v22, v66, v22
	v_exp_f32_e32 v107, v17
	v_sub_f32_e32 v17, v19, v20
	v_add_f32_e32 v22, v67, v22
	v_exp_f32_e32 v19, v17
	v_add_f32_e32 v16, v78, v22
	v_add_f32_e32 v16, v79, v16
	v_add_f32_e32 v16, v107, v16
	v_add_f32_e32 v16, v19, v16
	ds_bpermute_b32 v17, v212, v16
	v_cvt_pk_bf16_f32 v36, v21, v23
	v_cvt_pk_bf16_f32 v37, v52, v53
	v_cvt_pk_bf16_f32 v38, v48, v49
	v_cvt_pk_bf16_f32 v39, v50, v51
	s_waitcnt lgkmcnt(0)
	v_add_f32_e32 v16, v16, v17
	ds_bpermute_b32 v17, v176, v16
	v_cvt_pk_bf16_f32 v32, v40, v41
	v_cvt_pk_bf16_f32 v33, v42, v43
	v_cvt_pk_bf16_f32 v34, v54, v55
	v_cvt_pk_bf16_f32 v35, v70, v35
	s_waitcnt lgkmcnt(0)
	v_add_f32_e32 v16, v16, v17
	v_fma_f32 v17, v69, s2, -v20
	v_exp_f32_e32 v17, v17
	v_cvt_pk_bf16_f32 v28, v28, v29
	v_cvt_pk_bf16_f32 v29, v30, v31
	v_cvt_pk_bf16_f32 v30, v71, v72
	v_cvt_pk_bf16_f32 v31, v73, v74
	v_cvt_pk_bf16_f32 v24, v44, v45
	s_nop 0
	v_add_f32_e32 v69, v17, v16
	v_div_scale_f32 v40, s[0:1], v69, v69, 1.0
	v_rcp_f32_e32 v41, v40
	v_cvt_pk_bf16_f32 v25, v46, v47
	v_cvt_pk_bf16_f32 v26, v75, v76
	v_cvt_pk_bf16_f32 v27, v77, v27
	v_cvt_pk_bf16_f32 v20, v56, v57
	v_cvt_pk_bf16_f32 v21, v58, v59
	s_nop 0
	v_fma_f32 v42, -v40, v41, 1.0
	v_fmac_f32_e32 v41, v42, v41
	v_div_scale_f32 v42, vcc, 1.0, v69, 1.0
	v_mul_f32_e32 v43, v42, v41
	v_fma_f32 v44, -v40, v43, v42
	v_fmac_f32_e32 v43, v44, v41
	v_fma_f32 v40, -v40, v43, v42
	v_cvt_pk_bf16_f32 v22, v60, v61
	v_cvt_pk_bf16_f32 v23, v62, v63
	v_cvt_pk_bf16_f32 v16, v64, v65
	v_cvt_pk_bf16_f32 v17, v66, v67
	v_cvt_pk_bf16_f32 v18, v78, v79
	v_cvt_pk_bf16_f32 v19, v107, v19
	v_div_fmas_f32 v40, v40, v41, v43
	s_waitcnt lgkmcnt(0)
	ds_read_b128 v[112:115], v106 offset:55296
	ds_read_b128 v[116:119], v106 offset:55360
	ds_read_b128 v[120:123], v106 offset:61760
	ds_read_b128 v[124:127], v105 offset:12864
	ds_read_b128 v[128:131], v106 offset:55424
	ds_read_b128 v[132:135], v106 offset:55488
	ds_read_b128 v[136:139], v106 offset:55552
	ds_read_b128 v[140:143], v106 offset:55616
	ds_read_b128 v[144:147], v106 offset:61696
	ds_read_b128 v[160:163], v106 offset:61824
	ds_read_b128 v[164:167], v106 offset:61888
	ds_read_b128 v[168:171], v106 offset:61952
	ds_read_b128 v[172:175], v106 offset:62016
	ds_read_b128 v[180:183], v105 offset:12800
	s_waitcnt lgkmcnt(13)
	v_mfma_f32_16x16x32_bf16 v[42:45], v[112:115], v[36:39], 0
	ds_read_b128 v[196:199], v105 offset:12928
	v_div_fixup_f32 v40, v40, v69, 1.0
	s_waitcnt lgkmcnt(13)
	v_mfma_f32_16x16x32_bf16 v[42:45], v[116:119], v[32:35], v[42:45]
	ds_read_b128 v[200:203], v105 offset:12992
	s_waitcnt lgkmcnt(11)
	v_mfma_f32_16x16x32_bf16 v[42:45], v[128:131], v[28:31], v[42:45]
	ds_read_b128 v[204:207], v105 offset:13056
	ds_read_b128 v[224:227], v105 offset:13120
	s_waitcnt lgkmcnt(12)
	v_mfma_f32_16x16x32_bf16 v[42:45], v[132:135], v[24:27], v[42:45]
	ds_read_b128 v[228:231], v105 offset:19200
	s_waitcnt lgkmcnt(12)
	v_mfma_f32_16x16x32_bf16 v[42:45], v[136:139], v[20:23], v[42:45]
	ds_read_b128 v[232:235], v105 offset:19264
	s_waitcnt lgkmcnt(12)
	v_mfma_f32_16x16x32_bf16 v[44:47], v[140:143], v[16:19], v[42:45]
	s_nop 7
	v_pk_mul_f32 v[42:43], v[46:47], v[40:41] op_sel_hi:[1,0]
	ds_read_b128 v[236:239], v105 offset:19328
	s_waitcnt lgkmcnt(12)
	v_mfma_f32_16x16x32_bf16 v[46:49], v[144:147], v[36:39], 0
	v_mul_f32_e64 v44, v44, v40
	v_mul_f32_e64 v45, v45, v40
	v_mfma_f32_16x16x32_bf16 v[46:49], v[120:123], v[32:35], v[46:49]
	ds_read_b128 v[240:243], v105 offset:19392
	s_waitcnt lgkmcnt(12)
	v_mfma_f32_16x16x32_bf16 v[46:49], v[160:163], v[28:31], v[46:49]
	ds_read_b128 v[244:247], v105 offset:19456
	s_waitcnt lgkmcnt(12)
	v_mfma_f32_16x16x32_bf16 v[46:49], v[164:167], v[24:27], v[46:49]
	ds_read_b128 v[112:115], v105 offset:19520
	s_waitcnt lgkmcnt(12)
; __device__ __forceinline__ float quad_sum(float s) { s += __shfl_xor(s, 16); s += __shfl_xor(s, 32); return s; }
; __device__ __forceinline__ float sq4(const f32x4 a) { return (a[0] * a[0] + a[1] * a[1]) + (a[2] * a[2] + a[3] * a[3]); }
; __device__ __forceinline__ unsigned pk2(float lo, float hi) { return pg8::cvt_pk_bf16(lo, hi); }
; template <bool DO_SWA, bool DO_MEM>
; __device__ __forceinline__ void attn_unit(const Args& a, unsigned char* ws, LAS unsigned char* lds, int l, int tid_in, int lane_in, int wave, int unit) {
;     ...
;                 attn_core<12, 400, true>(lds + A_KS + g * 192 * 144 + fq * 16, lds + A_VT1 + (g * 64 + fr) * 400 + fq * 16, qsw[hh][0], qsw[hh][1], sk, mskbits, fr, o);
; #pragma unroll
;                 for (int dt = 0; dt < 4; ++dt) { ssq += pg8::sq4(o[dt]); osv[hh][dt] = (v2u){pk2(o[dt][0], o[dt][1]), pk2(o[dt][2], o[dt][3])}; }
;             }
;             ssq = pg8::quad_sum(ssq);
;             if (fq == 0) red_a[g * 64 + qs * 16 + fr] = ssq;
;         }
;         if constexpr (DO_MEM) {
; #pragma unroll
;             for (int i = 0; i < 8; ++i) {
;                 const int chn = tid + 512 * i;
;                 mkst[i] = DO_SWA ? *(const v4u*)(MKb + (size_t)(chn >> 4) * 256 + (chn & 15) * 8) : __builtin_nontemporal_load((const v4u*)(MKb + (size_t)(chn >> 4) * 256 + (chn & 15) * 8));
;                 mvst[i] = DO_SWA ? *(const v4u*)(MVTb + (size_t)(chn >> 5) * 256 + (chn & 31) * 8) : __builtin_nontemporal_load((const v4u*)(MVTb + (size_t)(chn >> 5) * 256 + (chn & 31) * 8));
	v_mfma_f32_16x16x32_bf16 v[46:49], v[168:171], v[20:23], v[46:49]
	s_waitcnt lgkmcnt(11)
	v_mfma_f32_16x16x32_bf16 v[48:51], v[172:175], v[16:19], v[46:49]
	s_nop 7
	v_pk_mul_f32 v[46:47], v[50:51], v[40:41] op_sel_hi:[1,0]
	s_waitcnt lgkmcnt(10)
	v_mfma_f32_16x16x32_bf16 v[50:53], v[180:183], v[36:39], 0
	v_mul_f32_e64 v48, v48, v40
	v_mul_f32_e64 v49, v49, v40
	v_mfma_f32_16x16x32_bf16 v[50:53], v[124:127], v[32:35], v[50:53]
	s_waitcnt lgkmcnt(9)
	v_mfma_f32_16x16x32_bf16 v[50:53], v[196:199], v[28:31], v[50:53]
	s_waitcnt lgkmcnt(8)
	v_mfma_f32_16x16x32_bf16 v[50:53], v[200:203], v[24:27], v[50:53]
	s_waitcnt lgkmcnt(7)
	v_mfma_f32_16x16x32_bf16 v[50:53], v[204:207], v[20:23], v[50:53]
	s_waitcnt lgkmcnt(6)
	v_mfma_f32_16x16x32_bf16 v[50:53], v[224:227], v[16:19], v[50:53]
	s_nop 7
	v_pk_mul_f32 v[54:55], v[40:41], v[52:53] op_sel_hi:[0,1]
	v_pk_mul_f32 v[56:57], v[40:41], v[50:51] op_sel_hi:[0,1]
	s_waitcnt lgkmcnt(5)
	v_mfma_f32_16x16x32_bf16 v[36:39], v[228:231], v[36:39], 0
	s_waitcnt lgkmcnt(4)
	v_mfma_f32_16x16x32_bf16 v[32:35], v[232:235], v[32:35], v[36:39]
	s_waitcnt lgkmcnt(3)
	v_mfma_f32_16x16x32_bf16 v[28:31], v[236:239], v[28:31], v[32:35]
	s_waitcnt lgkmcnt(2)
	v_mfma_f32_16x16x32_bf16 v[24:27], v[240:243], v[24:27], v[28:31]
	s_waitcnt lgkmcnt(1)
	v_mfma_f32_16x16x32_bf16 v[20:23], v[244:247], v[20:23], v[24:27]
	v_cvt_pk_bf16_f32 v106, v44, v45
	v_cvt_pk_bf16_f32 v105, v42, v43
	s_waitcnt lgkmcnt(0)
	v_mfma_f32_16x16x32_bf16 v[16:19], v[112:115], v[16:19], v[20:23]
	s_nop 2
	v_mul_f32_e32 v20, v45, v45
	v_mul_f32_e32 v21, v43, v43
	v_fmac_f32_e32 v20, v44, v44
	v_fmac_f32_e32 v21, v42, v42
	v_add_f32_e32 v20, v20, v21
	v_mul_f32_e32 v21, v49, v49
	v_mul_f32_e32 v22, v47, v47
	v_fmac_f32_e32 v21, v48, v48
	v_fmac_f32_e32 v22, v46, v46
	v_add_f32_e32 v20, v68, v20
	v_add_f32_e32 v21, v21, v22
	v_add_f32_e32 v20, v21, v20
	v_mul_f32_e32 v21, v57, v57
	v_mul_f32_e32 v22, v55, v55
	v_fmac_f32_e32 v21, v56, v56
	v_fmac_f32_e32 v22, v54, v54
	v_pk_mul_f32 v[18:19], v[40:41], v[18:19] op_sel_hi:[0,1]
	v_pk_mul_f32 v[16:17], v[40:41], v[16:17] op_sel_hi:[0,1]
	v_add_f32_e32 v21, v21, v22
	v_add_f32_e32 v20, v21, v20
	v_mul_f32_e32 v21, v17, v17
	v_mul_f32_e32 v22, v19, v19
	v_fmac_f32_e32 v21, v16, v16
	v_fmac_f32_e32 v22, v18, v18
	v_add_f32_e32 v21, v21, v22
	v_add_f32_e32 v20, v20, v21
	v_cvt_pk_bf16_f32 v112, v48, v49
	v_cvt_pk_bf16_f32 v107, v46, v47
	v_cvt_pk_bf16_f32 v114, v56, v57
	v_cvt_pk_bf16_f32 v113, v54, v55
	v_cvt_pk_bf16_f32 v116, v16, v17
	ds_bpermute_b32 v16, v212, v20
	v_cvt_pk_bf16_f32 v115, v18, v19
	s_waitcnt lgkmcnt(0)
	v_add_f32_e32 v16, v20, v16
	ds_bpermute_b32 v17, v176, v16
	s_and_saveexec_b64 s[0:1], s[36:37]
	s_cbranch_execz .LBB0_292
	v_readlane_b32 s2, v251, 30
	s_waitcnt lgkmcnt(0)
	v_add_f32_e32 v16, v16, v17
	v_lshl_add_u32 v18, v210, 2, s2
	ds_write_b32 v18, v16
.LBB0_292:
	s_or_b64 exec, exec, s[0:1]
	s_add_i32 s0, s95, s25
	s_ashr_i32 s1, s0, 31
	s_lshl_b64 s[2:3], s[0:1], 17
	s_add_u32 s0, s7, s2
	s_addc_u32 s1, s24, s3
	v_add_u32_e32 v30, 0x400, v213
	s_add_u32 s2, s26, s2
	v_ashrrev_i32_e32 v224, 5, v30
	s_addc_u32 s3, s27, s3
	v_ashrrev_i32_e32 v225, 31, v224
	v_lshl_add_u64 v[18:19], s[2:3], 0, v[184:185]
	v_ashrrev_i32_e32 v182, 4, v30
	v_lshlrev_b64 v[30:31], 9, v[224:225]
	v_lshl_add_u64 v[34:35], v[18:19], 0, v[30:31]
	v_add_u32_e32 v30, 0x600, v213
	v_ashrrev_i32_e32 v234, 5, v30
	v_ashrrev_i32_e32 v235, 31, v234
	v_ashrrev_i32_e32 v232, 4, v30
	v_lshlrev_b64 v[30:31], 9, v[234:235]
	v_lshl_add_u64 v[42:43], v[18:19], 0, v[30:31]
	v_add_u32_e32 v30, 0x800, v213
	v_ashrrev_i32_e32 v238, 5, v30
	v_ashrrev_i32_e32 v239, 31, v238
	v_ashrrev_i32_e32 v236, 4, v30
	v_lshlrev_b64 v[30:31], 9, v[238:239]
	v_mov_b32_e32 v151, v185
	v_lshl_add_u64 v[50:51], v[18:19], 0, v[30:31]
	v_add_u32_e32 v30, 0xa00, v213
	s_waitcnt lgkmcnt(0)
	v_lshl_add_u64 v[16:17], s[0:1], 0, v[150:151]
	v_lshlrev_b64 v[20:21], 9, v[148:149]
	v_ashrrev_i32_e32 v157, 31, v156
	v_ashrrev_i32_e32 v174, 5, v215
	v_ashrrev_i32_e32 v242, 5, v30
	v_lshl_add_u64 v[22:23], v[16:17], 0, v[20:21]
	v_lshlrev_b64 v[24:25], 9, v[156:157]
	v_lshlrev_b64 v[26:27], 9, v[152:153]
	v_ashrrev_i32_e32 v175, 31, v174
	v_ashrrev_i32_e32 v183, 31, v182
	v_ashrrev_i32_e32 v243, 31, v242
	v_lshl_add_u64 v[24:25], v[18:19], 0, v[24:25]
	global_load_dwordx4 v[118:121], v[22:23], off
	global_load_dwordx4 v[122:125], v[24:25], off
	v_lshl_add_u64 v[22:23], v[16:17], 0, v[26:27]
	v_lshlrev_b64 v[28:29], 9, v[174:175]
	v_lshlrev_b64 v[32:33], 9, v[182:183]
	v_ashrrev_i32_e32 v233, 31, v232
	v_ashrrev_i32_e32 v240, 4, v30
	v_lshlrev_b64 v[30:31], 9, v[242:243]
	v_lshl_add_u64 v[28:29], v[18:19], 0, v[28:29]
	global_load_dwordx4 v[126:129], v[22:23], off
	global_load_dwordx4 v[130:133], v[28:29], off
	v_lshl_add_u64 v[22:23], v[16:17], 0, v[32:33]
	v_lshlrev_b64 v[40:41], 9, v[232:233]
	v_ashrrev_i32_e32 v237, 31, v236
	v_lshl_add_u64 v[58:59], v[18:19], 0, v[30:31]
	v_add_u32_e32 v30, 0xc00, v213
	global_load_dwordx4 v[134:137], v[22:23], off
	global_load_dwordx4 v[138:141], v[34:35], off
	v_lshl_add_u64 v[22:23], v[16:17], 0, v[40:41]
	v_lshlrev_b64 v[48:49], 9, v[236:237]
	v_ashrrev_i32_e32 v241, 31, v240
	v_ashrrev_i32_e32 v244, 4, v30
	global_load_dwordx4 v[158:161], v[22:23], off
	global_load_dwordx4 v[162:165], v[42:43], off
	v_lshl_add_u64 v[22:23], v[16:17], 0, v[48:49]
	v_lshlrev_b64 v[56:57], 9, v[240:241]
	v_ashrrev_i32_e32 v245, 31, v244
	v_ashrrev_i32_e32 v246, 5, v30
	global_load_dwordx4 v[166:169], v[22:23], off
	global_load_dwordx4 v[170:173], v[50:51], off
	v_lshl_add_u64 v[22:23], v[16:17], 0, v[56:57]
	v_lshlrev_b64 v[64:65], 9, v[244:245]
; #define LAS __attribute__((address_space(3)))
; #define LAS __attribute__((address_space(3)))
; template <bool DO_SWA, bool DO_MEM>
; __device__ __forceinline__ void attn_unit(const Args& a, unsigned char* ws, LAS unsigned char* lds, int l, int tid_in, int lane_in, int wave, int unit) {
;     ...
;         if constexpr (DO_MEM) {
; #pragma unroll
;             for (int i = 0; i < 8; ++i) {
;                 const int chn = tid + 512 * i;
;                 mkst[i] = DO_SWA ? *(const v4u*)(MKb + (size_t)(chn >> 4) * 256 + (chn & 15) * 8) : __builtin_nontemporal_load((const v4u*)(MKb + (size_t)(chn >> 4) * 256 + (chn & 15) * 8));
;                 mvst[i] = DO_SWA ? *(const v4u*)(MVTb + (size_t)(chn >> 5) * 256 + (chn & 31) * 8) : __builtin_nontemporal_load((const v4u*)(MVTb + (size_t)(chn >> 5) * 256 + (chn & 31) * 8));
;             }
;         }
;         __syncthreads();
;         if constexpr (DO_MEM)
; #pragma unroll
;         for (int i = 0; i < 8; ++i) {
;             const int chn = tid + 512 * i;
;             { const int key = chn >> 4, c16 = chn & 15; *(LAS v4u*)(lds + A_KS + ((c16 >> 3) * 256 + key) * 144 + (c16 & 7) * 16) = mkst[i]; }
;             { const int col = chn >> 5, kc = chn & 31; *(LAS v4u*)(lds + A_VT2 + col * 528 + kc * 16) = mvst[i]; }
;         }
;         if constexpr (DO_MEM)
; #pragma unroll
;         for (int i = 0; i < 8; ++i) {
;             const int chn = tid + 512 * i;
;             mkst[i] = DO_SWA ? *(const v4u*)(MKb + (size_t)(chn >> 4) * 256 + 128 + (chn & 15) * 8) : __builtin_nontemporal_load((const v4u*)(MKb + (size_t)(chn >> 4) * 256 + 128 + (chn & 15) * 8));
;             mvst[i] = DO_SWA ? *(const v4u*)(MVTb + (size_t)(128 + (chn >> 5)) * 256 + (chn & 31) * 8) : __builtin_nontemporal_load((const v4u*)(MVTb + (size_t)(128 + (chn >> 5)) * 256 + (chn & 31) * 8));
;         }
;         __builtin_amdgcn_sched_barrier(0);
;         if constexpr (DO_SWA) {
;             const float tot = red_a[qs * 16 + fr] + red_a[64 + qs * 16 + fr];
;             const float rs = 1.0f / sqrtf(tot * (1.0f / 512.0f) + EPS);
	v_ashrrev_i32_e32 v247, 31, v246
	global_load_dwordx4 v[178:181], v[22:23], off
	global_load_dwordx4 v[194:197], v[58:59], off
	v_lshl_add_u64 v[22:23], v[16:17], 0, v[64:65]
	v_lshlrev_b64 v[30:31], 9, v[246:247]
	v_lshl_add_u64 v[66:67], v[18:19], 0, v[30:31]
	global_load_dwordx4 v[198:201], v[22:23], off
	global_load_dwordx4 v[202:205], v[66:67], off
	v_add_u32_e32 v22, 0xe00, v213
	v_ashrrev_i32_e32 v248, 4, v22
	v_ashrrev_i32_e32 v249, 31, v248
	v_ashrrev_i32_e32 v226, 5, v22
	v_lshlrev_b64 v[72:73], 9, v[248:249]
	v_ashrrev_i32_e32 v227, 31, v226
	v_lshl_add_u64 v[16:17], v[16:17], 0, v[72:73]
	v_lshlrev_b64 v[22:23], 9, v[226:227]
	s_mov_b32 s2, 0x10000
	v_lshl_add_u64 v[74:75], v[18:19], 0, v[22:23]
	global_load_dwordx4 v[206:209], v[16:17], off
	global_load_dwordx4 v[228:231], v[74:75], off
	v_lshl_add_u64 v[16:17], s[0:1], 0, v[20:21]
	v_add_co_u32_e32 v20, vcc, s2, v24
	v_lshl_add_u64 v[32:33], s[0:1], 0, v[32:33]
	s_nop 0
	v_addc_co_u32_e32 v21, vcc, 0, v25, vcc
	v_add_co_u32_e32 v28, vcc, s2, v28
	v_lshl_add_u64 v[24:25], s[0:1], 0, v[26:27]
	s_nop 0
	v_addc_co_u32_e32 v29, vcc, 0, v29, vcc
	v_add_co_u32_e32 v36, vcc, s2, v34
	v_lshl_add_u64 v[40:41], s[0:1], 0, v[40:41]
	s_nop 0
	v_addc_co_u32_e32 v37, vcc, 0, v35, vcc
	v_add_co_u32_e32 v44, vcc, s2, v42
	v_lshl_add_u64 v[48:49], s[0:1], 0, v[48:49]
	s_nop 0
	v_addc_co_u32_e32 v45, vcc, 0, v43, vcc
	v_add_co_u32_e32 v52, vcc, s2, v50
	v_lshl_add_u64 v[56:57], s[0:1], 0, v[56:57]
	s_nop 0
	v_addc_co_u32_e32 v53, vcc, 0, v51, vcc
	v_add_co_u32_e32 v60, vcc, s2, v58
	v_lshl_add_u64 v[64:65], s[0:1], 0, v[64:65]
	s_nop 0
	v_addc_co_u32_e32 v61, vcc, 0, v59, vcc
	v_add_co_u32_e32 v68, vcc, s2, v66
	v_lshl_add_u64 v[72:73], s[0:1], 0, v[72:73]
	s_nop 0
	v_addc_co_u32_e32 v69, vcc, 0, v67, vcc
	v_add_co_u32_e32 v76, vcc, s2, v74
	v_lshl_add_u64 v[16:17], v[16:17], 0, v[150:151]
	v_lshl_add_u64 v[24:25], v[24:25], 0, v[150:151]
	v_lshl_add_u64 v[32:33], v[32:33], 0, v[150:151]
	v_lshl_add_u64 v[40:41], v[40:41], 0, v[150:151]
	v_lshl_add_u64 v[48:49], v[48:49], 0, v[150:151]
	v_lshl_add_u64 v[56:57], v[56:57], 0, v[150:151]
	v_lshl_add_u64 v[64:65], v[64:65], 0, v[150:151]
	v_lshl_add_u64 v[72:73], v[72:73], 0, v[150:151]
	v_addc_co_u32_e32 v77, vcc, 0, v75, vcc
	s_barrier
	global_load_dwordx4 v[16:19], v[16:17], off offset:256
	s_nop 0
	global_load_dwordx4 v[20:23], v[20:21], off
	s_nop 0
	global_load_dwordx4 v[24:27], v[24:25], off offset:256
	s_nop 0
	global_load_dwordx4 v[28:31], v[28:29], off
	s_nop 0
	global_load_dwordx4 v[32:35], v[32:33], off offset:256
	s_nop 0
	global_load_dwordx4 v[36:39], v[36:37], off
	s_nop 0
	global_load_dwordx4 v[40:43], v[40:41], off offset:256
	s_nop 0
	global_load_dwordx4 v[44:47], v[44:45], off
	s_nop 0
	global_load_dwordx4 v[48:51], v[48:49], off offset:256
	s_nop 0
	global_load_dwordx4 v[52:55], v[52:53], off
	s_nop 0
	global_load_dwordx4 v[56:59], v[56:57], off offset:256
	s_nop 0
	global_load_dwordx4 v[60:63], v[60:61], off
	s_nop 0
	global_load_dwordx4 v[64:67], v[64:65], off offset:256
	s_nop 0
	global_load_dwordx4 v[68:71], v[68:69], off
	s_nop 0
	global_load_dwordx4 v[72:75], v[72:73], off offset:256
	s_nop 0
	global_load_dwordx4 v[76:79], v[76:77], off
	v_lshlrev_b32_e32 v117, 5, v213
	v_and_b32_e32 v117, 0x100, v117
	v_add_u32_e32 v142, v117, v148
	s_movk_i32 s3, 0x90
	v_mad_u64_u32 v[142:143], s[0:1], v142, s3, v[100:101]
	s_waitcnt vmcnt(31)
	ds_write_b128 v142, v[118:121]
	v_add_u32_e32 v118, v152, v117
	v_and_b32_e32 v104, 0x1f0, v104
	s_add_i32 s2, 0, 0x12000
	v_mad_u64_u32 v[146:147], s[0:1], v118, s3, v[100:101]
	v_add_u32_e32 v118, v182, v117
	v_add_u32_e32 v104, s2, v104
	s_movk_i32 s4, 0x210
	v_mad_u64_u32 v[150:151], s[0:1], v118, s3, v[100:101]
	v_add_u32_e32 v118, v232, v117
	v_mad_u64_u32 v[144:145], s[0:1], v156, s4, v[104:105]
	v_mad_u64_u32 v[148:149], s[0:1], v174, s4, v[104:105]
	v_mad_u64_u32 v[152:153], s[0:1], v224, s4, v[104:105]
	v_mad_u64_u32 v[156:157], s[0:1], v118, s3, v[100:101]
	v_add_u32_e32 v118, v236, v117
	s_waitcnt vmcnt(30)
	ds_write_b128 v144, v[122:125]
	s_waitcnt vmcnt(29)
	ds_write_b128 v146, v[126:129]
	s_waitcnt vmcnt(28)
	ds_write_b128 v148, v[130:133]
	s_waitcnt vmcnt(27)
	ds_write_b128 v150, v[134:137]
	s_waitcnt vmcnt(26)
	ds_write_b128 v152, v[138:141]
	s_waitcnt vmcnt(25)
	ds_write_b128 v156, v[158:161]
	v_mad_u64_u32 v[158:159], s[0:1], v234, s4, v[104:105]
	v_mad_u64_u32 v[160:161], s[0:1], v118, s3, v[100:101]
	v_add_u32_e32 v118, v240, v117
	s_waitcnt vmcnt(24)
	ds_write_b128 v158, v[162:165]
	v_mad_u64_u32 v[162:163], s[0:1], v238, s4, v[104:105]
	v_mad_u64_u32 v[164:165], s[0:1], v118, s3, v[100:101]
	v_add_u32_e32 v118, v244, v117
	v_add_u32_e32 v117, v248, v117
	s_waitcnt vmcnt(23)
	ds_write_b128 v160, v[166:169]
	s_waitcnt vmcnt(22)
	ds_write_b128 v162, v[170:173]
	v_mad_u64_u32 v[166:167], s[0:1], v242, s4, v[104:105]
	v_mad_u64_u32 v[168:169], s[0:1], v118, s3, v[100:101]
	v_mad_u64_u32 v[170:171], s[0:1], v246, s4, v[104:105]
	v_mad_u64_u32 v[172:173], s[0:1], v117, s3, v[100:101]
	v_mad_u64_u32 v[174:175], s[0:1], v226, s4, v[104:105]
	s_waitcnt vmcnt(21)
	ds_write_b128 v164, v[178:181]
	s_waitcnt vmcnt(20)
	ds_write_b128 v166, v[194:197]
	s_waitcnt vmcnt(19)
	ds_write_b128 v168, v[198:201]
	s_waitcnt vmcnt(18)
	ds_write_b128 v170, v[202:205]
	s_waitcnt vmcnt(17)
	ds_write_b128 v172, v[206:209]
	s_waitcnt vmcnt(16)
	ds_write_b128 v174, v[228:231]
	s_add_i32 s0, 0, 0x22800
	v_or_b32_e32 v143, 64, v211
	v_lshl_add_u32 v100, v211, 2, s0
	v_lshl_add_u32 v104, v143, 2, s0
	ds_read_b32 v100, v100
	ds_read_b32 v104, v104
	s_mov_b32 s0, 0xf800000
	s_waitcnt lgkmcnt(0)
; __device__ __forceinline__ unsigned pk2(float lo, float hi) { return pg8::cvt_pk_bf16(lo, hi); }
; template <bool DO_SWA, bool DO_MEM>
; __device__ __forceinline__ void attn_unit(const Args& a, unsigned char* ws, LAS unsigned char* lds, int l, int tid_in, int lane_in, int wave, int unit) {
;     ...
;         if constexpr (DO_SWA) {
;             const float tot = red_a[qs * 16 + fr] + red_a[64 + qs * 16 + fr];
;             const float rs = 1.0f / sqrtf(tot * (1.0f / 512.0f) + EPS);
; #pragma unroll
;             for (int hh = 0; hh < 4; ++hh)
; #pragma unroll
;                 for (int dt = 0; dt < 4; ++dt) {
;                     const v2u p = osv[hh][dt];
;                     v2u w; w.x = pk2(__uint_as_float(p.x << 16) * rs, __uint_as_float(p.x & 0xffff0000u) * rs); w.y = pk2(__uint_as_float(p.y << 16) * rs, __uint_as_float(p.y & 0xffff0000u) * rs);
;                     *(v2u*)(MIX + qrow * D + (g * 4 + hh) * 64 + dt * 16 + 4 * fq) = w;
;                 }
	v_add_f32_e32 v100, v100, v104
	v_fmamk_f32 v100, v100, 0x3b000000, v218
	v_cmp_gt_f32_e32 vcc, s0, v100
	v_mul_f32_e32 v104, 0x4f800000, v100
	s_nop 0
	v_cndmask_b32_e32 v100, v100, v104, vcc
	v_sqrt_f32_e32 v104, v100
	s_nop 0
	v_add_u32_e32 v117, -1, v104
	v_fma_f32 v118, -v117, v104, v100
	v_cmp_ge_f32_e64 s[0:1], 0, v118
	v_add_u32_e32 v118, 1, v104
	s_nop 0
	v_cndmask_b32_e64 v117, v104, v117, s[0:1]
	v_fma_f32 v104, -v118, v104, v100
	v_cmp_lt_f32_e64 s[0:1], 0, v104
	s_nop 1
	v_cndmask_b32_e64 v104, v117, v118, s[0:1]
	v_mul_f32_e32 v117, 0x37800000, v104
	v_cndmask_b32_e32 v104, v104, v117, vcc
	v_cmp_class_f32_e32 vcc, v100, v219
	s_nop 1
	v_cndmask_b32_e32 v100, v104, v100, vcc
	v_div_scale_f32 v104, s[0:1], v100, v100, 1.0
	v_rcp_f32_e32 v117, v104
	v_readlane_b32 s0, v253, 49
	v_readlane_b32 s1, v253, 50
	v_fma_f32 v118, -v104, v117, 1.0
	v_fmac_f32_e32 v117, v118, v117
	v_div_scale_f32 v118, vcc, 1.0, v100, 1.0
	v_mul_f32_e32 v119, v118, v117
	v_fma_f32 v120, -v104, v119, v118
	v_fmac_f32_e32 v119, v120, v117
	v_fma_f32 v104, -v104, v119, v118
	v_div_fmas_f32 v104, v104, v117, v119
	v_div_fixup_f32 v100, v104, v100, 1.0
	v_lshlrev_b64 v[118:119], 11, v[154:155]
	v_lshlrev_b32_e32 v120, 2, v214
	v_lshlrev_b32_e32 v104, 16, v93
	v_and_b32_e32 v93, 0xffff0000, v93
	v_lshl_add_u64 v[118:119], s[20:21], 0, v[118:119]
	v_ashrrev_i32_e32 v121, 31, v120
	v_mul_f32_e32 v93, v100, v93
	v_lshl_add_u64 v[140:141], v[120:121], 1, v[118:119]
	v_mul_f32_e32 v104, v100, v104
	v_cvt_pk_bf16_f32 v120, v104, v93
	v_lshlrev_b32_e32 v93, 16, v92
	v_and_b32_e32 v92, 0xffff0000, v92
	v_mul_f32_e32 v93, v100, v93
	v_mul_f32_e32 v92, v100, v92
	v_cvt_pk_bf16_f32 v121, v93, v92
	v_lshlrev_b32_e32 v92, 16, v95
	v_and_b32_e32 v93, 0xffff0000, v95
	v_lshl_add_u64 v[118:119], v[140:141], 0, s[34:35]
	v_mul_f32_e32 v92, v100, v92
	v_mul_f32_e32 v93, v100, v93
	global_store_dwordx2 v[118:119], v[120:121], off
	v_cvt_pk_bf16_f32 v92, v92, v93
	v_lshlrev_b32_e32 v93, 16, v94
	v_mul_f32_e32 v93, v100, v93
	v_and_b32_e32 v94, 0xffff0000, v94
	v_mul_f32_e32 v94, v100, v94
	v_cvt_pk_bf16_f32 v93, v93, v94
	global_store_dwordx2 v[118:119], v[92:93], off offset:32
	v_lshlrev_b32_e32 v92, 16, v97
	v_and_b32_e32 v93, 0xffff0000, v97
	v_mul_f32_e32 v92, v100, v92
	v_mul_f32_e32 v93, v100, v93
	v_cvt_pk_bf16_f32 v92, v92, v93
	v_lshlrev_b32_e32 v93, 16, v96
	v_mul_f32_e32 v93, v100, v93
	v_and_b32_e32 v94, 0xffff0000, v96
	v_mul_f32_e32 v94, v100, v94
	v_cvt_pk_bf16_f32 v93, v93, v94
	global_store_dwordx2 v[118:119], v[92:93], off offset:64
	v_lshlrev_b32_e32 v92, 16, v99
	v_and_b32_e32 v93, 0xffff0000, v99
	v_mul_f32_e32 v92, v100, v92
	v_mul_f32_e32 v93, v100, v93
	v_cvt_pk_bf16_f32 v92, v92, v93
	v_lshlrev_b32_e32 v93, 16, v98
	v_mul_f32_e32 v93, v100, v93
	v_and_b32_e32 v94, 0xffff0000, v98
	v_mul_f32_e32 v94, v100, v94
	v_cvt_pk_bf16_f32 v93, v93, v94
	global_store_dwordx2 v[118:119], v[92:93], off offset:96
	v_lshlrev_b32_e32 v92, 16, v85
	v_and_b32_e32 v85, 0xffff0000, v85
	v_mul_f32_e32 v92, v100, v92
	v_mul_f32_e32 v85, v100, v85
	v_cvt_pk_bf16_f32 v92, v92, v85
	v_lshlrev_b32_e32 v85, 16, v84
	v_and_b32_e32 v84, 0xffff0000, v84
	v_mul_f32_e32 v85, v100, v85
	v_mul_f32_e32 v84, v100, v84
	v_cvt_pk_bf16_f32 v93, v85, v84
	v_lshlrev_b32_e32 v84, 16, v87
	v_and_b32_e32 v85, 0xffff0000, v87
	v_mul_f32_e32 v84, v100, v84
	v_mul_f32_e32 v85, v100, v85
	global_store_dwordx2 v[118:119], v[92:93], off offset:128
	v_cvt_pk_bf16_f32 v84, v84, v85
	v_lshlrev_b32_e32 v85, 16, v86
	v_mul_f32_e32 v85, v100, v85
	v_and_b32_e32 v86, 0xffff0000, v86
	v_mul_f32_e32 v86, v100, v86
	v_cvt_pk_bf16_f32 v85, v85, v86
	global_store_dwordx2 v[118:119], v[84:85], off offset:160
	v_lshlrev_b32_e32 v84, 16, v89
	v_and_b32_e32 v85, 0xffff0000, v89
	v_mul_f32_e32 v84, v100, v84
	v_mul_f32_e32 v85, v100, v85
	v_cvt_pk_bf16_f32 v84, v84, v85
	v_lshlrev_b32_e32 v85, 16, v88
	v_mul_f32_e32 v85, v100, v85
	v_and_b32_e32 v86, 0xffff0000, v88
	v_mul_f32_e32 v86, v100, v86
	v_cvt_pk_bf16_f32 v85, v85, v86
	global_store_dwordx2 v[118:119], v[84:85], off offset:192
	v_lshlrev_b32_e32 v84, 16, v91
	v_and_b32_e32 v85, 0xffff0000, v91
	v_mul_f32_e32 v84, v100, v84
	v_mul_f32_e32 v85, v100, v85
	v_cvt_pk_bf16_f32 v84, v84, v85
	v_lshlrev_b32_e32 v85, 16, v90
	v_mul_f32_e32 v85, v100, v85
	v_and_b32_e32 v86, 0xffff0000, v90
	v_mul_f32_e32 v86, v100, v86
	v_cvt_pk_bf16_f32 v85, v85, v86
	global_store_dwordx2 v[118:119], v[84:85], off offset:224
	v_lshlrev_b32_e32 v84, 16, v81
	v_and_b32_e32 v81, 0xffff0000, v81
	v_mul_f32_e32 v84, v100, v84
	v_mul_f32_e32 v81, v100, v81
	v_cvt_pk_bf16_f32 v84, v84, v81
	v_lshlrev_b32_e32 v81, 16, v80
	v_and_b32_e32 v80, 0xffff0000, v80
	v_mul_f32_e32 v81, v100, v81
	v_mul_f32_e32 v80, v100, v80
	v_cvt_pk_bf16_f32 v85, v81, v80
	v_lshlrev_b32_e32 v80, 16, v83
	v_and_b32_e32 v81, 0xffff0000, v83
	v_mul_f32_e32 v80, v100, v80
	v_mul_f32_e32 v81, v100, v81
	global_store_dwordx2 v[118:119], v[84:85], off offset:256
	v_cvt_pk_bf16_f32 v80, v80, v81
	v_lshlrev_b32_e32 v81, 16, v82
	v_mul_f32_e32 v81, v100, v81
	v_and_b32_e32 v82, 0xffff0000, v82
	v_mul_f32_e32 v82, v100, v82
	v_cvt_pk_bf16_f32 v81, v81, v82
	global_store_dwordx2 v[118:119], v[80:81], off offset:288
	v_lshlrev_b32_e32 v80, 16, v109
	v_and_b32_e32 v81, 0xffff0000, v109
	v_mul_f32_e32 v80, v100, v80
	v_mul_f32_e32 v81, v100, v81
	v_cvt_pk_bf16_f32 v80, v80, v81
	v_lshlrev_b32_e32 v81, 16, v108
	v_mul_f32_e32 v81, v100, v81
	v_and_b32_e32 v82, 0xffff0000, v108
	v_mul_f32_e32 v82, v100, v82
	v_cvt_pk_bf16_f32 v81, v81, v82
	global_store_dwordx2 v[118:119], v[80:81], off offset:320
	v_lshlrev_b32_e32 v80, 16, v111
; #define LAS __attribute__((address_space(3)))
; #define LAS __attribute__((address_space(3)))
; __device__ __forceinline__ unsigned pk2(float lo, float hi) { return pg8::cvt_pk_bf16(lo, hi); }
; __device__ __forceinline__ f32x4 mfma16(bf16x8 a, bf16x8 b, f32x4 c) { return __builtin_amdgcn_mfma_f32_16x16x32_bf16(a, b, c, 0, 0, 0); }
; template <int NKT, int VSTR, bool SINK>
; __device__ __forceinline__ void attn_core(LAS const unsigned char* kb_, LAS const unsigned char* vb_, bf16x8 q0, bf16x8 q1, float sk, unsigned mskbits, int fr, f32x4 (&o)[4]) {
;     ...
;     for (int kt = 0; kt < NKT; ++kt) {
;         const int key = (kt >> 1) * 32 + ((kt & 1) << 2) + krow;
;         LAS const unsigned char* kp = kb_ + key * 144;
;         const bf16x8 a0 = *(LAS const bf16x8*)kp, a1 = *(LAS const bf16x8*)(kp + 64);
;         const float bias = ((mskbits >> (kt >> 2)) & 1u) ? -1e30f : 0.f;
;         f32x4 s = mfma16(a0, q0, (f32x4){bias, bias, bias, bias});
;         s = mfma16(a1, q1, s);
;         S[kt] = s;
; template <bool DO_SWA, bool DO_MEM>
; __device__ __forceinline__ void attn_unit(const Args& a, unsigned char* ws, LAS unsigned char* lds, int l, int tid_in, int lane_in, int wave, int unit) {
;     ...
;                     const v2u p = osv[hh][dt];
;                     v2u w; w.x = pk2(__uint_as_float(p.x << 16) * rs, __uint_as_float(p.x & 0xffff0000u) * rs); w.y = pk2(__uint_as_float(p.y << 16) * rs, __uint_as_float(p.y & 0xffff0000u) * rs);
;                     *(v2u*)(MIX + qrow * D + (g * 4 + hh) * 64 + dt * 16 + 4 * fq) = w;
;                 }
;         }
;         __syncthreads();
;         f32x4 omem[2][4];
;         if constexpr (DO_MEM) attn_core<16, 528, false>(lds + A_KS + g * 256 * 144 + fq * 16, lds + A_VT2 + (g * 64 + fr) * 528 + fq * 16, qmm[0][0], qmm[0][1], 0.f, 0u, fr, omem[0]);
	v_and_b32_e32 v81, 0xffff0000, v111
	v_mul_f32_e32 v80, v100, v80
	v_mul_f32_e32 v81, v100, v81
	v_cvt_pk_bf16_f32 v80, v80, v81
	v_lshlrev_b32_e32 v81, 16, v110
	v_and_b32_e32 v82, 0xffff0000, v110
	v_mul_f32_e32 v81, v100, v81
	v_mul_f32_e32 v82, v100, v82
	v_cvt_pk_bf16_f32 v81, v81, v82
	v_lshlrev_b32_e32 v82, 16, v106
	v_and_b32_e32 v83, 0xffff0000, v106
	v_mul_f32_e32 v82, v100, v82
	v_mul_f32_e32 v83, v100, v83
	global_store_dwordx2 v[118:119], v[80:81], off offset:352
	v_cvt_pk_bf16_f32 v82, v82, v83
	v_lshlrev_b32_e32 v83, 16, v105
	v_mul_f32_e32 v83, v100, v83
	v_and_b32_e32 v84, 0xffff0000, v105
	v_lshl_add_u64 v[80:81], s[0:1], 1, v[140:141]
	v_mul_f32_e32 v84, v100, v84
	v_cvt_pk_bf16_f32 v83, v83, v84
	global_store_dwordx2 v[80:81], v[82:83], off offset:384
	v_lshlrev_b32_e32 v82, 16, v112
	v_and_b32_e32 v83, 0xffff0000, v112
	v_mul_f32_e32 v82, v100, v82
	v_mul_f32_e32 v83, v100, v83
	v_cvt_pk_bf16_f32 v82, v82, v83
	v_lshlrev_b32_e32 v83, 16, v107
	v_mul_f32_e32 v83, v100, v83
	v_and_b32_e32 v84, 0xffff0000, v107
	v_mul_f32_e32 v84, v100, v84
	v_cvt_pk_bf16_f32 v83, v83, v84
	global_store_dwordx2 v[80:81], v[82:83], off offset:416
	v_lshlrev_b32_e32 v82, 16, v114
	v_and_b32_e32 v83, 0xffff0000, v114
	v_mul_f32_e32 v82, v100, v82
	v_mul_f32_e32 v83, v100, v83
	v_cvt_pk_bf16_f32 v82, v82, v83
	v_lshlrev_b32_e32 v83, 16, v113
	v_mul_f32_e32 v83, v100, v83
	v_and_b32_e32 v84, 0xffff0000, v113
	v_mul_f32_e32 v84, v100, v84
	v_cvt_pk_bf16_f32 v83, v83, v84
	global_store_dwordx2 v[80:81], v[82:83], off offset:448
	v_lshlrev_b32_e32 v82, 16, v116
	v_and_b32_e32 v83, 0xffff0000, v116
	v_mul_f32_e32 v82, v100, v82
	v_mul_f32_e32 v83, v100, v83
	v_cvt_pk_bf16_f32 v82, v82, v83
	v_lshlrev_b32_e32 v83, 16, v115
	v_mul_f32_e32 v83, v100, v83
	v_and_b32_e32 v84, 0xffff0000, v115
	v_readlane_b32 s0, v251, 23
	v_mul_f32_e32 v84, v100, v84
	v_cvt_pk_bf16_f32 v83, v83, v84
	global_store_dwordx2 v[80:81], v[82:83], off offset:480
	v_mul_lo_u32 v80, v102, s4
	v_add3_u32 v147, s0, v101, v103
	s_barrier
	v_add3_u32 v145, s2, v80, v101
	s_waitcnt lgkmcnt(0)
	ds_read_b128 v[200:203], v147
	ds_read_b128 v[204:207], v147 offset:64
	ds_read_b128 v[228:231], v147 offset:576
	ds_read_b128 v[232:235], v147 offset:640
	ds_read_b128 v[236:239], v147 offset:4608
	ds_read_b128 v[240:243], v147 offset:4672
	ds_read_b128 v[244:247], v147 offset:5184
	s_waitcnt lgkmcnt(6)
	v_mfma_f32_16x16x32_bf16 v[80:83], v[200:203], v[12:15], 0
	s_waitcnt lgkmcnt(5)
	v_mfma_f32_16x16x32_bf16 v[136:139], v[204:207], v[8:11], v[80:83]
	ds_read_b128 v[200:203], v147 offset:5248
	ds_read_b128 v[204:207], v147 offset:9216
	s_waitcnt lgkmcnt(6)
	v_mfma_f32_16x16x32_bf16 v[80:83], v[228:231], v[12:15], 0
	s_waitcnt lgkmcnt(5)
	v_mfma_f32_16x16x32_bf16 v[132:135], v[232:235], v[8:11], v[80:83]
	ds_read_b128 v[228:231], v147 offset:9280
	ds_read_b128 v[232:235], v147 offset:9792
	s_waitcnt lgkmcnt(6)
	v_mfma_f32_16x16x32_bf16 v[80:83], v[236:239], v[12:15], 0
	s_waitcnt lgkmcnt(5)
	v_mfma_f32_16x16x32_bf16 v[128:131], v[240:243], v[8:11], v[80:83]
	ds_read_b128 v[236:239], v147 offset:9856
	ds_read_b128 v[240:243], v147 offset:13824
	s_waitcnt lgkmcnt(6)
	v_mfma_f32_16x16x32_bf16 v[80:83], v[244:247], v[12:15], 0
	s_waitcnt lgkmcnt(5)
	v_mfma_f32_16x16x32_bf16 v[124:127], v[200:203], v[8:11], v[80:83]
	ds_read_b128 v[244:247], v147 offset:13888
	ds_read_b128 v[200:203], v147 offset:14400
	s_waitcnt lgkmcnt(6)
	v_mfma_f32_16x16x32_bf16 v[80:83], v[204:207], v[12:15], 0
	s_waitcnt lgkmcnt(5)
	v_mfma_f32_16x16x32_bf16 v[120:123], v[228:231], v[8:11], v[80:83]
	ds_read_b128 v[204:207], v147 offset:14464
	ds_read_b128 v[228:231], v147 offset:18432
	s_waitcnt lgkmcnt(6)
	v_mfma_f32_16x16x32_bf16 v[80:83], v[232:235], v[12:15], 0
	s_waitcnt lgkmcnt(5)
	v_mfma_f32_16x16x32_bf16 v[116:119], v[236:239], v[8:11], v[80:83]
	ds_read_b128 v[232:235], v147 offset:18496
	ds_read_b128 v[236:239], v147 offset:19008
	s_waitcnt lgkmcnt(6)
	v_mfma_f32_16x16x32_bf16 v[80:83], v[240:243], v[12:15], 0
	s_waitcnt lgkmcnt(5)
	v_mfma_f32_16x16x32_bf16 v[112:115], v[244:247], v[8:11], v[80:83]
	ds_read_b128 v[240:243], v147 offset:19072
	ds_read_b128 v[244:247], v147 offset:23040
	s_waitcnt lgkmcnt(6)
	v_mfma_f32_16x16x32_bf16 v[80:83], v[200:203], v[12:15], 0
	s_waitcnt lgkmcnt(5)
	v_mfma_f32_16x16x32_bf16 v[108:111], v[204:207], v[8:11], v[80:83]
	ds_read_b128 v[200:203], v147 offset:23104
	ds_read_b128 v[204:207], v147 offset:23616
	s_waitcnt lgkmcnt(6)
	v_mfma_f32_16x16x32_bf16 v[80:83], v[228:231], v[12:15], 0
	s_waitcnt lgkmcnt(5)
	v_mfma_f32_16x16x32_bf16 v[104:107], v[232:235], v[8:11], v[80:83]
	ds_read_b128 v[228:231], v147 offset:23680
	ds_read_b128 v[232:235], v147 offset:27648
	s_waitcnt lgkmcnt(6)
	v_mfma_f32_16x16x32_bf16 v[80:83], v[236:239], v[12:15], 0
	s_waitcnt lgkmcnt(5)
	v_mfma_f32_16x16x32_bf16 v[100:103], v[240:243], v[8:11], v[80:83]
	ds_read_b128 v[236:239], v147 offset:27712
	ds_read_b128 v[240:243], v147 offset:28224
	s_waitcnt lgkmcnt(6)
	v_mfma_f32_16x16x32_bf16 v[80:83], v[244:247], v[12:15], 0
	s_waitcnt lgkmcnt(5)
	v_mfma_f32_16x16x32_bf16 v[96:99], v[200:203], v[8:11], v[80:83]
	ds_read_b128 v[244:247], v147 offset:28288
	ds_read_b128 v[200:203], v147 offset:32256
	s_waitcnt lgkmcnt(6)
	v_mfma_f32_16x16x32_bf16 v[80:83], v[204:207], v[12:15], 0
	s_waitcnt lgkmcnt(5)
	v_mfma_f32_16x16x32_bf16 v[92:95], v[228:231], v[8:11], v[80:83]
	ds_read_b128 v[204:207], v147 offset:32320
	ds_read_b128 v[228:231], v147 offset:32832
	s_waitcnt lgkmcnt(6)
	v_mfma_f32_16x16x32_bf16 v[80:83], v[232:235], v[12:15], 0
	s_waitcnt lgkmcnt(5)
; template <int NKT, int VSTR, bool SINK>
; __device__ __forceinline__ void attn_core(LAS const unsigned char* kb_, LAS const unsigned char* vb_, bf16x8 q0, bf16x8 q1, float sk, unsigned mskbits, int fr, f32x4 (&o)[4]) {
;     ...
;     float mx = S[0][0];
; #pragma unroll
;     for (int kt = 0; kt < NKT; ++kt) mx = fmaxf(fmaxf(mx, fmaxf(S[kt][0], S[kt][1])), fmaxf(S[kt][2], S[kt][3]));
;     mx = fmaxf(mx, __shfl_xor(mx, 16)); mx = fmaxf(mx, __shfl_xor(mx, 32));
;     if (SINK) mx = fmaxf(mx, sk);
;     float sum = 0.f;
; #pragma unroll
;     for (int kt = 0; kt < NKT; ++kt)
; #pragma unroll
;         for (int r = 0; r < 4; ++r) { const float p = __builtin_amdgcn_exp2f(S[kt][r] - mx); S[kt][r] = p; sum += p; }
	v_mfma_f32_16x16x32_bf16 v[88:91], v[236:239], v[8:11], v[80:83]
	ds_read_b128 v[232:235], v147 offset:32896
	s_waitcnt lgkmcnt(5)
	v_mfma_f32_16x16x32_bf16 v[80:83], v[240:243], v[12:15], 0
	s_waitcnt lgkmcnt(4)
	v_mfma_f32_16x16x32_bf16 v[84:87], v[244:247], v[8:11], v[80:83]
	s_waitcnt lgkmcnt(3)
	v_mfma_f32_16x16x32_bf16 v[80:83], v[200:203], v[12:15], 0
	s_waitcnt lgkmcnt(2)
	v_mfma_f32_16x16x32_bf16 v[80:83], v[204:207], v[8:11], v[80:83]
	s_waitcnt lgkmcnt(1)
	v_mfma_f32_16x16x32_bf16 v[12:15], v[228:231], v[12:15], 0
	s_waitcnt lgkmcnt(0)
	v_mfma_f32_16x16x32_bf16 v[8:11], v[232:235], v[8:11], v[12:15]
	s_nop 5
	s_nop 0
	s_nop 0
	v_max_f32_e32 v12, v138, v139
	s_nop 0
	s_nop 0
	v_max_f32_e32 v13, v132, v133
	s_nop 0
	s_nop 0
	v_max3_f32 v12, v136, v137, v12
	v_max_f32_e32 v14, v134, v135
	v_max3_f32 v12, v12, v13, v14
	s_nop 0
	s_nop 0
	v_max_f32_e32 v13, v128, v129
	s_nop 0
	s_nop 0
	v_max_f32_e32 v14, v130, v131
	v_max3_f32 v12, v12, v13, v14
	s_nop 0
	s_nop 0
	v_max_f32_e32 v13, v124, v125
	s_nop 0
	s_nop 0
	v_max_f32_e32 v14, v126, v127
	v_max3_f32 v12, v12, v13, v14
	v_max_f32_e32 v13, v120, v121
	v_max_f32_e32 v14, v122, v123
	v_max3_f32 v12, v12, v13, v14
	v_max_f32_e32 v13, v116, v117
	v_max_f32_e32 v14, v118, v119
	v_max3_f32 v12, v12, v13, v14
	v_max_f32_e32 v13, v112, v113
	v_max_f32_e32 v14, v114, v115
	v_max3_f32 v12, v12, v13, v14
	v_max_f32_e32 v13, v108, v109
	v_max_f32_e32 v14, v110, v111
	v_max3_f32 v12, v12, v13, v14
	v_max_f32_e32 v13, v104, v105
	v_max_f32_e32 v14, v106, v107
	v_max3_f32 v12, v12, v13, v14
	v_max_f32_e32 v13, v100, v101
	v_max_f32_e32 v14, v102, v103
	v_max3_f32 v12, v12, v13, v14
	v_max_f32_e32 v13, v96, v97
	v_max_f32_e32 v14, v98, v99
	v_max3_f32 v12, v12, v13, v14
	v_max_f32_e32 v13, v92, v93
	v_max_f32_e32 v14, v94, v95
	v_max3_f32 v12, v12, v13, v14
	v_max_f32_e32 v13, v88, v89
	v_max_f32_e32 v14, v90, v91
	v_max3_f32 v12, v12, v13, v14
	v_max_f32_e32 v13, v84, v85
	v_max_f32_e32 v14, v86, v87
	v_max3_f32 v12, v12, v13, v14
	v_max_f32_e32 v13, v80, v81
	v_max_f32_e32 v14, v82, v83
	v_max3_f32 v12, v12, v13, v14
	v_max_f32_e32 v13, v8, v9
	v_max_f32_e32 v14, v10, v11
	v_max3_f32 v12, v12, v13, v14
	ds_bpermute_b32 v13, v212, v12
	s_waitcnt lgkmcnt(0)
	s_nop 0
	v_max_f32_e32 v12, v12, v13
	ds_bpermute_b32 v13, v176, v12
	s_waitcnt lgkmcnt(0)
	s_nop 0
	v_max_f32_e32 v149, v12, v13
	v_sub_f32_e32 v12, v136, v149
	v_exp_f32_e32 v12, v12
	v_sub_f32_e32 v13, v137, v149
	v_exp_f32_e32 v13, v13
	v_sub_f32_e32 v132, v132, v149
	v_add_f32_e32 v14, 0, v12
	v_exp_f32_e32 v132, v132
	v_add_f32_e32 v15, v13, v14
	v_sub_f32_e32 v14, v138, v149
	v_exp_f32_e32 v14, v14
	v_sub_f32_e32 v133, v133, v149
	v_exp_f32_e32 v133, v133
	v_sub_f32_e32 v134, v134, v149
	v_add_f32_e32 v136, v14, v15
	v_sub_f32_e32 v15, v139, v149
	v_exp_f32_e32 v15, v15
	v_exp_f32_e32 v134, v134
	v_sub_f32_e32 v135, v135, v149
	v_exp_f32_e32 v135, v135
	v_add_f32_e32 v136, v15, v136
	v_sub_f32_e32 v128, v128, v149
	v_add_f32_e32 v136, v132, v136
	v_exp_f32_e32 v128, v128
	v_sub_f32_e32 v129, v129, v149
	v_add_f32_e32 v136, v133, v136
	v_exp_f32_e32 v129, v129
	v_sub_f32_e32 v130, v130, v149
	v_add_f32_e32 v136, v134, v136
	v_exp_f32_e32 v130, v130
	v_sub_f32_e32 v131, v131, v149
	v_add_f32_e32 v136, v135, v136
	v_exp_f32_e32 v131, v131
	v_sub_f32_e32 v124, v124, v149
	v_add_f32_e32 v136, v128, v136
	v_exp_f32_e32 v124, v124
	v_sub_f32_e32 v125, v125, v149
	v_add_f32_e32 v136, v129, v136
	v_exp_f32_e32 v125, v125
	v_sub_f32_e32 v126, v126, v149
	v_add_f32_e32 v136, v130, v136
	v_exp_f32_e32 v126, v126
	v_sub_f32_e32 v127, v127, v149
	v_add_f32_e32 v136, v131, v136
	v_exp_f32_e32 v127, v127
	v_sub_f32_e32 v120, v120, v149
	v_add_f32_e32 v136, v124, v136
	v_exp_f32_e32 v120, v120
	v_sub_f32_e32 v121, v121, v149
	v_add_f32_e32 v136, v125, v136
	v_exp_f32_e32 v121, v121
	v_sub_f32_e32 v122, v122, v149
	v_add_f32_e32 v136, v126, v136
	v_exp_f32_e32 v122, v122
	v_sub_f32_e32 v123, v123, v149
	v_add_f32_e32 v136, v127, v136
	v_exp_f32_e32 v123, v123
	v_sub_f32_e32 v116, v116, v149
	v_add_f32_e32 v136, v120, v136
	v_exp_f32_e32 v116, v116
	v_sub_f32_e32 v117, v117, v149
	v_add_f32_e32 v136, v121, v136
	v_exp_f32_e32 v117, v117
	v_sub_f32_e32 v118, v118, v149
	v_add_f32_e32 v136, v122, v136
	v_exp_f32_e32 v118, v118
	v_sub_f32_e32 v119, v119, v149
	v_add_f32_e32 v136, v123, v136
	v_exp_f32_e32 v119, v119
	v_sub_f32_e32 v112, v112, v149
	v_add_f32_e32 v136, v116, v136
	v_exp_f32_e32 v112, v112
	v_sub_f32_e32 v113, v113, v149
	v_add_f32_e32 v136, v117, v136
	v_exp_f32_e32 v113, v113
	v_sub_f32_e32 v114, v114, v149
	v_add_f32_e32 v136, v118, v136
	v_exp_f32_e32 v114, v114
	v_sub_f32_e32 v115, v115, v149
	v_add_f32_e32 v136, v119, v136
	v_exp_f32_e32 v115, v115
	v_sub_f32_e32 v108, v108, v149
	v_add_f32_e32 v136, v112, v136
	v_exp_f32_e32 v108, v108
	v_sub_f32_e32 v109, v109, v149
	v_add_f32_e32 v136, v113, v136
	v_exp_f32_e32 v109, v109
	v_sub_f32_e32 v110, v110, v149
	v_add_f32_e32 v136, v114, v136
	v_exp_f32_e32 v110, v110
	v_sub_f32_e32 v111, v111, v149
	v_add_f32_e32 v136, v115, v136
	v_exp_f32_e32 v111, v111
	v_sub_f32_e32 v104, v104, v149
	v_add_f32_e32 v136, v108, v136
	v_exp_f32_e32 v104, v104
	v_sub_f32_e32 v105, v105, v149
	v_add_f32_e32 v136, v109, v136
	v_exp_f32_e32 v105, v105
	v_sub_f32_e32 v106, v106, v149
	v_add_f32_e32 v136, v110, v136
	v_exp_f32_e32 v106, v106
	v_sub_f32_e32 v107, v107, v149
	v_add_f32_e32 v136, v111, v136
	v_exp_f32_e32 v107, v107
	v_sub_f32_e32 v100, v100, v149
	v_add_f32_e32 v136, v104, v136
	v_exp_f32_e32 v100, v100
	v_sub_f32_e32 v101, v101, v149
	v_add_f32_e32 v136, v105, v136
	v_exp_f32_e32 v101, v101
; #define LAS __attribute__((address_space(3)))
; #define LAS __attribute__((address_space(3)))
; __device__ __forceinline__ unsigned pk2(float lo, float hi) { return pg8::cvt_pk_bf16(lo, hi); }
; __device__ __forceinline__ f32x4 mfma16(bf16x8 a, bf16x8 b, f32x4 c) { return __builtin_amdgcn_mfma_f32_16x16x32_bf16(a, b, c, 0, 0, 0); }
; template <int NKT, int VSTR, bool SINK>
; __device__ __forceinline__ void attn_core(LAS const unsigned char* kb_, LAS const unsigned char* vb_, bf16x8 q0, bf16x8 q1, float sk, unsigned mskbits, int fr, f32x4 (&o)[4]) {
;     ...
; #pragma unroll
;     for (int kt = 0; kt < NKT; ++kt)
; #pragma unroll
;         for (int r = 0; r < 4; ++r) { const float p = __builtin_amdgcn_exp2f(S[kt][r] - mx); S[kt][r] = p; sum += p; }
;     sum += __shfl_xor(sum, 16); sum += __shfl_xor(sum, 32);
;     if (SINK) sum += __builtin_amdgcn_exp2f(sk - mx);
;     const float inv = 1.0f / sum;
;     bf16x8 pf[NKT / 2];
; #pragma unroll
;     for (int kb = 0; kb < NKT / 2; ++kb) {
;         v4u w; w.x = pk2(S[2 * kb][0], S[2 * kb][1]); w.y = pk2(S[2 * kb][2], S[2 * kb][3]); w.z = pk2(S[2 * kb + 1][0], S[2 * kb + 1][1]); w.w = pk2(S[2 * kb + 1][2], S[2 * kb + 1][3]);
;         pf[kb] = __builtin_bit_cast(bf16x8, w);
;     }
; #pragma unroll
;     for (int dt = 0; dt < 4; ++dt) {
;         f32x4 acc = (f32x4){0.f, 0.f, 0.f, 0.f};
; #pragma unroll
;         for (int kb = 0; kb < NKT / 2; ++kb) {
;             const bf16x8 vf = *(LAS const bf16x8*)(vb_ + dt * 16 * VSTR + kb * 64);
;             acc = mfma16(vf, pf[kb], acc);
;         }
;         o[dt] = acc * inv;
;     }
	v_sub_f32_e32 v102, v102, v149
	v_add_f32_e32 v136, v106, v136
	v_exp_f32_e32 v102, v102
	v_sub_f32_e32 v103, v103, v149
	v_add_f32_e32 v136, v107, v136
	v_exp_f32_e32 v103, v103
	v_sub_f32_e32 v96, v96, v149
	v_add_f32_e32 v136, v100, v136
	v_exp_f32_e32 v96, v96
	v_sub_f32_e32 v97, v97, v149
	v_add_f32_e32 v136, v101, v136
	v_exp_f32_e32 v97, v97
	v_sub_f32_e32 v98, v98, v149
	v_add_f32_e32 v136, v102, v136
	v_exp_f32_e32 v98, v98
	v_sub_f32_e32 v99, v99, v149
	v_add_f32_e32 v136, v103, v136
	v_exp_f32_e32 v99, v99
	v_sub_f32_e32 v92, v92, v149
	v_add_f32_e32 v136, v96, v136
	v_exp_f32_e32 v137, v92
	v_add_f32_e32 v136, v97, v136
	v_add_f32_e32 v136, v98, v136
	v_add_f32_e32 v136, v99, v136
	v_sub_f32_e32 v93, v93, v149
	v_add_f32_e32 v92, v137, v136
	v_exp_f32_e32 v136, v93
	v_sub_f32_e32 v93, v94, v149
	v_exp_f32_e32 v138, v93
	v_sub_f32_e32 v93, v95, v149
	v_exp_f32_e32 v95, v93
	v_sub_f32_e32 v88, v88, v149
	v_exp_f32_e32 v139, v88
	v_sub_f32_e32 v89, v89, v149
	v_add_f32_e32 v92, v136, v92
	v_exp_f32_e32 v151, v89
	v_sub_f32_e32 v89, v90, v149
	v_add_f32_e32 v92, v138, v92
	v_exp_f32_e32 v153, v89
	v_sub_f32_e32 v89, v91, v149
	v_add_f32_e32 v92, v95, v92
	v_exp_f32_e32 v154, v89
	v_sub_f32_e32 v84, v84, v149
	v_add_f32_e32 v88, v139, v92
	v_exp_f32_e32 v155, v84
	v_sub_f32_e32 v85, v85, v149
	v_add_f32_e32 v88, v151, v88
	v_exp_f32_e32 v157, v85
	v_sub_f32_e32 v85, v86, v149
	v_add_f32_e32 v88, v153, v88
	v_exp_f32_e32 v159, v85
	v_sub_f32_e32 v85, v87, v149
	v_add_f32_e32 v88, v154, v88
	v_exp_f32_e32 v161, v85
	v_sub_f32_e32 v80, v80, v149
	v_add_f32_e32 v84, v155, v88
	v_exp_f32_e32 v163, v80
	v_sub_f32_e32 v81, v81, v149
	v_add_f32_e32 v84, v157, v84
	v_exp_f32_e32 v165, v81
	v_sub_f32_e32 v81, v82, v149
	v_add_f32_e32 v84, v159, v84
	v_exp_f32_e32 v167, v81
	v_sub_f32_e32 v81, v83, v149
	v_add_f32_e32 v84, v161, v84
	v_exp_f32_e32 v169, v81
	v_sub_f32_e32 v8, v8, v149
	v_add_f32_e32 v80, v163, v84
	v_exp_f32_e32 v171, v8
	v_sub_f32_e32 v9, v9, v149
	v_add_f32_e32 v80, v165, v80
	v_exp_f32_e32 v173, v9
	v_sub_f32_e32 v9, v10, v149
	v_add_f32_e32 v80, v167, v80
	v_exp_f32_e32 v175, v9
	v_sub_f32_e32 v9, v11, v149
	v_add_f32_e32 v80, v169, v80
	v_exp_f32_e32 v149, v9
	v_add_f32_e32 v8, v171, v80
	v_add_f32_e32 v8, v173, v8
	v_add_f32_e32 v8, v175, v8
	v_add_f32_e32 v8, v149, v8
	ds_bpermute_b32 v9, v212, v8
	v_cvt_pk_bf16_f32 v84, v12, v13
	v_cvt_pk_bf16_f32 v85, v14, v15
	v_cvt_pk_bf16_f32 v86, v132, v133
	v_cvt_pk_bf16_f32 v87, v134, v135
	s_waitcnt lgkmcnt(0)
	v_add_f32_e32 v8, v8, v9
	ds_bpermute_b32 v9, v176, v8
	v_cvt_pk_bf16_f32 v80, v128, v129
	v_cvt_pk_bf16_f32 v81, v130, v131
	v_cvt_pk_bf16_f32 v82, v124, v125
	v_cvt_pk_bf16_f32 v83, v126, v127
	s_waitcnt lgkmcnt(0)
	v_add_f32_e32 v177, v8, v9
	v_cvt_pk_bf16_f32 v12, v120, v121
	v_cvt_pk_bf16_f32 v13, v122, v123
	v_cvt_pk_bf16_f32 v14, v116, v117
	v_cvt_pk_bf16_f32 v15, v118, v119
	v_cvt_pk_bf16_f32 v8, v112, v113
	v_cvt_pk_bf16_f32 v9, v114, v115
	v_cvt_pk_bf16_f32 v10, v108, v109
	v_cvt_pk_bf16_f32 v11, v110, v111
	v_cvt_pk_bf16_f32 v88, v104, v105
	v_div_scale_f32 v104, s[0:1], v177, v177, 1.0
	v_rcp_f32_e32 v105, v104
	v_cvt_pk_bf16_f32 v89, v106, v107
	v_cvt_pk_bf16_f32 v90, v100, v101
	v_cvt_pk_bf16_f32 v91, v102, v103
	v_cvt_pk_bf16_f32 v92, v96, v97
	v_cvt_pk_bf16_f32 v93, v98, v99
	s_nop 0
	v_fma_f32 v106, -v104, v105, 1.0
	v_fmac_f32_e32 v105, v106, v105
	v_div_scale_f32 v106, vcc, 1.0, v177, 1.0
	v_mul_f32_e32 v107, v106, v105
	v_fma_f32 v108, -v104, v107, v106
	v_fmac_f32_e32 v107, v108, v105
	v_fma_f32 v104, -v104, v107, v106
	v_div_fmas_f32 v104, v104, v105, v107
	v_cvt_pk_bf16_f32 v94, v137, v136
	v_cvt_pk_bf16_f32 v95, v138, v95
	v_cvt_pk_bf16_f32 v96, v139, v151
	v_cvt_pk_bf16_f32 v97, v153, v154
	v_cvt_pk_bf16_f32 v98, v155, v157
	v_cvt_pk_bf16_f32 v99, v159, v161
	v_cvt_pk_bf16_f32 v100, v163, v165
	v_cvt_pk_bf16_f32 v101, v167, v169
	v_cvt_pk_bf16_f32 v102, v171, v173
	v_cvt_pk_bf16_f32 v103, v175, v149
	v_div_fixup_f32 v116, v104, v177, 1.0
	ds_read_b128 v[104:107], v145
	ds_read_b128 v[108:111], v145 offset:64
	s_waitcnt lgkmcnt(1)
	v_mfma_f32_16x16x32_bf16 v[104:107], v[104:107], v[84:87], 0
	ds_read_b128 v[112:115], v145 offset:8512
	ds_read_b128 v[118:121], v145 offset:16960
	s_waitcnt lgkmcnt(2)
	v_mfma_f32_16x16x32_bf16 v[104:107], v[108:111], v[80:83], v[104:107]
	ds_read_b128 v[108:111], v145 offset:128
	s_waitcnt lgkmcnt(0)
	v_mfma_f32_16x16x32_bf16 v[104:107], v[108:111], v[12:15], v[104:107]
	ds_read_b128 v[108:111], v145 offset:192
	s_waitcnt lgkmcnt(0)
	v_mfma_f32_16x16x32_bf16 v[104:107], v[108:111], v[8:11], v[104:107]
	ds_read_b128 v[108:111], v145 offset:256
	s_waitcnt lgkmcnt(0)
	v_mfma_f32_16x16x32_bf16 v[104:107], v[108:111], v[88:91], v[104:107]
	ds_read_b128 v[108:111], v145 offset:320
	s_waitcnt lgkmcnt(0)
	v_mfma_f32_16x16x32_bf16 v[104:107], v[108:111], v[92:95], v[104:107]
	ds_read_b128 v[108:111], v145 offset:384
	s_waitcnt lgkmcnt(0)
	v_mfma_f32_16x16x32_bf16 v[104:107], v[108:111], v[96:99], v[104:107]
	ds_read_b128 v[108:111], v145 offset:448
	s_waitcnt lgkmcnt(0)
	v_mfma_f32_16x16x32_bf16 v[106:109], v[108:111], v[100:103], v[104:107]
	s_nop 7
	v_pk_mul_f32 v[104:105], v[108:109], v[116:117] op_sel_hi:[1,0]
	ds_read_b128 v[108:111], v145 offset:8448
	s_waitcnt lgkmcnt(0)
	v_mfma_f32_16x16x32_bf16 v[108:111], v[108:111], v[84:87], 0
	v_mul_f32_e64 v106, v106, v116
	v_mul_f32_e64 v107, v107, v116
	v_mfma_f32_16x16x32_bf16 v[108:111], v[112:115], v[80:83], v[108:111]
	ds_read_b128 v[112:115], v145 offset:8576
	s_waitcnt lgkmcnt(0)
	v_mfma_f32_16x16x32_bf16 v[108:111], v[112:115], v[12:15], v[108:111]
	ds_read_b128 v[112:115], v145 offset:8640
	s_waitcnt lgkmcnt(0)
; #define LAS __attribute__((address_space(3)))
; #define LAS __attribute__((address_space(3)))
; template <bool DO_SWA, bool DO_MEM>
; __device__ __forceinline__ void attn_unit(const Args& a, unsigned char* ws, LAS unsigned char* lds, int l, int tid_in, int lane_in, int wave, int unit) {
;     ...
;         if constexpr (DO_MEM) attn_core<16, 528, false>(lds + A_KS + g * 256 * 144 + fq * 16, lds + A_VT2 + (g * 64 + fr) * 528 + fq * 16, qmm[0][0], qmm[0][1], 0.f, 0u, fr, omem[0]);
;         __syncthreads();
;         if constexpr (DO_MEM)
; #pragma unroll
;         for (int i = 0; i < 8; ++i) {
;             const int chn = tid + 512 * i;
;             { const int key = chn >> 4, c16 = chn & 15; *(LAS v4u*)(lds + A_KS + ((c16 >> 3) * 256 + key) * 144 + (c16 & 7) * 16) = mkst[i]; }
;             { const int col = chn >> 5, kc = chn & 31; *(LAS v4u*)(lds + A_VT2 + col * 528 + kc * 16) = mvst[i]; }
;         }
;         __syncthreads();
;         if constexpr (DO_MEM) {
;             attn_core<16, 528, false>(lds + A_KS + g * 256 * 144 + fq * 16, lds + A_VT2 + (g * 64 + fr) * 528 + fq * 16, qmm[1][0], qmm[1][1], 0.f, 0u, fr, omem[1]);
	v_mfma_f32_16x16x32_bf16 v[108:111], v[112:115], v[8:11], v[108:111]
	ds_read_b128 v[112:115], v145 offset:8704
	s_waitcnt lgkmcnt(0)
	v_mfma_f32_16x16x32_bf16 v[108:111], v[112:115], v[88:91], v[108:111]
	ds_read_b128 v[112:115], v145 offset:8768
	s_waitcnt lgkmcnt(0)
	v_mfma_f32_16x16x32_bf16 v[108:111], v[112:115], v[92:95], v[108:111]
	ds_read_b128 v[112:115], v145 offset:8832
	s_waitcnt lgkmcnt(0)
	v_mfma_f32_16x16x32_bf16 v[108:111], v[112:115], v[96:99], v[108:111]
	ds_read_b128 v[112:115], v145 offset:8896
	s_waitcnt lgkmcnt(0)
	v_mfma_f32_16x16x32_bf16 v[110:113], v[112:115], v[100:103], v[108:111]
	s_nop 7
	v_pk_mul_f32 v[108:109], v[112:113], v[116:117] op_sel_hi:[1,0]
	ds_read_b128 v[112:115], v145 offset:16896
	s_waitcnt lgkmcnt(0)
	v_mfma_f32_16x16x32_bf16 v[112:115], v[112:115], v[84:87], 0
	v_mul_f32_e64 v110, v110, v116
	v_mul_f32_e64 v111, v111, v116
	v_mfma_f32_16x16x32_bf16 v[112:115], v[118:121], v[80:83], v[112:115]
	ds_read_b128 v[118:121], v145 offset:17024
	s_waitcnt lgkmcnt(0)
	v_mfma_f32_16x16x32_bf16 v[112:115], v[118:121], v[12:15], v[112:115]
	ds_read_b128 v[118:121], v145 offset:17088
	s_waitcnt lgkmcnt(0)
	v_mfma_f32_16x16x32_bf16 v[112:115], v[118:121], v[8:11], v[112:115]
	ds_read_b128 v[118:121], v145 offset:17152
	s_waitcnt lgkmcnt(0)
	v_mfma_f32_16x16x32_bf16 v[112:115], v[118:121], v[88:91], v[112:115]
	ds_read_b128 v[118:121], v145 offset:17216
	s_waitcnt lgkmcnt(0)
	v_mfma_f32_16x16x32_bf16 v[112:115], v[118:121], v[92:95], v[112:115]
	ds_read_b128 v[118:121], v145 offset:17280
	s_waitcnt lgkmcnt(0)
	v_mfma_f32_16x16x32_bf16 v[112:115], v[118:121], v[96:99], v[112:115]
	ds_read_b128 v[118:121], v145 offset:17344
	s_waitcnt lgkmcnt(0)
	v_mfma_f32_16x16x32_bf16 v[118:121], v[118:121], v[100:103], v[112:115]
	s_nop 7
	v_pk_mul_f32 v[112:113], v[116:117], v[120:121] op_sel_hi:[0,1]
	v_pk_mul_f32 v[114:115], v[116:117], v[118:119] op_sel_hi:[0,1]
	ds_read_b128 v[118:121], v145 offset:25344
	s_waitcnt lgkmcnt(0)
	v_mfma_f32_16x16x32_bf16 v[84:87], v[118:121], v[84:87], 0
	ds_read_b128 v[118:121], v145 offset:25408
	s_waitcnt lgkmcnt(0)
	v_mfma_f32_16x16x32_bf16 v[80:83], v[118:121], v[80:83], v[84:87]
	s_nop 4
	ds_read_b128 v[84:87], v145 offset:25472
	s_waitcnt lgkmcnt(0)
	v_mfma_f32_16x16x32_bf16 v[12:15], v[84:87], v[12:15], v[80:83]
	s_nop 2
	ds_read_b128 v[80:83], v145 offset:25536
	s_waitcnt lgkmcnt(0)
	v_mfma_f32_16x16x32_bf16 v[8:11], v[80:83], v[8:11], v[12:15]
	s_nop 2
	ds_read_b128 v[12:15], v145 offset:25600
	s_waitcnt lgkmcnt(0)
	v_mfma_f32_16x16x32_bf16 v[8:11], v[12:15], v[88:91], v[8:11]
	ds_read_b128 v[12:15], v145 offset:25664
	s_waitcnt lgkmcnt(0)
	v_mfma_f32_16x16x32_bf16 v[8:11], v[12:15], v[92:95], v[8:11]
	ds_read_b128 v[12:15], v145 offset:25728
	s_waitcnt lgkmcnt(0)
	v_mfma_f32_16x16x32_bf16 v[8:11], v[12:15], v[96:99], v[8:11]
	ds_read_b128 v[12:15], v145 offset:25792
	s_waitcnt lgkmcnt(0)
	s_barrier
	v_mfma_f32_16x16x32_bf16 v[8:11], v[12:15], v[100:103], v[8:11]
	s_waitcnt vmcnt(31)
	ds_write_b128 v142, v[16:19]
	s_waitcnt vmcnt(30)
	ds_write_b128 v144, v[20:23]
	s_waitcnt vmcnt(29)
	ds_write_b128 v146, v[24:27]
	s_waitcnt vmcnt(28)
	ds_write_b128 v148, v[28:31]
	s_waitcnt vmcnt(27)
	ds_write_b128 v150, v[32:35]
	s_waitcnt vmcnt(26)
	ds_write_b128 v152, v[36:39]
	s_waitcnt vmcnt(25)
	ds_write_b128 v156, v[40:43]
	s_waitcnt vmcnt(24)
	ds_write_b128 v158, v[44:47]
	s_waitcnt vmcnt(23)
	ds_write_b128 v160, v[48:51]
	s_waitcnt vmcnt(22)
	ds_write_b128 v162, v[52:55]
	s_waitcnt vmcnt(21)
	ds_write_b128 v164, v[56:59]
	s_waitcnt vmcnt(20)
	ds_write_b128 v166, v[60:63]
	s_waitcnt vmcnt(19)
	ds_write_b128 v168, v[64:67]
	s_waitcnt vmcnt(18)
	ds_write_b128 v170, v[68:71]
	s_waitcnt vmcnt(17)
	ds_write_b128 v172, v[72:75]
	s_waitcnt vmcnt(16)
	ds_write_b128 v174, v[76:79]
	s_waitcnt lgkmcnt(0)
	v_pk_mul_f32 v[80:81], v[116:117], v[10:11] op_sel_hi:[0,1]
	v_pk_mul_f32 v[82:83], v[116:117], v[8:9] op_sel_hi:[0,1]
	s_barrier
	s_waitcnt lgkmcnt(0)
	ds_read_b128 v[84:87], v147
	ds_read_b128 v[88:91], v147 offset:64
	ds_read_b128 v[92:95], v147 offset:576
	ds_read_b128 v[196:199], v147 offset:640
	ds_read_b128 v[200:203], v147 offset:4608
	ds_read_b128 v[204:207], v147 offset:4672
	ds_read_b128 v[228:231], v147 offset:5184
	ds_read_b128 v[232:235], v147 offset:5248
	ds_read_b128 v[236:239], v147 offset:9216
	ds_read_b128 v[240:243], v147 offset:9280
	ds_read_b128 v[244:247], v147 offset:9792
	s_waitcnt lgkmcnt(10)
	v_mfma_f32_16x16x32_bf16 v[8:11], v[84:87], v[4:7], 0
	s_waitcnt lgkmcnt(9)
	v_mfma_f32_16x16x32_bf16 v[64:67], v[88:91], v[0:3], v[8:11]
	ds_read_b128 v[84:87], v147 offset:9856
	ds_read_b128 v[88:91], v147 offset:13824
	s_waitcnt lgkmcnt(10)
	v_mfma_f32_16x16x32_bf16 v[8:11], v[92:95], v[4:7], 0
	s_waitcnt lgkmcnt(9)
	v_mfma_f32_16x16x32_bf16 v[60:63], v[196:199], v[0:3], v[8:11]
	ds_read_b128 v[92:95], v147 offset:13888
	ds_read_b128 v[196:199], v147 offset:14400
	s_waitcnt lgkmcnt(10)
	v_mfma_f32_16x16x32_bf16 v[8:11], v[200:203], v[4:7], 0
	s_waitcnt lgkmcnt(9)
	v_mfma_f32_16x16x32_bf16 v[20:23], v[204:207], v[0:3], v[8:11]
	ds_read_b128 v[200:203], v147 offset:14464
	ds_read_b128 v[204:207], v147 offset:18432
	s_waitcnt lgkmcnt(10)
	v_mfma_f32_16x16x32_bf16 v[8:11], v[228:231], v[4:7], 0
	s_waitcnt lgkmcnt(9)
	v_mfma_f32_16x16x32_bf16 v[12:15], v[232:235], v[0:3], v[8:11]
	ds_read_b128 v[228:231], v147 offset:18496
	ds_read_b128 v[232:235], v147 offset:19008
	s_waitcnt lgkmcnt(10)
	v_mfma_f32_16x16x32_bf16 v[8:11], v[236:239], v[4:7], 0
	s_waitcnt lgkmcnt(9)
	v_mfma_f32_16x16x32_bf16 v[8:11], v[240:243], v[0:3], v[8:11]
	ds_read_b128 v[236:239], v147 offset:19072
	ds_read_b128 v[240:243], v147 offset:23040
	s_waitcnt lgkmcnt(10)
; #define LAS __attribute__((address_space(3)))
; #define LAS __attribute__((address_space(3)))
; __device__ __forceinline__ f32x4 mfma16(bf16x8 a, bf16x8 b, f32x4 c) { return __builtin_amdgcn_mfma_f32_16x16x32_bf16(a, b, c, 0, 0, 0); }
; template <int NKT, int VSTR, bool SINK>
; __device__ __forceinline__ void attn_core(LAS const unsigned char* kb_, LAS const unsigned char* vb_, bf16x8 q0, bf16x8 q1, float sk, unsigned mskbits, int fr, f32x4 (&o)[4]) {
;     ...
;     for (int kt = 0; kt < NKT; ++kt) {
;         const int key = (kt >> 1) * 32 + ((kt & 1) << 2) + krow;
;         LAS const unsigned char* kp = kb_ + key * 144;
;         const bf16x8 a0 = *(LAS const bf16x8*)kp, a1 = *(LAS const bf16x8*)(kp + 64);
;         const float bias = ((mskbits >> (kt >> 2)) & 1u) ? -1e30f : 0.f;
;         f32x4 s = mfma16(a0, q0, (f32x4){bias, bias, bias, bias});
;         s = mfma16(a1, q1, s);
;         S[kt] = s;
;     }
;     float mx = S[0][0];
; #pragma unroll
;     for (int kt = 0; kt < NKT; ++kt) mx = fmaxf(fmaxf(mx, fmaxf(S[kt][0], S[kt][1])), fmaxf(S[kt][2], S[kt][3]));
;     mx = fmaxf(mx, __shfl_xor(mx, 16)); mx = fmaxf(mx, __shfl_xor(mx, 32));
;     if (SINK) mx = fmaxf(mx, sk);
;     float sum = 0.f;
; #pragma unroll
;     for (int kt = 0; kt < NKT; ++kt)
; #pragma unroll
;         for (int r = 0; r < 4; ++r) { const float p = __builtin_amdgcn_exp2f(S[kt][r] - mx); S[kt][r] = p; sum += p; }
	v_mfma_f32_16x16x32_bf16 v[16:19], v[244:247], v[4:7], 0
	s_waitcnt lgkmcnt(9)
	v_mfma_f32_16x16x32_bf16 v[16:19], v[84:87], v[0:3], v[16:19]
	ds_read_b128 v[244:247], v147 offset:23104
	ds_read_b128 v[84:87], v147 offset:23616
	s_waitcnt lgkmcnt(10)
	v_mfma_f32_16x16x32_bf16 v[24:27], v[88:91], v[4:7], 0
	s_waitcnt lgkmcnt(9)
	v_mfma_f32_16x16x32_bf16 v[24:27], v[92:95], v[0:3], v[24:27]
	ds_read_b128 v[88:91], v147 offset:23680
	ds_read_b128 v[92:95], v147 offset:27648
	s_waitcnt lgkmcnt(10)
	v_mfma_f32_16x16x32_bf16 v[28:31], v[196:199], v[4:7], 0
	s_waitcnt lgkmcnt(9)
	v_mfma_f32_16x16x32_bf16 v[28:31], v[200:203], v[0:3], v[28:31]
	ds_read_b128 v[196:199], v147 offset:27712
	ds_read_b128 v[200:203], v147 offset:28224
	s_waitcnt lgkmcnt(10)
	v_mfma_f32_16x16x32_bf16 v[32:35], v[204:207], v[4:7], 0
	s_waitcnt lgkmcnt(9)
	v_mfma_f32_16x16x32_bf16 v[32:35], v[228:231], v[0:3], v[32:35]
	ds_read_b128 v[204:207], v147 offset:28288
	ds_read_b128 v[228:231], v147 offset:32256
	s_waitcnt lgkmcnt(10)
	v_mfma_f32_16x16x32_bf16 v[36:39], v[232:235], v[4:7], 0
	s_waitcnt lgkmcnt(9)
	v_mfma_f32_16x16x32_bf16 v[36:39], v[236:239], v[0:3], v[36:39]
	ds_read_b128 v[232:235], v147 offset:32320
	ds_read_b128 v[236:239], v147 offset:32832
	s_waitcnt lgkmcnt(10)
	v_mfma_f32_16x16x32_bf16 v[40:43], v[240:243], v[4:7], 0
	s_waitcnt lgkmcnt(9)
	v_mfma_f32_16x16x32_bf16 v[40:43], v[244:247], v[0:3], v[40:43]
	ds_read_b128 v[240:243], v147 offset:32896
	s_waitcnt lgkmcnt(9)
	v_mfma_f32_16x16x32_bf16 v[44:47], v[84:87], v[4:7], 0
	s_waitcnt lgkmcnt(8)
	v_mfma_f32_16x16x32_bf16 v[48:51], v[88:91], v[0:3], v[44:47]
	s_waitcnt lgkmcnt(7)
	v_mfma_f32_16x16x32_bf16 v[44:47], v[92:95], v[4:7], 0
	s_waitcnt lgkmcnt(6)
	v_mfma_f32_16x16x32_bf16 v[52:55], v[196:199], v[0:3], v[44:47]
	s_waitcnt lgkmcnt(5)
	v_mfma_f32_16x16x32_bf16 v[44:47], v[200:203], v[4:7], 0
	s_waitcnt lgkmcnt(4)
	v_mfma_f32_16x16x32_bf16 v[56:59], v[204:207], v[0:3], v[44:47]
	s_waitcnt lgkmcnt(3)
	v_mfma_f32_16x16x32_bf16 v[44:47], v[228:231], v[4:7], 0
	s_waitcnt lgkmcnt(2)
	v_mfma_f32_16x16x32_bf16 v[44:47], v[232:235], v[0:3], v[44:47]
	s_waitcnt lgkmcnt(1)
	v_mfma_f32_16x16x32_bf16 v[4:7], v[236:239], v[4:7], 0
	s_waitcnt lgkmcnt(0)
	v_mfma_f32_16x16x32_bf16 v[0:3], v[240:243], v[0:3], v[4:7]
	s_nop 5
	s_nop 0
	s_nop 0
	v_max_f32_e32 v4, v66, v67
	s_nop 0
	s_nop 0
	v_max_f32_e32 v5, v60, v61
	s_nop 0
	s_nop 0
	v_max3_f32 v4, v64, v65, v4
	v_max_f32_e32 v6, v62, v63
	v_max3_f32 v4, v4, v5, v6
	s_nop 0
	s_nop 0
	v_max_f32_e32 v5, v20, v21
	s_nop 0
	s_nop 0
	v_max_f32_e32 v6, v22, v23
	v_max3_f32 v4, v4, v5, v6
	s_nop 0
	s_nop 0
	v_max_f32_e32 v5, v12, v13
	s_nop 0
	s_nop 0
	v_max_f32_e32 v6, v14, v15
	v_max3_f32 v4, v4, v5, v6
	v_max_f32_e32 v5, v8, v9
	v_max_f32_e32 v6, v10, v11
	v_max3_f32 v4, v4, v5, v6
	v_max_f32_e32 v5, v16, v17
	v_max_f32_e32 v6, v18, v19
	v_max3_f32 v4, v4, v5, v6
	v_max_f32_e32 v5, v24, v25
	v_max_f32_e32 v6, v26, v27
	v_max3_f32 v4, v4, v5, v6
	v_max_f32_e32 v5, v28, v29
	v_max_f32_e32 v6, v30, v31
	v_max3_f32 v4, v4, v5, v6
	v_max_f32_e32 v5, v32, v33
	v_max_f32_e32 v6, v34, v35
	v_max3_f32 v4, v4, v5, v6
	v_max_f32_e32 v5, v36, v37
	v_max_f32_e32 v6, v38, v39
	v_max3_f32 v4, v4, v5, v6
	v_max_f32_e32 v5, v40, v41
	v_max_f32_e32 v6, v42, v43
	v_max3_f32 v4, v4, v5, v6
	v_max_f32_e32 v5, v48, v49
	v_max_f32_e32 v6, v50, v51
	v_max3_f32 v4, v4, v5, v6
	v_max_f32_e32 v5, v52, v53
	v_max_f32_e32 v6, v54, v55
	v_max3_f32 v4, v4, v5, v6
	v_max_f32_e32 v5, v56, v57
	v_max_f32_e32 v6, v58, v59
	v_max3_f32 v4, v4, v5, v6
	v_max_f32_e32 v5, v44, v45
	v_max_f32_e32 v6, v46, v47
	v_max3_f32 v4, v4, v5, v6
	v_max_f32_e32 v5, v0, v1
	v_max_f32_e32 v6, v2, v3
	v_max3_f32 v4, v4, v5, v6
	ds_bpermute_b32 v5, v212, v4
	s_waitcnt lgkmcnt(0)
	s_nop 0
	v_max_f32_e32 v4, v4, v5
	ds_bpermute_b32 v5, v176, v4
	s_waitcnt lgkmcnt(0)
	s_nop 0
	v_max_f32_e32 v7, v4, v5
	v_sub_f32_e32 v4, v64, v7
	v_exp_f32_e32 v4, v4
	v_sub_f32_e32 v5, v65, v7
	v_exp_f32_e32 v5, v5
	v_sub_f32_e32 v60, v60, v7
	v_add_f32_e32 v6, 0, v4
	v_exp_f32_e32 v60, v60
	v_add_f32_e32 v64, v5, v6
	v_sub_f32_e32 v6, v66, v7
	v_exp_f32_e32 v6, v6
	v_sub_f32_e32 v61, v61, v7
	v_exp_f32_e32 v61, v61
	v_sub_f32_e32 v62, v62, v7
	v_add_f32_e32 v65, v6, v64
	v_sub_f32_e32 v64, v67, v7
	v_exp_f32_e32 v64, v64
	v_exp_f32_e32 v62, v62
	v_sub_f32_e32 v63, v63, v7
	v_exp_f32_e32 v63, v63
	v_add_f32_e32 v65, v64, v65
	v_sub_f32_e32 v20, v20, v7
	v_add_f32_e32 v65, v60, v65
	v_exp_f32_e32 v20, v20
	v_sub_f32_e32 v21, v21, v7
	v_add_f32_e32 v65, v61, v65
	v_exp_f32_e32 v21, v21
	v_sub_f32_e32 v22, v22, v7
	v_add_f32_e32 v65, v62, v65
	v_exp_f32_e32 v22, v22
	v_sub_f32_e32 v23, v23, v7
	v_add_f32_e32 v65, v63, v65
	v_exp_f32_e32 v23, v23
	v_sub_f32_e32 v12, v12, v7
	v_add_f32_e32 v65, v20, v65
	v_exp_f32_e32 v12, v12
	v_sub_f32_e32 v13, v13, v7
	v_add_f32_e32 v65, v21, v65
	v_exp_f32_e32 v13, v13
	v_sub_f32_e32 v14, v14, v7
	v_add_f32_e32 v65, v22, v65
	v_exp_f32_e32 v14, v14
	v_sub_f32_e32 v15, v15, v7
	v_add_f32_e32 v65, v23, v65
	v_exp_f32_e32 v15, v15
	v_sub_f32_e32 v8, v8, v7
	v_add_f32_e32 v65, v12, v65
	v_exp_f32_e32 v8, v8
	v_sub_f32_e32 v9, v9, v7
	v_add_f32_e32 v65, v13, v65
	v_exp_f32_e32 v9, v9
	v_sub_f32_e32 v10, v10, v7
	v_add_f32_e32 v65, v14, v65
	v_exp_f32_e32 v10, v10
	v_sub_f32_e32 v11, v11, v7
	v_add_f32_e32 v65, v15, v65
	v_exp_f32_e32 v11, v11
	v_sub_f32_e32 v16, v16, v7
	v_add_f32_e32 v65, v8, v65
	v_exp_f32_e32 v16, v16
	v_sub_f32_e32 v17, v17, v7
	v_add_f32_e32 v65, v9, v65
	v_exp_f32_e32 v17, v17
	v_sub_f32_e32 v18, v18, v7
	v_add_f32_e32 v65, v10, v65
	v_exp_f32_e32 v18, v18
	v_sub_f32_e32 v19, v19, v7
; #define LAS __attribute__((address_space(3)))
; #define LAS __attribute__((address_space(3)))
; __device__ __forceinline__ unsigned pk2(float lo, float hi) { return pg8::cvt_pk_bf16(lo, hi); }
; __device__ __forceinline__ f32x4 mfma16(bf16x8 a, bf16x8 b, f32x4 c) { return __builtin_amdgcn_mfma_f32_16x16x32_bf16(a, b, c, 0, 0, 0); }
; template <int NKT, int VSTR, bool SINK>
; __device__ __forceinline__ void attn_core(LAS const unsigned char* kb_, LAS const unsigned char* vb_, bf16x8 q0, bf16x8 q1, float sk, unsigned mskbits, int fr, f32x4 (&o)[4]) {
;     ...
; #pragma unroll
;     for (int kt = 0; kt < NKT; ++kt)
; #pragma unroll
;         for (int r = 0; r < 4; ++r) { const float p = __builtin_amdgcn_exp2f(S[kt][r] - mx); S[kt][r] = p; sum += p; }
;     sum += __shfl_xor(sum, 16); sum += __shfl_xor(sum, 32);
;     if (SINK) sum += __builtin_amdgcn_exp2f(sk - mx);
;     const float inv = 1.0f / sum;
;     bf16x8 pf[NKT / 2];
; #pragma unroll
;     for (int kb = 0; kb < NKT / 2; ++kb) {
;         v4u w; w.x = pk2(S[2 * kb][0], S[2 * kb][1]); w.y = pk2(S[2 * kb][2], S[2 * kb][3]); w.z = pk2(S[2 * kb + 1][0], S[2 * kb + 1][1]); w.w = pk2(S[2 * kb + 1][2], S[2 * kb + 1][3]);
;         pf[kb] = __builtin_bit_cast(bf16x8, w);
;     }
; #pragma unroll
;     for (int dt = 0; dt < 4; ++dt) {
;         f32x4 acc = (f32x4){0.f, 0.f, 0.f, 0.f};
; #pragma unroll
;         for (int kb = 0; kb < NKT / 2; ++kb) {
;             const bf16x8 vf = *(LAS const bf16x8*)(vb_ + dt * 16 * VSTR + kb * 64);
;             acc = mfma16(vf, pf[kb], acc);
;         }
;         o[dt] = acc * inv;
;     }
	v_add_f32_e32 v65, v11, v65
	v_exp_f32_e32 v19, v19
	v_sub_f32_e32 v24, v24, v7
	v_add_f32_e32 v65, v16, v65
	v_exp_f32_e32 v66, v24
	v_add_f32_e32 v65, v17, v65
	v_add_f32_e32 v65, v18, v65
	v_add_f32_e32 v65, v19, v65
	v_sub_f32_e32 v25, v25, v7
	v_add_f32_e32 v24, v66, v65
	v_exp_f32_e32 v65, v25
	v_sub_f32_e32 v25, v26, v7
	v_exp_f32_e32 v67, v25
	v_sub_f32_e32 v25, v27, v7
	v_exp_f32_e32 v68, v25
	v_sub_f32_e32 v25, v28, v7
	v_exp_f32_e32 v69, v25
	v_sub_f32_e32 v25, v29, v7
	v_add_f32_e32 v24, v65, v24
	v_exp_f32_e32 v70, v25
	v_sub_f32_e32 v25, v30, v7
	v_add_f32_e32 v24, v67, v24
	v_exp_f32_e32 v71, v25
	v_sub_f32_e32 v25, v31, v7
	v_add_f32_e32 v24, v68, v24
	v_exp_f32_e32 v72, v25
	v_sub_f32_e32 v25, v32, v7
	v_add_f32_e32 v24, v69, v24
	v_exp_f32_e32 v32, v25
	v_sub_f32_e32 v25, v33, v7
	v_add_f32_e32 v24, v70, v24
	v_exp_f32_e32 v33, v25
	v_sub_f32_e32 v25, v34, v7
	v_add_f32_e32 v24, v71, v24
	v_exp_f32_e32 v34, v25
	v_sub_f32_e32 v25, v35, v7
	v_add_f32_e32 v24, v72, v24
	v_exp_f32_e32 v35, v25
	v_sub_f32_e32 v25, v36, v7
	v_add_f32_e32 v24, v32, v24
	v_exp_f32_e32 v36, v25
	v_sub_f32_e32 v25, v37, v7
	v_add_f32_e32 v24, v33, v24
	v_exp_f32_e32 v37, v25
	v_sub_f32_e32 v25, v38, v7
	v_add_f32_e32 v24, v34, v24
	v_exp_f32_e32 v38, v25
	v_sub_f32_e32 v25, v39, v7
	v_add_f32_e32 v24, v35, v24
	v_exp_f32_e32 v39, v25
	v_sub_f32_e32 v25, v40, v7
	v_add_f32_e32 v24, v36, v24
	v_exp_f32_e32 v40, v25
	v_sub_f32_e32 v25, v41, v7
	v_add_f32_e32 v24, v37, v24
	v_exp_f32_e32 v41, v25
	v_sub_f32_e32 v25, v42, v7
	v_add_f32_e32 v24, v38, v24
	v_exp_f32_e32 v42, v25
	v_sub_f32_e32 v25, v43, v7
	v_add_f32_e32 v24, v39, v24
	v_exp_f32_e32 v43, v25
	v_sub_f32_e32 v25, v48, v7
	v_add_f32_e32 v24, v40, v24
	v_exp_f32_e32 v48, v25
	v_sub_f32_e32 v25, v49, v7
	v_add_f32_e32 v24, v41, v24
	v_exp_f32_e32 v49, v25
	v_sub_f32_e32 v25, v50, v7
	v_add_f32_e32 v24, v42, v24
	v_exp_f32_e32 v50, v25
	v_sub_f32_e32 v25, v51, v7
	v_add_f32_e32 v24, v43, v24
	v_exp_f32_e32 v51, v25
	v_sub_f32_e32 v25, v52, v7
	v_add_f32_e32 v24, v48, v24
	v_exp_f32_e32 v52, v25
	v_sub_f32_e32 v25, v53, v7
	v_add_f32_e32 v24, v49, v24
	v_exp_f32_e32 v53, v25
	v_sub_f32_e32 v25, v54, v7
	v_add_f32_e32 v24, v50, v24
	v_exp_f32_e32 v54, v25
	v_sub_f32_e32 v25, v55, v7
	v_add_f32_e32 v24, v51, v24
	v_exp_f32_e32 v55, v25
	v_sub_f32_e32 v25, v56, v7
	v_add_f32_e32 v24, v52, v24
	v_exp_f32_e32 v56, v25
	v_sub_f32_e32 v25, v57, v7
	v_add_f32_e32 v24, v53, v24
	v_exp_f32_e32 v57, v25
	v_sub_f32_e32 v25, v58, v7
	v_add_f32_e32 v24, v54, v24
	v_exp_f32_e32 v58, v25
	v_sub_f32_e32 v25, v59, v7
	v_add_f32_e32 v24, v55, v24
	v_exp_f32_e32 v59, v25
	v_sub_f32_e32 v25, v44, v7
	v_add_f32_e32 v24, v56, v24
	v_exp_f32_e32 v44, v25
	v_sub_f32_e32 v25, v45, v7
	v_add_f32_e32 v24, v57, v24
	v_exp_f32_e32 v45, v25
	v_sub_f32_e32 v25, v46, v7
	v_add_f32_e32 v24, v58, v24
	v_exp_f32_e32 v46, v25
	v_sub_f32_e32 v25, v47, v7
	v_add_f32_e32 v24, v59, v24
	v_exp_f32_e32 v47, v25
	v_sub_f32_e32 v0, v0, v7
	v_add_f32_e32 v24, v44, v24
	v_exp_f32_e32 v73, v0
	v_sub_f32_e32 v1, v1, v7
	v_add_f32_e32 v24, v45, v24
	v_exp_f32_e32 v74, v1
	v_sub_f32_e32 v1, v2, v7
	v_add_f32_e32 v24, v46, v24
	v_exp_f32_e32 v75, v1
	v_sub_f32_e32 v1, v3, v7
	v_add_f32_e32 v24, v47, v24
	v_exp_f32_e32 v3, v1
	v_add_f32_e32 v0, v73, v24
	v_add_f32_e32 v0, v74, v0
	v_add_f32_e32 v0, v75, v0
	v_add_f32_e32 v0, v3, v0
	ds_bpermute_b32 v1, v212, v0
	v_cvt_pk_bf16_f32 v28, v4, v5
	v_cvt_pk_bf16_f32 v29, v6, v64
	v_cvt_pk_bf16_f32 v30, v60, v61
	v_cvt_pk_bf16_f32 v31, v62, v63
	s_waitcnt lgkmcnt(0)
	v_add_f32_e32 v0, v0, v1
	ds_bpermute_b32 v1, v176, v0
	v_cvt_pk_bf16_f32 v24, v20, v21
	v_cvt_pk_bf16_f32 v25, v22, v23
	v_cvt_pk_bf16_f32 v26, v12, v13
	v_cvt_pk_bf16_f32 v27, v14, v15
	s_waitcnt lgkmcnt(0)
	v_add_f32_e32 v76, v0, v1
	v_cvt_pk_bf16_f32 v20, v8, v9
	v_cvt_pk_bf16_f32 v21, v10, v11
	v_cvt_pk_bf16_f32 v22, v16, v17
	v_cvt_pk_bf16_f32 v23, v18, v19
	v_cvt_pk_bf16_f32 v16, v66, v65
	v_cvt_pk_bf16_f32 v17, v67, v68
	v_cvt_pk_bf16_f32 v18, v69, v70
	v_cvt_pk_bf16_f32 v19, v71, v72
	v_cvt_pk_bf16_f32 v12, v32, v33
	v_div_scale_f32 v32, s[0:1], v76, v76, 1.0
	v_rcp_f32_e32 v33, v32
	v_cvt_pk_bf16_f32 v13, v34, v35
	v_cvt_pk_bf16_f32 v14, v36, v37
	v_cvt_pk_bf16_f32 v15, v38, v39
	v_cvt_pk_bf16_f32 v8, v40, v41
	v_cvt_pk_bf16_f32 v9, v42, v43
	s_nop 0
	v_fma_f32 v34, -v32, v33, 1.0
	v_fmac_f32_e32 v33, v34, v33
	v_div_scale_f32 v34, vcc, 1.0, v76, 1.0
	v_mul_f32_e32 v35, v34, v33
	v_fma_f32 v36, -v32, v35, v34
	v_fmac_f32_e32 v35, v36, v33
	v_fma_f32 v32, -v32, v35, v34
	v_div_fmas_f32 v32, v32, v33, v35
	v_cvt_pk_bf16_f32 v10, v48, v49
	v_cvt_pk_bf16_f32 v11, v50, v51
	v_cvt_pk_bf16_f32 v4, v52, v53
	v_cvt_pk_bf16_f32 v5, v54, v55
	v_cvt_pk_bf16_f32 v6, v56, v57
	v_cvt_pk_bf16_f32 v7, v58, v59
	v_cvt_pk_bf16_f32 v0, v44, v45
	v_cvt_pk_bf16_f32 v1, v46, v47
	v_cvt_pk_bf16_f32 v2, v73, v74
	v_cvt_pk_bf16_f32 v3, v75, v3
	v_div_fixup_f32 v36, v32, v76, 1.0
	s_waitcnt lgkmcnt(0)
	ds_read_b128 v[60:63], v145
	ds_read_b128 v[64:67], v145 offset:64
	ds_read_b128 v[68:71], v145 offset:8512
	ds_read_b128 v[84:87], v145 offset:16960
	ds_read_b128 v[88:91], v145 offset:128
	ds_read_b128 v[92:95], v145 offset:192
	ds_read_b128 v[196:199], v145 offset:256
	ds_read_b128 v[200:203], v145 offset:320
	ds_read_b128 v[204:207], v145 offset:384
	ds_read_b128 v[228:231], v145 offset:448
	ds_read_b128 v[232:235], v145 offset:8448
	ds_read_b128 v[236:239], v145 offset:8576
	ds_read_b128 v[240:243], v145 offset:8640
	ds_read_b128 v[244:247], v145 offset:8704
	s_waitcnt lgkmcnt(13)
; __device__ __forceinline__ float quad_sum(float s) { s += __shfl_xor(s, 16); s += __shfl_xor(s, 32); return s; }
; __device__ __forceinline__ float sq4(const f32x4 a) { return (a[0] * a[0] + a[1] * a[1]) + (a[2] * a[2] + a[3] * a[3]); }
; template <bool DO_SWA, bool DO_MEM>
; __device__ __forceinline__ void attn_unit(const Args& a, unsigned char* ws, LAS unsigned char* lds, int l, int tid_in, int lane_in, int wave, int unit) {
;     ...
;             attn_core<16, 528, false>(lds + A_KS + g * 256 * 144 + fq * 16, lds + A_VT2 + (g * 64 + fr) * 528 + fq * 16, qmm[1][0], qmm[1][1], 0.f, 0u, fr, omem[1]);
;             float ssq = 0.f;
; #pragma unroll
;             for (int hp = 0; hp < 2; ++hp)
; #pragma unroll
;                 for (int dt = 0; dt < 4; ++dt) ssq += pg8::sq4(omem[hp][dt]);
;             ssq = pg8::quad_sum(ssq);
;             if (fq == 0) red_m[g * 64 + qs * 16 + fr] = ssq;
	v_mfma_f32_16x16x32_bf16 v[32:35], v[60:63], v[28:31], 0
	ds_read_b128 v[60:63], v145 offset:8768
	s_waitcnt lgkmcnt(13)
	v_mfma_f32_16x16x32_bf16 v[32:35], v[64:67], v[24:27], v[32:35]
	ds_read_b128 v[64:67], v145 offset:8832
	s_waitcnt lgkmcnt(11)
	v_mfma_f32_16x16x32_bf16 v[32:35], v[88:91], v[20:23], v[32:35]
	ds_read_b128 v[88:91], v145 offset:8896
	s_waitcnt lgkmcnt(11)
	v_mfma_f32_16x16x32_bf16 v[32:35], v[92:95], v[16:19], v[32:35]
	ds_read_b128 v[92:95], v145 offset:16896
	s_waitcnt lgkmcnt(11)
	v_mfma_f32_16x16x32_bf16 v[32:35], v[196:199], v[12:15], v[32:35]
	ds_read_b128 v[196:199], v145 offset:17024
	s_waitcnt lgkmcnt(11)
	v_mfma_f32_16x16x32_bf16 v[32:35], v[200:203], v[8:11], v[32:35]
	ds_read_b128 v[200:203], v145 offset:17088
	s_waitcnt lgkmcnt(11)
	v_mfma_f32_16x16x32_bf16 v[32:35], v[204:207], v[4:7], v[32:35]
	ds_read_b128 v[204:207], v145 offset:17152
	s_waitcnt lgkmcnt(11)
	v_mfma_f32_16x16x32_bf16 v[38:41], v[228:231], v[0:3], v[32:35]
	ds_read_b128 v[228:231], v145 offset:17216
	s_nop 7
	v_pk_mul_f32 v[32:33], v[40:41], v[36:37] op_sel_hi:[1,0]
	v_pk_mul_f32 v[34:35], v[38:39], v[36:37] op_sel_hi:[1,0]
	s_waitcnt lgkmcnt(11)
	v_mfma_f32_16x16x32_bf16 v[38:41], v[232:235], v[28:31], 0
	ds_read_b128 v[232:235], v145 offset:17280
	v_mfma_f32_16x16x32_bf16 v[38:41], v[68:71], v[24:27], v[38:41]
	ds_read_b128 v[68:71], v145 offset:17344
	s_waitcnt lgkmcnt(12)
	v_mfma_f32_16x16x32_bf16 v[38:41], v[236:239], v[20:23], v[38:41]
	ds_read_b128 v[236:239], v145 offset:25344
	s_waitcnt lgkmcnt(12)
	v_mfma_f32_16x16x32_bf16 v[38:41], v[240:243], v[16:19], v[38:41]
	ds_read_b128 v[240:243], v145 offset:25408
	s_waitcnt lgkmcnt(12)
	v_mfma_f32_16x16x32_bf16 v[38:41], v[244:247], v[12:15], v[38:41]
	ds_read_b128 v[244:247], v145 offset:25472
	s_waitcnt lgkmcnt(12)
	v_mfma_f32_16x16x32_bf16 v[38:41], v[60:63], v[8:11], v[38:41]
	ds_read_b128 v[60:63], v145 offset:25536
	s_waitcnt lgkmcnt(12)
	v_mfma_f32_16x16x32_bf16 v[38:41], v[64:67], v[4:7], v[38:41]
	ds_read_b128 v[64:67], v145 offset:25600
	s_waitcnt lgkmcnt(12)
	v_mfma_f32_16x16x32_bf16 v[40:43], v[88:91], v[0:3], v[38:41]
	s_nop 7
	v_pk_mul_f32 v[38:39], v[42:43], v[36:37] op_sel_hi:[1,0]
	ds_read_b128 v[88:91], v145 offset:25664
	s_waitcnt lgkmcnt(12)
	v_mfma_f32_16x16x32_bf16 v[42:45], v[92:95], v[28:31], 0
	v_mul_f32_e64 v40, v40, v36
	v_mul_f32_e64 v41, v41, v36
	v_mfma_f32_16x16x32_bf16 v[42:45], v[84:87], v[24:27], v[42:45]
	ds_read_b128 v[92:95], v145 offset:25728
	s_waitcnt lgkmcnt(12)
	v_mfma_f32_16x16x32_bf16 v[42:45], v[196:199], v[20:23], v[42:45]
	ds_read_b128 v[84:87], v145 offset:25792
	s_waitcnt lgkmcnt(12)
	v_mfma_f32_16x16x32_bf16 v[42:45], v[200:203], v[16:19], v[42:45]
	s_waitcnt lgkmcnt(11)
	v_mfma_f32_16x16x32_bf16 v[42:45], v[204:207], v[12:15], v[42:45]
	s_waitcnt lgkmcnt(10)
	v_mfma_f32_16x16x32_bf16 v[42:45], v[228:231], v[8:11], v[42:45]
	s_waitcnt lgkmcnt(9)
	v_mfma_f32_16x16x32_bf16 v[42:45], v[232:235], v[4:7], v[42:45]
	s_waitcnt lgkmcnt(8)
	v_mfma_f32_16x16x32_bf16 v[44:47], v[68:71], v[0:3], v[42:45]
	s_nop 7
	v_pk_mul_f32 v[42:43], v[36:37], v[46:47] op_sel_hi:[0,1]
	s_waitcnt lgkmcnt(7)
	v_mfma_f32_16x16x32_bf16 v[28:31], v[236:239], v[28:31], 0
	v_pk_mul_f32 v[44:45], v[36:37], v[44:45] op_sel_hi:[0,1]
	s_waitcnt lgkmcnt(6)
	v_mfma_f32_16x16x32_bf16 v[24:27], v[240:243], v[24:27], v[28:31]
	s_waitcnt lgkmcnt(5)
	v_mfma_f32_16x16x32_bf16 v[20:23], v[244:247], v[20:23], v[24:27]
	s_waitcnt lgkmcnt(4)
	v_mfma_f32_16x16x32_bf16 v[16:19], v[60:63], v[16:19], v[20:23]
	s_waitcnt lgkmcnt(3)
	v_mfma_f32_16x16x32_bf16 v[12:15], v[64:67], v[12:15], v[16:19]
	s_waitcnt lgkmcnt(2)
	v_mfma_f32_16x16x32_bf16 v[8:11], v[88:91], v[8:11], v[12:15]
	s_waitcnt lgkmcnt(1)
	v_mfma_f32_16x16x32_bf16 v[4:7], v[92:95], v[4:7], v[8:11]
	s_waitcnt lgkmcnt(0)
	v_mfma_f32_16x16x32_bf16 v[2:5], v[84:87], v[0:3], v[4:7]
	s_nop 2
	v_mul_f32_e32 v6, v109, v109
	v_fmac_f32_e32 v6, v108, v108
	s_nop 2
	v_pk_mul_f32 v[0:1], v[36:37], v[4:5] op_sel_hi:[0,1]
	v_mul_f32_e32 v4, v107, v107
	v_mul_f32_e32 v5, v105, v105
	v_fmac_f32_e32 v4, v106, v106
	v_fmac_f32_e32 v5, v104, v104
	v_add_f32_e32 v4, v4, v5
	v_mul_f32_e32 v5, v111, v111
	v_fmac_f32_e32 v5, v110, v110
	v_add_f32_e32 v5, v5, v6
	v_add_f32_e32 v4, v4, v5
	v_mul_f32_e32 v5, v115, v115
	v_mul_f32_e32 v6, v113, v113
	v_fmac_f32_e32 v5, v114, v114
	v_fmac_f32_e32 v6, v112, v112
	v_add_f32_e32 v5, v5, v6
	v_add_f32_e32 v4, v4, v5
	v_mul_f32_e32 v5, v83, v83
	v_mul_f32_e32 v6, v81, v81
	v_fmac_f32_e32 v5, v82, v82
	v_fmac_f32_e32 v6, v80, v80
	v_add_f32_e32 v5, v5, v6
	v_add_f32_e32 v4, v4, v5
	v_mul_f32_e32 v5, v35, v35
	v_mul_f32_e32 v6, v33, v33
	v_fmac_f32_e32 v5, v34, v34
	v_fmac_f32_e32 v6, v32, v32
	v_add_f32_e32 v5, v5, v6
	v_add_f32_e32 v4, v4, v5
	v_mul_f32_e32 v5, v41, v41
	v_mul_f32_e32 v6, v39, v39
	v_fmac_f32_e32 v5, v40, v40
	v_fmac_f32_e32 v6, v38, v38
	v_add_f32_e32 v5, v5, v6
	v_add_f32_e32 v4, v5, v4
	v_mul_f32_e32 v5, v45, v45
	v_mul_f32_e32 v6, v43, v43
	v_fmac_f32_e32 v5, v44, v44
	v_fmac_f32_e32 v6, v42, v42
	v_pk_mul_f32 v[2:3], v[36:37], v[2:3] op_sel_hi:[0,1]
	v_add_f32_e32 v5, v5, v6
	v_add_f32_e32 v4, v4, v5
	v_mul_f32_e32 v5, v3, v3
	v_mul_f32_e32 v6, v1, v1
	v_fmac_f32_e32 v5, v2, v2
	v_fmac_f32_e32 v6, v0, v0
	v_add_f32_e32 v5, v5, v6
	v_add_f32_e32 v4, v4, v5
	ds_bpermute_b32 v5, v212, v4
	s_waitcnt lgkmcnt(0)
	v_add_f32_e32 v4, v4, v5
	ds_bpermute_b32 v5, v176, v4
	s_and_saveexec_b64 s[0:1], s[36:37]
	s_cbranch_execz .LBB0_255
	v_readlane_b32 s2, v251, 26
	s_waitcnt lgkmcnt(0)
	v_add_f32_e32 v4, v4, v5
	v_lshl_add_u32 v6, v210, 2, s2
	ds_write_b32 v6, v4
	s_branch .LBB0_255
